# on top of merged K-loops: f32->bf16 bit-trick pairs (bfe/add3/shift/and_or, 6 VALU) replaced by one v_cvt_pk_bf16_f32 at 311 sites (same RNE rounding, identical outputs)
# speedup vs baseline: 1.0281x; 1.0162x over previous
.LBB0_199:
	ds_read2_b32 v[52:53], v89 offset1:65
	ds_read2_b32 v[78:79], v89 offset0:130 offset1:195
	s_ashr_i32 s28, s35, 31
	s_waitcnt lgkmcnt(1)
	s_nop 0
	v_cvt_pk_bf16_f32 v106, v52, v53
	s_nop 0
	s_nop 0
	s_waitcnt lgkmcnt(0)
	ds_read2_b32 v[52:53], v101 offset0:4 offset1:69
	v_cvt_pk_bf16_f32 v107, v78, v79
	ds_read2_b32 v[78:79], v101 offset0:134 offset1:199
	s_waitcnt lgkmcnt(1)
	v_cvt_pk_bf16_f32 v108, v52, v53
	s_waitcnt lgkmcnt(0)
	v_cvt_pk_bf16_f32 v109, v78, v79
	v_or_b32_e32 v51, s35, v88
	v_mul_lo_u32 v78, s39, v51
	s_mul_i32 s35, s38, s28
	v_mad_u64_u32 v[52:53], s[28:29], s38, v51, 0
	v_add3_u32 v53, v53, s35, v78
	ds_read2_b32 v[78:79], v90 offset1:65
	v_lshl_add_u64 v[52:53], v[52:53], 1, s[36:37]
	s_ashr_i32 s35, s34, 31
	v_lshl_add_u64 v[52:53], s[34:35], 1, v[52:53]
	v_lshl_add_u64 v[110:111], v[70:71], 1, v[52:53]
	global_store_dwordx4 v[110:111], v[106:109], off
	s_waitcnt lgkmcnt(0)
	s_nop 0
	ds_read2_b32 v[108:109], v90 offset0:130 offset1:195
	v_cvt_pk_bf16_f32 v106, v78, v79
	ds_read2_b32 v[78:79], v102 offset0:4 offset1:69
	s_waitcnt lgkmcnt(1)
	v_cvt_pk_bf16_f32 v107, v108, v109
	ds_read2_b32 v[110:111], v102 offset0:134 offset1:199
	s_waitcnt lgkmcnt(1)
	v_cvt_pk_bf16_f32 v108, v78, v79
	ds_read2_b32 v[78:79], v91 offset1:65
	s_waitcnt lgkmcnt(1)
	v_cvt_pk_bf16_f32 v109, v110, v111
	v_lshl_add_u64 v[110:111], v[72:73], 1, v[52:53]
	global_store_dwordx4 v[110:111], v[106:109], off
	s_waitcnt lgkmcnt(0)
	v_cvt_pk_bf16_f32 v106, v78, v79
	ds_read2_b32 v[108:109], v91 offset0:130 offset1:195
	ds_read2_b32 v[78:79], v103 offset0:4 offset1:69
	s_waitcnt lgkmcnt(1)
	v_cvt_pk_bf16_f32 v107, v108, v109
	ds_read2_b32 v[102:103], v103 offset0:134 offset1:199
	s_waitcnt lgkmcnt(1)
	v_cvt_pk_bf16_f32 v108, v78, v79
	ds_read2_b32 v[78:79], v92 offset1:65
	s_waitcnt lgkmcnt(1)
	v_cvt_pk_bf16_f32 v109, v102, v103
	v_lshl_add_u64 v[102:103], v[74:75], 1, v[52:53]
	global_store_dwordx4 v[102:103], v[106:109], off
	s_waitcnt lgkmcnt(0)
	v_cvt_pk_bf16_f32 v102, v78, v79
	ds_read2_b32 v[106:107], v92 offset0:130 offset1:195
	ds_read2_b32 v[78:79], v104 offset0:4 offset1:69
	s_waitcnt lgkmcnt(1)
	v_cvt_pk_bf16_f32 v103, v106, v107
	ds_read2_b32 v[106:107], v104 offset0:134 offset1:199
	s_waitcnt lgkmcnt(1)
	v_cvt_pk_bf16_f32 v104, v78, v79
	s_waitcnt lgkmcnt(0)
	v_bfe_u32 v51, v106, 16, 1
	v_add3_u32 v51, v106, v51, s84
	v_bfe_u32 v78, v107, 16, 1
	v_lshrrev_b32_e32 v51, 16, v51
	v_add3_u32 v78, v107, v78, s84
	v_and_or_b32 v105, v78, s85, v51
	v_lshl_add_u64 v[52:53], v[76:77], 1, v[52:53]
	global_store_dwordx4 v[52:53], v[102:105], off
	s_waitcnt lgkmcnt(0)
	s_barrier

.LBB0_308:
	ds_read2_b32 v[52:53], v89 offset1:65
	ds_read2_b32 v[78:79], v89 offset0:130 offset1:195
	s_ashr_i32 s28, s35, 31
	s_waitcnt lgkmcnt(1)
	s_nop 0
	v_cvt_pk_bf16_f32 v102, v52, v53
	s_nop 0
	s_nop 0
	v_add_u32_e32 v101, 0x400, v89
	s_waitcnt lgkmcnt(0)
	v_cvt_pk_bf16_f32 v103, v78, v79
	ds_read2_b32 v[52:53], v101 offset0:4 offset1:69
	ds_read2_b32 v[78:79], v101 offset0:134 offset1:199
	s_waitcnt lgkmcnt(1)
	v_cvt_pk_bf16_f32 v104, v52, v53
	s_waitcnt lgkmcnt(0)
	v_cvt_pk_bf16_f32 v105, v78, v79
	v_or_b32_e32 v51, s35, v88
	v_mul_lo_u32 v78, s39, v51
	s_mul_i32 s35, s38, s28
	v_mad_u64_u32 v[52:53], s[28:29], s38, v51, 0
	v_add3_u32 v53, v53, s35, v78
	v_lshl_add_u64 v[52:53], v[52:53], 1, s[36:37]
	ds_read2_b32 v[78:79], v90 offset1:65
	s_ashr_i32 s35, s34, 31
	v_lshl_add_u64 v[52:53], s[34:35], 1, v[52:53]
	v_lshl_add_u64 v[106:107], v[70:71], 1, v[52:53]
	global_store_dwordx4 v[106:107], v[102:105], off
	ds_read2_b32 v[102:103], v90 offset0:130 offset1:195
	s_waitcnt lgkmcnt(1)
	v_cvt_pk_bf16_f32 v104, v78, v79
	s_waitcnt lgkmcnt(0)
	v_cvt_pk_bf16_f32 v105, v102, v103
	v_add_u32_e32 v102, 0x400, v90
	ds_read2_b32 v[78:79], v102 offset0:4 offset1:69
	ds_read2_b32 v[108:109], v102 offset0:134 offset1:199
	s_waitcnt lgkmcnt(1)
	v_cvt_pk_bf16_f32 v106, v78, v79
	ds_read2_b32 v[78:79], v91 offset1:65
	s_waitcnt lgkmcnt(1)
	v_cvt_pk_bf16_f32 v107, v108, v109
	v_lshl_add_u64 v[108:109], v[72:73], 1, v[52:53]
	global_store_dwordx4 v[108:109], v[104:107], off
	s_waitcnt lgkmcnt(0)
	v_cvt_pk_bf16_f32 v104, v78, v79
	ds_read2_b32 v[106:107], v91 offset0:130 offset1:195
	v_add_u32_e32 v103, 0x400, v91
	ds_read2_b32 v[78:79], v103 offset0:4 offset1:69
	s_waitcnt lgkmcnt(1)
	v_cvt_pk_bf16_f32 v105, v106, v107
	ds_read2_b32 v[108:109], v103 offset0:134 offset1:199
	s_waitcnt lgkmcnt(1)
	v_cvt_pk_bf16_f32 v106, v78, v79
	s_waitcnt lgkmcnt(0)
	v_cvt_pk_bf16_f32 v107, v108, v109
	ds_read2_b32 v[78:79], v92 offset1:65
	v_lshl_add_u64 v[108:109], v[74:75], 1, v[52:53]
	global_store_dwordx4 v[108:109], v[104:107], off
	ds_read2_b32 v[104:105], v92 offset0:130 offset1:195
	s_waitcnt lgkmcnt(1)
	v_cvt_pk_bf16_f32 v106, v78, v79
	s_waitcnt lgkmcnt(0)
	v_cvt_pk_bf16_f32 v107, v104, v105
	v_add_u32_e32 v104, 0x400, v92
	ds_read2_b32 v[78:79], v104 offset0:4 offset1:69
	ds_read2_b32 v[110:111], v104 offset0:134 offset1:199
	s_waitcnt lgkmcnt(1)
	v_cvt_pk_bf16_f32 v108, v78, v79
	s_waitcnt lgkmcnt(0)
	v_bfe_u32 v51, v110, 16, 1
	v_add3_u32 v51, v110, v51, s84
	v_bfe_u32 v78, v111, 16, 1
	v_lshrrev_b32_e32 v51, 16, v51
	v_add3_u32 v78, v111, v78, s84
	v_and_or_b32 v109, v78, s85, v51
	v_lshl_add_u64 v[52:53], v[76:77], 1, v[52:53]
	global_store_dwordx4 v[52:53], v[106:109], off
	s_waitcnt lgkmcnt(0)
	s_barrier
	s_add_i32 s28, s24, s87
	s_cmpk_gt_i32 s28, 0x127f
	s_cbranch_scc1 .LBB0_200
	s_cmpk_gt_i32 s28, 0xe3f
	s_cbranch_scc0 .LBB0_312
	s_add_i32 s29, s80, s67
	s_cmpk_gt_u32 s28, 0x123f
	s_cbranch_scc0 .LBB0_313
	s_add_i32 s34, s78, s68
	s_and_b32 s34, s34, 0x7fffff00
	s_and_b32 s35, s29, 0x3c0
	s_add_i32 s34, s34, 0xfffedc00
	s_mov_b64 s[36:37], s[22:23]
	s_mov_b64 s[38:39], 0x400
	s_cbranch_execz .LBB0_314
	s_branch .LBB0_315

.LBB0_596:
	s_or_b64 exec, exec, s[14:15]
	v_lshl_add_u64 v[52:53], v[52:53], 2, s[6:7]
	v_lshl_add_u64 v[76:77], v[52:53], 0, s[8:9]
	s_waitcnt lgkmcnt(0)
	s_barrier
	v_lshl_add_u64 v[64:65], v[76:77], 0, v[34:35]
	s_waitcnt lgkmcnt(0)
	global_load_dwordx4 v[60:63], v[38:39], off
	v_lshl_add_u64 v[68:69], v[52:53], 0, v[34:35]
	global_load_dwordx4 v[64:67], v[64:65], off
	v_ashrrev_i32_e32 v34, 6, v51
	global_load_dwordx4 v[68:71], v[68:69], off
	v_lshlrev_b32_e32 v34, 2, v34
	v_and_b32_e32 v51, -16, v34
	v_add_u32_e32 v51, 0, v51
	ds_read_b96 v[72:74], v51
	v_or_b32_e32 v34, 12, v34
	v_add_u32_e32 v34, 0, v34
	v_lshlrev_b64 v[54:55], 13, v[54:55]
	v_mov_b32_e32 v51, v35
	s_waitcnt lgkmcnt(0)
	v_mov_b32_e32 v78, v73
	ds_read_b32 v73, v34
	v_mov_b32_e32 v79, v74
	v_add_u32_e32 v1, s21, v1
	s_waitcnt lgkmcnt(0)
	v_pk_add_f32 v[72:73], v[78:79], v[72:73]
	s_nop 0
	v_add_f32_e32 v34, v72, v73
	v_fmamk_f32 v34, v34, 0x39800000, v59
	v_mul_f32_e32 v72, 0x4b800000, v34
	v_cmp_gt_f32_e32 vcc, s22, v34
	s_nop 1
	v_cndmask_b32_e32 v34, v34, v72, vcc
	v_rsq_f32_e32 v74, v34
	v_lshl_add_u64 v[72:73], s[4:5], 0, v[54:55]
	v_lshlrev_b32_e32 v34, 1, v36
	v_lshl_add_u64 v[54:55], v[72:73], 0, v[34:35]
	v_mul_f32_e32 v34, 0x45800000, v74
	v_cndmask_b32_e32 v74, v74, v34, vcc
	v_pk_mul_f32 v[20:21], v[20:21], v[74:75] op_sel_hi:[1,0]
	v_pk_mul_f32 v[18:19], v[18:19], v[74:75] op_sel_hi:[1,0]
	v_pk_mul_f32 v[12:13], v[12:13], v[74:75] op_sel_hi:[1,0]
	v_pk_mul_f32 v[10:11], v[10:11], v[74:75] op_sel_hi:[1,0]
	v_pk_mul_f32 v[8:9], v[8:9], v[74:75] op_sel_hi:[1,0]
	v_pk_mul_f32 v[6:7], v[6:7], v[74:75] op_sel_hi:[1,0]
	s_andn2_b64 vcc, exec, s[12:13]
	s_waitcnt vmcnt(2)
	v_pk_mul_f32 v[18:19], v[60:61], v[18:19]
	v_pk_mul_f32 v[20:21], v[62:63], v[20:21]
	s_waitcnt vmcnt(1)
	v_pk_add_f32 v[60:61], v[66:67], 1.0 op_sel_hi:[1,0]
	v_pk_add_f32 v[62:63], v[64:65], 1.0 op_sel_hi:[1,0]
	s_waitcnt vmcnt(0)
	v_pk_fma_f32 v[20:21], v[60:61], v[20:21], v[70:71]
	v_pk_fma_f32 v[18:19], v[62:63], v[18:19], v[68:69]
	v_bfe_u32 v61, v20, 16, 1
	v_cvt_pk_bf16_f32 v18, v18, v19
	v_bfe_u32 v62, v21, 16, 1
	v_add3_u32 v20, v20, v61, s23
	v_add3_u32 v21, v21, v62, s23
	v_lshrrev_b32_e32 v20, 16, v20
	v_and_or_b32 v19, v21, s25, v20
	global_store_dwordx2 v[54:55], v[18:19], off
	v_lshl_add_u64 v[60:61], v[76:77], 0, v[50:51]
	global_load_dwordx4 v[18:21], v[44:45], off
	v_lshl_add_u64 v[64:65], v[52:53], 0, v[50:51]
	global_load_dwordx4 v[60:63], v[60:61], off
	v_lshlrev_b32_e32 v34, 2, v40
	global_load_dwordx4 v[64:67], v[64:65], off
	v_pk_mul_f32 v[70:71], v[4:5], v[74:75] op_sel_hi:[1,0]
	v_mov_b32_e32 v4, v16
	s_waitcnt vmcnt(2)
	v_pk_mul_f32 v[10:11], v[18:19], v[10:11]
	v_pk_mul_f32 v[12:13], v[20:21], v[12:13]
	s_waitcnt vmcnt(1)
	v_pk_add_f32 v[18:19], v[62:63], 1.0 op_sel_hi:[1,0]
	v_pk_add_f32 v[20:21], v[60:61], 1.0 op_sel_hi:[1,0]
	s_waitcnt vmcnt(0)
	v_pk_fma_f32 v[12:13], v[18:19], v[12:13], v[66:67]
	v_pk_fma_f32 v[10:11], v[20:21], v[10:11], v[64:65]
	v_bfe_u32 v20, v12, 16, 1
	v_cvt_pk_bf16_f32 v10, v10, v11
	v_bfe_u32 v21, v13, 16, 1
	v_add3_u32 v12, v12, v20, s23
	v_add3_u32 v13, v13, v21, s23
	v_lshrrev_b32_e32 v12, 16, v12
	v_and_or_b32 v11, v13, s25, v12
	global_store_dwordx2 v[54:55], v[10:11], off offset:2048
	v_lshl_add_u64 v[18:19], v[76:77], 0, v[34:35]
	global_load_dwordx4 v[10:13], v[46:47], off
	v_lshl_add_u64 v[54:55], v[52:53], 0, v[34:35]
	global_load_dwordx4 v[18:21], v[18:19], off
	v_lshlrev_b32_e32 v34, 1, v40
	global_load_dwordx4 v[60:63], v[54:55], off
	v_lshl_add_u64 v[54:55], v[72:73], 0, v[34:35]
	v_lshlrev_b32_e32 v34, 2, v42
	s_waitcnt vmcnt(2)
	v_pk_mul_f32 v[6:7], v[10:11], v[6:7]
	v_pk_mul_f32 v[8:9], v[12:13], v[8:9]
	s_waitcnt vmcnt(1)
	v_pk_add_f32 v[10:11], v[20:21], 1.0 op_sel_hi:[1,0]
	v_pk_add_f32 v[12:13], v[18:19], 1.0 op_sel_hi:[1,0]
	s_waitcnt vmcnt(0)
	v_pk_fma_f32 v[8:9], v[10:11], v[8:9], v[62:63]
	v_pk_fma_f32 v[6:7], v[12:13], v[6:7], v[60:61]
	v_bfe_u32 v12, v8, 16, 1
	v_cvt_pk_bf16_f32 v6, v6, v7
	v_bfe_u32 v13, v9, 16, 1
	v_add3_u32 v8, v8, v12, s23
	v_add3_u32 v9, v9, v13, s23
	v_lshrrev_b32_e32 v8, 16, v8
	v_and_or_b32 v7, v9, s25, v8
	global_store_dwordx2 v[54:55], v[6:7], off
	v_lshl_add_u64 v[6:7], v[76:77], 0, v[34:35]
	global_load_dwordx4 v[60:63], v[48:49], off
	global_load_dwordx4 v[64:67], v[6:7], off
	v_lshl_add_u64 v[6:7], v[52:53], 0, v[34:35]
	global_load_dwordx4 v[52:55], v[6:7], off
	v_lshlrev_b32_e32 v34, 1, v42
	v_lshl_add_u64 v[68:69], v[72:73], 0, v[34:35]
	v_pk_mul_f32 v[72:73], v[2:3], v[74:75] op_sel_hi:[1,0]
	v_mov_b32_e32 v10, v22
	v_mov_b32_e32 v11, v23
	v_mov_b32_e32 v12, v24
	v_mov_b32_e32 v13, v25
	v_mov_b32_e32 v6, v26
	v_mov_b32_e32 v7, v27
	v_mov_b32_e32 v2, v14
	v_mov_b32_e32 v3, v15
	v_mov_b32_e32 v18, v30
	v_mov_b32_e32 v19, v31
	v_mov_b32_e32 v20, v32
	v_mov_b32_e32 v21, v33
	v_mov_b32_e32 v8, v28
	v_mov_b32_e32 v9, v29
	s_waitcnt vmcnt(2)
	v_pk_mul_f32 v[14:15], v[72:73], v[60:61]
	v_pk_mul_f32 v[22:23], v[70:71], v[62:63]
	s_waitcnt vmcnt(1)
	v_pk_add_f32 v[24:25], v[66:67], 1.0 op_sel_hi:[1,0]
	v_pk_add_f32 v[26:27], v[64:65], 1.0 op_sel_hi:[1,0]
	s_waitcnt vmcnt(0)
	v_pk_fma_f32 v[22:23], v[22:23], v[24:25], v[54:55]
	v_pk_fma_f32 v[14:15], v[14:15], v[26:27], v[52:53]
	v_bfe_u32 v24, v22, 16, 1
	v_cvt_pk_bf16_f32 v14, v14, v15
	v_bfe_u32 v25, v23, 16, 1
	v_add3_u32 v15, v22, v24, s23
	v_add3_u32 v16, v23, v25, s23
	v_lshrrev_b32_e32 v15, 16, v15
	v_and_or_b32 v15, v16, s25, v15
	v_mov_b32_e32 v5, v17
	global_store_dwordx2 v[68:69], v[14:15], off
	s_cbranch_vccz .LBB0_603

.LBB0_885:
	ds_read2_b32 v[52:53], v89 offset1:65
	ds_read2_b32 v[78:79], v89 offset0:130 offset1:195
	s_waitcnt lgkmcnt(1)
	s_nop 0
	v_cvt_pk_bf16_f32 v106, v52, v53
	s_nop 0
	s_nop 0
	s_nop 0
	s_waitcnt lgkmcnt(0)
	ds_read2_b32 v[52:53], v101 offset0:4 offset1:69
	v_cvt_pk_bf16_f32 v107, v78, v79
	ds_read2_b32 v[78:79], v101 offset0:134 offset1:199
	s_waitcnt lgkmcnt(1)
	v_cvt_pk_bf16_f32 v108, v52, v53
	s_waitcnt lgkmcnt(0)
	v_cvt_pk_bf16_f32 v109, v78, v79
	v_or_b32_e32 v51, s21, v88
	s_ashr_i32 s21, s21, 31
	v_mul_lo_u32 v78, s23, v51
	s_mul_i32 s21, s22, s21
	v_mad_u64_u32 v[52:53], s[22:23], s22, v51, 0
	v_add3_u32 v53, v53, s21, v78
	ds_read2_b32 v[78:79], v90 offset1:65
	v_lshl_add_u64 v[52:53], v[52:53], 1, s[26:27]
	s_ashr_i32 s21, s20, 31
	v_lshl_add_u64 v[52:53], s[20:21], 1, v[52:53]
	v_lshl_add_u64 v[110:111], v[70:71], 1, v[52:53]
	global_store_dwordx4 v[110:111], v[106:109], off
	s_waitcnt lgkmcnt(0)
	s_nop 0
	ds_read2_b32 v[108:109], v90 offset0:130 offset1:195
	v_cvt_pk_bf16_f32 v106, v78, v79
	ds_read2_b32 v[78:79], v102 offset0:4 offset1:69
	s_waitcnt lgkmcnt(1)
	v_cvt_pk_bf16_f32 v107, v108, v109
	ds_read2_b32 v[110:111], v102 offset0:134 offset1:199
	s_waitcnt lgkmcnt(1)
	v_cvt_pk_bf16_f32 v108, v78, v79
	ds_read2_b32 v[78:79], v91 offset1:65
	s_waitcnt lgkmcnt(1)
	v_cvt_pk_bf16_f32 v109, v110, v111
	v_lshl_add_u64 v[110:111], v[72:73], 1, v[52:53]
	global_store_dwordx4 v[110:111], v[106:109], off
	s_waitcnt lgkmcnt(0)
	v_cvt_pk_bf16_f32 v106, v78, v79
	ds_read2_b32 v[108:109], v91 offset0:130 offset1:195
	ds_read2_b32 v[78:79], v103 offset0:4 offset1:69
	s_waitcnt lgkmcnt(1)
	v_cvt_pk_bf16_f32 v107, v108, v109
	ds_read2_b32 v[102:103], v103 offset0:134 offset1:199
	s_waitcnt lgkmcnt(1)
	v_cvt_pk_bf16_f32 v108, v78, v79
	ds_read2_b32 v[78:79], v92 offset1:65
	s_waitcnt lgkmcnt(1)
	v_cvt_pk_bf16_f32 v109, v102, v103
	v_lshl_add_u64 v[102:103], v[74:75], 1, v[52:53]
	global_store_dwordx4 v[102:103], v[106:109], off
	s_waitcnt lgkmcnt(0)
	v_cvt_pk_bf16_f32 v102, v78, v79
	ds_read2_b32 v[106:107], v92 offset0:130 offset1:195
	ds_read2_b32 v[78:79], v104 offset0:4 offset1:69
	s_waitcnt lgkmcnt(1)
	v_cvt_pk_bf16_f32 v103, v106, v107
	ds_read2_b32 v[106:107], v104 offset0:134 offset1:199
	s_waitcnt lgkmcnt(1)
	v_cvt_pk_bf16_f32 v104, v78, v79
	s_waitcnt lgkmcnt(0)
	v_bfe_u32 v51, v106, 16, 1
	v_add3_u32 v51, v106, v51, s80
	v_bfe_u32 v78, v107, 16, 1
	v_lshrrev_b32_e32 v51, 16, v51
	v_add3_u32 v78, v107, v78, s80
	v_and_or_b32 v105, v78, s81, v51
	v_lshl_add_u64 v[52:53], v[76:77], 1, v[52:53]
	global_store_dwordx4 v[52:53], v[102:105], off
	s_waitcnt lgkmcnt(0)
	s_barrier

.LBB0_994:
	ds_read2_b32 v[52:53], v89 offset1:65
	ds_read2_b32 v[78:79], v89 offset0:130 offset1:195
	s_add_i32 s28, s62, s83
	s_waitcnt lgkmcnt(1)
	s_nop 0
	v_cvt_pk_bf16_f32 v102, v52, v53
	s_nop 0
	s_nop 0
	v_add_u32_e32 v101, 0x400, v89
	s_waitcnt lgkmcnt(0)
	v_cvt_pk_bf16_f32 v103, v78, v79
	ds_read2_b32 v[52:53], v101 offset0:4 offset1:69
	ds_read2_b32 v[78:79], v101 offset0:134 offset1:199
	s_waitcnt lgkmcnt(1)
	v_cvt_pk_bf16_f32 v104, v52, v53
	s_waitcnt lgkmcnt(0)
	v_cvt_pk_bf16_f32 v105, v78, v79
	v_or_b32_e32 v51, s21, v88
	s_ashr_i32 s21, s21, 31
	v_mul_lo_u32 v78, s23, v51
	s_mul_i32 s21, s22, s21
	v_mad_u64_u32 v[52:53], s[22:23], s22, v51, 0
	v_add3_u32 v53, v53, s21, v78
	v_lshl_add_u64 v[52:53], v[52:53], 1, s[26:27]
	ds_read2_b32 v[78:79], v90 offset1:65
	s_ashr_i32 s21, s20, 31
	v_lshl_add_u64 v[52:53], s[20:21], 1, v[52:53]
	v_lshl_add_u64 v[106:107], v[70:71], 1, v[52:53]
	global_store_dwordx4 v[106:107], v[102:105], off
	ds_read2_b32 v[102:103], v90 offset0:130 offset1:195
	s_waitcnt lgkmcnt(1)
	v_cvt_pk_bf16_f32 v104, v78, v79
	s_waitcnt lgkmcnt(0)
	v_cvt_pk_bf16_f32 v105, v102, v103
	v_add_u32_e32 v102, 0x400, v90
	ds_read2_b32 v[78:79], v102 offset0:4 offset1:69
	ds_read2_b32 v[108:109], v102 offset0:134 offset1:199
	s_waitcnt lgkmcnt(1)
	v_cvt_pk_bf16_f32 v106, v78, v79
	ds_read2_b32 v[78:79], v91 offset1:65
	s_waitcnt lgkmcnt(1)
	v_cvt_pk_bf16_f32 v107, v108, v109
	v_lshl_add_u64 v[108:109], v[72:73], 1, v[52:53]
	global_store_dwordx4 v[108:109], v[104:107], off
	s_waitcnt lgkmcnt(0)
	v_cvt_pk_bf16_f32 v104, v78, v79
	ds_read2_b32 v[106:107], v91 offset0:130 offset1:195
	v_add_u32_e32 v103, 0x400, v91
	ds_read2_b32 v[78:79], v103 offset0:4 offset1:69
	s_waitcnt lgkmcnt(1)
	v_cvt_pk_bf16_f32 v105, v106, v107
	ds_read2_b32 v[108:109], v103 offset0:134 offset1:199
	s_waitcnt lgkmcnt(1)
	v_cvt_pk_bf16_f32 v106, v78, v79
	s_waitcnt lgkmcnt(0)
	v_cvt_pk_bf16_f32 v107, v108, v109
	ds_read2_b32 v[78:79], v92 offset1:65
	v_lshl_add_u64 v[108:109], v[74:75], 1, v[52:53]
	global_store_dwordx4 v[108:109], v[104:107], off
	ds_read2_b32 v[104:105], v92 offset0:130 offset1:195
	s_waitcnt lgkmcnt(1)
	v_cvt_pk_bf16_f32 v106, v78, v79
	s_waitcnt lgkmcnt(0)
	v_cvt_pk_bf16_f32 v107, v104, v105
	v_add_u32_e32 v104, 0x400, v92
	ds_read2_b32 v[78:79], v104 offset0:4 offset1:69
	ds_read2_b32 v[110:111], v104 offset0:134 offset1:199
	s_waitcnt lgkmcnt(1)
	v_cvt_pk_bf16_f32 v108, v78, v79
	s_waitcnt lgkmcnt(0)
	v_bfe_u32 v51, v110, 16, 1
	v_add3_u32 v51, v110, v51, s80
	v_bfe_u32 v78, v111, 16, 1
	v_lshrrev_b32_e32 v51, 16, v51
	v_add3_u32 v78, v111, v78, s80
	v_and_or_b32 v109, v78, s81, v51
	v_lshl_add_u64 v[52:53], v[76:77], 1, v[52:53]
	global_store_dwordx4 v[52:53], v[106:109], off
	s_waitcnt lgkmcnt(0)
	s_barrier
	s_cmpk_gt_i32 s28, 0x43f
	s_cbranch_scc1 .LBB0_886
	s_addk_i32 s28, 0xe40
	s_cmpk_gt_i32 s28, 0xe3f
	s_mov_b64 s[34:35], -1
	s_cbranch_scc0 .LBB0_1001
	s_add_i32 s29, s76, s69
	s_cmpk_gt_u32 s28, 0x123f
	s_mov_b64 s[26:27], -1
	s_cbranch_scc0 .LBB0_998
	s_add_i32 s20, s74, s64
	s_and_b32 s20, s20, 0xffffff00
	s_and_b32 s21, s29, 0x3c0
	s_add_i32 s20, s20, 0xfffedc00
	s_mov_b64 s[26:27], 0

.LBB0_1630:
	s_or_b64 exec, exec, s[12:13]
	v_lshlrev_b32_e32 v2, 2, v9
	v_add_u32_e32 v37, s31, v2
	v_add_u32_e32 v2, 0, v2
	v_add_u32_e32 v54, 0x1bc00, v2
	v_lshl_add_u32 v2, v26, 9, v37
	s_waitcnt lgkmcnt(0)
	s_barrier
	ds_read_b128 v[40:43], v2
	ds_read_b128 v[44:47], v54
	s_lshl_b64 s[12:13], s[8:9], 14
	s_add_u32 s0, s85, s12
	s_addc_u32 s1, s84, s13
	v_mov_b32_e32 v33, v3
	s_waitcnt lgkmcnt(1)
	v_mul_f32_e32 v15, 0x3fb8aa3b, v40
	v_lshl_add_u64 v[34:35], s[0:1], 0, v[32:33]
	v_add_u32_e32 v2, 0, v32
	v_exp_f32_e32 v32, v15
	s_waitcnt lgkmcnt(0)
	v_sub_f32_e32 v15, v40, v44
	v_mul_f32_e32 v15, 0x3fb8aa3b, v15
	v_exp_f32_e32 v48, v15
	v_sub_f32_e32 v15, v44, v40
	v_mul_f32_e32 v15, 0x3fb8aa3b, v15
	v_exp_f32_e32 v40, v15
	v_mul_f32_e32 v15, 0x3fb8aa3b, v41
	v_exp_f32_e32 v44, v15
	v_sub_f32_e32 v15, v41, v45
	v_mul_f32_e32 v15, 0x3fb8aa3b, v15
	v_exp_f32_e32 v50, v15
	v_sub_f32_e32 v15, v45, v41
	v_mul_f32_e32 v15, 0x3fb8aa3b, v15
	v_exp_f32_e32 v52, v15
	v_mul_f32_e32 v15, 0x3fb8aa3b, v42
	v_exp_f32_e32 v33, v15
	v_sub_f32_e32 v15, v42, v46
	v_mul_f32_e32 v15, 0x3fb8aa3b, v15
	v_exp_f32_e32 v49, v15
	v_sub_f32_e32 v15, v46, v42
	v_mul_f32_e32 v15, 0x3fb8aa3b, v15
	v_exp_f32_e32 v41, v15
	v_mul_f32_e32 v15, 0x3fb8aa3b, v43
	v_exp_f32_e32 v45, v15
	v_sub_f32_e32 v15, v43, v47
	v_mul_f32_e32 v15, 0x3fb8aa3b, v15
	v_exp_f32_e32 v51, v15
	v_sub_f32_e32 v15, v47, v43
	v_lshlrev_b32_e32 v43, 16, v31
	v_lshlrev_b32_e32 v42, 16, v30
	v_and_b32_e32 v31, 0xffff0000, v31
	v_and_b32_e32 v30, 0xffff0000, v30
	v_pk_mul_f32 v[30:31], v[30:31], s[6:7] op_sel_hi:[1,0]
	v_pk_mul_f32 v[42:43], v[42:43], s[6:7] op_sel_hi:[1,0]
	v_pk_mul_f32 v[44:45], v[30:31], v[44:45]
	v_mul_f32_e32 v15, 0x3fb8aa3b, v15
	v_pk_mul_f32 v[32:33], v[42:43], v[32:33]
	s_nop 0
	v_exp_f32_e32 v53, v15
	v_cvt_pk_bf16_f32 v33, v33, v45
	s_nop 0
	s_nop 0
	s_nop 0
	s_nop 0
	v_cvt_pk_bf16_f32 v32, v32, v44
	s_nop 0
	s_nop 0
	v_ashrrev_i32_e32 v27, 31, v26
	v_lshlrev_b64 v[44:45], 8, v[26:27]
	v_lshl_add_u64 v[44:45], v[34:35], 0, v[44:45]
	global_store_dwordx2 v[44:45], v[32:33], off
	v_pk_mul_f32 v[32:33], v[42:43], v[48:49]
	v_pk_mul_f32 v[30:31], v[30:31], v[50:51]
	s_nop 0
	s_nop 0
	s_nop 0
	v_cvt_pk_bf16_f32 v30, v32, v30
	v_cvt_pk_bf16_f32 v31, v33, v31
	s_nop 0
	s_nop 0
	v_lshlrev_b32_e32 v43, 16, v29
	v_lshlrev_b32_e32 v42, 16, v28
	v_and_b32_e32 v29, 0xffff0000, v29
	v_and_b32_e32 v28, 0xffff0000, v28
	v_mad_u64_u32 v[32:33], s[0:1], v26, s46, v[2:3]
	v_pk_mul_f32 v[40:41], v[40:41], v[42:43]
	v_pk_mul_f32 v[28:29], v[52:53], v[28:29]
	s_nop 0
	s_nop 0
	v_and_b32_sdwa v21, v40, v38 dst_sel:DWORD dst_unused:UNUSED_PAD src0_sel:WORD_1 src1_sel:DWORD
	v_and_b32_sdwa v27, v29, v38 dst_sel:DWORD dst_unused:UNUSED_PAD src0_sel:WORD_1 src1_sel:DWORD
	v_and_b32_sdwa v33, v28, v38 dst_sel:DWORD dst_unused:UNUSED_PAD src0_sel:WORD_1 src1_sel:DWORD
	v_and_b32_sdwa v15, v41, v38 dst_sel:DWORD dst_unused:UNUSED_PAD src0_sel:WORD_1 src1_sel:DWORD
	v_add3_u32 v21, v40, v21, s45
	v_add3_u32 v40, v29, v27, s45
	v_add3_u32 v33, v28, v33, s45
	v_add3_u32 v15, v41, v15, s45
	v_and_b32_e32 v27, 0xffff0000, v40
	v_and_b32_e32 v28, 0xffff0000, v33
	v_lshlrev_b32_e32 v26, 1, v26
	v_mul_u32_u24_e32 v48, 0x90, v9
	v_or_b32_sdwa v29, v27, v15 dst_sel:DWORD dst_unused:UNUSED_PAD src0_sel:DWORD src1_sel:WORD_1
	v_or_b32_sdwa v28, v28, v21 dst_sel:DWORD dst_unused:UNUSED_PAD src0_sel:DWORD src1_sel:WORD_1
	v_add3_u32 v9, s22, v26, v48
	ds_write2st64_b64 v32, v[30:31], v[28:29] offset1:66
	ds_write_b16_d16_hi v9, v21
	v_lshl_add_u32 v21, v20, 9, v37
	ds_read_b128 v[26:29], v21
	ds_write_b16_d16_hi v9, v33 offset:144
	ds_read_b128 v[30:33], v54
	ds_write_b16_d16_hi v9, v15 offset:288
	ds_write_b16_d16_hi v9, v40 offset:432
	v_ashrrev_i32_e32 v36, 6, v6
	s_waitcnt lgkmcnt(4)
	v_mul_f32_e32 v9, 0x3fb8aa3b, v26
	v_exp_f32_e32 v40, v9
	s_waitcnt lgkmcnt(2)
	v_sub_f32_e32 v9, v26, v30
	v_mul_f32_e32 v9, 0x3fb8aa3b, v9
	v_exp_f32_e32 v42, v9
	v_sub_f32_e32 v9, v30, v26
	v_mul_f32_e32 v9, 0x3fb8aa3b, v9
	v_exp_f32_e32 v26, v9
	v_mul_f32_e32 v9, 0x3fb8aa3b, v27
	v_exp_f32_e32 v30, v9
	v_sub_f32_e32 v9, v27, v31
	v_mul_f32_e32 v9, 0x3fb8aa3b, v9
	v_exp_f32_e32 v44, v9
	v_sub_f32_e32 v9, v31, v27
	v_mul_f32_e32 v9, 0x3fb8aa3b, v9
	v_exp_f32_e32 v46, v9
	v_mul_f32_e32 v9, 0x3fb8aa3b, v28
	v_exp_f32_e32 v41, v9
	v_sub_f32_e32 v9, v28, v32
	v_mul_f32_e32 v9, 0x3fb8aa3b, v9
	v_exp_f32_e32 v43, v9
	v_sub_f32_e32 v9, v32, v28
	v_mul_f32_e32 v9, 0x3fb8aa3b, v9
	v_exp_f32_e32 v27, v9
	v_mul_f32_e32 v9, 0x3fb8aa3b, v29
	v_exp_f32_e32 v31, v9
	v_sub_f32_e32 v9, v29, v33
	v_mul_f32_e32 v9, 0x3fb8aa3b, v9
	v_exp_f32_e32 v45, v9
	v_sub_f32_e32 v9, v33, v29
	v_lshlrev_b32_e32 v29, 16, v25
	v_lshlrev_b32_e32 v28, 16, v24
	v_and_b32_e32 v25, 0xffff0000, v25
	v_and_b32_e32 v24, 0xffff0000, v24
	v_pk_mul_f32 v[28:29], v[28:29], s[6:7] op_sel_hi:[1,0]
	v_pk_mul_f32 v[24:25], v[24:25], s[6:7] op_sel_hi:[1,0]
	v_pk_mul_f32 v[32:33], v[28:29], v[40:41]
	v_pk_mul_f32 v[30:31], v[24:25], v[30:31]
	v_mul_f32_e32 v9, 0x3fb8aa3b, v9
	s_nop 0
	s_nop 0
	v_exp_f32_e32 v47, v9
	v_cvt_pk_bf16_f32 v31, v33, v31
	s_nop 0
	v_cvt_pk_bf16_f32 v30, v32, v30
	s_nop 0
	s_nop 0
	v_ashrrev_i32_e32 v21, 31, v20
	v_pk_mul_f32 v[28:29], v[28:29], v[42:43]
	v_lshlrev_b64 v[32:33], 8, v[20:21]
	v_pk_mul_f32 v[24:25], v[24:25], v[44:45]
	s_nop 0
	v_lshl_add_u64 v[32:33], v[34:35], 0, v[32:33]
	s_nop 0
	v_cvt_pk_bf16_f32 v24, v28, v24
	global_store_dwordx2 v[32:33], v[30:31], off
	s_nop 0
	s_nop 0
	v_lshlrev_b32_e32 v31, 16, v23
	v_lshlrev_b32_e32 v30, 16, v22
	v_cvt_pk_bf16_f32 v25, v29, v25
	s_nop 0
	s_nop 0
	v_and_b32_e32 v23, 0xffff0000, v23
	v_and_b32_e32 v22, 0xffff0000, v22
	v_pk_mul_f32 v[26:27], v[26:27], v[30:31]
	s_nop 0
	s_nop 0
	s_nop 0
	v_pk_mul_f32 v[22:23], v[46:47], v[22:23]
	v_and_b32_sdwa v15, v26, v38 dst_sel:DWORD dst_unused:UNUSED_PAD src0_sel:WORD_1 src1_sel:DWORD
	s_nop 0
	v_mad_u64_u32 v[28:29], s[0:1], v20, s46, v[2:3]
	v_add3_u32 v15, v26, v15, s45
	v_and_b32_sdwa v21, v23, v38 dst_sel:DWORD dst_unused:UNUSED_PAD src0_sel:WORD_1 src1_sel:DWORD
	v_and_b32_sdwa v26, v22, v38 dst_sel:DWORD dst_unused:UNUSED_PAD src0_sel:WORD_1 src1_sel:DWORD
	v_and_b32_sdwa v9, v27, v38 dst_sel:DWORD dst_unused:UNUSED_PAD src0_sel:WORD_1 src1_sel:DWORD
	v_add3_u32 v29, v23, v21, s45
	v_add3_u32 v26, v22, v26, s45
	v_add3_u32 v9, v27, v9, s45
	v_and_b32_e32 v21, 0xffff0000, v29
	v_and_b32_e32 v22, 0xffff0000, v26
	v_or_b32_sdwa v23, v21, v9 dst_sel:DWORD dst_unused:UNUSED_PAD src0_sel:DWORD src1_sel:WORD_1
	v_or_b32_sdwa v22, v22, v15 dst_sel:DWORD dst_unused:UNUSED_PAD src0_sel:DWORD src1_sel:WORD_1
	v_lshlrev_b32_e32 v20, 1, v20
	ds_write2st64_b64 v28, v[24:25], v[22:23] offset1:66
	v_add3_u32 v28, s22, v20, v48
	ds_write_b16_d16_hi v28, v15
	v_lshl_add_u32 v15, v14, 9, v37
	ds_read_b128 v[20:23], v15
	ds_write_b16_d16_hi v28, v26 offset:144
	ds_read_b128 v[24:27], v54
	ds_write_b16_d16_hi v28, v9 offset:288
	ds_write_b16_d16_hi v28, v29 offset:432
	v_bfe_u32 v7, v6, 4, 2
	s_waitcnt lgkmcnt(4)
	v_mul_f32_e32 v9, 0x3fb8aa3b, v20
	v_exp_f32_e32 v28, v9
	s_waitcnt lgkmcnt(2)
	v_sub_f32_e32 v9, v20, v24
	v_mul_f32_e32 v9, 0x3fb8aa3b, v9
	v_exp_f32_e32 v30, v9
	v_sub_f32_e32 v9, v24, v20
	v_mul_f32_e32 v9, 0x3fb8aa3b, v9
	v_exp_f32_e32 v20, v9
	v_mul_f32_e32 v9, 0x3fb8aa3b, v21
	v_exp_f32_e32 v24, v9
	v_sub_f32_e32 v9, v21, v25
	v_mul_f32_e32 v9, 0x3fb8aa3b, v9
	v_exp_f32_e32 v32, v9
	v_sub_f32_e32 v9, v25, v21
	v_mul_f32_e32 v9, 0x3fb8aa3b, v9
	v_exp_f32_e32 v40, v9
	v_mul_f32_e32 v9, 0x3fb8aa3b, v22
	v_exp_f32_e32 v29, v9
	v_sub_f32_e32 v9, v22, v26
	v_mul_f32_e32 v9, 0x3fb8aa3b, v9
	v_exp_f32_e32 v31, v9
	v_sub_f32_e32 v9, v26, v22
	v_mul_f32_e32 v9, 0x3fb8aa3b, v9
	v_exp_f32_e32 v21, v9
	v_mul_f32_e32 v9, 0x3fb8aa3b, v23
	v_exp_f32_e32 v25, v9
	v_sub_f32_e32 v9, v23, v27
	v_mul_f32_e32 v9, 0x3fb8aa3b, v9
	v_exp_f32_e32 v33, v9
	v_sub_f32_e32 v9, v27, v23
	v_lshlrev_b32_e32 v23, 16, v19
	v_lshlrev_b32_e32 v22, 16, v18
	v_and_b32_e32 v19, 0xffff0000, v19
	v_and_b32_e32 v18, 0xffff0000, v18
	v_pk_mul_f32 v[22:23], v[22:23], s[6:7] op_sel_hi:[1,0]
	v_mul_f32_e32 v9, 0x3fb8aa3b, v9
	v_pk_mul_f32 v[18:19], v[18:19], s[6:7] op_sel_hi:[1,0]
	v_pk_mul_f32 v[26:27], v[22:23], v[28:29]
	v_exp_f32_e32 v41, v9
	v_pk_mul_f32 v[24:25], v[18:19], v[24:25]
	v_and_b32_sdwa v9, v27, v38 dst_sel:DWORD dst_unused:UNUSED_PAD src0_sel:WORD_1 src1_sel:DWORD
	s_nop 0
	v_add3_u32 v9, v27, v9, s45
	v_cvt_pk_bf16_f32 v24, v26, v24
	s_nop 0
	v_and_b32_sdwa v26, v25, v38 dst_sel:DWORD dst_unused:UNUSED_PAD src0_sel:WORD_1 src1_sel:DWORD
	s_nop 0
	v_add3_u32 v25, v25, v26, s45
	v_and_b32_e32 v25, 0xffff0000, v25
	v_ashrrev_i32_e32 v15, 31, v14
	v_pk_mul_f32 v[22:23], v[22:23], v[30:31]
	v_or_b32_sdwa v25, v25, v9 dst_sel:DWORD dst_unused:UNUSED_PAD src0_sel:DWORD src1_sel:WORD_1
	v_lshlrev_b64 v[26:27], 8, v[14:15]
	v_pk_mul_f32 v[18:19], v[18:19], v[32:33]
	s_nop 0
	v_and_b32_sdwa v15, v22, v38 dst_sel:DWORD dst_unused:UNUSED_PAD src0_sel:WORD_1 src1_sel:DWORD
	v_lshl_add_u64 v[26:27], v[34:35], 0, v[26:27]
	v_add3_u32 v15, v22, v15, s45
	s_nop 0
	v_cvt_pk_bf16_f32 v19, v23, v19
	v_and_b32_sdwa v23, v18, v38 dst_sel:DWORD dst_unused:UNUSED_PAD src0_sel:WORD_1 src1_sel:DWORD
	global_store_dwordx2 v[26:27], v[24:25], off
	s_nop 0
	v_add3_u32 v18, v18, v23, s45
	v_lshlrev_b32_e32 v25, 16, v17
	v_lshlrev_b32_e32 v24, 16, v16
	v_and_b32_e32 v18, 0xffff0000, v18
	v_and_b32_e32 v17, 0xffff0000, v17
	v_and_b32_e32 v16, 0xffff0000, v16
	v_pk_mul_f32 v[20:21], v[20:21], v[24:25]
	s_nop 0
	v_or_b32_sdwa v18, v18, v15 dst_sel:DWORD dst_unused:UNUSED_PAD src0_sel:DWORD src1_sel:WORD_1
	v_pk_mul_f32 v[16:17], v[40:41], v[16:17]
	v_and_b32_sdwa v9, v21, v38 dst_sel:DWORD dst_unused:UNUSED_PAD src0_sel:WORD_1 src1_sel:DWORD
	v_and_b32_sdwa v15, v20, v38 dst_sel:DWORD dst_unused:UNUSED_PAD src0_sel:WORD_1 src1_sel:DWORD
	v_mad_u64_u32 v[22:23], s[0:1], v14, s46, v[2:3]
	v_add3_u32 v15, v20, v15, s45
	v_add3_u32 v9, v21, v9, s45
	v_and_b32_sdwa v20, v17, v38 dst_sel:DWORD dst_unused:UNUSED_PAD src0_sel:WORD_1 src1_sel:DWORD
	v_and_b32_sdwa v21, v16, v38 dst_sel:DWORD dst_unused:UNUSED_PAD src0_sel:WORD_1 src1_sel:DWORD
	v_add3_u32 v23, v17, v20, s45
	v_add3_u32 v20, v16, v21, s45
	v_and_b32_e32 v16, 0xffff0000, v23
	v_and_b32_e32 v21, 0xffff0000, v20
	v_or_b32_sdwa v17, v16, v9 dst_sel:DWORD dst_unused:UNUSED_PAD src0_sel:DWORD src1_sel:WORD_1
	v_or_b32_sdwa v16, v21, v15 dst_sel:DWORD dst_unused:UNUSED_PAD src0_sel:DWORD src1_sel:WORD_1
	v_lshlrev_b32_e32 v14, 1, v14
	ds_write2st64_b64 v22, v[18:19], v[16:17] offset1:66
	v_add3_u32 v22, s22, v14, v48
	v_lshl_add_u32 v14, v8, 9, v37
	ds_write_b16_d16_hi v22, v15
	ds_read_b128 v[14:17], v14
	ds_write_b16_d16_hi v22, v20 offset:144
	ds_read_b128 v[18:21], v54
	ds_write_b16_d16_hi v22, v9 offset:288
	ds_write_b16_d16_hi v22, v23 offset:432
	s_waitcnt lgkmcnt(4)
	v_mul_f32_e32 v9, 0x3fb8aa3b, v14
	v_exp_f32_e32 v22, v9
	s_waitcnt lgkmcnt(2)
	v_sub_f32_e32 v9, v14, v18
	v_mul_f32_e32 v9, 0x3fb8aa3b, v9
	v_exp_f32_e32 v24, v9
	v_sub_f32_e32 v9, v18, v14
	v_mul_f32_e32 v9, 0x3fb8aa3b, v9
	v_exp_f32_e32 v14, v9
	v_mul_f32_e32 v9, 0x3fb8aa3b, v15
	v_exp_f32_e32 v18, v9
	v_sub_f32_e32 v9, v15, v19
	v_mul_f32_e32 v9, 0x3fb8aa3b, v9
	v_exp_f32_e32 v26, v9
	v_sub_f32_e32 v9, v19, v15
	v_mul_f32_e32 v9, 0x3fb8aa3b, v9
	v_exp_f32_e32 v28, v9
	v_mul_f32_e32 v9, 0x3fb8aa3b, v16
	v_exp_f32_e32 v23, v9
	v_sub_f32_e32 v9, v16, v20
	v_mul_f32_e32 v9, 0x3fb8aa3b, v9
	v_exp_f32_e32 v25, v9
	v_sub_f32_e32 v9, v20, v16
	v_mul_f32_e32 v9, 0x3fb8aa3b, v9
	v_exp_f32_e32 v15, v9
	v_mul_f32_e32 v9, 0x3fb8aa3b, v17
	v_exp_f32_e32 v19, v9
	v_sub_f32_e32 v9, v17, v21
	v_mul_f32_e32 v9, 0x3fb8aa3b, v9
	v_exp_f32_e32 v27, v9
	v_sub_f32_e32 v9, v21, v17
	v_lshlrev_b32_e32 v17, 16, v13
	v_lshlrev_b32_e32 v16, 16, v12
	v_and_b32_e32 v13, 0xffff0000, v13
	v_and_b32_e32 v12, 0xffff0000, v12
	v_pk_mul_f32 v[16:17], v[16:17], s[6:7] op_sel_hi:[1,0]
	v_mul_f32_e32 v9, 0x3fb8aa3b, v9
	v_pk_mul_f32 v[12:13], v[12:13], s[6:7] op_sel_hi:[1,0]
	v_pk_mul_f32 v[20:21], v[16:17], v[22:23]
	v_exp_f32_e32 v29, v9
	v_pk_mul_f32 v[18:19], v[12:13], v[18:19]
	s_nop 0
	v_and_b32_sdwa v22, v20, v38 dst_sel:DWORD dst_unused:UNUSED_PAD src0_sel:WORD_1 src1_sel:DWORD
	s_nop 0
	v_cvt_pk_bf16_f32 v19, v21, v19
	v_add3_u32 v20, v20, v22, s45
	v_and_b32_sdwa v22, v18, v38 dst_sel:DWORD dst_unused:UNUSED_PAD src0_sel:WORD_1 src1_sel:DWORD
	s_nop 0
	v_add3_u32 v18, v18, v22, s45
	v_and_b32_e32 v18, 0xffff0000, v18
	s_nop 0
	v_ashrrev_i32_e32 v9, 31, v8
	v_or_b32_sdwa v18, v18, v20 dst_sel:DWORD dst_unused:UNUSED_PAD src0_sel:DWORD src1_sel:WORD_1
	v_lshlrev_b64 v[20:21], 8, v[8:9]
	v_lshl_add_u64 v[20:21], v[34:35], 0, v[20:21]
	v_pk_mul_f32 v[16:17], v[16:17], v[24:25]
	global_store_dwordx2 v[20:21], v[18:19], off
	v_pk_mul_f32 v[12:13], v[12:13], v[26:27]
	s_nop 0
	v_and_b32_sdwa v18, v16, v38 dst_sel:DWORD dst_unused:UNUSED_PAD src0_sel:WORD_1 src1_sel:DWORD
	v_add3_u32 v16, v16, v18, s45
	s_nop 0
	v_cvt_pk_bf16_f32 v13, v17, v13
	v_and_b32_sdwa v18, v12, v38 dst_sel:DWORD dst_unused:UNUSED_PAD src0_sel:WORD_1 src1_sel:DWORD
	s_nop 0
	v_add3_u32 v12, v12, v18, s45
	v_lshlrev_b32_e32 v19, 16, v11
	v_lshlrev_b32_e32 v18, 16, v10
	v_and_b32_e32 v12, 0xffff0000, v12
	v_and_b32_e32 v11, 0xffff0000, v11
	v_and_b32_e32 v10, 0xffff0000, v10
	v_pk_mul_f32 v[14:15], v[14:15], v[18:19]
	s_nop 0
	v_or_b32_sdwa v12, v12, v16 dst_sel:DWORD dst_unused:UNUSED_PAD src0_sel:DWORD src1_sel:WORD_1
	v_mad_u64_u32 v[16:17], s[0:1], v8, s46, v[2:3]
	v_pk_mul_f32 v[10:11], v[28:29], v[10:11]
	v_and_b32_sdwa v2, v15, v38 dst_sel:DWORD dst_unused:UNUSED_PAD src0_sel:WORD_1 src1_sel:DWORD
	v_and_b32_sdwa v9, v14, v38 dst_sel:DWORD dst_unused:UNUSED_PAD src0_sel:WORD_1 src1_sel:DWORD
	v_add3_u32 v9, v14, v9, s45
	v_add3_u32 v2, v15, v2, s45
	v_and_b32_sdwa v14, v11, v38 dst_sel:DWORD dst_unused:UNUSED_PAD src0_sel:WORD_1 src1_sel:DWORD
	v_and_b32_sdwa v15, v10, v38 dst_sel:DWORD dst_unused:UNUSED_PAD src0_sel:WORD_1 src1_sel:DWORD
	v_add3_u32 v14, v11, v14, s45
	v_add3_u32 v15, v10, v15, s45
	v_and_b32_e32 v10, 0xffff0000, v14
	v_and_b32_e32 v17, 0xffff0000, v15
	v_lshlrev_b32_e32 v8, 1, v8
	v_or_b32_sdwa v11, v10, v2 dst_sel:DWORD dst_unused:UNUSED_PAD src0_sel:DWORD src1_sel:WORD_1
	v_or_b32_sdwa v10, v17, v9 dst_sel:DWORD dst_unused:UNUSED_PAD src0_sel:DWORD src1_sel:WORD_1
	v_add3_u32 v8, s22, v8, v48
	ds_write2st64_b64 v16, v[12:13], v[10:11] offset1:66
	ds_write_b16_d16_hi v8, v9
	ds_write_b16_d16_hi v8, v15 offset:144
	ds_write_b16_d16_hi v8, v2 offset:288
	ds_write_b16_d16_hi v8, v14 offset:432
	v_lshlrev_b32_e32 v2, 3, v36
	v_and_or_b32 v8, v2, s48, v39
	v_lshl_add_u32 v2, v7, 4, 0
	v_mad_u64_u32 v[28:29], s[0:1], v8, s46, v[2:3]
	s_waitcnt lgkmcnt(0)
	s_barrier
	ds_read_b128 v[8:11], v28
	v_lshlrev_b32_e32 v12, 5, v36
	v_and_or_b32 v36, v12, 32, v39
	v_mad_u32_u24 v2, v36, s46, v2
	ds_read_b128 v[12:15], v28 offset:64
	ds_read_b128 v[16:19], v2 offset:33792
	ds_read_b128 v[20:23], v2 offset:33856
	ds_read_b128 v[24:27], v28 offset:128
	s_waitcnt lgkmcnt(2)
	v_mfma_f32_16x16x32_bf16 v[16:19], v[8:11], v[16:19], 0
	s_waitcnt lgkmcnt(1)
	v_mfma_f32_16x16x32_bf16 v[16:19], v[12:15], v[20:23], v[16:19]
	ds_read_b128 v[20:23], v28 offset:192
	ds_read_b128 v[28:31], v2 offset:33920
	ds_read_b128 v[32:35], v2 offset:33984
	s_waitcnt lgkmcnt(1)
	v_mfma_f32_16x16x32_bf16 v[16:19], v[24:27], v[28:31], v[16:19]
	s_waitcnt lgkmcnt(0)
	v_mfma_f32_16x16x32_bf16 v[16:19], v[20:23], v[32:35], v[16:19]
	ds_read_b128 v[28:31], v2 offset:42240
	ds_read_b128 v[32:35], v2 offset:42304
	s_waitcnt lgkmcnt(1)
	v_mfma_f32_16x16x32_bf16 v[8:11], v[8:11], v[28:31], 0
	s_waitcnt lgkmcnt(0)
	v_mfma_f32_16x16x32_bf16 v[8:11], v[12:15], v[32:35], v[8:11]
	ds_read_b128 v[12:15], v2 offset:42368
	ds_read_b128 v[28:31], v2 offset:42432
	v_ashrrev_i32_e32 v2, 3, v6
	v_and_b32_e32 v2, -16, v2
	v_lshl_or_b32 v2, v7, 2, v2
	v_cmp_le_i32_e64 s[0:1], v36, v2
	s_waitcnt lgkmcnt(1)
	v_mfma_f32_16x16x32_bf16 v[8:11], v[24:27], v[12:15], v[8:11]
	v_lshl_add_u32 v6, v36, 1, s49
	v_cndmask_b32_e64 v7, 0, 1, s[0:1]
	v_cmp_ge_i32_e64 s[0:1], v36, v2
	s_waitcnt lgkmcnt(0)
	v_mfma_f32_16x16x32_bf16 v[8:11], v[20:23], v[28:31], v[8:11]
	v_cndmask_b32_e64 v12, 0, 1, s[0:1]
	v_cndmask_b32_e32 v7, v12, v7, vcc
	v_and_b32_e32 v7, 1, v7
	v_cmp_eq_u32_e64 s[0:1], 1, v7
	s_nop 1
	v_cndmask_b32_e64 v7, 0, v16, s[0:1]
	v_bfe_u32 v12, v7, 16, 1
	v_add3_u32 v7, v7, v12, s45
	v_mul_lo_u32 v12, v2, s47
	v_add_u32_e32 v13, v6, v12
	ds_write_b16_d16_hi v13, v7
	v_or_b32_e32 v7, 1, v2
	v_cmp_gt_i32_e64 s[0:1], v36, v2
	s_nop 1
	v_cndmask_b32_e64 v13, 0, 1, s[0:1]
	v_cmp_le_i32_e64 s[0:1], v36, v7
	s_nop 1
	v_cndmask_b32_e64 v14, 0, 1, s[0:1]
	v_cndmask_b32_e32 v13, v13, v14, vcc
	v_and_b32_e32 v13, 1, v13
	v_cmp_eq_u32_e64 s[0:1], 1, v13
	s_nop 1
	v_cndmask_b32_e64 v13, 0, v17, s[0:1]
	v_bfe_u32 v14, v13, 16, 1
	v_add3_u32 v13, v13, v14, s45
	v_add_u32_e32 v14, 0x90, v12
	v_add_u32_e32 v15, v6, v14
	ds_write_b16_d16_hi v15, v13
	v_or_b32_e32 v13, 2, v2
	v_cmp_le_i32_e64 s[0:1], v36, v13
	s_nop 1
	v_cndmask_b32_e64 v15, 0, 1, s[0:1]
	v_cmp_ge_i32_e64 s[0:1], v36, v13
	s_nop 1
	v_cndmask_b32_e64 v16, 0, 1, s[0:1]
	v_cndmask_b32_e32 v15, v16, v15, vcc
	v_and_b32_e32 v15, 1, v15
	v_cmp_eq_u32_e64 s[0:1], 1, v15
	s_nop 1
	v_cndmask_b32_e64 v15, 0, v18, s[0:1]
	v_bfe_u32 v16, v15, 16, 1
	v_add3_u32 v15, v15, v16, s45
	v_add_u32_e32 v16, 0x120, v12
	v_add_u32_e32 v17, v6, v16
	ds_write_b16_d16_hi v17, v15
	v_or_b32_e32 v15, 3, v2
	v_cmp_le_i32_e64 s[0:1], v36, v15
	s_nop 1
	v_cndmask_b32_e64 v17, 0, 1, s[0:1]
	v_cmp_ge_i32_e64 s[0:1], v36, v15
	s_nop 1
	v_cndmask_b32_e64 v18, 0, 1, s[0:1]
	v_cndmask_b32_e32 v17, v18, v17, vcc
	v_and_b32_e32 v17, 1, v17
	v_cmp_eq_u32_e64 s[0:1], 1, v17
	s_nop 1
	v_cndmask_b32_e64 v17, 0, v19, s[0:1]
	v_bfe_u32 v18, v17, 16, 1
	v_add3_u32 v17, v17, v18, s45
	v_add_u32_e32 v18, 0x1b0, v12
	v_add_u32_e32 v6, v6, v18
	ds_write_b16_d16_hi v6, v17
	v_or_b32_e32 v6, 16, v36
	v_cmp_le_i32_e64 s[0:1], v6, v2
	s_nop 1
	v_cndmask_b32_e64 v17, 0, 1, s[0:1]
	v_cmp_ge_i32_e64 s[0:1], v6, v2
	s_nop 1
	v_cndmask_b32_e64 v19, 0, 1, s[0:1]
	v_cndmask_b32_e32 v17, v19, v17, vcc
	v_and_b32_e32 v17, 1, v17
	v_cmp_eq_u32_e64 s[0:1], 1, v17
	s_nop 1
	v_cndmask_b32_e64 v8, 0, v8, s[0:1]
	v_cmp_le_i32_e64 s[0:1], v6, v7
	v_bfe_u32 v17, v8, 16, 1
	v_add3_u32 v8, v8, v17, s45
	v_cndmask_b32_e64 v7, 0, 1, s[0:1]
	v_cmp_gt_i32_e64 s[0:1], v6, v2
	v_lshlrev_b32_e32 v17, 1, v6
	v_add3_u32 v12, s49, v12, v17
	v_cndmask_b32_e64 v2, 0, 1, s[0:1]
	v_cndmask_b32_e32 v2, v2, v7, vcc
	v_and_b32_e32 v2, 1, v2
	v_cmp_eq_u32_e64 s[0:1], 1, v2
	ds_write_b16_d16_hi v12, v8
	s_nop 0
	v_cndmask_b32_e64 v2, 0, v9, s[0:1]
	v_bfe_u32 v7, v2, 16, 1
	v_add3_u32 v2, v2, v7, s45
	v_add3_u32 v7, s49, v14, v17
	v_cmp_le_i32_e64 s[0:1], v6, v13
	ds_write_b16_d16_hi v7, v2
	s_nop 0
	v_cndmask_b32_e64 v2, 0, 1, s[0:1]
	v_cmp_ge_i32_e64 s[0:1], v6, v13
	s_nop 1
	v_cndmask_b32_e64 v7, 0, 1, s[0:1]
	v_cndmask_b32_e32 v2, v7, v2, vcc
	v_and_b32_e32 v2, 1, v2
	v_cmp_eq_u32_e64 s[0:1], 1, v2
	s_nop 1
	v_cndmask_b32_e64 v2, 0, v10, s[0:1]
	v_bfe_u32 v7, v2, 16, 1
	v_add3_u32 v2, v2, v7, s45
	v_add3_u32 v7, s49, v16, v17
	v_cmp_le_i32_e64 s[0:1], v6, v15
	ds_write_b16_d16_hi v7, v2
	s_nop 0
	v_cndmask_b32_e64 v2, 0, 1, s[0:1]
	v_cmp_ge_i32_e64 s[0:1], v6, v15
	s_nop 1
	v_cndmask_b32_e64 v6, 0, 1, s[0:1]
	v_cndmask_b32_e32 v2, v6, v2, vcc
	v_and_b32_e32 v2, 1, v2
	v_cmp_eq_u32_e64 s[0:1], 1, v2
	s_nop 1
	v_cndmask_b32_e64 v2, 0, v11, s[0:1]
	v_bfe_u32 v6, v2, 16, 1
	v_add3_u32 v2, v2, v6, s45
	v_add3_u32 v6, s49, v18, v17
	ds_write_b16_d16_hi v6, v2
	v_mov_b32_e32 v6, v0
	s_waitcnt lgkmcnt(0)
	s_barrier
	s_nop 0
	v_cmp_gt_i32_e64 s[0:1], s19, v6
	s_and_saveexec_b64 s[14:15], s[0:1]
	s_cbranch_execz .LBB0_1633
	s_lshl_b64 s[0:1], s[8:9], 13
	v_readlane_b32 s8, v238, 9
	s_add_u32 s8, s8, s0
	v_readlane_b32 s0, v238, 7
	s_addc_u32 s9, s0, s1
	v_lshlrev_b32_e32 v7, 3, v6
	s_mov_b64 s[16:17], 0

.LBB0_1701:
	v_add_u32_e32 v27, 0x400, v26
	v_lshlrev_b32_e32 v38, 16, v10
	ds_read2_b32 v[30:31], v26 offset1:65
	ds_read2_b32 v[32:33], v26 offset0:130 offset1:195
	ds_read2_b32 v[34:35], v27 offset0:4 offset1:69
	ds_read2_b32 v[36:37], v27 offset0:134 offset1:199
	v_mul_f32_e32 v27, 0xbfb8aa3b, v38
	v_exp_f32_e32 v27, v27
	v_lshlrev_b32_e32 v39, 16, v11
	v_mul_f32_e32 v40, 0xbfb8aa3b, v39
	v_exp_f32_e32 v41, v40
	v_and_b32_e32 v10, 0xffff0000, v10
	v_add_f32_e32 v27, 1.0, v27
	v_and_b32_e32 v11, 0xffff0000, v11
	v_rcp_f32_e32 v40, v27
	v_mul_f32_e32 v27, 0xbfb8aa3b, v10
	v_exp_f32_e32 v27, v27
	v_add_f32_e32 v41, 1.0, v41
	v_mul_f32_e32 v42, 0xbfb8aa3b, v11
	v_rcp_f32_e32 v41, v41
	v_exp_f32_e32 v43, v42
	v_add_f32_e32 v27, 1.0, v27
	v_rcp_f32_e32 v42, v27
	v_pk_mul_f32 v[38:39], v[40:41], v[38:39]
	v_add_f32_e32 v27, 1.0, v43
	s_waitcnt lgkmcnt(3)
	v_mov_b32_e32 v40, v30
	v_lshlrev_b32_e32 v30, 16, v12
	v_rcp_f32_e32 v43, v27
	v_mul_f32_e32 v27, 0xbfb8aa3b, v30
	v_exp_f32_e32 v27, v27
	s_waitcnt lgkmcnt(2)
	v_mov_b32_e32 v41, v32
	v_pk_mul_f32 v[10:11], v[42:43], v[10:11]
	v_mov_b32_e32 v32, v31
	v_lshlrev_b32_e32 v31, 16, v13
	v_pk_mul_f32 v[10:11], v[10:11], v[32:33]
	v_and_b32_e32 v12, 0xffff0000, v12
	v_add_f32_e32 v27, 1.0, v27
	v_mul_f32_e32 v32, 0xbfb8aa3b, v31
	v_and_b32_e32 v13, 0xffff0000, v13
	v_exp_f32_e32 v33, v32
	v_rcp_f32_e32 v32, v27
	v_mul_f32_e32 v27, 0xbfb8aa3b, v12
	v_pk_mul_f32 v[38:39], v[38:39], v[40:41]
	v_exp_f32_e32 v27, v27
	v_mul_f32_e32 v40, 0xbfb8aa3b, v13
	v_exp_f32_e32 v41, v40
	v_add_f32_e32 v33, 1.0, v33
	v_add_f32_e32 v27, 1.0, v27
	v_rcp_f32_e32 v40, v27
	v_add_f32_e32 v27, 1.0, v41
	v_rcp_f32_e32 v33, v33
	v_rcp_f32_e32 v41, v27
	s_and_b32 s26, s47, 0xffffffc0
	v_add_u32_e32 v28, s26, v23
	v_pk_mul_f32 v[30:31], v[32:33], v[30:31]
	s_waitcnt lgkmcnt(0)
	v_mov_b32_e32 v33, v36
	v_pk_mul_f32 v[12:13], v[40:41], v[12:13]
	v_mov_b32_e32 v36, v35
	v_mov_b32_e32 v32, v34
	v_pk_mul_f32 v[12:13], v[12:13], v[36:37]
	v_ashrrev_i32_e32 v29, 31, v28
	v_pk_mul_f32 v[30:31], v[30:31], v[32:33]
	v_bfe_u32 v27, v13, 16, 1
	v_bfe_u32 v32, v12, 16, 1
	v_bfe_u32 v33, v11, 16, 1
	v_cvt_pk_bf16_f32 v10, v38, v10
	s_and_b32 s36, s46, 0x3c0
	v_add3_u32 v11, v11, v33, s44
	v_add3_u32 v12, v12, v32, s44
	v_add3_u32 v13, v13, v27, s44
	v_bfe_u32 v32, v39, 16, 1
	v_bfe_u32 v33, v30, 16, 1
	v_bfe_u32 v34, v31, 16, 1
	v_lshlrev_b64 v[28:29], 13, v[28:29]
	v_add3_u32 v31, v31, v34, s44
	v_add3_u32 v30, v30, v33, s44
	v_add3_u32 v32, v39, v32, s44
	v_lshl_add_u64 v[28:29], s[12:13], 0, v[28:29]
	s_lshl_b32 s26, s36, 1
	v_lshrrev_b32_e32 v32, 16, v32
	v_lshrrev_b32_e32 v30, 16, v30
	v_lshrrev_b32_e32 v31, 16, v31
	v_lshl_add_u64 v[28:29], v[28:29], 0, s[26:27]
	v_and_or_b32 v13, v13, s41, v31
	v_and_or_b32 v12, v12, s41, v30
	v_and_or_b32 v11, v11, s41, v32
	v_lshl_add_u64 v[28:29], v[28:29], 0, v[18:19]
	global_store_dwordx4 v[28:29], v[10:13], off offset:2048
	s_waitcnt lgkmcnt(0)
	s_barrier
	s_andn2_b64 vcc, exec, s[34:35]
	s_mov_b32 s46, s45
	s_waitcnt vmcnt(1)
	v_mov_b64_e32 v[10:11], v[14:15]
	s_mov_b32 s47, s29
	v_mov_b64_e32 v[12:13], v[16:17]
	s_cbranch_vccz .LBB0_1706

.LBB0_1709:
	v_ashrrev_i32_e32 v37, 8, v18
	v_and_b32_e32 v34, 0xff, v18
	v_lshlrev_b32_e32 v19, 13, v37
	v_lshlrev_b32_e32 v20, 1, v34
	v_add3_u32 v38, s25, v19, v20
	v_add3_u32 v19, s54, v19, v20
	ds_read_u16 v20, v38
	ds_read_u16 v22, v38 offset:512
	ds_read_u16 v24, v38 offset:1024
	ds_read_u16 v26, v38 offset:1536
	ds_read_u16 v28, v38 offset:2048
	ds_read_u16 v39, v38 offset:2560
	ds_read_u16 v42, v38 offset:3072
	ds_read_u16 v44, v38 offset:3584
	ds_read_u16 v21, v19
	ds_read_u16 v23, v19 offset:512
	ds_read_u16 v25, v19 offset:1024
	ds_read_u16 v27, v19 offset:1536
	ds_read_u16 v29, v19 offset:2048
	ds_read_u16 v41, v19 offset:2560
	ds_read_u16 v43, v19 offset:3072
	ds_read_u16 v45, v19 offset:3584
	s_waitcnt lgkmcnt(7)
	v_lshlrev_b32_e32 v21, 16, v21
	v_lshlrev_b32_e32 v40, 16, v39
	s_waitcnt lgkmcnt(2)
	v_lshlrev_b32_e32 v39, 16, v41
	v_xor_b32_e32 v41, 0x80000000, v39
	s_waitcnt lgkmcnt(1)
	v_lshlrev_b32_e32 v39, 16, v43
	v_xor_b32_e32 v43, 0x80000000, v39
	s_waitcnt lgkmcnt(0)
	v_lshlrev_b32_e32 v39, 16, v45
	v_xor_b32_e32 v45, 0x80000000, v39
	ds_read_u16 v39, v38 offset:4096
	ds_read_u16 v48, v38 offset:4608
	ds_read_u16 v50, v38 offset:5120
	ds_read_u16 v52, v38 offset:5632
	ds_read_u16 v54, v38 offset:6144
	ds_read_u16 v56, v38 offset:6656
	ds_read_u16 v58, v38 offset:7168
	ds_read_u16 v38, v38 offset:7680
	s_waitcnt lgkmcnt(7)
	v_lshlrev_b32_e32 v46, 16, v39
	ds_read_u16 v39, v19 offset:4096
	ds_read_u16 v49, v19 offset:4608
	ds_read_u16 v51, v19 offset:5120
	ds_read_u16 v53, v19 offset:5632
	ds_read_u16 v55, v19 offset:6144
	ds_read_u16 v57, v19 offset:6656
	ds_read_u16 v59, v19 offset:7168
	ds_read_u16 v19, v19 offset:7680
	s_waitcnt lgkmcnt(7)
	v_lshlrev_b32_e32 v39, 16, v39
	v_xor_b32_e32 v47, 0x80000000, v39
	s_waitcnt lgkmcnt(6)
	v_lshlrev_b32_e32 v39, 16, v49
	v_xor_b32_e32 v49, 0x80000000, v39
	s_waitcnt lgkmcnt(5)
	v_lshlrev_b32_e32 v39, 16, v51
	v_xor_b32_e32 v51, 0x80000000, v39
	s_waitcnt lgkmcnt(4)
	v_lshlrev_b32_e32 v39, 16, v53
	v_lshlrev_b32_e32 v29, 16, v29
	v_xor_b32_e32 v53, 0x80000000, v39
	s_waitcnt lgkmcnt(3)
	v_lshlrev_b32_e32 v39, 16, v55
	v_lshlrev_b32_e32 v20, 16, v20
	v_xor_b32_e32 v21, 0x80000000, v21
	v_lshlrev_b32_e32 v23, 16, v23
	v_lshlrev_b32_e32 v28, 16, v28
	v_xor_b32_e32 v29, 0x80000000, v29
	v_lshlrev_b32_e32 v54, 16, v54
	v_xor_b32_e32 v55, 0x80000000, v39
	s_waitcnt lgkmcnt(2)
	v_lshlrev_b32_e32 v39, 16, v57
	s_waitcnt lgkmcnt(0)
	v_lshlrev_b32_e32 v19, 16, v19
	v_lshlrev_b32_e32 v22, 16, v22
	v_xor_b32_e32 v23, 0x80000000, v23
	v_lshlrev_b32_e32 v25, 16, v25
	v_lshlrev_b32_e32 v48, 16, v48
	v_lshlrev_b32_e32 v56, 16, v56
	v_xor_b32_e32 v57, 0x80000000, v39
	v_lshlrev_b32_e32 v39, 16, v59
	v_lshlrev_b32_e32 v60, 16, v38
	v_xor_b32_e32 v61, 0x80000000, v19
	v_bfe_u32 v38, v18, 4, 4
	v_pk_add_f32 v[18:19], v[20:21], v[46:47]
	v_pk_add_f32 v[20:21], v[20:21], v[46:47] neg_lo:[0,1] neg_hi:[0,1]
	v_pk_add_f32 v[46:47], v[28:29], v[54:55]
	v_pk_add_f32 v[28:29], v[28:29], v[54:55] neg_lo:[0,1] neg_hi:[0,1]
	v_lshlrev_b32_e32 v24, 16, v24
	v_xor_b32_e32 v25, 0x80000000, v25
	v_lshlrev_b32_e32 v27, 16, v27
	v_lshlrev_b32_e32 v42, 16, v42
	v_lshlrev_b32_e32 v50, 16, v50
	v_lshlrev_b32_e32 v58, 16, v58
	v_xor_b32_e32 v59, 0x80000000, v39
	v_pk_add_f32 v[54:55], v[18:19], v[46:47]
	v_pk_add_f32 v[46:47], v[18:19], v[46:47] neg_lo:[0,1] neg_hi:[0,1]
	v_pk_add_f32 v[62:63], v[20:21], v[28:29] op_sel:[0,1] op_sel_hi:[1,0] neg_hi:[0,1]
	v_pk_add_f32 v[64:65], v[20:21], v[28:29] op_sel:[0,1] op_sel_hi:[1,0] neg_lo:[0,1]
	v_pk_add_f32 v[18:19], v[22:23], v[48:49]
	v_pk_add_f32 v[20:21], v[22:23], v[48:49] neg_lo:[0,1] neg_hi:[0,1]
	v_pk_add_f32 v[22:23], v[40:41], v[56:57]
	v_pk_add_f32 v[28:29], v[40:41], v[56:57] neg_lo:[0,1] neg_hi:[0,1]
	v_lshlrev_b32_e32 v26, 16, v26
	v_xor_b32_e32 v27, 0x80000000, v27
	v_lshlrev_b32_e32 v44, 16, v44
	v_lshlrev_b32_e32 v52, 16, v52
	v_pk_add_f32 v[40:41], v[18:19], v[22:23]
	v_pk_add_f32 v[22:23], v[18:19], v[22:23] neg_lo:[0,1] neg_hi:[0,1]
	v_pk_add_f32 v[18:19], v[20:21], v[28:29] op_sel:[0,1] op_sel_hi:[1,0] neg_hi:[0,1]
	v_pk_add_f32 v[28:29], v[20:21], v[28:29] op_sel:[0,1] op_sel_hi:[1,0] neg_lo:[0,1]
	v_pk_add_f32 v[20:21], v[24:25], v[50:51]
	v_pk_add_f32 v[24:25], v[24:25], v[50:51] neg_lo:[0,1] neg_hi:[0,1]
	v_pk_add_f32 v[48:49], v[42:43], v[58:59]
	v_pk_add_f32 v[42:43], v[42:43], v[58:59] neg_lo:[0,1] neg_hi:[0,1]
	v_pk_add_f32 v[50:51], v[20:21], v[48:49]
	v_pk_add_f32 v[48:49], v[20:21], v[48:49] neg_lo:[0,1] neg_hi:[0,1]
	v_pk_add_f32 v[56:57], v[24:25], v[42:43] op_sel:[0,1] op_sel_hi:[1,0] neg_hi:[0,1]
	v_pk_add_f32 v[42:43], v[24:25], v[42:43] op_sel:[0,1] op_sel_hi:[1,0] neg_lo:[0,1]
	v_pk_add_f32 v[20:21], v[26:27], v[52:53]
	v_pk_add_f32 v[24:25], v[26:27], v[52:53] neg_lo:[0,1] neg_hi:[0,1]
	v_pk_add_f32 v[26:27], v[44:45], v[60:61]
	v_pk_add_f32 v[44:45], v[44:45], v[60:61] neg_lo:[0,1] neg_hi:[0,1]
	v_pk_add_f32 v[52:53], v[20:21], v[26:27]
	v_pk_add_f32 v[58:59], v[20:21], v[26:27] neg_lo:[0,1] neg_hi:[0,1]
	v_pk_add_f32 v[26:27], v[24:25], v[44:45] op_sel:[0,1] op_sel_hi:[1,0] neg_hi:[0,1]
	v_pk_add_f32 v[44:45], v[24:25], v[44:45] op_sel:[0,1] op_sel_hi:[1,0] neg_lo:[0,1]
	v_mov_b64_e32 v[24:25], s[38:39]
	v_pk_mul_f32 v[20:21], v[18:19], v[24:25] op_sel:[0,0] op_sel_hi:[0,1]
	v_mad_i32_i24 v35, v37, s3, 0
	v_pk_fma_f32 v[60:61], v[18:19], v[24:25], v[20:21] op_sel:[1,1,0] op_sel_hi:[1,0,1] neg_lo:[0,1,0]
	v_mov_b64_e32 v[20:21], s[40:41]
	v_pk_mul_f32 v[18:19], v[56:57], v[20:21] op_sel:[0,0] op_sel_hi:[0,1]
	v_lshlrev_b32_e32 v39, 3, v34
	v_pk_fma_f32 v[56:57], v[56:57], v[20:21], v[18:19] op_sel:[1,1,0] op_sel_hi:[1,0,1] neg_lo:[0,1,0]
	v_mov_b64_e32 v[18:19], s[44:45]
	v_pk_mul_f32 v[66:67], v[26:27], v[18:19] op_sel:[0,0] op_sel_hi:[0,1]
	v_lshlrev_b32_e32 v74, 3, v38
	v_pk_fma_f32 v[66:67], v[26:27], v[18:19], v[66:67] op_sel:[1,1,0] op_sel_hi:[1,0,1] neg_lo:[0,1,0]
	v_pk_mul_f32 v[26:27], v[22:23], v[20:21] op_sel:[0,0] op_sel_hi:[0,1]
	v_add3_u32 v74, v35, v39, v74
	v_pk_fma_f32 v[68:69], v[22:23], v[20:21], v[26:27] op_sel:[1,1,0] op_sel_hi:[1,0,1] neg_lo:[0,1,0]
	v_mov_b64_e32 v[26:27], s[36:37]
	v_pk_mul_f32 v[22:23], v[48:49], v[26:27] op_sel:[0,0] op_sel_hi:[0,1]
	v_lshl_add_u32 v78, v38, 11, v35
	v_pk_fma_f32 v[48:49], v[48:49], v[26:27], v[22:23] op_sel:[1,1,0] op_sel_hi:[1,0,1] neg_lo:[0,1,0]
	v_mov_b64_e32 v[22:23], s[46:47]
	v_pk_mul_f32 v[70:71], v[58:59], v[22:23] op_sel:[0,0] op_sel_hi:[0,1]
	v_add_u32_e32 v39, v78, v39
	v_pk_fma_f32 v[58:59], v[58:59], v[22:23], v[70:71] op_sel:[1,1,0] op_sel_hi:[1,0,1] neg_lo:[0,1,0]
	v_pk_mul_f32 v[70:71], v[28:29], v[18:19] op_sel:[0,0] op_sel_hi:[0,1]
	s_nop 0
	v_pk_fma_f32 v[70:71], v[28:29], v[18:19], v[70:71] op_sel:[1,1,0] op_sel_hi:[1,0,1] neg_lo:[0,1,0]
	v_pk_mul_f32 v[28:29], v[42:43], v[22:23] op_sel:[0,0] op_sel_hi:[0,1]
	s_nop 0
	v_pk_fma_f32 v[42:43], v[42:43], v[22:23], v[28:29] op_sel:[1,1,0] op_sel_hi:[1,0,1] neg_lo:[0,1,0]
	v_mov_b64_e32 v[28:29], s[48:49]
	v_pk_mul_f32 v[72:73], v[44:45], v[28:29] op_sel:[0,0] op_sel_hi:[0,1]
	s_nop 0
	v_pk_fma_f32 v[44:45], v[44:45], v[28:29], v[72:73] op_sel:[1,1,0] op_sel_hi:[1,0,1] neg_lo:[0,1,0]
	v_pk_add_f32 v[72:73], v[54:55], v[50:51]
	v_pk_add_f32 v[50:51], v[54:55], v[50:51] neg_lo:[0,1] neg_hi:[0,1]
	v_pk_add_f32 v[54:55], v[40:41], v[52:53]
	v_pk_add_f32 v[40:41], v[40:41], v[52:53] neg_lo:[0,1] neg_hi:[0,1]
	v_pk_add_f32 v[52:53], v[72:73], v[54:55]
	v_pk_add_f32 v[54:55], v[72:73], v[54:55] neg_lo:[0,1] neg_hi:[0,1]
	v_pk_add_f32 v[72:73], v[50:51], v[40:41] op_sel:[0,1] op_sel_hi:[1,0] neg_hi:[0,1]
	v_pk_add_f32 v[40:41], v[50:51], v[40:41] op_sel:[0,1] op_sel_hi:[1,0] neg_lo:[0,1]
	v_pk_add_f32 v[50:51], v[62:63], v[56:57]
	v_pk_add_f32 v[56:57], v[62:63], v[56:57] neg_lo:[0,1] neg_hi:[0,1]
	v_pk_add_f32 v[62:63], v[60:61], v[66:67]
	v_pk_add_f32 v[60:61], v[60:61], v[66:67] neg_lo:[0,1] neg_hi:[0,1]
	v_pk_add_f32 v[66:67], v[50:51], v[62:63]
	v_pk_add_f32 v[50:51], v[50:51], v[62:63] neg_lo:[0,1] neg_hi:[0,1]
	v_pk_add_f32 v[62:63], v[56:57], v[60:61] op_sel:[0,1] op_sel_hi:[1,0] neg_hi:[0,1]
	v_pk_add_f32 v[56:57], v[56:57], v[60:61] op_sel:[0,1] op_sel_hi:[1,0] neg_lo:[0,1]
	v_pk_add_f32 v[60:61], v[46:47], v[48:49]
	v_pk_add_f32 v[46:47], v[46:47], v[48:49] neg_lo:[0,1] neg_hi:[0,1]
	v_pk_add_f32 v[48:49], v[68:69], v[58:59]
	v_pk_add_f32 v[58:59], v[68:69], v[58:59] neg_lo:[0,1] neg_hi:[0,1]
	v_pk_add_f32 v[68:69], v[60:61], v[48:49]
	v_pk_add_f32 v[48:49], v[60:61], v[48:49] neg_lo:[0,1] neg_hi:[0,1]
	v_pk_add_f32 v[60:61], v[46:47], v[58:59] op_sel:[0,1] op_sel_hi:[1,0] neg_hi:[0,1]
	v_pk_add_f32 v[46:47], v[46:47], v[58:59] op_sel:[0,1] op_sel_hi:[1,0] neg_lo:[0,1]
	v_pk_add_f32 v[58:59], v[64:65], v[42:43]
	v_pk_add_f32 v[42:43], v[64:65], v[42:43] neg_lo:[0,1] neg_hi:[0,1]
	v_pk_add_f32 v[64:65], v[70:71], v[44:45]
	v_pk_add_f32 v[44:45], v[70:71], v[44:45] neg_lo:[0,1] neg_hi:[0,1]
	v_pk_add_f32 v[70:71], v[58:59], v[64:65]
	v_pk_add_f32 v[58:59], v[58:59], v[64:65] neg_lo:[0,1] neg_hi:[0,1]
	v_pk_add_f32 v[64:65], v[42:43], v[44:45] op_sel:[0,1] op_sel_hi:[1,0] neg_hi:[0,1]
	v_pk_add_f32 v[42:43], v[42:43], v[44:45] op_sel:[0,1] op_sel_hi:[1,0] neg_lo:[0,1]
	v_mov_b32_e32 v44, v1
	v_mov_b32_e32 v45, v31
	ds_write_b64 v74, v[52:53]
	v_pk_mul_f32 v[52:53], v[66:67], v[44:45] op_sel:[0,0] op_sel_hi:[0,1]
	s_nop 0
	v_pk_fma_f32 v[52:53], v[66:67], v[44:45], v[52:53] op_sel:[1,1,0] op_sel_hi:[1,0,1] neg_lo:[0,1,0]
	ds_write_b64 v74, v[52:53] offset:2176
	v_pk_mul_f32 v[52:53], v[44:45], v[44:45] op_sel:[0,0] op_sel_hi:[0,1]
	s_nop 0
	v_pk_fma_f32 v[52:53], v[44:45], v[44:45], v[52:53] op_sel:[1,1,0] op_sel_hi:[1,0,1] neg_lo:[0,1,0]
	s_nop 0
	v_pk_mul_f32 v[66:67], v[68:69], v[52:53] op_sel:[0,0] op_sel_hi:[0,1]
	s_nop 0
	v_pk_fma_f32 v[66:67], v[68:69], v[52:53], v[66:67] op_sel:[1,1,0] op_sel_hi:[1,0,1] neg_lo:[0,1,0]
	ds_write_b64 v74, v[66:67] offset:4352
	v_pk_mul_f32 v[66:67], v[52:53], v[44:45] op_sel:[0,0] op_sel_hi:[0,1]
	s_nop 0
	v_pk_fma_f32 v[52:53], v[52:53], v[44:45], v[66:67] op_sel:[1,1,0] op_sel_hi:[1,0,1] neg_lo:[0,1,0]
	s_nop 0
	v_pk_mul_f32 v[66:67], v[70:71], v[52:53] op_sel:[0,0] op_sel_hi:[0,1]
	s_nop 0
	v_pk_fma_f32 v[66:67], v[70:71], v[52:53], v[66:67] op_sel:[1,1,0] op_sel_hi:[1,0,1] neg_lo:[0,1,0]
	ds_write_b64 v74, v[66:67] offset:6528
	v_pk_mul_f32 v[66:67], v[52:53], v[44:45] op_sel:[0,0] op_sel_hi:[0,1]
	s_nop 0
	v_pk_fma_f32 v[52:53], v[52:53], v[44:45], v[66:67] op_sel:[1,1,0] op_sel_hi:[1,0,1] neg_lo:[0,1,0]
	s_nop 0
	v_pk_mul_f32 v[66:67], v[72:73], v[52:53] op_sel:[0,0] op_sel_hi:[0,1]
	s_nop 0
	v_pk_fma_f32 v[66:67], v[72:73], v[52:53], v[66:67] op_sel:[1,1,0] op_sel_hi:[1,0,1] neg_lo:[0,1,0]
	ds_write_b64 v74, v[66:67] offset:8704
	v_pk_mul_f32 v[66:67], v[52:53], v[44:45] op_sel:[0,0] op_sel_hi:[0,1]
	s_nop 0
	v_pk_fma_f32 v[52:53], v[52:53], v[44:45], v[66:67] op_sel:[1,1,0] op_sel_hi:[1,0,1] neg_lo:[0,1,0]
	s_nop 0
	v_pk_mul_f32 v[66:67], v[62:63], v[52:53] op_sel:[0,0] op_sel_hi:[0,1]
	s_nop 0
	v_pk_fma_f32 v[62:63], v[62:63], v[52:53], v[66:67] op_sel:[1,1,0] op_sel_hi:[1,0,1] neg_lo:[0,1,0]
	ds_write_b64 v74, v[62:63] offset:10880
	v_pk_mul_f32 v[62:63], v[52:53], v[44:45] op_sel:[0,0] op_sel_hi:[0,1]
	s_nop 0
	v_pk_fma_f32 v[52:53], v[52:53], v[44:45], v[62:63] op_sel:[1,1,0] op_sel_hi:[1,0,1] neg_lo:[0,1,0]
	s_nop 0
	v_pk_mul_f32 v[62:63], v[60:61], v[52:53] op_sel:[0,0] op_sel_hi:[0,1]
	s_nop 0
	v_pk_fma_f32 v[60:61], v[60:61], v[52:53], v[62:63] op_sel:[1,1,0] op_sel_hi:[1,0,1] neg_lo:[0,1,0]
	ds_write_b64 v74, v[60:61] offset:13056
	v_pk_mul_f32 v[60:61], v[52:53], v[44:45] op_sel:[0,0] op_sel_hi:[0,1]
	s_nop 0
	v_pk_fma_f32 v[52:53], v[52:53], v[44:45], v[60:61] op_sel:[1,1,0] op_sel_hi:[1,0,1] neg_lo:[0,1,0]
	s_nop 0
	v_pk_mul_f32 v[60:61], v[64:65], v[52:53] op_sel:[0,0] op_sel_hi:[0,1]
	s_nop 0
	v_pk_fma_f32 v[60:61], v[64:65], v[52:53], v[60:61] op_sel:[1,1,0] op_sel_hi:[1,0,1] neg_lo:[0,1,0]
	ds_write_b64 v74, v[60:61] offset:15232
	v_pk_mul_f32 v[60:61], v[52:53], v[44:45] op_sel:[0,0] op_sel_hi:[0,1]
	s_nop 0
	v_pk_fma_f32 v[52:53], v[52:53], v[44:45], v[60:61] op_sel:[1,1,0] op_sel_hi:[1,0,1] neg_lo:[0,1,0]
	s_nop 0
	v_pk_mul_f32 v[60:61], v[54:55], v[52:53] op_sel:[0,0] op_sel_hi:[0,1]
	s_nop 0
	v_pk_fma_f32 v[54:55], v[54:55], v[52:53], v[60:61] op_sel:[1,1,0] op_sel_hi:[1,0,1] neg_lo:[0,1,0]
	ds_write_b64 v74, v[54:55] offset:17408
	v_pk_mul_f32 v[54:55], v[52:53], v[44:45] op_sel:[0,0] op_sel_hi:[0,1]
	s_nop 0
	v_pk_fma_f32 v[52:53], v[52:53], v[44:45], v[54:55] op_sel:[1,1,0] op_sel_hi:[1,0,1] neg_lo:[0,1,0]
	s_nop 0
	v_pk_mul_f32 v[54:55], v[50:51], v[52:53] op_sel:[0,0] op_sel_hi:[0,1]
	s_nop 0
	v_pk_fma_f32 v[50:51], v[50:51], v[52:53], v[54:55] op_sel:[1,1,0] op_sel_hi:[1,0,1] neg_lo:[0,1,0]
	ds_write_b64 v74, v[50:51] offset:19584
	v_pk_mul_f32 v[50:51], v[52:53], v[44:45] op_sel:[0,0] op_sel_hi:[0,1]
	s_nop 0
	v_pk_fma_f32 v[50:51], v[52:53], v[44:45], v[50:51] op_sel:[1,1,0] op_sel_hi:[1,0,1] neg_lo:[0,1,0]
	s_nop 0
	v_pk_mul_f32 v[52:53], v[48:49], v[50:51] op_sel:[0,0] op_sel_hi:[0,1]
	s_nop 0
	v_pk_fma_f32 v[48:49], v[48:49], v[50:51], v[52:53] op_sel:[1,1,0] op_sel_hi:[1,0,1] neg_lo:[0,1,0]
	ds_write_b64 v74, v[48:49] offset:21760
	v_pk_mul_f32 v[48:49], v[50:51], v[44:45] op_sel:[0,0] op_sel_hi:[0,1]
	s_nop 0
	v_pk_fma_f32 v[48:49], v[50:51], v[44:45], v[48:49] op_sel:[1,1,0] op_sel_hi:[1,0,1] neg_lo:[0,1,0]
	s_nop 0
	v_pk_mul_f32 v[50:51], v[58:59], v[48:49] op_sel:[0,0] op_sel_hi:[0,1]
	s_nop 0
	v_pk_fma_f32 v[50:51], v[58:59], v[48:49], v[50:51] op_sel:[1,1,0] op_sel_hi:[1,0,1] neg_lo:[0,1,0]
	ds_write_b64 v74, v[50:51] offset:23936
	v_pk_mul_f32 v[50:51], v[48:49], v[44:45] op_sel:[0,0] op_sel_hi:[0,1]
	s_nop 0
	v_pk_fma_f32 v[48:49], v[48:49], v[44:45], v[50:51] op_sel:[1,1,0] op_sel_hi:[1,0,1] neg_lo:[0,1,0]
	s_nop 0
	v_pk_mul_f32 v[50:51], v[40:41], v[48:49] op_sel:[0,0] op_sel_hi:[0,1]
	s_nop 0
	v_pk_fma_f32 v[40:41], v[40:41], v[48:49], v[50:51] op_sel:[1,1,0] op_sel_hi:[1,0,1] neg_lo:[0,1,0]
	ds_write_b64 v74, v[40:41] offset:26112
	v_pk_mul_f32 v[40:41], v[48:49], v[44:45] op_sel:[0,0] op_sel_hi:[0,1]
	s_nop 0
	v_pk_fma_f32 v[40:41], v[48:49], v[44:45], v[40:41] op_sel:[1,1,0] op_sel_hi:[1,0,1] neg_lo:[0,1,0]
	s_nop 0
	v_pk_mul_f32 v[48:49], v[56:57], v[40:41] op_sel:[0,0] op_sel_hi:[0,1]
	s_nop 0
	v_pk_fma_f32 v[48:49], v[56:57], v[40:41], v[48:49] op_sel:[1,1,0] op_sel_hi:[1,0,1] neg_lo:[0,1,0]
	ds_write_b64 v74, v[48:49] offset:28288
	v_pk_mul_f32 v[48:49], v[40:41], v[44:45] op_sel:[0,0] op_sel_hi:[0,1]
	s_nop 0
	v_pk_fma_f32 v[40:41], v[40:41], v[44:45], v[48:49] op_sel:[1,1,0] op_sel_hi:[1,0,1] neg_lo:[0,1,0]
	s_nop 0
	v_pk_mul_f32 v[48:49], v[46:47], v[40:41] op_sel:[0,0] op_sel_hi:[0,1]
	s_nop 0
	v_pk_fma_f32 v[46:47], v[46:47], v[40:41], v[48:49] op_sel:[1,1,0] op_sel_hi:[1,0,1] neg_lo:[0,1,0]
	ds_write_b64 v74, v[46:47] offset:30464
	v_pk_mul_f32 v[46:47], v[40:41], v[44:45] op_sel:[0,0] op_sel_hi:[0,1]
	s_nop 0
	v_pk_fma_f32 v[40:41], v[40:41], v[44:45], v[46:47] op_sel:[1,1,0] op_sel_hi:[1,0,1] neg_lo:[0,1,0]
	s_nop 0
	v_pk_mul_f32 v[44:45], v[42:43], v[40:41] op_sel:[0,0] op_sel_hi:[0,1]
	s_nop 0
	v_pk_fma_f32 v[40:41], v[42:43], v[40:41], v[44:45] op_sel:[1,1,0] op_sel_hi:[1,0,1] neg_lo:[0,1,0]
	ds_write_b64 v74, v[40:41] offset:32640
	s_waitcnt lgkmcnt(0)
	s_barrier
	ds_read2_b64 v[40:43], v39 offset1:17
	ds_read2_b64 v[44:47], v39 offset0:34 offset1:51
	ds_read2_b64 v[48:51], v39 offset0:68 offset1:85
	ds_read2_b64 v[52:55], v39 offset0:136 offset1:153
	ds_read2_b64 v[56:59], v39 offset0:102 offset1:119
	ds_read2_b64 v[60:63], v39 offset0:204 offset1:221
	ds_read2_b64 v[64:67], v39 offset0:170 offset1:187
	ds_read2_b64 v[68:71], v39 offset0:238 offset1:255
	s_waitcnt lgkmcnt(4)
	v_pk_add_f32 v[72:73], v[40:41], v[52:53]
	v_pk_add_f32 v[40:41], v[40:41], v[52:53] neg_lo:[0,1] neg_hi:[0,1]
	s_waitcnt lgkmcnt(2)
	v_pk_add_f32 v[52:53], v[48:49], v[60:61]
	v_pk_add_f32 v[48:49], v[48:49], v[60:61] neg_lo:[0,1] neg_hi:[0,1]
	v_pk_add_f32 v[60:61], v[72:73], v[52:53]
	v_pk_add_f32 v[52:53], v[72:73], v[52:53] neg_lo:[0,1] neg_hi:[0,1]
	v_pk_add_f32 v[72:73], v[40:41], v[48:49] op_sel:[0,1] op_sel_hi:[1,0] neg_hi:[0,1]
	v_pk_add_f32 v[40:41], v[40:41], v[48:49] op_sel:[0,1] op_sel_hi:[1,0] neg_lo:[0,1]
	v_pk_add_f32 v[48:49], v[42:43], v[54:55]
	v_pk_add_f32 v[42:43], v[42:43], v[54:55] neg_lo:[0,1] neg_hi:[0,1]
	v_pk_add_f32 v[54:55], v[50:51], v[62:63]
	v_pk_add_f32 v[50:51], v[50:51], v[62:63] neg_lo:[0,1] neg_hi:[0,1]
	v_pk_add_f32 v[62:63], v[48:49], v[54:55]
	v_pk_add_f32 v[48:49], v[48:49], v[54:55] neg_lo:[0,1] neg_hi:[0,1]
	v_pk_add_f32 v[54:55], v[42:43], v[50:51] op_sel:[0,1] op_sel_hi:[1,0] neg_hi:[0,1]
	v_pk_add_f32 v[42:43], v[42:43], v[50:51] op_sel:[0,1] op_sel_hi:[1,0] neg_lo:[0,1]
	s_waitcnt lgkmcnt(1)
	v_pk_add_f32 v[50:51], v[44:45], v[64:65]
	v_pk_add_f32 v[44:45], v[44:45], v[64:65] neg_lo:[0,1] neg_hi:[0,1]
	s_waitcnt lgkmcnt(0)
	v_pk_add_f32 v[64:65], v[56:57], v[68:69]
	v_pk_add_f32 v[56:57], v[56:57], v[68:69] neg_lo:[0,1] neg_hi:[0,1]
	v_pk_add_f32 v[68:69], v[50:51], v[64:65]
	v_pk_add_f32 v[50:51], v[50:51], v[64:65] neg_lo:[0,1] neg_hi:[0,1]
	v_pk_add_f32 v[64:65], v[44:45], v[56:57] op_sel:[0,1] op_sel_hi:[1,0] neg_hi:[0,1]
	v_pk_add_f32 v[44:45], v[44:45], v[56:57] op_sel:[0,1] op_sel_hi:[1,0] neg_lo:[0,1]
	v_pk_add_f32 v[56:57], v[46:47], v[66:67]
	v_pk_add_f32 v[46:47], v[46:47], v[66:67] neg_lo:[0,1] neg_hi:[0,1]
	v_pk_add_f32 v[66:67], v[58:59], v[70:71]
	v_pk_add_f32 v[58:59], v[58:59], v[70:71] neg_lo:[0,1] neg_hi:[0,1]
	v_pk_add_f32 v[70:71], v[56:57], v[66:67]
	v_pk_add_f32 v[56:57], v[56:57], v[66:67] neg_lo:[0,1] neg_hi:[0,1]
	v_pk_add_f32 v[66:67], v[46:47], v[58:59] op_sel:[0,1] op_sel_hi:[1,0] neg_hi:[0,1]
	v_pk_add_f32 v[46:47], v[46:47], v[58:59] op_sel:[0,1] op_sel_hi:[1,0] neg_lo:[0,1]
	v_pk_mul_f32 v[58:59], v[54:55], v[24:25] op_sel:[0,0] op_sel_hi:[0,1]
	s_nop 0
	v_pk_fma_f32 v[54:55], v[54:55], v[24:25], v[58:59] op_sel:[1,1,0] op_sel_hi:[1,0,1] neg_lo:[0,1,0]
	v_pk_mul_f32 v[58:59], v[64:65], v[20:21] op_sel:[0,0] op_sel_hi:[0,1]
	s_nop 0
	v_pk_fma_f32 v[58:59], v[64:65], v[20:21], v[58:59] op_sel:[1,1,0] op_sel_hi:[1,0,1] neg_lo:[0,1,0]
	v_pk_mul_f32 v[64:65], v[66:67], v[18:19] op_sel:[0,0] op_sel_hi:[0,1]
	s_nop 0
	v_pk_fma_f32 v[64:65], v[66:67], v[18:19], v[64:65] op_sel:[1,1,0] op_sel_hi:[1,0,1] neg_lo:[0,1,0]
	v_pk_mul_f32 v[66:67], v[48:49], v[20:21] op_sel:[0,0] op_sel_hi:[0,1]
	s_nop 0
	v_pk_fma_f32 v[48:49], v[48:49], v[20:21], v[66:67] op_sel:[1,1,0] op_sel_hi:[1,0,1] neg_lo:[0,1,0]
	v_pk_mul_f32 v[66:67], v[50:51], v[26:27] op_sel:[0,0] op_sel_hi:[0,1]
	s_nop 0
	v_pk_fma_f32 v[50:51], v[50:51], v[26:27], v[66:67] op_sel:[1,1,0] op_sel_hi:[1,0,1] neg_lo:[0,1,0]
	v_pk_mul_f32 v[66:67], v[56:57], v[22:23] op_sel:[0,0] op_sel_hi:[0,1]
	s_nop 0
	v_pk_fma_f32 v[56:57], v[56:57], v[22:23], v[66:67] op_sel:[1,1,0] op_sel_hi:[1,0,1] neg_lo:[0,1,0]
	v_pk_mul_f32 v[66:67], v[42:43], v[18:19] op_sel:[0,0] op_sel_hi:[0,1]
	s_nop 0
	v_pk_fma_f32 v[42:43], v[42:43], v[18:19], v[66:67] op_sel:[1,1,0] op_sel_hi:[1,0,1] neg_lo:[0,1,0]
	v_pk_mul_f32 v[66:67], v[44:45], v[22:23] op_sel:[0,0] op_sel_hi:[0,1]
	s_nop 0
	v_pk_fma_f32 v[44:45], v[44:45], v[22:23], v[66:67] op_sel:[1,1,0] op_sel_hi:[1,0,1] neg_lo:[0,1,0]
	v_pk_mul_f32 v[66:67], v[46:47], v[28:29] op_sel:[0,0] op_sel_hi:[0,1]
	s_nop 0
	v_pk_fma_f32 v[46:47], v[46:47], v[28:29], v[66:67] op_sel:[1,1,0] op_sel_hi:[1,0,1] neg_lo:[0,1,0]
	v_pk_add_f32 v[66:67], v[60:61], v[68:69]
	v_pk_add_f32 v[60:61], v[60:61], v[68:69] neg_lo:[0,1] neg_hi:[0,1]
	v_pk_add_f32 v[68:69], v[62:63], v[70:71]
	v_pk_add_f32 v[62:63], v[62:63], v[70:71] neg_lo:[0,1] neg_hi:[0,1]
	v_pk_add_f32 v[70:71], v[66:67], v[68:69]
	v_pk_add_f32 v[66:67], v[66:67], v[68:69] neg_lo:[0,1] neg_hi:[0,1]
	v_pk_add_f32 v[68:69], v[60:61], v[62:63] op_sel:[0,1] op_sel_hi:[1,0] neg_hi:[0,1]
	v_pk_add_f32 v[60:61], v[60:61], v[62:63] op_sel:[0,1] op_sel_hi:[1,0] neg_lo:[0,1]
	v_pk_add_f32 v[62:63], v[72:73], v[58:59]
	v_pk_add_f32 v[58:59], v[72:73], v[58:59] neg_lo:[0,1] neg_hi:[0,1]
	v_pk_add_f32 v[72:73], v[54:55], v[64:65]
	v_pk_add_f32 v[54:55], v[54:55], v[64:65] neg_lo:[0,1] neg_hi:[0,1]
	v_pk_add_f32 v[64:65], v[62:63], v[72:73]
	v_pk_add_f32 v[62:63], v[62:63], v[72:73] neg_lo:[0,1] neg_hi:[0,1]
	v_pk_add_f32 v[72:73], v[58:59], v[54:55] op_sel:[0,1] op_sel_hi:[1,0] neg_hi:[0,1]
	v_pk_add_f32 v[54:55], v[58:59], v[54:55] op_sel:[0,1] op_sel_hi:[1,0] neg_lo:[0,1]
	v_pk_add_f32 v[58:59], v[52:53], v[50:51]
	v_pk_add_f32 v[50:51], v[52:53], v[50:51] neg_lo:[0,1] neg_hi:[0,1]
	v_pk_add_f32 v[52:53], v[48:49], v[56:57]
	v_pk_add_f32 v[48:49], v[48:49], v[56:57] neg_lo:[0,1] neg_hi:[0,1]
	v_pk_add_f32 v[56:57], v[58:59], v[52:53]
	v_pk_add_f32 v[52:53], v[58:59], v[52:53] neg_lo:[0,1] neg_hi:[0,1]
	v_pk_add_f32 v[58:59], v[50:51], v[48:49] op_sel:[0,1] op_sel_hi:[1,0] neg_hi:[0,1]
	v_pk_add_f32 v[48:49], v[50:51], v[48:49] op_sel:[0,1] op_sel_hi:[1,0] neg_lo:[0,1]
	v_pk_add_f32 v[50:51], v[40:41], v[44:45]
	v_pk_add_f32 v[40:41], v[40:41], v[44:45] neg_lo:[0,1] neg_hi:[0,1]
	v_pk_add_f32 v[44:45], v[42:43], v[46:47]
	v_pk_add_f32 v[42:43], v[42:43], v[46:47] neg_lo:[0,1] neg_hi:[0,1]
	v_pk_add_f32 v[46:47], v[50:51], v[44:45]
	v_pk_add_f32 v[44:45], v[50:51], v[44:45] neg_lo:[0,1] neg_hi:[0,1]
	v_pk_add_f32 v[50:51], v[40:41], v[42:43] op_sel:[0,1] op_sel_hi:[1,0] neg_hi:[0,1]
	v_pk_add_f32 v[40:41], v[40:41], v[42:43] op_sel:[0,1] op_sel_hi:[1,0] neg_lo:[0,1]
	v_mov_b32_e32 v42, v30
	v_mov_b32_e32 v43, v32
	s_nop 0
	v_pk_mul_f32 v[74:75], v[64:65], v[42:43] op_sel:[0,0] op_sel_hi:[0,1]
	s_nop 0
	v_pk_fma_f32 v[64:65], v[64:65], v[42:43], v[74:75] op_sel:[1,1,0] op_sel_hi:[1,0,1] neg_lo:[0,1,0]
	ds_write2_b64 v39, v[70:71], v[64:65] offset1:17
	v_pk_mul_f32 v[64:65], v[42:43], v[42:43] op_sel:[0,0] op_sel_hi:[0,1]
	s_nop 0
	v_pk_fma_f32 v[64:65], v[42:43], v[42:43], v[64:65] op_sel:[1,1,0] op_sel_hi:[1,0,1] neg_lo:[0,1,0]
	s_nop 0
	v_pk_mul_f32 v[70:71], v[56:57], v[64:65] op_sel:[0,0] op_sel_hi:[0,1]
	s_nop 0
	v_pk_fma_f32 v[56:57], v[56:57], v[64:65], v[70:71] op_sel:[1,1,0] op_sel_hi:[1,0,1] neg_lo:[0,1,0]
	v_pk_mul_f32 v[70:71], v[64:65], v[42:43] op_sel:[0,0] op_sel_hi:[0,1]
	s_nop 0
	v_pk_fma_f32 v[64:65], v[64:65], v[42:43], v[70:71] op_sel:[1,1,0] op_sel_hi:[1,0,1] neg_lo:[0,1,0]
	s_nop 0
	v_pk_mul_f32 v[70:71], v[46:47], v[64:65] op_sel:[0,0] op_sel_hi:[0,1]
	s_nop 0
	v_pk_fma_f32 v[46:47], v[46:47], v[64:65], v[70:71] op_sel:[1,1,0] op_sel_hi:[1,0,1] neg_lo:[0,1,0]
	ds_write2_b64 v39, v[56:57], v[46:47] offset0:34 offset1:51
	v_pk_mul_f32 v[46:47], v[64:65], v[42:43] op_sel:[0,0] op_sel_hi:[0,1]
	s_nop 0
	v_pk_fma_f32 v[46:47], v[64:65], v[42:43], v[46:47] op_sel:[1,1,0] op_sel_hi:[1,0,1] neg_lo:[0,1,0]
	s_nop 0
	v_pk_mul_f32 v[56:57], v[68:69], v[46:47] op_sel:[0,0] op_sel_hi:[0,1]
	v_pk_mul_f32 v[64:65], v[46:47], v[42:43] op_sel:[0,0] op_sel_hi:[0,1]
	s_nop 0
	v_pk_fma_f32 v[56:57], v[68:69], v[46:47], v[56:57] op_sel:[1,1,0] op_sel_hi:[1,0,1] neg_lo:[0,1,0]
	v_pk_fma_f32 v[46:47], v[46:47], v[42:43], v[64:65] op_sel:[1,1,0] op_sel_hi:[1,0,1] neg_lo:[0,1,0]
	s_nop 0
	v_pk_mul_f32 v[64:65], v[72:73], v[46:47] op_sel:[0,0] op_sel_hi:[0,1]
	s_nop 0
	v_pk_fma_f32 v[64:65], v[72:73], v[46:47], v[64:65] op_sel:[1,1,0] op_sel_hi:[1,0,1] neg_lo:[0,1,0]
	ds_write2_b64 v39, v[56:57], v[64:65] offset0:68 offset1:85
	v_pk_mul_f32 v[56:57], v[46:47], v[42:43] op_sel:[0,0] op_sel_hi:[0,1]
	s_nop 0
	v_pk_fma_f32 v[46:47], v[46:47], v[42:43], v[56:57] op_sel:[1,1,0] op_sel_hi:[1,0,1] neg_lo:[0,1,0]
	s_nop 0
	v_pk_mul_f32 v[56:57], v[58:59], v[46:47] op_sel:[0,0] op_sel_hi:[0,1]
	s_nop 0
	v_pk_fma_f32 v[56:57], v[58:59], v[46:47], v[56:57] op_sel:[1,1,0] op_sel_hi:[1,0,1] neg_lo:[0,1,0]
	v_pk_mul_f32 v[58:59], v[46:47], v[42:43] op_sel:[0,0] op_sel_hi:[0,1]
	s_nop 0
	v_pk_fma_f32 v[46:47], v[46:47], v[42:43], v[58:59] op_sel:[1,1,0] op_sel_hi:[1,0,1] neg_lo:[0,1,0]
	s_nop 0
	v_pk_mul_f32 v[58:59], v[50:51], v[46:47] op_sel:[0,0] op_sel_hi:[0,1]
	s_nop 0
	v_pk_fma_f32 v[50:51], v[50:51], v[46:47], v[58:59] op_sel:[1,1,0] op_sel_hi:[1,0,1] neg_lo:[0,1,0]
	ds_write2_b64 v39, v[56:57], v[50:51] offset0:102 offset1:119
	v_pk_mul_f32 v[50:51], v[46:47], v[42:43] op_sel:[0,0] op_sel_hi:[0,1]
	s_nop 0
	v_pk_fma_f32 v[46:47], v[46:47], v[42:43], v[50:51] op_sel:[1,1,0] op_sel_hi:[1,0,1] neg_lo:[0,1,0]
	s_nop 0
	v_pk_mul_f32 v[50:51], v[66:67], v[46:47] op_sel:[0,0] op_sel_hi:[0,1]
	v_pk_mul_f32 v[56:57], v[46:47], v[42:43] op_sel:[0,0] op_sel_hi:[0,1]
	s_nop 0
	v_pk_fma_f32 v[50:51], v[66:67], v[46:47], v[50:51] op_sel:[1,1,0] op_sel_hi:[1,0,1] neg_lo:[0,1,0]
	v_pk_fma_f32 v[46:47], v[46:47], v[42:43], v[56:57] op_sel:[1,1,0] op_sel_hi:[1,0,1] neg_lo:[0,1,0]
	s_nop 0
	v_pk_mul_f32 v[56:57], v[62:63], v[46:47] op_sel:[0,0] op_sel_hi:[0,1]
	s_nop 0
	v_pk_fma_f32 v[56:57], v[62:63], v[46:47], v[56:57] op_sel:[1,1,0] op_sel_hi:[1,0,1] neg_lo:[0,1,0]
	ds_write2_b64 v39, v[50:51], v[56:57] offset0:136 offset1:153
	v_pk_mul_f32 v[50:51], v[46:47], v[42:43] op_sel:[0,0] op_sel_hi:[0,1]
	s_nop 0
	v_pk_fma_f32 v[46:47], v[46:47], v[42:43], v[50:51] op_sel:[1,1,0] op_sel_hi:[1,0,1] neg_lo:[0,1,0]
	s_nop 0
	v_pk_mul_f32 v[50:51], v[52:53], v[46:47] op_sel:[0,0] op_sel_hi:[0,1]
	s_nop 0
	v_pk_fma_f32 v[50:51], v[52:53], v[46:47], v[50:51] op_sel:[1,1,0] op_sel_hi:[1,0,1] neg_lo:[0,1,0]
	v_pk_mul_f32 v[52:53], v[46:47], v[42:43] op_sel:[0,0] op_sel_hi:[0,1]
	s_nop 0
	v_pk_fma_f32 v[46:47], v[46:47], v[42:43], v[52:53] op_sel:[1,1,0] op_sel_hi:[1,0,1] neg_lo:[0,1,0]
	s_nop 0
	v_pk_mul_f32 v[52:53], v[44:45], v[46:47] op_sel:[0,0] op_sel_hi:[0,1]
	s_nop 0
	v_pk_fma_f32 v[44:45], v[44:45], v[46:47], v[52:53] op_sel:[1,1,0] op_sel_hi:[1,0,1] neg_lo:[0,1,0]
	ds_write2_b64 v39, v[50:51], v[44:45] offset0:170 offset1:187
	v_pk_mul_f32 v[44:45], v[46:47], v[42:43] op_sel:[0,0] op_sel_hi:[0,1]
	s_nop 0
	v_pk_fma_f32 v[44:45], v[46:47], v[42:43], v[44:45] op_sel:[1,1,0] op_sel_hi:[1,0,1] neg_lo:[0,1,0]
	s_nop 0
	v_pk_mul_f32 v[46:47], v[60:61], v[44:45] op_sel:[0,0] op_sel_hi:[0,1]
	v_pk_mul_f32 v[50:51], v[44:45], v[42:43] op_sel:[0,0] op_sel_hi:[0,1]
	s_nop 0
	v_pk_fma_f32 v[46:47], v[60:61], v[44:45], v[46:47] op_sel:[1,1,0] op_sel_hi:[1,0,1] neg_lo:[0,1,0]
	v_pk_fma_f32 v[44:45], v[44:45], v[42:43], v[50:51] op_sel:[1,1,0] op_sel_hi:[1,0,1] neg_lo:[0,1,0]
	s_nop 0
	v_pk_mul_f32 v[50:51], v[54:55], v[44:45] op_sel:[0,0] op_sel_hi:[0,1]
	s_nop 0
	v_pk_fma_f32 v[50:51], v[54:55], v[44:45], v[50:51] op_sel:[1,1,0] op_sel_hi:[1,0,1] neg_lo:[0,1,0]
	ds_write2_b64 v39, v[46:47], v[50:51] offset0:204 offset1:221
	v_pk_mul_f32 v[46:47], v[44:45], v[42:43] op_sel:[0,0] op_sel_hi:[0,1]
	s_nop 0
	v_pk_fma_f32 v[44:45], v[44:45], v[42:43], v[46:47] op_sel:[1,1,0] op_sel_hi:[1,0,1] neg_lo:[0,1,0]
	s_nop 0
	v_pk_mul_f32 v[46:47], v[48:49], v[44:45] op_sel:[0,0] op_sel_hi:[0,1]
	s_nop 0
	v_pk_fma_f32 v[46:47], v[48:49], v[44:45], v[46:47] op_sel:[1,1,0] op_sel_hi:[1,0,1] neg_lo:[0,1,0]
	v_pk_mul_f32 v[48:49], v[44:45], v[42:43] op_sel:[0,0] op_sel_hi:[0,1]
	s_nop 0
	v_pk_fma_f32 v[42:43], v[44:45], v[42:43], v[48:49] op_sel:[1,1,0] op_sel_hi:[1,0,1] neg_lo:[0,1,0]
	s_nop 0
	v_pk_mul_f32 v[44:45], v[40:41], v[42:43] op_sel:[0,0] op_sel_hi:[0,1]
	s_nop 0
	v_pk_fma_f32 v[40:41], v[40:41], v[42:43], v[44:45] op_sel:[1,1,0] op_sel_hi:[1,0,1] neg_lo:[0,1,0]
	ds_write2_b64 v39, v[46:47], v[40:41] offset0:238 offset1:255
	v_mad_u32_u24 v39, v34, s55, v35
	s_waitcnt lgkmcnt(0)
	s_barrier
	ds_read2_b64 v[40:43], v39 offset1:1
	ds_read2_b64 v[44:47], v39 offset0:2 offset1:3
	ds_read2_b64 v[48:51], v39 offset0:8 offset1:9
	ds_read2_b64 v[52:55], v39 offset0:4 offset1:5
	ds_read2_b64 v[56:59], v39 offset0:6 offset1:7
	ds_read2_b64 v[60:63], v39 offset0:12 offset1:13
	ds_read2_b64 v[64:67], v39 offset0:10 offset1:11
	ds_read2_b64 v[68:71], v39 offset0:14 offset1:15
	s_waitcnt lgkmcnt(5)
	v_pk_add_f32 v[72:73], v[40:41], v[48:49]
	v_pk_add_f32 v[40:41], v[40:41], v[48:49] neg_lo:[0,1] neg_hi:[0,1]
	s_waitcnt lgkmcnt(2)
	v_pk_add_f32 v[48:49], v[52:53], v[60:61]
	v_pk_add_f32 v[52:53], v[52:53], v[60:61] neg_lo:[0,1] neg_hi:[0,1]
	v_pk_add_f32 v[60:61], v[72:73], v[48:49]
	v_pk_add_f32 v[48:49], v[72:73], v[48:49] neg_lo:[0,1] neg_hi:[0,1]
	v_pk_add_f32 v[72:73], v[40:41], v[52:53] op_sel:[0,1] op_sel_hi:[1,0] neg_hi:[0,1]
	v_pk_add_f32 v[40:41], v[40:41], v[52:53] op_sel:[0,1] op_sel_hi:[1,0] neg_lo:[0,1]
	v_pk_add_f32 v[52:53], v[42:43], v[50:51]
	v_pk_add_f32 v[42:43], v[42:43], v[50:51] neg_lo:[0,1] neg_hi:[0,1]
	v_pk_add_f32 v[50:51], v[54:55], v[62:63]
	v_pk_add_f32 v[54:55], v[54:55], v[62:63] neg_lo:[0,1] neg_hi:[0,1]
	v_pk_add_f32 v[62:63], v[52:53], v[50:51]
	v_pk_add_f32 v[50:51], v[52:53], v[50:51] neg_lo:[0,1] neg_hi:[0,1]
	v_pk_add_f32 v[52:53], v[42:43], v[54:55] op_sel:[0,1] op_sel_hi:[1,0] neg_hi:[0,1]
	v_pk_add_f32 v[42:43], v[42:43], v[54:55] op_sel:[0,1] op_sel_hi:[1,0] neg_lo:[0,1]
	s_waitcnt lgkmcnt(1)
	v_pk_add_f32 v[54:55], v[44:45], v[64:65]
	v_pk_add_f32 v[44:45], v[44:45], v[64:65] neg_lo:[0,1] neg_hi:[0,1]
	s_waitcnt lgkmcnt(0)
	v_pk_add_f32 v[64:65], v[56:57], v[68:69]
	v_pk_add_f32 v[56:57], v[56:57], v[68:69] neg_lo:[0,1] neg_hi:[0,1]
	v_pk_add_f32 v[68:69], v[54:55], v[64:65]
	v_pk_add_f32 v[54:55], v[54:55], v[64:65] neg_lo:[0,1] neg_hi:[0,1]
	v_pk_add_f32 v[64:65], v[44:45], v[56:57] op_sel:[0,1] op_sel_hi:[1,0] neg_hi:[0,1]
	v_pk_add_f32 v[44:45], v[44:45], v[56:57] op_sel:[0,1] op_sel_hi:[1,0] neg_lo:[0,1]
	v_pk_add_f32 v[56:57], v[46:47], v[66:67]
	v_pk_add_f32 v[46:47], v[46:47], v[66:67] neg_lo:[0,1] neg_hi:[0,1]
	v_pk_add_f32 v[66:67], v[58:59], v[70:71]
	v_pk_add_f32 v[58:59], v[58:59], v[70:71] neg_lo:[0,1] neg_hi:[0,1]
	v_pk_add_f32 v[70:71], v[56:57], v[66:67]
	v_pk_add_f32 v[56:57], v[56:57], v[66:67] neg_lo:[0,1] neg_hi:[0,1]
	v_pk_add_f32 v[66:67], v[46:47], v[58:59] op_sel:[0,1] op_sel_hi:[1,0] neg_hi:[0,1]
	v_pk_add_f32 v[46:47], v[46:47], v[58:59] op_sel:[0,1] op_sel_hi:[1,0] neg_lo:[0,1]
	v_pk_mul_f32 v[58:59], v[52:53], v[24:25] op_sel:[0,0] op_sel_hi:[0,1]
	s_nop 0
	v_pk_fma_f32 v[24:25], v[52:53], v[24:25], v[58:59] op_sel:[1,1,0] op_sel_hi:[1,0,1] neg_lo:[0,1,0]
	v_pk_mul_f32 v[52:53], v[64:65], v[20:21] op_sel:[0,0] op_sel_hi:[0,1]
	v_pk_mul_f32 v[58:59], v[66:67], v[18:19] op_sel:[0,0] op_sel_hi:[0,1]
	s_barrier
	v_pk_fma_f32 v[52:53], v[64:65], v[20:21], v[52:53] op_sel:[1,1,0] op_sel_hi:[1,0,1] neg_lo:[0,1,0]
	v_pk_mul_f32 v[64:65], v[50:51], v[20:21] op_sel:[0,0] op_sel_hi:[0,1]
	v_pk_fma_f32 v[58:59], v[66:67], v[18:19], v[58:59] op_sel:[1,1,0] op_sel_hi:[1,0,1] neg_lo:[0,1,0]
	s_nop 0
	v_pk_fma_f32 v[20:21], v[50:51], v[20:21], v[64:65] op_sel:[1,1,0] op_sel_hi:[1,0,1] neg_lo:[0,1,0]
	v_pk_mul_f32 v[50:51], v[54:55], v[26:27] op_sel:[0,0] op_sel_hi:[0,1]
	s_nop 0
	v_pk_fma_f32 v[26:27], v[54:55], v[26:27], v[50:51] op_sel:[1,1,0] op_sel_hi:[1,0,1] neg_lo:[0,1,0]
	v_pk_mul_f32 v[50:51], v[56:57], v[22:23] op_sel:[0,0] op_sel_hi:[0,1]
	v_pk_mul_f32 v[54:55], v[42:43], v[18:19] op_sel:[0,0] op_sel_hi:[0,1]
	s_nop 0
	v_pk_fma_f32 v[18:19], v[42:43], v[18:19], v[54:55] op_sel:[1,1,0] op_sel_hi:[1,0,1] neg_lo:[0,1,0]
	v_pk_mul_f32 v[42:43], v[44:45], v[22:23] op_sel:[0,0] op_sel_hi:[0,1]
	v_pk_fma_f32 v[50:51], v[56:57], v[22:23], v[50:51] op_sel:[1,1,0] op_sel_hi:[1,0,1] neg_lo:[0,1,0]
	v_pk_add_f32 v[54:55], v[24:25], v[58:59] neg_lo:[0,1] neg_hi:[0,1]
	v_pk_fma_f32 v[22:23], v[44:45], v[22:23], v[42:43] op_sel:[1,1,0] op_sel_hi:[1,0,1] neg_lo:[0,1,0]
	v_pk_mul_f32 v[42:43], v[46:47], v[28:29] op_sel:[0,0] op_sel_hi:[0,1]
	v_pk_add_f32 v[44:45], v[62:63], v[70:71] neg_lo:[0,1] neg_hi:[0,1]
	v_pk_fma_f32 v[28:29], v[46:47], v[28:29], v[42:43] op_sel:[1,1,0] op_sel_hi:[1,0,1] neg_lo:[0,1,0]
	v_pk_add_f32 v[42:43], v[60:61], v[68:69] neg_lo:[0,1] neg_hi:[0,1]
	v_pk_add_f32 v[74:75], v[18:19], v[28:29] neg_lo:[0,1] neg_hi:[0,1]
	v_pk_add_f32 v[46:47], v[42:43], v[44:45] op_sel:[0,1] op_sel_hi:[1,0] neg_hi:[0,1]
	v_pk_add_f32 v[42:43], v[42:43], v[44:45] op_sel:[0,1] op_sel_hi:[1,0] neg_lo:[0,1]
	v_pk_add_f32 v[44:45], v[72:73], v[52:53] neg_lo:[0,1] neg_hi:[0,1]
	v_and_b32_e32 v19, 0xf0, v36
	v_pk_add_f32 v[56:57], v[44:45], v[54:55] op_sel:[0,1] op_sel_hi:[1,0] neg_hi:[0,1]
	v_pk_add_f32 v[44:45], v[44:45], v[54:55] op_sel:[0,1] op_sel_hi:[1,0] neg_lo:[0,1]
	v_pk_add_f32 v[54:55], v[48:49], v[26:27] neg_lo:[0,1] neg_hi:[0,1]
	v_pk_add_f32 v[64:65], v[20:21], v[50:51] neg_lo:[0,1] neg_hi:[0,1]
	v_mul_i32_i24_e32 v21, 0xfffff804, v38
	v_lshlrev_b32_e32 v19, 2, v19
	v_pk_add_f32 v[66:67], v[54:55], v[64:65] op_sel:[0,1] op_sel_hi:[1,0] neg_hi:[0,1]
	v_pk_add_f32 v[54:55], v[54:55], v[64:65] op_sel:[0,1] op_sel_hi:[1,0] neg_lo:[0,1]
	v_pk_add_f32 v[64:65], v[40:41], v[22:23] neg_lo:[0,1] neg_hi:[0,1]
	v_add3_u32 v19, v78, v21, v19
	v_add_f32_e32 v21, v62, v70
	v_add_f32_e32 v23, v60, v68
	v_add_f32_e32 v24, v24, v58
	v_add_f32_e32 v27, v72, v52
	v_add_f32_e32 v25, v23, v21
	v_add_f32_e32 v29, v27, v24
	v_mul_f32_e32 v25, 0x3a800000, v25
	v_mul_f32_e32 v29, 0x3a800000, v29
	ds_write2st64_b32 v19, v25, v29 offset1:4
	v_add_f32_e32 v20, v20, v50
	v_add_f32_e32 v25, v48, v26
	v_add_f32_e32 v18, v18, v28
	v_add_f32_e32 v22, v40, v22
	v_add_f32_e32 v26, v25, v20
	v_add_f32_e32 v28, v22, v18
	v_sub_f32_e32 v20, v25, v20
	v_sub_f32_e32 v18, v22, v18
	v_mul_f32_e32 v26, 0x3a800000, v26
	v_mul_f32_e32 v28, 0x3a800000, v28
	v_mul_f32_e32 v20, 0x3a800000, v20
	v_mul_f32_e32 v18, 0x3a800000, v18
	ds_write2st64_b32 v19, v26, v28 offset0:8 offset1:12
	v_mul_f32_e32 v26, 0x3a800000, v46
	v_mul_f32_e32 v28, 0x3a800000, v56
	v_sub_f32_e32 v21, v23, v21
	v_sub_f32_e32 v23, v27, v24
	ds_write2st64_b32 v19, v20, v18 offset0:40 offset1:44
	v_mul_f32_e32 v18, 0x3a800000, v42
	v_mul_f32_e32 v20, 0x3a800000, v44
	v_pk_add_f32 v[76:77], v[64:65], v[74:75] op_sel:[0,1] op_sel_hi:[1,0] neg_hi:[0,1]
	v_pk_add_f32 v[64:65], v[64:65], v[74:75] op_sel:[0,1] op_sel_hi:[1,0] neg_lo:[0,1]
	ds_write2st64_b32 v19, v26, v28 offset0:16 offset1:20
	v_mul_f32_e32 v26, 0x3a800000, v66
	v_mul_f32_e32 v28, 0x3a800000, v76
	v_mul_f32_e32 v21, 0x3a800000, v21
	v_mul_f32_e32 v23, 0x3a800000, v23
	ds_write2st64_b32 v19, v18, v20 offset0:48 offset1:52
	v_mul_f32_e32 v18, 0x3a800000, v54
	v_mul_f32_e32 v20, 0x3a800000, v64
	v_mov_b32_e32 v22, v34
	ds_write2st64_b32 v19, v26, v28 offset0:24 offset1:28
	ds_write2st64_b32 v19, v21, v23 offset0:32 offset1:36
	ds_write2st64_b32 v19, v18, v20 offset0:56 offset1:60
	s_waitcnt lgkmcnt(0)
	s_barrier
	v_lshlrev_b32_e32 v26, 12, v37
	v_lshl_add_u32 v23, v22, 5, v35
	ds_read_b128 v[18:21], v23
	v_lshlrev_b32_e32 v28, 3, v22
	ds_read_b128 v[22:25], v23 offset:16
	v_ashrrev_i32_e32 v27, 31, v26
	v_lshlrev_b64 v[26:27], 1, v[26:27]
	s_waitcnt lgkmcnt(1)
	v_bfe_u32 v29, v18, 16, 1
	v_add3_u32 v18, v18, v29, s56
	v_bfe_u32 v29, v19, 16, 1
	v_lshrrev_b32_e32 v18, 16, v18
	v_add3_u32 v19, v19, v29, s56
	v_and_or_b32 v18, v19, s57, v18
	v_cvt_pk_bf16_f32 v19, v20, v21
	s_waitcnt lgkmcnt(0)
	v_cvt_pk_bf16_f32 v20, v22, v23
	v_cvt_pk_bf16_f32 v21, v24, v25
	v_ashrrev_i32_e32 v29, 31, v28
	v_lshl_add_u64 v[22:23], v[28:29], 1, v[26:27]
	v_lshl_add_u64 v[22:23], s[26:27], 0, v[22:23]
	global_store_dwordx4 v[22:23], v[18:21], off
	s_nop 0
	v_lshl_add_u32 v22, v34, 5, v35
	ds_read_b128 v[18:21], v22 offset:8192
	ds_read_b128 v[22:25], v22 offset:8208
	v_lshl_add_u32 v28, v34, 3, v33
	s_waitcnt lgkmcnt(1)
	v_bfe_u32 v29, v18, 16, 1
	v_add3_u32 v18, v18, v29, s56
	v_bfe_u32 v29, v19, 16, 1
	v_lshrrev_b32_e32 v18, 16, v18
	v_add3_u32 v19, v19, v29, s56
	v_and_or_b32 v18, v19, s57, v18
	v_cvt_pk_bf16_f32 v19, v20, v21
	s_waitcnt lgkmcnt(0)
	v_cvt_pk_bf16_f32 v20, v22, v23
	v_cvt_pk_bf16_f32 v21, v24, v25
	v_ashrrev_i32_e32 v29, 31, v28
	v_lshl_add_u64 v[22:23], v[28:29], 1, v[26:27]
	v_lshl_add_u64 v[22:23], s[26:27], 0, v[22:23]
	s_add_u32 s26, s26, s34
	s_addc_u32 s27, s27, s35
	s_andn2_b64 vcc, exec, s[50:51]
	global_store_dwordx4 v[22:23], v[18:21], off
	s_barrier
	s_cbranch_vccz .LBB0_1712

.LBB0_1768:
	s_or_b64 exec, exec, s[52:53]
	s_lshl_b64 s[52:53], s[50:51], 15
	v_ashrrev_i32_e32 v91, 6, v38
	s_add_u32 s28, s65, s52
	v_lshlrev_b32_e32 v50, 3, v91
	v_lshlrev_b32_e32 v34, 1, v34
	s_addc_u32 s29, s64, s53
	v_add_u32_e32 v90, 0, v34
	v_lshl_add_u64 v[54:55], s[28:29], 0, v[34:35]
	v_add_u32_e32 v34, s91, v50
	v_and_b32_e32 v34, 0xfffffef8, v34
	v_cmp_eq_u32_e32 vcc, 0, v34
	s_waitcnt vmcnt(25)
	v_lshlrev_b32_e32 v96, 16, v66
	v_and_b32_e32 v94, 0xffff0000, v66
	v_lshlrev_b32_e32 v97, 16, v67
	v_and_b32_e32 v95, 0xffff0000, v67
	v_lshlrev_b32_e32 v67, 16, v59
	v_lshlrev_b32_e32 v66, 16, v58
	v_and_b32_e32 v101, 0xffff0000, v59
	v_and_b32_e32 v100, 0xffff0000, v58
	s_waitcnt vmcnt(3)
	v_mov_b32_e32 v58, v2
	v_mov_b32_e32 v59, v4
	v_mov_b32_e32 v4, v3
	v_mov_b32_e32 v2, v30
	v_mov_b32_e32 v3, v32
	v_cndmask_b32_e64 v34, 1.0, 0, vcc
	v_lshlrev_b32_e32 v87, 16, v65
	v_lshlrev_b32_e32 v86, 16, v64
	v_and_b32_e32 v105, 0xffff0000, v65
	v_and_b32_e32 v104, 0xffff0000, v64
	v_pk_mul_f32 v[64:65], v[2:3], v[66:67]
	v_pk_mul_f32 v[102:103], v[58:59], v[86:87]
	v_pk_mul_f32 v[66:67], v[64:65], v[34:35] op_sel_hi:[1,0]
	v_mov_b32_e32 v64, v26
	v_mov_b32_e32 v65, v28
	v_lshlrev_b32_e32 v89, 16, v69
	v_lshlrev_b32_e32 v88, 16, v68
	v_and_b32_e32 v87, 0xffff0000, v69
	v_and_b32_e32 v86, 0xffff0000, v68
	v_pk_fma_f32 v[68:69], v[64:65], v[96:97], v[66:67]
	v_mov_b32_e32 v66, v18
	v_mov_b32_e32 v67, v20
	v_mov_b32_e32 v32, v31
	v_pk_fma_f32 v[106:107], v[66:67], v[88:89], v[68:69]
	v_mov_b32_e32 v68, v22
	v_mov_b32_e32 v69, v24
	v_pk_mul_f32 v[30:31], v[32:33], v[100:101]
	v_pk_add_f32 v[106:107], v[68:69], v[106:107]
	v_pk_mul_f32 v[30:31], v[30:31], v[34:35] op_sel_hi:[1,0]
	v_mov_b32_e32 v28, v27
	v_mul_f32_e32 v18, 0xbfb8aa3b, v106
	v_pk_fma_f32 v[26:27], v[28:29], v[94:95], v[30:31]
	v_mov_b32_e32 v20, v19
	v_exp_f32_e32 v22, v18
	v_pk_fma_f32 v[18:19], v[20:21], v[86:87], v[26:27]
	v_mov_b32_e32 v24, v23
	v_pk_add_f32 v[18:19], v[24:25], v[18:19]
	v_mul_f32_e32 v26, 0xbfb8aa3b, v107
	v_mul_f32_e32 v23, 0xbfb8aa3b, v18
	v_exp_f32_e32 v23, v23
	v_exp_f32_e32 v27, v26
	v_mul_f32_e32 v26, 0xbfb8aa3b, v19
	v_exp_f32_e32 v51, v26
	v_add_f32_e32 v23, 1.0, v23
	v_add_f32_e32 v22, 1.0, v22
	v_rcp_f32_e32 v26, v23
	v_add_f32_e32 v23, 1.0, v27
	v_rcp_f32_e32 v22, v22
	v_rcp_f32_e32 v23, v23
	v_add_f32_e32 v27, 1.0, v51
	v_rcp_f32_e32 v27, v27
	v_lshlrev_b32_e32 v93, 16, v81
	v_lshlrev_b32_e32 v92, 16, v80
	v_and_b32_e32 v101, 0xffff0000, v81
	v_and_b32_e32 v100, 0xffff0000, v80
	v_pk_mul_f32 v[80:81], v[106:107], v[22:23]
	v_pk_mul_f32 v[30:31], v[4:5], v[104:105]
	v_pk_mul_f32 v[104:105], v[18:19], v[26:27]
	s_nop 0
	s_nop 0
	s_nop 0
	v_cvt_pk_bf16_f32 v107, v81, v105
	v_cvt_pk_bf16_f32 v106, v80, v104
	s_nop 0
	s_nop 0
	v_pk_mul_f32 v[22:23], v[34:35], v[102:103] op_sel_hi:[0,1]
	s_waitcnt vmcnt(2)
	v_mov_b32_e32 v18, v14
	v_mov_b32_e32 v19, v16
	v_lshlrev_b32_e32 v84, 16, v82
	v_lshlrev_b32_e32 v85, 16, v83
	v_pk_fma_f32 v[26:27], v[18:19], v[92:93], v[22:23]
	s_waitcnt vmcnt(1)
	v_mov_b32_e32 v22, v10
	v_mov_b32_e32 v23, v12
	v_pk_fma_f32 v[102:103], v[22:23], v[84:85], v[26:27]
	s_waitcnt vmcnt(0)
	v_mov_b32_e32 v26, v6
	v_mov_b32_e32 v27, v8
	v_pk_mul_f32 v[30:31], v[34:35], v[30:31] op_sel_hi:[0,1]
	v_mov_b32_e32 v16, v15
	v_and_b32_e32 v82, 0xffff0000, v82
	v_and_b32_e32 v83, 0xffff0000, v83
	v_pk_add_f32 v[102:103], v[26:27], v[102:103]
	v_pk_fma_f32 v[14:15], v[16:17], v[100:101], v[30:31]
	v_mov_b32_e32 v12, v11
	v_mul_f32_e32 v6, 0xbfb8aa3b, v102
	v_pk_fma_f32 v[10:11], v[12:13], v[82:83], v[14:15]
	v_mov_b32_e32 v8, v7
	v_exp_f32_e32 v108, v6
	v_pk_add_f32 v[6:7], v[8:9], v[10:11]
	v_mul_f32_e32 v14, 0xbfb8aa3b, v103
	v_mul_f32_e32 v10, 0xbfb8aa3b, v6
	v_exp_f32_e32 v11, v10
	v_exp_f32_e32 v15, v14
	v_mul_f32_e32 v14, 0xbfb8aa3b, v7
	v_exp_f32_e32 v30, v14
	v_add_f32_e32 v11, 1.0, v11
	v_add_f32_e32 v10, 1.0, v108
	v_rcp_f32_e32 v14, v11
	v_add_f32_e32 v11, 1.0, v15
	v_rcp_f32_e32 v10, v10
	v_rcp_f32_e32 v11, v11
	v_add_f32_e32 v15, 1.0, v30
	v_rcp_f32_e32 v15, v15
	s_movk_i32 s28, 0x1080
	v_pk_mul_f32 v[10:11], v[102:103], v[10:11]
	v_mad_u64_u32 v[30:31], s[28:29], v91, s28, v[90:91]
	v_pk_mul_f32 v[10:11], v[10:11], s[48:49] op_sel_hi:[1,0]
	v_pk_mul_f32 v[6:7], v[6:7], v[14:15]
	s_nop 0
	v_pk_mul_f32 v[6:7], v[6:7], s[48:49] op_sel_hi:[1,0]
	s_nop 0
	s_nop 0
	s_nop 0
	v_cvt_pk_bf16_f32 v15, v11, v7
	s_nop 0
	s_nop 0
	s_nop 0
	s_nop 0
	s_nop 0
	s_nop 0
	s_nop 0
	v_cvt_pk_bf16_f32 v14, v10, v6
	s_add_i32 s54, 0, 0x1be00
	v_lshlrev_b32_e32 v34, 5, v91
	s_waitcnt lgkmcnt(0)
	s_barrier
	ds_write2st64_b64 v30, v[106:107], v[14:15] offset1:66
	v_add_u32_e32 v14, s54, v34
	ds_read_b32 v14, v14
	s_add_i32 s55, 0, 0x1bf00
	v_add_u32_e32 v15, s55, v34
	ds_read_b32 v102, v15
	v_ashrrev_i32_e32 v51, 31, v50
	s_waitcnt lgkmcnt(1)
	v_pk_mul_f32 v[30:31], v[80:81], v[14:15] op_sel_hi:[1,0]
	v_pk_mul_f32 v[14:15], v[104:105], v[14:15] op_sel_hi:[1,0]
	v_and_b32_sdwa v80, v31, v98 dst_sel:DWORD dst_unused:UNUSED_PAD src0_sel:WORD_1 src1_sel:DWORD
	v_and_b32_sdwa v81, v30, v98 dst_sel:DWORD dst_unused:UNUSED_PAD src0_sel:WORD_1 src1_sel:DWORD
	v_add3_u32 v30, v30, v81, s49
	v_add3_u32 v31, v31, v80, s49
	v_and_b32_sdwa v80, v15, v98 dst_sel:DWORD dst_unused:UNUSED_PAD src0_sel:WORD_1 src1_sel:DWORD
	v_and_b32_sdwa v81, v14, v98 dst_sel:DWORD dst_unused:UNUSED_PAD src0_sel:WORD_1 src1_sel:DWORD
	v_add3_u32 v15, v15, v80, s49
	v_add3_u32 v14, v14, v81, s49
	v_and_b32_e32 v15, 0xffff0000, v15
	v_and_b32_e32 v14, 0xffff0000, v14
	v_or_b32_sdwa v15, v15, v31 dst_sel:DWORD dst_unused:UNUSED_PAD src0_sel:DWORD src1_sel:WORD_1
	v_or_b32_sdwa v14, v14, v30 dst_sel:DWORD dst_unused:UNUSED_PAD src0_sel:DWORD src1_sel:WORD_1
	v_lshlrev_b64 v[30:31], 9, v[50:51]
	v_lshl_add_u64 v[30:31], v[54:55], 0, v[30:31]
	s_waitcnt lgkmcnt(0)
	v_mul_f32_e32 v10, v10, v102
	global_store_dwordx2 v[30:31], v[14:15], off
	v_bfe_u32 v14, v10, 16, 1
	v_add3_u32 v10, v10, v14, s49
	v_mov_b32_e32 v14, s80
	s_movk_i32 s28, 0x240
	v_mad_u32_u24 v51, v99, s28, v14
	v_lshl_add_u32 v14, v91, 4, v51
	v_mul_f32_e32 v6, v6, v102
	ds_write_b16_d16_hi v14, v10
	v_bfe_u32 v10, v6, 16, 1
	v_add3_u32 v6, v6, v10, s49
	ds_write_b16_d16_hi v14, v6 offset:144
	v_mul_f32_e32 v6, v11, v102
	v_bfe_u32 v10, v6, 16, 1
	v_add3_u32 v6, v6, v10, s49
	ds_write_b16_d16_hi v14, v6 offset:288
	v_mul_f32_e32 v6, v7, v102
	v_bfe_u32 v7, v6, 16, 1
	v_add3_u32 v6, v6, v7, s49
	ds_write_b16_d16_hi v14, v6 offset:432
	v_pk_mul_f32 v[6:7], v[64:65], v[88:89]
	v_lshlrev_b32_e32 v81, 16, v79
	v_lshlrev_b32_e32 v80, 16, v78
	v_pk_fma_f32 v[6:7], v[2:3], v[96:97], v[6:7]
	v_pk_mul_f32 v[14:15], v[28:29], v[86:87]
	v_and_b32_e32 v79, 0xffff0000, v79
	v_and_b32_e32 v78, 0xffff0000, v78
	v_pk_fma_f32 v[6:7], v[66:67], v[80:81], v[6:7]
	v_pk_fma_f32 v[14:15], v[32:33], v[94:95], v[14:15]
	v_pk_add_f32 v[6:7], v[68:69], v[6:7]
	v_pk_fma_f32 v[14:15], v[20:21], v[78:79], v[14:15]
	v_mul_f32_e32 v11, 0xbfb8aa3b, v6
	v_pk_add_f32 v[94:95], v[24:25], v[14:15]
	v_exp_f32_e32 v11, v11
	v_mul_f32_e32 v14, 0xbfb8aa3b, v94
	v_exp_f32_e32 v15, v14
	v_mul_f32_e32 v31, 0xbfb8aa3b, v95
	v_add_f32_e32 v11, 1.0, v11
	v_rcp_f32_e32 v96, v11
	v_add_f32_e32 v11, 1.0, v15
	v_mul_f32_e32 v15, 0xbfb8aa3b, v7
	v_exp_f32_e32 v15, v15
	v_exp_f32_e32 v31, v31
	v_rcp_f32_e32 v102, v11
	v_lshlrev_b32_e32 v10, 16, v76
	v_add_f32_e32 v11, 1.0, v15
	v_rcp_f32_e32 v97, v11
	v_add_f32_e32 v11, 1.0, v31
	v_rcp_f32_e32 v103, v11
	v_and_b32_e32 v14, 0xffff0000, v76
	v_lshlrev_b32_e32 v11, 16, v77
	v_and_b32_e32 v15, 0xffff0000, v77
	v_pk_mul_f32 v[94:95], v[94:95], v[102:103]
	v_pk_mul_f32 v[76:77], v[6:7], v[96:97]
	s_nop 0
	s_nop 0
	v_cvt_pk_bf16_f32 v97, v77, v95
	v_cvt_pk_bf16_f32 v96, v76, v94
	s_nop 0
	s_nop 0
	v_pk_mul_f32 v[6:7], v[18:19], v[84:85]
	v_or_b32_e32 v30, 1, v50
	v_pk_fma_f32 v[6:7], v[58:59], v[92:93], v[6:7]
	v_and_b32_e32 v39, 15, v38
	v_pk_fma_f32 v[6:7], v[22:23], v[10:11], v[6:7]
	s_nop 0
	v_pk_add_f32 v[92:93], v[26:27], v[6:7]
	s_nop 0
	v_mul_f32_e32 v6, 0xbfb8aa3b, v92
	v_exp_f32_e32 v31, v6
	v_pk_mul_f32 v[6:7], v[16:17], v[82:83]
	s_nop 0
	v_pk_fma_f32 v[6:7], v[4:5], v[100:101], v[6:7]
	s_nop 0
	v_pk_fma_f32 v[6:7], v[12:13], v[14:15], v[6:7]
	s_nop 0
	v_pk_add_f32 v[100:101], v[8:9], v[6:7]
	s_nop 0
	v_mul_f32_e32 v6, 0xbfb8aa3b, v100
	v_exp_f32_e32 v91, v6
	s_nop 0
	v_mad_u64_u32 v[6:7], s[28:29], v30, s81, v[90:91]
	v_add_f32_e32 v7, 1.0, v31
	v_mul_f32_e32 v31, 0xbfb8aa3b, v93
	v_rcp_f32_e32 v90, v7
	v_add_f32_e32 v7, 1.0, v91
	v_exp_f32_e32 v31, v31
	v_mul_f32_e32 v91, 0xbfb8aa3b, v101
	v_exp_f32_e32 v103, v91
	v_rcp_f32_e32 v102, v7
	v_add_f32_e32 v7, 1.0, v31
	v_rcp_f32_e32 v91, v7
	v_add_f32_e32 v7, 1.0, v103
	v_rcp_f32_e32 v103, v7
	ds_write_b64 v6, v[96:97]
	v_pk_mul_f32 v[90:91], v[92:93], v[90:91]
	s_mov_b32 s28, 0xffffff0
	v_pk_mul_f32 v[92:93], v[100:101], v[102:103]
	v_pk_mul_f32 v[90:91], v[90:91], s[48:49] op_sel_hi:[1,0]
	v_pk_mul_f32 v[92:93], v[92:93], s[48:49] op_sel_hi:[1,0]
	s_nop 0
	s_nop 0
	s_nop 0
	s_nop 0
	s_nop 0
	s_nop 0
	s_nop 0
	s_nop 0
	s_nop 0
	s_nop 0
	v_cvt_pk_bf16_f32 v97, v91, v93
	v_cvt_pk_bf16_f32 v96, v90, v92
	ds_write_b64 v6, v[96:97] offset:33792
	v_lshlrev_b32_e32 v97, 2, v30
	v_add_u32_e32 v7, s54, v97
	ds_read_b32 v96, v7
	v_add_u32_e32 v97, s55, v97
	ds_read_b32 v100, v97
	v_ashrrev_i32_e32 v31, 31, v30
	v_mul_u32_u24_e32 v7, 0x240, v99
	s_waitcnt lgkmcnt(1)
	v_pk_mul_f32 v[76:77], v[76:77], v[96:97] op_sel_hi:[1,0]
	v_pk_mul_f32 v[94:95], v[94:95], v[96:97] op_sel_hi:[1,0]
	v_and_b32_sdwa v96, v77, v98 dst_sel:DWORD dst_unused:UNUSED_PAD src0_sel:WORD_1 src1_sel:DWORD
	v_and_b32_sdwa v97, v76, v98 dst_sel:DWORD dst_unused:UNUSED_PAD src0_sel:WORD_1 src1_sel:DWORD
	v_add3_u32 v76, v76, v97, s49
	v_add3_u32 v77, v77, v96, s49
	v_and_b32_sdwa v96, v95, v98 dst_sel:DWORD dst_unused:UNUSED_PAD src0_sel:WORD_1 src1_sel:DWORD
	v_and_b32_sdwa v97, v94, v98 dst_sel:DWORD dst_unused:UNUSED_PAD src0_sel:WORD_1 src1_sel:DWORD
	v_add3_u32 v95, v95, v96, s49
	v_add3_u32 v94, v94, v97, s49
	v_and_b32_e32 v95, 0xffff0000, v95
	v_and_b32_e32 v94, 0xffff0000, v94
	v_or_b32_sdwa v95, v95, v77 dst_sel:DWORD dst_unused:UNUSED_PAD src0_sel:DWORD src1_sel:WORD_1
	v_or_b32_sdwa v94, v94, v76 dst_sel:DWORD dst_unused:UNUSED_PAD src0_sel:DWORD src1_sel:WORD_1
	v_lshlrev_b64 v[76:77], 9, v[30:31]
	s_waitcnt lgkmcnt(0)
	v_mul_f32_e32 v31, v90, v100
	v_lshl_add_u64 v[96:97], v[54:55], 0, v[76:77]
	v_lshlrev_b32_e32 v30, 1, v30
	v_bfe_u32 v76, v31, 16, 1
	v_add3_u32 v31, v31, v76, s49
	v_add_u32_e32 v76, v51, v30
	ds_write_b16_d16_hi v76, v31
	v_mul_f32_e32 v31, v92, v100
	v_bfe_u32 v76, v31, 16, 1
	v_add3_u32 v31, v31, v76, s49
	v_add3_u32 v30, s80, v30, v7
	ds_write_b16_d16_hi v30, v31 offset:144
	v_mul_f32_e32 v31, v91, v100
	v_bfe_u32 v76, v31, 16, 1
	v_add3_u32 v31, v31, v76, s49
	ds_write_b16_d16_hi v30, v31 offset:288
	v_mul_f32_e32 v31, v93, v100
	v_pk_mul_f32 v[92:93], v[64:65], v[80:81]
	v_lshlrev_b32_e32 v91, 16, v75
	v_lshlrev_b32_e32 v90, 16, v74
	v_pk_fma_f32 v[88:89], v[2:3], v[88:89], v[92:93]
	v_pk_mul_f32 v[92:93], v[28:29], v[78:79]
	v_bfe_u32 v76, v31, 16, 1
	v_and_b32_e32 v75, 0xffff0000, v75
	v_and_b32_e32 v74, 0xffff0000, v74
	v_pk_fma_f32 v[88:89], v[66:67], v[90:91], v[88:89]
	v_pk_fma_f32 v[86:87], v[32:33], v[86:87], v[92:93]
	v_add3_u32 v31, v31, v76, s49
	v_pk_add_f32 v[88:89], v[68:69], v[88:89]
	v_pk_fma_f32 v[86:87], v[20:21], v[74:75], v[86:87]
	ds_write_b16_d16_hi v30, v31 offset:432
	v_mul_f32_e32 v31, 0xbfb8aa3b, v88
	v_pk_add_f32 v[86:87], v[24:25], v[86:87]
	v_exp_f32_e32 v31, v31
	v_mul_f32_e32 v77, 0xbfb8aa3b, v86
	v_exp_f32_e32 v77, v77
	v_mul_f32_e32 v93, 0xbfb8aa3b, v87
	v_add_f32_e32 v31, 1.0, v31
	v_rcp_f32_e32 v92, v31
	v_add_f32_e32 v31, 1.0, v77
	v_mul_f32_e32 v77, 0xbfb8aa3b, v89
	v_exp_f32_e32 v77, v77
	v_exp_f32_e32 v101, v93
	v_rcp_f32_e32 v100, v31
	v_lshlrev_b32_e32 v76, 16, v72
	v_add_f32_e32 v31, 1.0, v77
	v_rcp_f32_e32 v93, v31
	v_add_f32_e32 v31, 1.0, v101
	v_rcp_f32_e32 v101, v31
	v_lshlrev_b32_e32 v77, 16, v73
	v_pk_mul_f32 v[88:89], v[88:89], v[92:93]
	v_and_b32_e32 v72, 0xffff0000, v72
	v_pk_mul_f32 v[86:87], v[86:87], v[100:101]
	v_and_b32_e32 v73, 0xffff0000, v73
	v_pk_mul_f32 v[100:101], v[18:19], v[10:11]
	v_pk_fma_f32 v[84:85], v[58:59], v[84:85], v[100:101]
	v_pk_mul_f32 v[100:101], v[16:17], v[14:15]
	v_cvt_pk_bf16_f32 v93, v89, v87
	s_nop 0
	v_pk_fma_f32 v[84:85], v[22:23], v[76:77], v[84:85]
	v_pk_fma_f32 v[82:83], v[4:5], v[82:83], v[100:101]
	v_pk_add_f32 v[84:85], v[26:27], v[84:85]
	v_pk_fma_f32 v[82:83], v[12:13], v[72:73], v[82:83]
	v_mul_f32_e32 v31, 0xbfb8aa3b, v84
	v_pk_add_f32 v[82:83], v[8:9], v[82:83]
	v_exp_f32_e32 v31, v31
	v_mul_f32_e32 v100, 0xbfb8aa3b, v82
	v_exp_f32_e32 v101, v100
	v_cvt_pk_bf16_f32 v92, v88, v86
	v_add_f32_e32 v31, 1.0, v31
	s_nop 0
	v_rcp_f32_e32 v100, v31
	v_add_f32_e32 v31, 1.0, v101
	v_mul_f32_e32 v101, 0xbfb8aa3b, v85
	v_exp_f32_e32 v101, v101
	v_mul_f32_e32 v102, 0xbfb8aa3b, v83
	v_exp_f32_e32 v103, v102
	v_rcp_f32_e32 v102, v31
	v_add_f32_e32 v31, 1.0, v101
	v_rcp_f32_e32 v101, v31
	v_add_f32_e32 v31, 1.0, v103
	v_rcp_f32_e32 v103, v31
	ds_write_b64 v6, v[92:93] offset:528
	v_pk_mul_f32 v[84:85], v[84:85], v[100:101]
	v_or_b32_e32 v30, 2, v50
	v_pk_mul_f32 v[82:83], v[82:83], v[102:103]
	v_pk_mul_f32 v[84:85], v[84:85], s[48:49] op_sel_hi:[1,0]
	v_pk_mul_f32 v[82:83], v[82:83], s[48:49] op_sel_hi:[1,0]
	s_nop 0
	v_cvt_pk_bf16_f32 v93, v85, v83
	s_nop 0
	v_cvt_pk_bf16_f32 v92, v84, v82
	s_nop 0
	s_nop 0
	ds_write_b64 v6, v[92:93] offset:34320
	v_lshlrev_b32_e32 v93, 2, v30
	v_add_u32_e32 v31, s54, v93
	v_add_u32_e32 v93, s55, v93
	ds_read_b32 v92, v31
	ds_read_b32 v93, v93
	global_store_dwordx2 v[96:97], v[94:95], off
	v_ashrrev_i32_e32 v31, 31, v30
	s_waitcnt lgkmcnt(0)
	v_pk_mul_f32 v[88:89], v[88:89], v[92:93] op_sel_hi:[1,0]
	v_pk_mul_f32 v[86:87], v[86:87], v[92:93] op_sel_hi:[1,0]
	v_and_b32_sdwa v92, v89, v98 dst_sel:DWORD dst_unused:UNUSED_PAD src0_sel:WORD_1 src1_sel:DWORD
	v_and_b32_sdwa v94, v88, v98 dst_sel:DWORD dst_unused:UNUSED_PAD src0_sel:WORD_1 src1_sel:DWORD
	v_add3_u32 v88, v88, v94, s49
	v_add3_u32 v89, v89, v92, s49
	v_and_b32_sdwa v92, v87, v98 dst_sel:DWORD dst_unused:UNUSED_PAD src0_sel:WORD_1 src1_sel:DWORD
	v_and_b32_sdwa v94, v86, v98 dst_sel:DWORD dst_unused:UNUSED_PAD src0_sel:WORD_1 src1_sel:DWORD
	v_add3_u32 v87, v87, v92, s49
	v_add3_u32 v86, v86, v94, s49
	v_and_b32_e32 v87, 0xffff0000, v87
	v_and_b32_e32 v86, 0xffff0000, v86
	v_or_b32_sdwa v87, v87, v89 dst_sel:DWORD dst_unused:UNUSED_PAD src0_sel:DWORD src1_sel:WORD_1
	v_or_b32_sdwa v86, v86, v88 dst_sel:DWORD dst_unused:UNUSED_PAD src0_sel:DWORD src1_sel:WORD_1
	v_lshlrev_b64 v[88:89], 9, v[30:31]
	v_mul_f32_e32 v31, v84, v93
	v_lshlrev_b32_e32 v30, 1, v30
	v_bfe_u32 v84, v31, 16, 1
	v_add3_u32 v31, v31, v84, s49
	v_add_u32_e32 v84, v51, v30
	ds_write_b16_d16_hi v84, v31
	v_mul_f32_e32 v31, v82, v93
	v_bfe_u32 v82, v31, 16, 1
	v_add3_u32 v31, v31, v82, s49
	v_add3_u32 v30, s80, v30, v7
	ds_write_b16_d16_hi v30, v31 offset:144
	v_mul_f32_e32 v31, v85, v93
	v_bfe_u32 v82, v31, 16, 1
	v_add3_u32 v31, v31, v82, s49
	ds_write_b16_d16_hi v30, v31 offset:288
	v_mul_f32_e32 v31, v83, v93
	v_bfe_u32 v82, v31, 16, 1
	v_pk_mul_f32 v[92:93], v[64:65], v[90:91]
	v_add3_u32 v31, v31, v82, s49
	v_lshlrev_b32_e32 v83, 16, v71
	v_lshlrev_b32_e32 v82, 16, v70
	v_pk_fma_f32 v[80:81], v[2:3], v[80:81], v[92:93]
	v_pk_mul_f32 v[92:93], v[28:29], v[74:75]
	v_and_b32_e32 v71, 0xffff0000, v71
	v_and_b32_e32 v70, 0xffff0000, v70
	v_pk_fma_f32 v[80:81], v[66:67], v[82:83], v[80:81]
	v_pk_fma_f32 v[78:79], v[32:33], v[78:79], v[92:93]
	v_pk_add_f32 v[80:81], v[68:69], v[80:81]
	v_pk_fma_f32 v[78:79], v[20:21], v[70:71], v[78:79]
	ds_write_b16_d16_hi v30, v31 offset:432
	v_mul_f32_e32 v31, 0xbfb8aa3b, v80
	v_pk_add_f32 v[78:79], v[24:25], v[78:79]
	v_exp_f32_e32 v31, v31
	v_mul_f32_e32 v85, 0xbfb8aa3b, v78
	v_exp_f32_e32 v85, v85
	v_mul_f32_e32 v93, 0xbfb8aa3b, v79
	v_add_f32_e32 v31, 1.0, v31
	v_rcp_f32_e32 v92, v31
	v_add_f32_e32 v31, 1.0, v85
	v_mul_f32_e32 v85, 0xbfb8aa3b, v81
	v_exp_f32_e32 v85, v85
	v_exp_f32_e32 v95, v93
	v_rcp_f32_e32 v94, v31
	v_lshlrev_b32_e32 v30, 16, v62
	v_add_f32_e32 v31, 1.0, v85
	v_rcp_f32_e32 v93, v31
	v_add_f32_e32 v31, 1.0, v95
	v_rcp_f32_e32 v95, v31
	v_lshlrev_b32_e32 v31, 16, v63
	v_pk_mul_f32 v[80:81], v[80:81], v[92:93]
	v_and_b32_e32 v62, 0xffff0000, v62
	v_pk_mul_f32 v[78:79], v[78:79], v[94:95]
	v_and_b32_e32 v63, 0xffff0000, v63
	v_pk_mul_f32 v[94:95], v[18:19], v[76:77]
	v_pk_fma_f32 v[10:11], v[58:59], v[10:11], v[94:95]
	v_pk_mul_f32 v[94:95], v[16:17], v[72:73]
	v_cvt_pk_bf16_f32 v93, v81, v79
	s_nop 0
	v_pk_fma_f32 v[10:11], v[22:23], v[30:31], v[10:11]
	v_pk_fma_f32 v[14:15], v[4:5], v[14:15], v[94:95]
	v_pk_add_f32 v[10:11], v[26:27], v[10:11]
	v_pk_fma_f32 v[14:15], v[12:13], v[62:63], v[14:15]
	v_mul_f32_e32 v85, 0xbfb8aa3b, v10
	v_pk_add_f32 v[14:15], v[8:9], v[14:15]
	v_exp_f32_e32 v85, v85
	v_mul_f32_e32 v94, 0xbfb8aa3b, v14
	v_exp_f32_e32 v95, v94
	v_cvt_pk_bf16_f32 v92, v80, v78
	v_add_f32_e32 v85, 1.0, v85
	s_nop 0
	v_rcp_f32_e32 v94, v85
	v_add_f32_e32 v85, 1.0, v95
	v_mul_f32_e32 v95, 0xbfb8aa3b, v11
	v_exp_f32_e32 v95, v95
	v_mul_f32_e32 v96, 0xbfb8aa3b, v15
	v_exp_f32_e32 v97, v96
	v_rcp_f32_e32 v96, v85
	v_add_f32_e32 v85, 1.0, v95
	v_rcp_f32_e32 v95, v85
	v_add_f32_e32 v85, 1.0, v97
	v_rcp_f32_e32 v97, v85
	ds_write_b64 v6, v[92:93] offset:1056
	v_pk_mul_f32 v[10:11], v[10:11], v[94:95]
	v_or_b32_e32 v84, 3, v50
	v_pk_mul_f32 v[14:15], v[14:15], v[96:97]
	v_pk_mul_f32 v[10:11], v[10:11], s[48:49] op_sel_hi:[1,0]
	v_pk_mul_f32 v[14:15], v[14:15], s[48:49] op_sel_hi:[1,0]
	s_nop 0
	v_cvt_pk_bf16_f32 v93, v11, v15
	v_and_b32_sdwa v94, v14, v98 dst_sel:DWORD dst_unused:UNUSED_PAD src0_sel:WORD_1 src1_sel:DWORD
	v_and_b32_sdwa v92, v10, v98 dst_sel:DWORD dst_unused:UNUSED_PAD src0_sel:WORD_1 src1_sel:DWORD
	s_nop 0
	v_add3_u32 v94, v14, v94, s49
	v_add3_u32 v92, v10, v92, s49
	s_nop 0
	s_nop 0
	v_and_b32_e32 v94, 0xffff0000, v94
	s_nop 0
	v_or_b32_sdwa v92, v94, v92 dst_sel:DWORD dst_unused:UNUSED_PAD src0_sel:DWORD src1_sel:WORD_1
	ds_write_b64 v6, v[92:93] offset:34848
	v_lshlrev_b32_e32 v93, 2, v84
	v_add_u32_e32 v85, s54, v93
	ds_read_b32 v92, v85
	v_lshl_add_u64 v[88:89], v[54:55], 0, v[88:89]
	global_store_dwordx2 v[88:89], v[86:87], off
	v_add_u32_e32 v86, s55, v93
	ds_read_b32 v88, v86
	s_waitcnt lgkmcnt(1)
	v_pk_mul_f32 v[80:81], v[80:81], v[92:93] op_sel_hi:[1,0]
	v_pk_mul_f32 v[78:79], v[78:79], v[92:93] op_sel_hi:[1,0]
	v_and_b32_sdwa v86, v81, v98 dst_sel:DWORD dst_unused:UNUSED_PAD src0_sel:WORD_1 src1_sel:DWORD
	v_and_b32_sdwa v87, v80, v98 dst_sel:DWORD dst_unused:UNUSED_PAD src0_sel:WORD_1 src1_sel:DWORD
	v_add3_u32 v80, v80, v87, s49
	v_add3_u32 v81, v81, v86, s49
	v_and_b32_sdwa v86, v79, v98 dst_sel:DWORD dst_unused:UNUSED_PAD src0_sel:WORD_1 src1_sel:DWORD
	v_and_b32_sdwa v87, v78, v98 dst_sel:DWORD dst_unused:UNUSED_PAD src0_sel:WORD_1 src1_sel:DWORD
	v_add3_u32 v79, v79, v86, s49
	v_add3_u32 v78, v78, v87, s49
	v_ashrrev_i32_e32 v85, 31, v84
	v_and_b32_e32 v79, 0xffff0000, v79
	v_and_b32_e32 v78, 0xffff0000, v78
	v_or_b32_sdwa v81, v79, v81 dst_sel:DWORD dst_unused:UNUSED_PAD src0_sel:DWORD src1_sel:WORD_1
	v_or_b32_sdwa v80, v78, v80 dst_sel:DWORD dst_unused:UNUSED_PAD src0_sel:DWORD src1_sel:WORD_1
	v_lshlrev_b64 v[78:79], 9, v[84:85]
	s_waitcnt lgkmcnt(0)
	v_mul_f32_e32 v10, v10, v88
	v_lshl_add_u64 v[86:87], v[54:55], 0, v[78:79]
	v_lshlrev_b32_e32 v78, 1, v84
	v_bfe_u32 v79, v10, 16, 1
	v_add3_u32 v10, v10, v79, s49
	v_add_u32_e32 v79, v51, v78
	ds_write_b16_d16_hi v79, v10
	v_mul_f32_e32 v10, v14, v88
	v_bfe_u32 v14, v10, 16, 1
	v_add3_u32 v10, v10, v14, s49
	v_add3_u32 v14, s80, v78, v7
	ds_write_b16_d16_hi v14, v10 offset:144
	v_mul_f32_e32 v10, v11, v88
	v_bfe_u32 v11, v10, 16, 1
	v_add3_u32 v10, v10, v11, s49
	v_pk_mul_f32 v[84:85], v[64:65], v[82:83]
	ds_write_b16_d16_hi v14, v10 offset:288
	v_mul_f32_e32 v10, v15, v88
	v_lshlrev_b32_e32 v79, 16, v61
	v_lshlrev_b32_e32 v78, 16, v60
	v_pk_fma_f32 v[84:85], v[2:3], v[90:91], v[84:85]
	v_pk_mul_f32 v[88:89], v[28:29], v[70:71]
	v_and_b32_e32 v61, 0xffff0000, v61
	v_and_b32_e32 v60, 0xffff0000, v60
	v_pk_fma_f32 v[84:85], v[66:67], v[78:79], v[84:85]
	v_pk_fma_f32 v[74:75], v[32:33], v[74:75], v[88:89]
	v_bfe_u32 v11, v10, 16, 1
	v_pk_add_f32 v[84:85], v[68:69], v[84:85]
	v_pk_fma_f32 v[74:75], v[20:21], v[60:61], v[74:75]
	v_add3_u32 v10, v10, v11, s49
	v_mul_f32_e32 v11, 0xbfb8aa3b, v84
	v_pk_add_f32 v[74:75], v[24:25], v[74:75]
	v_exp_f32_e32 v11, v11
	v_mul_f32_e32 v15, 0xbfb8aa3b, v74
	v_exp_f32_e32 v15, v15
	v_mul_f32_e32 v89, 0xbfb8aa3b, v75
	v_add_f32_e32 v11, 1.0, v11
	v_rcp_f32_e32 v88, v11
	v_add_f32_e32 v11, 1.0, v15
	v_mul_f32_e32 v15, 0xbfb8aa3b, v85
	v_exp_f32_e32 v15, v15
	v_exp_f32_e32 v91, v89
	v_rcp_f32_e32 v90, v11
	ds_write_b16_d16_hi v14, v10 offset:432
	v_add_f32_e32 v11, 1.0, v15
	v_rcp_f32_e32 v89, v11
	v_add_f32_e32 v11, 1.0, v91
	v_rcp_f32_e32 v91, v11
	v_lshlrev_b32_e32 v14, 16, v56
	v_lshlrev_b32_e32 v15, 16, v57
	v_pk_mul_f32 v[84:85], v[84:85], v[88:89]
	v_pk_mul_f32 v[74:75], v[74:75], v[90:91]
	v_and_b32_e32 v56, 0xffff0000, v56
	v_pk_mul_f32 v[90:91], v[18:19], v[30:31]
	v_pk_fma_f32 v[76:77], v[58:59], v[76:77], v[90:91]
	v_pk_mul_f32 v[90:91], v[16:17], v[62:63]
	v_and_b32_e32 v57, 0xffff0000, v57
	v_cvt_pk_bf16_f32 v89, v85, v75
	s_nop 0
	v_pk_fma_f32 v[76:77], v[22:23], v[14:15], v[76:77]
	v_pk_fma_f32 v[72:73], v[4:5], v[72:73], v[90:91]
	v_pk_add_f32 v[76:77], v[26:27], v[76:77]
	v_pk_fma_f32 v[72:73], v[12:13], v[56:57], v[72:73]
	v_mul_f32_e32 v11, 0xbfb8aa3b, v76
	v_pk_add_f32 v[72:73], v[8:9], v[72:73]
	v_exp_f32_e32 v11, v11
	v_mul_f32_e32 v90, 0xbfb8aa3b, v72
	v_exp_f32_e32 v91, v90
	v_cvt_pk_bf16_f32 v88, v84, v74
	v_add_f32_e32 v11, 1.0, v11
	s_nop 0
	v_rcp_f32_e32 v90, v11
	v_add_f32_e32 v11, 1.0, v91
	v_mul_f32_e32 v91, 0xbfb8aa3b, v77
	v_exp_f32_e32 v91, v91
	v_mul_f32_e32 v92, 0xbfb8aa3b, v73
	v_exp_f32_e32 v93, v92
	v_rcp_f32_e32 v92, v11
	v_add_f32_e32 v11, 1.0, v91
	v_rcp_f32_e32 v91, v11
	v_add_f32_e32 v11, 1.0, v93
	v_rcp_f32_e32 v93, v11
	ds_write_b64 v6, v[88:89] offset:1584
	v_pk_mul_f32 v[76:77], v[76:77], v[90:91]
	v_or_b32_e32 v10, 4, v50
	v_pk_mul_f32 v[72:73], v[72:73], v[92:93]
	v_pk_mul_f32 v[76:77], v[76:77], s[48:49] op_sel_hi:[1,0]
	v_pk_mul_f32 v[72:73], v[72:73], s[48:49] op_sel_hi:[1,0]
	s_nop 0
	v_cvt_pk_bf16_f32 v89, v77, v73
	v_and_b32_sdwa v90, v72, v98 dst_sel:DWORD dst_unused:UNUSED_PAD src0_sel:WORD_1 src1_sel:DWORD
	v_and_b32_sdwa v88, v76, v98 dst_sel:DWORD dst_unused:UNUSED_PAD src0_sel:WORD_1 src1_sel:DWORD
	s_nop 0
	v_add3_u32 v90, v72, v90, s49
	v_add3_u32 v88, v76, v88, s49
	s_nop 0
	s_nop 0
	v_and_b32_e32 v90, 0xffff0000, v90
	s_nop 0
	v_or_b32_sdwa v88, v90, v88 dst_sel:DWORD dst_unused:UNUSED_PAD src0_sel:DWORD src1_sel:WORD_1
	ds_write_b64 v6, v[88:89] offset:35376
	v_lshlrev_b32_e32 v89, 2, v10
	v_add_u32_e32 v11, s54, v89
	ds_read_b32 v88, v11
	global_store_dwordx2 v[86:87], v[80:81], off
	v_add_u32_e32 v80, s55, v89
	ds_read_b32 v86, v80
	v_ashrrev_i32_e32 v11, 31, v10
	s_waitcnt lgkmcnt(1)
	v_pk_mul_f32 v[80:81], v[84:85], v[88:89] op_sel_hi:[1,0]
	v_pk_mul_f32 v[74:75], v[74:75], v[88:89] op_sel_hi:[1,0]
	v_and_b32_sdwa v84, v81, v98 dst_sel:DWORD dst_unused:UNUSED_PAD src0_sel:WORD_1 src1_sel:DWORD
	v_and_b32_sdwa v85, v80, v98 dst_sel:DWORD dst_unused:UNUSED_PAD src0_sel:WORD_1 src1_sel:DWORD
	v_add3_u32 v80, v80, v85, s49
	v_add3_u32 v81, v81, v84, s49
	v_and_b32_sdwa v84, v75, v98 dst_sel:DWORD dst_unused:UNUSED_PAD src0_sel:WORD_1 src1_sel:DWORD
	v_and_b32_sdwa v85, v74, v98 dst_sel:DWORD dst_unused:UNUSED_PAD src0_sel:WORD_1 src1_sel:DWORD
	v_add3_u32 v75, v75, v84, s49
	v_add3_u32 v74, v74, v85, s49
	v_and_b32_e32 v75, 0xffff0000, v75
	v_and_b32_e32 v74, 0xffff0000, v74
	v_or_b32_sdwa v75, v75, v81 dst_sel:DWORD dst_unused:UNUSED_PAD src0_sel:DWORD src1_sel:WORD_1
	v_or_b32_sdwa v74, v74, v80 dst_sel:DWORD dst_unused:UNUSED_PAD src0_sel:DWORD src1_sel:WORD_1
	v_lshlrev_b64 v[80:81], 9, v[10:11]
	s_waitcnt lgkmcnt(0)
	v_mul_f32_e32 v11, v76, v86
	v_lshlrev_b32_e32 v10, 1, v10
	v_bfe_u32 v76, v11, 16, 1
	v_add3_u32 v11, v11, v76, s49
	v_add_u32_e32 v76, v51, v10
	ds_write_b16_d16_hi v76, v11
	v_mul_f32_e32 v11, v72, v86
	v_bfe_u32 v72, v11, 16, 1
	v_add3_u32 v11, v11, v72, s49
	v_add3_u32 v10, s80, v10, v7
	ds_write_b16_d16_hi v10, v11 offset:144
	v_mul_f32_e32 v11, v77, v86
	v_bfe_u32 v72, v11, 16, 1
	v_add3_u32 v11, v11, v72, s49
	ds_write_b16_d16_hi v10, v11 offset:288
	v_mul_f32_e32 v11, v73, v86
	v_bfe_u32 v72, v11, 16, 1
	v_pk_mul_f32 v[84:85], v[64:65], v[78:79]
	v_add3_u32 v11, v11, v72, s49
	v_lshlrev_b32_e32 v73, 16, v53
	v_lshlrev_b32_e32 v72, 16, v52
	v_pk_fma_f32 v[82:83], v[2:3], v[82:83], v[84:85]
	v_pk_mul_f32 v[84:85], v[28:29], v[60:61]
	v_and_b32_e32 v53, 0xffff0000, v53
	v_and_b32_e32 v52, 0xffff0000, v52
	v_pk_fma_f32 v[82:83], v[66:67], v[72:73], v[82:83]
	v_pk_fma_f32 v[70:71], v[32:33], v[70:71], v[84:85]
	v_pk_add_f32 v[82:83], v[68:69], v[82:83]
	v_pk_fma_f32 v[70:71], v[20:21], v[52:53], v[70:71]
	ds_write_b16_d16_hi v10, v11 offset:432
	v_mul_f32_e32 v11, 0xbfb8aa3b, v82
	v_pk_add_f32 v[70:71], v[24:25], v[70:71]
	v_exp_f32_e32 v11, v11
	v_mul_f32_e32 v77, 0xbfb8aa3b, v70
	v_exp_f32_e32 v77, v77
	v_mul_f32_e32 v85, 0xbfb8aa3b, v71
	v_add_f32_e32 v11, 1.0, v11
	v_rcp_f32_e32 v84, v11
	v_add_f32_e32 v11, 1.0, v77
	v_mul_f32_e32 v77, 0xbfb8aa3b, v83
	v_exp_f32_e32 v77, v77
	v_exp_f32_e32 v87, v85
	v_rcp_f32_e32 v86, v11
	v_lshlrev_b32_e32 v10, 16, v48
	v_add_f32_e32 v11, 1.0, v77
	v_rcp_f32_e32 v85, v11
	v_add_f32_e32 v11, 1.0, v87
	v_rcp_f32_e32 v87, v11
	v_lshlrev_b32_e32 v11, 16, v49
	v_pk_mul_f32 v[82:83], v[82:83], v[84:85]
	v_and_b32_e32 v48, 0xffff0000, v48
	v_pk_mul_f32 v[70:71], v[70:71], v[86:87]
	v_and_b32_e32 v49, 0xffff0000, v49
	v_pk_mul_f32 v[86:87], v[18:19], v[14:15]
	v_pk_fma_f32 v[30:31], v[58:59], v[30:31], v[86:87]
	v_pk_mul_f32 v[86:87], v[16:17], v[56:57]
	v_cvt_pk_bf16_f32 v85, v83, v71
	s_nop 0
	v_pk_fma_f32 v[30:31], v[22:23], v[10:11], v[30:31]
	v_pk_fma_f32 v[62:63], v[4:5], v[62:63], v[86:87]
	v_pk_add_f32 v[30:31], v[26:27], v[30:31]
	v_pk_fma_f32 v[62:63], v[12:13], v[48:49], v[62:63]
	v_mul_f32_e32 v77, 0xbfb8aa3b, v30
	v_pk_add_f32 v[62:63], v[8:9], v[62:63]
	v_exp_f32_e32 v77, v77
	v_mul_f32_e32 v86, 0xbfb8aa3b, v62
	v_exp_f32_e32 v87, v86
	v_cvt_pk_bf16_f32 v84, v82, v70
	v_add_f32_e32 v77, 1.0, v77
	s_nop 0
	v_rcp_f32_e32 v86, v77
	v_add_f32_e32 v77, 1.0, v87
	v_mul_f32_e32 v87, 0xbfb8aa3b, v31
	v_exp_f32_e32 v87, v87
	v_mul_f32_e32 v88, 0xbfb8aa3b, v63
	v_exp_f32_e32 v89, v88
	v_rcp_f32_e32 v88, v77
	v_add_f32_e32 v77, 1.0, v87
	v_rcp_f32_e32 v87, v77
	v_add_f32_e32 v77, 1.0, v89
	v_rcp_f32_e32 v89, v77
	ds_write_b64 v6, v[84:85] offset:2112
	v_pk_mul_f32 v[30:31], v[30:31], v[86:87]
	v_or_b32_e32 v76, 5, v50
	v_pk_mul_f32 v[62:63], v[62:63], v[88:89]
	v_pk_mul_f32 v[30:31], v[30:31], s[48:49] op_sel_hi:[1,0]
	v_pk_mul_f32 v[62:63], v[62:63], s[48:49] op_sel_hi:[1,0]
	s_nop 0
	v_cvt_pk_bf16_f32 v85, v31, v63
	v_and_b32_sdwa v86, v62, v98 dst_sel:DWORD dst_unused:UNUSED_PAD src0_sel:WORD_1 src1_sel:DWORD
	v_and_b32_sdwa v84, v30, v98 dst_sel:DWORD dst_unused:UNUSED_PAD src0_sel:WORD_1 src1_sel:DWORD
	s_nop 0
	v_add3_u32 v86, v62, v86, s49
	v_add3_u32 v84, v30, v84, s49
	s_nop 0
	s_nop 0
	v_and_b32_e32 v86, 0xffff0000, v86
	s_nop 0
	v_or_b32_sdwa v84, v86, v84 dst_sel:DWORD dst_unused:UNUSED_PAD src0_sel:DWORD src1_sel:WORD_1
	ds_write_b64 v6, v[84:85] offset:35904
	v_lshlrev_b32_e32 v85, 2, v76
	v_add_u32_e32 v77, s54, v85
	ds_read_b32 v84, v77
	v_lshl_add_u64 v[80:81], v[54:55], 0, v[80:81]
	global_store_dwordx2 v[80:81], v[74:75], off
	v_add_u32_e32 v74, s55, v85
	ds_read_b32 v80, v74
	s_waitcnt lgkmcnt(1)
	v_pk_mul_f32 v[74:75], v[82:83], v[84:85] op_sel_hi:[1,0]
	v_pk_mul_f32 v[70:71], v[70:71], v[84:85] op_sel_hi:[1,0]
	v_and_b32_sdwa v81, v75, v98 dst_sel:DWORD dst_unused:UNUSED_PAD src0_sel:WORD_1 src1_sel:DWORD
	v_and_b32_sdwa v82, v74, v98 dst_sel:DWORD dst_unused:UNUSED_PAD src0_sel:WORD_1 src1_sel:DWORD
	v_add3_u32 v74, v74, v82, s49
	v_add3_u32 v75, v75, v81, s49
	v_and_b32_sdwa v81, v71, v98 dst_sel:DWORD dst_unused:UNUSED_PAD src0_sel:WORD_1 src1_sel:DWORD
	v_and_b32_sdwa v82, v70, v98 dst_sel:DWORD dst_unused:UNUSED_PAD src0_sel:WORD_1 src1_sel:DWORD
	v_add3_u32 v71, v71, v81, s49
	v_add3_u32 v70, v70, v82, s49
	v_ashrrev_i32_e32 v77, 31, v76
	v_and_b32_e32 v71, 0xffff0000, v71
	v_and_b32_e32 v70, 0xffff0000, v70
	s_waitcnt lgkmcnt(0)
	v_mul_f32_e32 v30, v30, v80
	v_or_b32_sdwa v71, v71, v75 dst_sel:DWORD dst_unused:UNUSED_PAD src0_sel:DWORD src1_sel:WORD_1
	v_or_b32_sdwa v70, v70, v74 dst_sel:DWORD dst_unused:UNUSED_PAD src0_sel:DWORD src1_sel:WORD_1
	v_lshlrev_b64 v[74:75], 9, v[76:77]
	v_lshlrev_b32_e32 v76, 1, v76
	v_bfe_u32 v77, v30, 16, 1
	v_add3_u32 v30, v30, v77, s49
	v_add_u32_e32 v77, v51, v76
	ds_write_b16_d16_hi v77, v30
	v_mul_f32_e32 v30, v62, v80
	v_bfe_u32 v62, v30, 16, 1
	v_add3_u32 v30, v30, v62, s49
	v_add3_u32 v62, s80, v76, v7
	ds_write_b16_d16_hi v62, v30 offset:144
	v_mul_f32_e32 v30, v31, v80
	v_bfe_u32 v31, v30, 16, 1
	v_add3_u32 v30, v30, v31, s49
	ds_write_b16_d16_hi v62, v30 offset:288
	v_mul_f32_e32 v30, v63, v80
	v_pk_mul_f32 v[80:81], v[64:65], v[72:73]
	v_lshlrev_b32_e32 v77, 16, v47
	v_lshlrev_b32_e32 v76, 16, v46
	v_pk_fma_f32 v[78:79], v[2:3], v[78:79], v[80:81]
	v_pk_mul_f32 v[80:81], v[28:29], v[52:53]
	v_and_b32_e32 v47, 0xffff0000, v47
	v_and_b32_e32 v46, 0xffff0000, v46
	v_pk_fma_f32 v[78:79], v[66:67], v[76:77], v[78:79]
	v_pk_fma_f32 v[60:61], v[32:33], v[60:61], v[80:81]
	v_bfe_u32 v31, v30, 16, 1
	v_pk_add_f32 v[78:79], v[68:69], v[78:79]
	v_pk_fma_f32 v[60:61], v[20:21], v[46:47], v[60:61]
	v_add3_u32 v30, v30, v31, s49
	v_mul_f32_e32 v31, 0xbfb8aa3b, v78
	v_pk_add_f32 v[60:61], v[24:25], v[60:61]
	v_exp_f32_e32 v31, v31
	v_mul_f32_e32 v63, 0xbfb8aa3b, v60
	v_exp_f32_e32 v63, v63
	v_mul_f32_e32 v81, 0xbfb8aa3b, v61
	v_add_f32_e32 v31, 1.0, v31
	v_rcp_f32_e32 v80, v31
	v_add_f32_e32 v31, 1.0, v63
	v_mul_f32_e32 v63, 0xbfb8aa3b, v79
	v_exp_f32_e32 v63, v63
	v_exp_f32_e32 v83, v81
	v_rcp_f32_e32 v82, v31
	ds_write_b16_d16_hi v62, v30 offset:432
	v_add_f32_e32 v31, 1.0, v63
	v_rcp_f32_e32 v81, v31
	v_add_f32_e32 v31, 1.0, v83
	v_rcp_f32_e32 v83, v31
	v_lshlrev_b32_e32 v62, 16, v44
	v_lshlrev_b32_e32 v63, 16, v45
	v_pk_mul_f32 v[78:79], v[78:79], v[80:81]
	v_pk_mul_f32 v[60:61], v[60:61], v[82:83]
	v_and_b32_e32 v44, 0xffff0000, v44
	v_pk_mul_f32 v[82:83], v[18:19], v[10:11]
	v_pk_fma_f32 v[14:15], v[58:59], v[14:15], v[82:83]
	v_pk_mul_f32 v[82:83], v[16:17], v[48:49]
	v_and_b32_e32 v45, 0xffff0000, v45
	v_cvt_pk_bf16_f32 v81, v79, v61
	s_nop 0
	v_pk_fma_f32 v[14:15], v[22:23], v[62:63], v[14:15]
	v_pk_fma_f32 v[56:57], v[4:5], v[56:57], v[82:83]
	v_pk_add_f32 v[14:15], v[26:27], v[14:15]
	v_pk_fma_f32 v[56:57], v[12:13], v[44:45], v[56:57]
	v_mul_f32_e32 v31, 0xbfb8aa3b, v14
	v_pk_add_f32 v[56:57], v[8:9], v[56:57]
	v_exp_f32_e32 v31, v31
	v_mul_f32_e32 v82, 0xbfb8aa3b, v56
	v_exp_f32_e32 v83, v82
	v_cvt_pk_bf16_f32 v80, v78, v60
	v_add_f32_e32 v31, 1.0, v31
	s_nop 0
	v_rcp_f32_e32 v82, v31
	v_add_f32_e32 v31, 1.0, v83
	v_mul_f32_e32 v83, 0xbfb8aa3b, v15
	v_exp_f32_e32 v83, v83
	v_mul_f32_e32 v84, 0xbfb8aa3b, v57
	v_exp_f32_e32 v85, v84
	v_rcp_f32_e32 v84, v31
	v_add_f32_e32 v31, 1.0, v83
	v_rcp_f32_e32 v83, v31
	v_add_f32_e32 v31, 1.0, v85
	v_rcp_f32_e32 v85, v31
	ds_write_b64 v6, v[80:81] offset:2640
	v_pk_mul_f32 v[14:15], v[14:15], v[82:83]
	v_or_b32_e32 v30, 6, v50
	v_pk_mul_f32 v[56:57], v[56:57], v[84:85]
	v_pk_mul_f32 v[14:15], v[14:15], s[48:49] op_sel_hi:[1,0]
	v_pk_mul_f32 v[56:57], v[56:57], s[48:49] op_sel_hi:[1,0]
	s_nop 0
	v_cvt_pk_bf16_f32 v81, v15, v57
	v_and_b32_sdwa v82, v56, v98 dst_sel:DWORD dst_unused:UNUSED_PAD src0_sel:WORD_1 src1_sel:DWORD
	v_and_b32_sdwa v80, v14, v98 dst_sel:DWORD dst_unused:UNUSED_PAD src0_sel:WORD_1 src1_sel:DWORD
	s_nop 0
	v_add3_u32 v82, v56, v82, s49
	v_add3_u32 v80, v14, v80, s49
	s_nop 0
	s_nop 0
	v_and_b32_e32 v82, 0xffff0000, v82
	s_nop 0
	v_or_b32_sdwa v80, v82, v80 dst_sel:DWORD dst_unused:UNUSED_PAD src0_sel:DWORD src1_sel:WORD_1
	ds_write_b64 v6, v[80:81] offset:36432
	v_lshlrev_b32_e32 v81, 2, v30
	v_add_u32_e32 v31, s54, v81
	ds_read_b32 v80, v31
	v_lshl_add_u64 v[74:75], v[54:55], 0, v[74:75]
	global_store_dwordx2 v[74:75], v[70:71], off
	v_add_u32_e32 v70, s55, v81
	ds_read_b32 v74, v70
	s_waitcnt lgkmcnt(1)
	v_pk_mul_f32 v[70:71], v[78:79], v[80:81] op_sel_hi:[1,0]
	v_pk_mul_f32 v[60:61], v[60:61], v[80:81] op_sel_hi:[1,0]
	v_and_b32_sdwa v75, v71, v98 dst_sel:DWORD dst_unused:UNUSED_PAD src0_sel:WORD_1 src1_sel:DWORD
	v_and_b32_sdwa v78, v70, v98 dst_sel:DWORD dst_unused:UNUSED_PAD src0_sel:WORD_1 src1_sel:DWORD
	v_add3_u32 v70, v70, v78, s49
	v_add3_u32 v71, v71, v75, s49
	v_and_b32_sdwa v75, v61, v98 dst_sel:DWORD dst_unused:UNUSED_PAD src0_sel:WORD_1 src1_sel:DWORD
	v_and_b32_sdwa v78, v60, v98 dst_sel:DWORD dst_unused:UNUSED_PAD src0_sel:WORD_1 src1_sel:DWORD
	v_add3_u32 v61, v61, v75, s49
	v_add3_u32 v60, v60, v78, s49
	v_ashrrev_i32_e32 v31, 31, v30
	v_and_b32_e32 v61, 0xffff0000, v61
	v_and_b32_e32 v60, 0xffff0000, v60
	s_waitcnt lgkmcnt(0)
	v_mul_f32_e32 v14, v14, v74
	v_or_b32_sdwa v61, v61, v71 dst_sel:DWORD dst_unused:UNUSED_PAD src0_sel:DWORD src1_sel:WORD_1
	v_or_b32_sdwa v60, v60, v70 dst_sel:DWORD dst_unused:UNUSED_PAD src0_sel:DWORD src1_sel:WORD_1
	v_lshlrev_b64 v[70:71], 9, v[30:31]
	v_lshlrev_b32_e32 v30, 1, v30
	v_bfe_u32 v31, v14, 16, 1
	v_add3_u32 v14, v14, v31, s49
	v_add_u32_e32 v31, v51, v30
	ds_write_b16_d16_hi v31, v14
	v_mul_f32_e32 v14, v56, v74
	v_bfe_u32 v31, v14, 16, 1
	v_add3_u32 v14, v14, v31, s49
	v_add3_u32 v30, s80, v30, v7
	ds_write_b16_d16_hi v30, v14 offset:144
	v_mul_f32_e32 v14, v15, v74
	v_bfe_u32 v15, v14, 16, 1
	v_add3_u32 v14, v14, v15, s49
	ds_write_b16_d16_hi v30, v14 offset:288
	v_mul_f32_e32 v14, v57, v74
	v_bfe_u32 v15, v14, 16, 1
	v_add3_u32 v14, v14, v15, s49
	ds_write_b16_d16_hi v30, v14 offset:432
	v_or_b32_e32 v14, 7, v50
	v_add_u32_e32 v15, s91, v14
	v_and_b32_e32 v15, 0xffffefff, v15
	v_cmp_eq_u32_e32 vcc, s82, v15
	v_lshlrev_b32_e32 v56, 16, v42
	v_lshlrev_b32_e32 v57, 16, v43
	v_pk_mul_f32 v[64:65], v[64:65], v[76:77]
	v_cndmask_b32_e64 v30, 1.0, 0, vcc
	v_and_b32_e32 v42, 0xffff0000, v42
	v_and_b32_e32 v43, 0xffff0000, v43
	v_pk_fma_f32 v[2:3], v[2:3], v[72:73], v[64:65]
	v_pk_mul_f32 v[56:57], v[66:67], v[56:57]
	v_pk_mul_f32 v[28:29], v[28:29], v[46:47]
	v_pk_fma_f32 v[2:3], v[56:57], v[30:31], v[2:3] op_sel_hi:[1,0,1]
	v_pk_fma_f32 v[28:29], v[32:33], v[52:53], v[28:29]
	v_pk_mul_f32 v[20:21], v[20:21], v[42:43]
	v_pk_add_f32 v[2:3], v[68:69], v[2:3]
	v_pk_fma_f32 v[20:21], v[20:21], v[30:31], v[28:29] op_sel_hi:[1,0,1]
	v_mul_f32_e32 v15, 0xbfb8aa3b, v2
	v_pk_add_f32 v[20:21], v[24:25], v[20:21]
	v_exp_f32_e32 v15, v15
	v_mul_f32_e32 v24, 0xbfb8aa3b, v20
	v_exp_f32_e32 v25, v24
	v_mul_f32_e32 v28, 0xbfb8aa3b, v21
	v_add_f32_e32 v15, 1.0, v15
	v_rcp_f32_e32 v24, v15
	v_add_f32_e32 v15, 1.0, v25
	v_mul_f32_e32 v25, 0xbfb8aa3b, v3
	v_exp_f32_e32 v25, v25
	v_exp_f32_e32 v29, v28
	v_rcp_f32_e32 v28, v15
	v_lshlrev_b32_e32 v75, 16, v41
	v_add_f32_e32 v15, 1.0, v25
	v_rcp_f32_e32 v25, v15
	v_add_f32_e32 v15, 1.0, v29
	v_rcp_f32_e32 v29, v15
	v_lshlrev_b32_e32 v74, 16, v40
	v_pk_mul_f32 v[18:19], v[18:19], v[62:63]
	v_pk_mul_f32 v[2:3], v[2:3], v[24:25]
	v_pk_mul_f32 v[20:21], v[20:21], v[28:29]
	v_pk_fma_f32 v[10:11], v[58:59], v[10:11], v[18:19]
	v_pk_mul_f32 v[18:19], v[22:23], v[74:75]
	v_and_b32_e32 v33, 0xffff0000, v41
	v_and_b32_e32 v32, 0xffff0000, v40
	v_cvt_pk_bf16_f32 v25, v3, v21
	s_nop 0
	v_pk_fma_f32 v[10:11], v[30:31], v[18:19], v[10:11] op_sel_hi:[0,1,1]
	v_pk_mul_f32 v[16:17], v[16:17], v[44:45]
	s_nop 0
	v_pk_add_f32 v[10:11], v[26:27], v[10:11]
	v_pk_fma_f32 v[4:5], v[4:5], v[48:49], v[16:17]
	v_pk_mul_f32 v[12:13], v[12:13], v[32:33]
	v_mul_f32_e32 v15, 0xbfb8aa3b, v10
	v_pk_fma_f32 v[4:5], v[30:31], v[12:13], v[4:5] op_sel_hi:[0,1,1]
	v_exp_f32_e32 v15, v15
	v_pk_add_f32 v[4:5], v[8:9], v[4:5]
	v_mul_f32_e32 v12, 0xbfb8aa3b, v11
	v_mul_f32_e32 v8, 0xbfb8aa3b, v4
	v_exp_f32_e32 v9, v8
	v_exp_f32_e32 v13, v12
	v_mul_f32_e32 v12, 0xbfb8aa3b, v5
	v_add_f32_e32 v8, 1.0, v15
	v_exp_f32_e32 v15, v12
	v_add_f32_e32 v9, 1.0, v9
	v_rcp_f32_e32 v12, v9
	v_add_f32_e32 v9, 1.0, v13
	v_rcp_f32_e32 v8, v8
	v_rcp_f32_e32 v9, v9
	v_add_f32_e32 v13, 1.0, v15
	v_rcp_f32_e32 v13, v13
	v_cvt_pk_bf16_f32 v24, v2, v20
	v_pk_mul_f32 v[8:9], v[10:11], v[8:9]
	s_nop 0
	v_pk_mul_f32 v[8:9], v[8:9], s[48:49] op_sel_hi:[1,0]
	v_pk_mul_f32 v[4:5], v[4:5], v[12:13]
	s_nop 0
	v_pk_mul_f32 v[4:5], v[4:5], s[48:49] op_sel_hi:[1,0]
	s_nop 0
	s_nop 0
	s_nop 0
	v_cvt_pk_bf16_f32 v11, v9, v5
	s_nop 0
	s_nop 0
	s_nop 0
	s_nop 0
	s_nop 0
	s_nop 0
	s_nop 0
	s_nop 0
	s_nop 0
	v_cvt_pk_bf16_f32 v10, v8, v4
	s_nop 0
	ds_write_b64 v6, v[10:11] offset:36960
	v_lshlrev_b32_e32 v10, 2, v14
	ds_write_b64 v6, v[24:25] offset:3168
	v_add_u32_e32 v6, s54, v10
	ds_read_b32 v6, v6
	v_add_u32_e32 v10, s55, v10
	ds_read_b32 v12, v10
	v_ashrrev_i32_e32 v15, 31, v14
	v_lshl_add_u64 v[70:71], v[54:55], 0, v[70:71]
	s_waitcnt lgkmcnt(1)
	v_pk_mul_f32 v[2:3], v[2:3], v[6:7] op_sel_hi:[1,0]
	v_pk_mul_f32 v[10:11], v[20:21], v[6:7] op_sel_hi:[1,0]
	v_and_b32_sdwa v13, v2, v98 dst_sel:DWORD dst_unused:UNUSED_PAD src0_sel:WORD_1 src1_sel:DWORD
	v_and_b32_sdwa v6, v3, v98 dst_sel:DWORD dst_unused:UNUSED_PAD src0_sel:WORD_1 src1_sel:DWORD
	v_add3_u32 v2, v2, v13, s49
	v_and_b32_sdwa v13, v10, v98 dst_sel:DWORD dst_unused:UNUSED_PAD src0_sel:WORD_1 src1_sel:DWORD
	v_add3_u32 v3, v3, v6, s49
	v_and_b32_sdwa v6, v11, v98 dst_sel:DWORD dst_unused:UNUSED_PAD src0_sel:WORD_1 src1_sel:DWORD
	v_add3_u32 v10, v10, v13, s49
	v_add3_u32 v6, v11, v6, s49
	v_and_b32_e32 v10, 0xffff0000, v10
	v_and_b32_e32 v6, 0xffff0000, v6
	v_or_b32_sdwa v2, v10, v2 dst_sel:DWORD dst_unused:UNUSED_PAD src0_sel:DWORD src1_sel:WORD_1
	v_lshlrev_b64 v[10:11], 9, v[14:15]
	v_or_b32_sdwa v3, v6, v3 dst_sel:DWORD dst_unused:UNUSED_PAD src0_sel:DWORD src1_sel:WORD_1
	v_lshl_add_u64 v[10:11], v[54:55], 0, v[10:11]
	global_store_dwordx2 v[10:11], v[2:3], off
	s_waitcnt lgkmcnt(0)
	v_mul_f32_e32 v3, v8, v12
	v_lshlrev_b32_e32 v2, 1, v14
	v_bfe_u32 v6, v3, 16, 1
	v_add3_u32 v3, v3, v6, s49
	v_add_u32_e32 v6, v51, v2
	ds_write_b16_d16_hi v6, v3
	v_mul_f32_e32 v3, v4, v12
	v_bfe_u32 v4, v3, 16, 1
	v_add3_u32 v3, v3, v4, s49
	v_add3_u32 v2, s80, v2, v7
	ds_write_b16_d16_hi v2, v3 offset:144
	v_mul_f32_e32 v3, v9, v12
	v_bfe_u32 v4, v3, 16, 1
	v_add3_u32 v3, v3, v4, s49
	ds_write_b16_d16_hi v2, v3 offset:288
	v_mul_f32_e32 v3, v5, v12
	v_bfe_u32 v4, v3, 16, 1
	v_add3_u32 v3, v3, v4, s49
	ds_write_b16_d16_hi v2, v3 offset:432
	v_and_b32_e32 v3, 48, v99
	v_and_or_b32 v2, v50, s28, v39
	v_add_u32_e32 v6, 0, v3
	v_mad_u64_u32 v[32:33], s[28:29], v2, s81, v[6:7]
	global_store_dwordx2 v[70:71], v[60:61], off
	s_waitcnt lgkmcnt(0)
	s_barrier
	ds_read_b128 v[2:5], v32
	v_and_or_b32 v10, v34, 32, v39
	v_mad_u32_u24 v11, v10, s81, v6
	ds_read_b128 v[12:15], v32 offset:64
	ds_read_b128 v[6:9], v11 offset:33792
	ds_read_b128 v[16:19], v11 offset:33856
	ds_read_b128 v[20:23], v32 offset:128
	s_waitcnt lgkmcnt(2)
	v_mfma_f32_16x16x32_bf16 v[6:9], v[2:5], v[6:9], 0
	s_add_i32 s28, 0, 0x1bd00
	s_waitcnt lgkmcnt(1)
	v_mfma_f32_16x16x32_bf16 v[6:9], v[12:15], v[16:19], v[6:9]
	ds_read_b128 v[16:19], v32 offset:192
	ds_read_b128 v[24:27], v11 offset:33920
	ds_read_b128 v[28:31], v11 offset:33984
	s_waitcnt lgkmcnt(1)
	v_mfma_f32_16x16x32_bf16 v[6:9], v[20:23], v[24:27], v[6:9]
	ds_read_b128 v[24:27], v32 offset:256
	s_waitcnt lgkmcnt(1)
	v_mfma_f32_16x16x32_bf16 v[6:9], v[16:19], v[28:31], v[6:9]
	ds_read_b128 v[28:31], v32 offset:320
	ds_read_b128 v[40:43], v11 offset:34048
	ds_read_b128 v[44:47], v11 offset:34112
	s_waitcnt lgkmcnt(1)
	v_mfma_f32_16x16x32_bf16 v[6:9], v[24:27], v[40:43], v[6:9]
	ds_read_b128 v[40:43], v32 offset:384
	s_waitcnt lgkmcnt(1)
	v_mfma_f32_16x16x32_bf16 v[6:9], v[28:31], v[44:47], v[6:9]
	ds_read_b128 v[44:47], v32 offset:448
	ds_read_b128 v[48:51], v11 offset:34176
	ds_read_b128 v[52:55], v11 offset:34240
	s_waitcnt lgkmcnt(1)
	v_mfma_f32_16x16x32_bf16 v[6:9], v[40:43], v[48:51], v[6:9]
	s_waitcnt lgkmcnt(0)
	v_mfma_f32_16x16x32_bf16 v[6:9], v[44:47], v[52:55], v[6:9]
	ds_read_b128 v[48:51], v11 offset:42240
	ds_read_b128 v[52:55], v11 offset:42304
	s_waitcnt lgkmcnt(1)
	v_mfma_f32_16x16x32_bf16 v[2:5], v[2:5], v[48:51], 0
	s_waitcnt lgkmcnt(0)
	v_mfma_f32_16x16x32_bf16 v[2:5], v[12:15], v[52:55], v[2:5]
	ds_read_b128 v[12:15], v11 offset:42368
	ds_read_b128 v[48:51], v11 offset:42432
	s_waitcnt lgkmcnt(1)
	v_mfma_f32_16x16x32_bf16 v[2:5], v[20:23], v[12:15], v[2:5]
	s_waitcnt lgkmcnt(0)
	v_mfma_f32_16x16x32_bf16 v[2:5], v[16:19], v[48:51], v[2:5]
	ds_read_b128 v[12:15], v11 offset:42496
	ds_read_b128 v[16:19], v11 offset:42560
	s_waitcnt lgkmcnt(1)
	v_mfma_f32_16x16x32_bf16 v[2:5], v[24:27], v[12:15], v[2:5]
	s_waitcnt lgkmcnt(0)
	v_mfma_f32_16x16x32_bf16 v[2:5], v[28:31], v[16:19], v[2:5]
	ds_read_b128 v[12:15], v11 offset:42624
	ds_read_b128 v[16:19], v11 offset:42688
	v_ashrrev_i32_e32 v11, 3, v38
	v_and_b32_e32 v11, -16, v11
	s_waitcnt lgkmcnt(1)
	v_mfma_f32_16x16x32_bf16 v[2:5], v[40:43], v[12:15], v[2:5]
	v_lshrrev_b32_e32 v12, 2, v99
	v_and_or_b32 v11, v12, 12, v11
	v_cmp_le_i32_e32 vcc, v10, v11
	s_waitcnt lgkmcnt(0)
	v_mfma_f32_16x16x32_bf16 v[2:5], v[44:47], v[16:19], v[2:5]
	v_mov_b32_e32 v15, 0
	v_cndmask_b32_e64 v12, 0, 1, vcc
	v_cmp_ge_i32_e32 vcc, v10, v11
	v_lshl_add_u32 v19, v10, 2, s28
	s_nop 0
	v_cndmask_b32_e64 v13, 0, 1, vcc
	v_cndmask_b32_e64 v12, v13, v12, s[6:7]
	v_and_b32_e32 v12, 1, v12
	v_cmp_eq_u32_e32 vcc, 1, v12
	v_lshl_add_u32 v12, v11, 2, 0
	v_mov_b32_e32 v13, 0
	s_and_saveexec_b64 s[54:55], vcc
	s_cbranch_execz .LBB0_1770
	v_add_u32_e32 v13, 0x1bc00, v12
	ds_read_b32 v13, v13
	ds_read_b32 v14, v19
	s_waitcnt lgkmcnt(0)
	v_add_f32_e32 v13, v13, v14
	v_mul_f32_e32 v13, 0x3fb8aa3b, v13
	v_exp_f32_e32 v13, v13
	s_nop 0
	v_mul_f32_e32 v13, v6, v13

.LBB0_1805:
	v_add_u32_e32 v27, 0x400, v26
	v_lshlrev_b32_e32 v38, 16, v10
	ds_read2_b32 v[30:31], v26 offset1:65
	ds_read2_b32 v[32:33], v26 offset0:130 offset1:195
	ds_read2_b32 v[34:35], v27 offset0:4 offset1:69
	ds_read2_b32 v[36:37], v27 offset0:134 offset1:199
	v_mul_f32_e32 v27, 0xbfb8aa3b, v38
	v_exp_f32_e32 v27, v27
	v_lshlrev_b32_e32 v39, 16, v11
	v_mul_f32_e32 v40, 0xbfb8aa3b, v39
	v_exp_f32_e32 v41, v40
	v_and_b32_e32 v10, 0xffff0000, v10
	v_add_f32_e32 v27, 1.0, v27
	v_and_b32_e32 v11, 0xffff0000, v11
	v_rcp_f32_e32 v40, v27
	v_mul_f32_e32 v27, 0xbfb8aa3b, v10
	v_exp_f32_e32 v27, v27
	v_add_f32_e32 v41, 1.0, v41
	v_mul_f32_e32 v42, 0xbfb8aa3b, v11
	v_rcp_f32_e32 v41, v41
	v_exp_f32_e32 v43, v42
	v_add_f32_e32 v27, 1.0, v27
	v_rcp_f32_e32 v42, v27
	v_pk_mul_f32 v[38:39], v[40:41], v[38:39]
	v_add_f32_e32 v27, 1.0, v43
	s_waitcnt lgkmcnt(3)
	v_mov_b32_e32 v40, v30
	v_lshlrev_b32_e32 v30, 16, v12
	v_rcp_f32_e32 v43, v27
	v_mul_f32_e32 v27, 0xbfb8aa3b, v30
	v_exp_f32_e32 v27, v27
	s_waitcnt lgkmcnt(2)
	v_mov_b32_e32 v41, v32
	v_pk_mul_f32 v[10:11], v[42:43], v[10:11]
	v_mov_b32_e32 v32, v31
	v_lshlrev_b32_e32 v31, 16, v13
	v_pk_mul_f32 v[10:11], v[10:11], v[32:33]
	v_and_b32_e32 v12, 0xffff0000, v12
	v_add_f32_e32 v27, 1.0, v27
	v_mul_f32_e32 v32, 0xbfb8aa3b, v31
	v_and_b32_e32 v13, 0xffff0000, v13
	v_exp_f32_e32 v33, v32
	v_rcp_f32_e32 v32, v27
	v_mul_f32_e32 v27, 0xbfb8aa3b, v12
	v_pk_mul_f32 v[38:39], v[38:39], v[40:41]
	v_exp_f32_e32 v27, v27
	v_mul_f32_e32 v40, 0xbfb8aa3b, v13
	v_exp_f32_e32 v41, v40
	v_add_f32_e32 v33, 1.0, v33
	v_add_f32_e32 v27, 1.0, v27
	v_rcp_f32_e32 v40, v27
	v_add_f32_e32 v27, 1.0, v41
	v_rcp_f32_e32 v33, v33
	v_rcp_f32_e32 v41, v27
	s_and_b32 s4, s33, 0xffffffc0
	v_add_u32_e32 v28, s4, v23
	v_pk_mul_f32 v[30:31], v[32:33], v[30:31]
	s_waitcnt lgkmcnt(0)
	v_mov_b32_e32 v33, v36
	v_pk_mul_f32 v[12:13], v[40:41], v[12:13]
	v_mov_b32_e32 v36, v35
	v_mov_b32_e32 v32, v34
	v_pk_mul_f32 v[12:13], v[12:13], v[36:37]
	v_ashrrev_i32_e32 v29, 31, v28
	v_pk_mul_f32 v[30:31], v[30:31], v[32:33]
	v_bfe_u32 v27, v13, 16, 1
	v_bfe_u32 v32, v12, 16, 1
	v_bfe_u32 v33, v11, 16, 1
	v_cvt_pk_bf16_f32 v10, v38, v10
	s_and_b32 s14, s31, 0x3c0
	v_add3_u32 v11, v11, v33, s19
	v_add3_u32 v12, v12, v32, s19
	v_add3_u32 v13, v13, v27, s19
	v_bfe_u32 v32, v39, 16, 1
	v_bfe_u32 v33, v30, 16, 1
	v_bfe_u32 v34, v31, 16, 1
	v_lshlrev_b64 v[28:29], 13, v[28:29]
	v_add3_u32 v31, v31, v34, s19
	v_add3_u32 v30, v30, v33, s19
	v_add3_u32 v32, v39, v32, s19
	v_lshl_add_u64 v[28:29], s[12:13], 0, v[28:29]
	s_lshl_b32 s4, s14, 1
	v_lshrrev_b32_e32 v32, 16, v32
	v_lshrrev_b32_e32 v30, 16, v30
	v_lshrrev_b32_e32 v31, 16, v31
	v_lshl_add_u64 v[28:29], v[28:29], 0, s[4:5]
	v_and_or_b32 v13, v13, s18, v31
	v_and_or_b32 v12, v12, s18, v30
	v_and_or_b32 v11, v11, s18, v32
	v_lshl_add_u64 v[28:29], v[28:29], 0, v[18:19]
	global_store_dwordx4 v[28:29], v[10:13], off offset:2048
	s_waitcnt lgkmcnt(0)
	s_barrier
	s_andn2_b64 vcc, exec, s[6:7]
	s_mov_b32 s31, s21
	s_waitcnt vmcnt(1)
	v_mov_b64_e32 v[10:11], v[14:15]
	s_mov_b32 s33, s20
	v_mov_b64_e32 v[12:13], v[16:17]
	s_cbranch_vccz .LBB0_1810

.LBB0_1869:
	ds_read2_b32 v[20:21], v18 offset1:65
	ds_read2_b32 v[22:23], v18 offset0:130 offset1:195
	v_add_u32_e32 v19, 0x400, v18
	ds_read2_b32 v[26:27], v19 offset0:4 offset1:69
	ds_read2_b32 v[28:29], v19 offset0:134 offset1:199
	s_and_b32 s8, s46, 0xffffffc0
	s_waitcnt lgkmcnt(3)
	s_nop 0
	v_cvt_pk_bf16_f32 v20, v20, v21
	s_waitcnt lgkmcnt(2)
	v_cvt_pk_bf16_f32 v21, v22, v23
	s_waitcnt lgkmcnt(1)
	v_cvt_pk_bf16_f32 v22, v26, v27
	v_add_u32_e32 v24, s8, v15
	v_ashrrev_i32_e32 v25, 31, v24
	s_and_b32 s0, s0, 0x3c0
	s_waitcnt lgkmcnt(0)
	v_bfe_u32 v19, v28, 16, 1
	v_lshlrev_b64 v[24:25], 11, v[24:25]
	v_add3_u32 v19, v28, v19, s29
	v_bfe_u32 v23, v29, 16, 1
	v_lshl_add_u64 v[24:25], s[14:15], 0, v[24:25]
	s_lshl_b32 s0, s0, 1
	v_lshrrev_b32_e32 v19, 16, v19
	v_add3_u32 v23, v29, v23, s29
	v_lshl_add_u64 v[24:25], v[24:25], 0, s[0:1]
	v_and_or_b32 v23, v23, s28, v19
	v_lshl_add_u64 v[24:25], v[24:25], 0, v[10:11]
	global_store_dwordx4 v[24:25], v[20:23], off
	s_waitcnt lgkmcnt(0)
	s_barrier
	s_andn2_b64 vcc, exec, s[6:7]
	s_mov_b32 s0, s47
	s_mov_b32 s46, s45
	s_cbranch_vccz .LBB0_1874

.LBB0_1889:
	s_nop 0
	s_nop 0
	v_cvt_pk_bf16_f32 v90, v30, v31
	s_nop 0
	s_nop 0
	s_nop 0
	s_nop 0
	s_nop 0
	v_cvt_pk_bf16_f32 v91, v32, v33
	v_cvt_pk_bf16_f32 v92, v38, v39
	v_cvt_pk_bf16_f32 v93, v40, v41
	ds_write_b128 v78, v[90:93] offset:49664
	v_cvt_pk_bf16_f32 v90, v34, v35
	v_cvt_pk_bf16_f32 v91, v36, v37
	v_cvt_pk_bf16_f32 v92, v42, v43
	v_bfe_u32 v2, v44, 16, 1
	v_add3_u32 v2, v44, v2, s66
	v_bfe_u32 v4, v45, 16, 1
	v_lshrrev_b32_e32 v2, 16, v2
	v_add3_u32 v4, v45, v4, s66
	v_and_or_b32 v93, v4, s67, v2
	ds_write_b128 v78, v[90:93] offset:50688

.LBB0_1915:
	s_nop 0
	s_nop 0
	v_cvt_pk_bf16_f32 v154, v58, v59
	s_nop 0
	s_nop 0
	s_nop 0
	s_nop 0
	s_nop 0
	v_cvt_pk_bf16_f32 v155, v60, v61
	v_cvt_pk_bf16_f32 v156, v62, v63
	v_cvt_pk_bf16_f32 v157, v64, v65
	ds_write_b128 v141, v[154:157]
	v_cvt_pk_bf16_f32 v154, v54, v55
	v_cvt_pk_bf16_f32 v155, v56, v57
	v_cvt_pk_bf16_f32 v156, v74, v75
	v_cvt_pk_bf16_f32 v157, v76, v77
	ds_write_b128 v141, v[154:157] offset:1024
	v_cvt_pk_bf16_f32 v154, v50, v51
	v_cvt_pk_bf16_f32 v155, v52, v53
	v_cvt_pk_bf16_f32 v156, v90, v91
	v_cvt_pk_bf16_f32 v157, v92, v93
	ds_write_b128 v141, v[154:157] offset:2048
	v_cvt_pk_bf16_f32 v154, v66, v67
	v_cvt_pk_bf16_f32 v155, v68, v69
	v_cvt_pk_bf16_f32 v156, v82, v83
	v_cvt_pk_bf16_f32 v157, v84, v85
	ds_write_b128 v141, v[154:157] offset:3072
	v_cvt_pk_bf16_f32 v154, v70, v71
	v_cvt_pk_bf16_f32 v155, v72, v73
	v_cvt_pk_bf16_f32 v156, v86, v87
	v_cvt_pk_bf16_f32 v157, v88, v89
	ds_write_b128 v141, v[154:157] offset:4096
	v_cvt_pk_bf16_f32 v154, v78, v79
	v_cvt_pk_bf16_f32 v155, v80, v81
	v_cvt_pk_bf16_f32 v156, v94, v95
	v_bfe_u32 v2, v96, 16, 1
	v_add3_u32 v2, v96, v2, s66
	v_bfe_u32 v4, v97, 16, 1
	v_lshrrev_b32_e32 v2, 16, v2
	v_add3_u32 v4, v97, v4, s66
	v_and_or_b32 v157, v4, s67, v2
	ds_write_b128 v141, v[154:157] offset:5120

.LBB0_1933:
	ds_read2_b32 v[20:21], v18 offset1:65
	ds_read2_b32 v[22:23], v18 offset0:130 offset1:195
	v_add_u32_e32 v19, 0x400, v18
	ds_read2_b32 v[26:27], v19 offset0:4 offset1:69
	ds_read2_b32 v[28:29], v19 offset0:134 offset1:199
	s_and_b32 s0, s10, 0xffffffc0
	s_waitcnt lgkmcnt(3)
	s_nop 0
	v_cvt_pk_bf16_f32 v20, v20, v21
	s_waitcnt lgkmcnt(2)
	v_cvt_pk_bf16_f32 v21, v22, v23
	s_waitcnt lgkmcnt(1)
	v_cvt_pk_bf16_f32 v22, v26, v27
	v_add_u32_e32 v24, s0, v15
	v_ashrrev_i32_e32 v25, 31, v24
	s_and_b32 s3, s3, 0x3c0
	s_waitcnt lgkmcnt(0)
	v_bfe_u32 v19, v28, 16, 1
	v_lshlrev_b64 v[24:25], 11, v[24:25]
	v_add3_u32 v19, v28, v19, s9
	v_bfe_u32 v23, v29, 16, 1
	v_lshl_add_u64 v[24:25], s[14:15], 0, v[24:25]
	s_lshl_b32 s0, s3, 1
	v_lshrrev_b32_e32 v19, 16, v19
	v_add3_u32 v23, v29, v23, s9
	v_lshl_add_u64 v[24:25], v[24:25], 0, s[0:1]
	v_and_or_b32 v23, v23, s8, v19
	v_lshl_add_u64 v[24:25], v[24:25], 0, v[10:11]
	global_store_dwordx4 v[24:25], v[20:23], off
	s_waitcnt lgkmcnt(0)
	s_barrier
	s_andn2_b64 vcc, exec, s[4:5]
	s_mov_b32 s3, s19
	s_mov_b32 s10, s17
	s_cbranch_vccz .LBB0_1938

.LBB0_2009:
	v_pk_add_f32 v[28:29], v[28:29], v[32:33]
	v_pk_add_f32 v[30:31], v[30:31], v[34:35]
	v_pk_mul_f32 v[34:35], v[28:29], v[28:29]
	v_pk_mul_f32 v[32:33], v[30:31], v[30:31]
	v_add_f32_e32 v34, v34, v35
	v_add_f32_e32 v32, v32, v34
	v_add_f32_e32 v32, v33, v32
	ds_bpermute_b32 v33, v1, v32
	v_pk_add_f32 v[22:23], v[22:23], v[26:27]
	v_pk_add_f32 v[20:21], v[20:21], v[24:25]
	v_lshlrev_b32_e32 v25, 16, v60
	v_mul_f32_e32 v25, 0xbfb8aa3b, v25
	s_waitcnt lgkmcnt(0)
	v_add_f32_e32 v26, v32, v33
	ds_bpermute_b32 v27, v62, v26
	v_and_b32_e32 v32, 0xffff0000, v60
	v_exp_f32_e32 v25, v25
	v_lshlrev_b32_e32 v33, 16, v61
	v_and_b32_e32 v34, 0xffff0000, v61
	s_waitcnt lgkmcnt(0)
	v_add_f32_e32 v26, v26, v27
	ds_bpermute_b32 v27, v63, v26
	v_add_f32_e32 v25, 1.0, v25
	v_mul_f32_e32 v33, 0xbfb8aa3b, v33
	v_mul_f32_e32 v34, 0xbfb8aa3b, v34
	v_lshlrev_b32_e32 v24, 16, v52
	s_waitcnt lgkmcnt(0)
	v_add_f32_e32 v26, v26, v27
	ds_bpermute_b32 v27, v64, v26
	v_exp_f32_e32 v33, v33
	v_exp_f32_e32 v34, v34
	v_mul_f32_e32 v35, 0xbfb8aa3b, v24
	v_exp_f32_e32 v35, v35
	s_waitcnt lgkmcnt(0)
	v_add_f32_e32 v26, v26, v27
	ds_bpermute_b32 v27, v65, v26
	v_add_f32_e32 v33, 1.0, v33
	v_add_f32_e32 v34, 1.0, v34
	v_and_b32_e32 v52, 0xffff0000, v52
	v_add_f32_e32 v35, 1.0, v35
	s_waitcnt lgkmcnt(0)
	v_add_f32_e32 v27, v26, v27
	ds_bpermute_b32 v60, v66, v27
	v_rcp_f32_e32 v26, v25
	v_mov_b32_e32 v72, v20
	v_mul_f32_e32 v32, 0xbfb8aa3b, v32
	v_exp_f32_e32 v32, v32
	s_waitcnt lgkmcnt(0)
	v_add_f32_e32 v25, v27, v60
	v_fmamk_f32 v25, v25, 0x3b800000, v67
	v_mul_f32_e32 v27, 0x4b800000, v25
	v_cmp_gt_f32_e32 vcc, s3, v25
	v_mul_f32_e32 v60, 0xbfb8aa3b, v52
	v_exp_f32_e32 v61, v60
	v_cndmask_b32_e32 v25, v25, v27, vcc
	v_rsq_f32_e32 v25, v25
	v_rcp_f32_e32 v27, v33
	v_rcp_f32_e32 v33, v34
	v_rcp_f32_e32 v60, v35
	v_mul_f32_e32 v34, 0x45800000, v25
	v_cndmask_b32_e32 v34, v25, v34, vcc
	v_lshlrev_b32_e32 v25, 16, v53
	v_mul_f32_e32 v35, 0xbfb8aa3b, v25
	v_exp_f32_e32 v35, v35
	v_and_b32_e32 v53, 0xffff0000, v53
	v_add_f32_e32 v61, 1.0, v61
	v_rcp_f32_e32 v70, v61
	v_add_f32_e32 v20, 1.0, v35
	v_rcp_f32_e32 v61, v20
	v_mul_f32_e32 v20, 0xbfb8aa3b, v53
	v_exp_f32_e32 v20, v20
	v_add_f32_e32 v32, 1.0, v32
	v_rcp_f32_e32 v32, v32
	v_mov_b32_e32 v73, v22
	v_add_f32_e32 v20, 1.0, v20
	v_rcp_f32_e32 v71, v20
	v_pk_mul_f32 v[26:27], v[72:73], v[26:27]
	v_pk_mul_f32 v[24:25], v[60:61], v[24:25]
	v_mov_b32_e32 v22, v21
	v_pk_mul_f32 v[24:25], v[26:27], v[24:25]
	v_pk_mul_f32 v[20:21], v[22:23], v[32:33]
	v_pk_mul_f32 v[22:23], v[70:71], v[52:53]
	v_lshl_add_u64 v[42:43], v[42:43], 0, s[0:1]
	v_pk_mul_f32 v[20:21], v[20:21], v[22:23]
	s_nop 0
	v_and_b32_sdwa v23, v24, v68 dst_sel:DWORD dst_unused:UNUSED_PAD src0_sel:WORD_1 src1_sel:DWORD
	v_add3_u32 v23, v24, v23, s10
	s_nop 0
	v_cvt_pk_bf16_f32 v21, v25, v21
	v_and_b32_sdwa v25, v20, v68 dst_sel:DWORD dst_unused:UNUSED_PAD src0_sel:WORD_1 src1_sel:DWORD
	s_nop 0
	v_add3_u32 v20, v20, v25, s10
	s_nop 0
	v_and_b32_e32 v20, 0xffff0000, v20
	s_nop 0
	v_or_b32_sdwa v20, v20, v23 dst_sel:DWORD dst_unused:UNUSED_PAD src0_sel:DWORD src1_sel:WORD_1
	v_lshl_add_u64 v[22:23], v[50:51], 0, v[36:37]
	v_add_co_u32_e32 v22, vcc, s11, v22
	v_and_b32_e32 v24, 0xffff0000, v40
	s_nop 0
	v_addc_co_u32_e32 v23, vcc, 0, v23, vcc
	global_store_dwordx2 v[22:23], v[20:21], off
	v_lshlrev_b32_e32 v20, 16, v40
	v_mul_f32_e32 v25, 0xbfb8aa3b, v20
	v_exp_f32_e32 v26, v25
	v_mul_f32_e32 v25, 0xbfb8aa3b, v24
	v_exp_f32_e32 v27, v25
	v_lshlrev_b32_e32 v21, 16, v41
	v_and_b32_e32 v25, 0xffff0000, v41
	v_add_f32_e32 v26, 1.0, v26
	v_add_f32_e32 v27, 1.0, v27
	v_rcp_f32_e32 v32, v27
	v_mul_f32_e32 v27, 0xbfb8aa3b, v21
	v_exp_f32_e32 v27, v27
	v_mov_b32_e32 v40, v28
	v_mul_f32_e32 v28, 0xbfb8aa3b, v25
	v_rcp_f32_e32 v26, v26
	v_add_f32_e32 v27, 1.0, v27
	v_rcp_f32_e32 v27, v27
	v_exp_f32_e32 v28, v28
	v_mov_b32_e32 v41, v30
	v_pk_mul_f32 v[40:41], v[40:41], v[34:35] op_sel_hi:[1,0]
	v_pk_mul_f32 v[20:21], v[26:27], v[20:21]
	v_add_f32_e32 v26, 1.0, v28
	v_rcp_f32_e32 v33, v26
	v_mov_b32_e32 v30, v29
	v_pk_mul_f32 v[40:41], v[2:3], v[40:41]
	v_pk_mul_f32 v[26:27], v[30:31], v[34:35] op_sel_hi:[1,0]
	v_pk_mul_f32 v[20:21], v[20:21], v[40:41]
	v_pk_mul_f32 v[26:27], v[38:39], v[26:27]
	v_pk_mul_f32 v[24:25], v[32:33], v[24:25]
	s_waitcnt vmcnt(5)
	v_mov_b64_e32 v[30:31], v[14:15]
	v_pk_mul_f32 v[24:25], v[24:25], v[26:27]
	v_and_b32_sdwa v26, v21, v68 dst_sel:DWORD dst_unused:UNUSED_PAD src0_sel:WORD_1 src1_sel:DWORD
	v_and_b32_sdwa v27, v20, v68 dst_sel:DWORD dst_unused:UNUSED_PAD src0_sel:WORD_1 src1_sel:DWORD
	v_add3_u32 v20, v20, v27, s10
	v_add3_u32 v21, v21, v26, s10
	v_and_b32_sdwa v26, v25, v68 dst_sel:DWORD dst_unused:UNUSED_PAD src0_sel:WORD_1 src1_sel:DWORD
	v_and_b32_sdwa v27, v24, v68 dst_sel:DWORD dst_unused:UNUSED_PAD src0_sel:WORD_1 src1_sel:DWORD
	v_add3_u32 v25, v25, v26, s10
	v_add3_u32 v24, v24, v27, s10
	v_and_b32_e32 v25, 0xffff0000, v25
	v_and_b32_e32 v24, 0xffff0000, v24
	v_or_b32_sdwa v21, v25, v21 dst_sel:DWORD dst_unused:UNUSED_PAD src0_sel:DWORD src1_sel:WORD_1
	v_or_b32_sdwa v20, v24, v20 dst_sel:DWORD dst_unused:UNUSED_PAD src0_sel:DWORD src1_sel:WORD_1
	global_store_dwordx2 v[22:23], v[20:21], off offset:2048
	v_mov_b64_e32 v[22:23], v[6:7]
	v_mov_b64_e32 v[26:27], v[10:11]
	s_waitcnt vmcnt(5)
	v_mov_b64_e32 v[34:35], v[18:19]
	v_lshl_add_u64 v[46:47], v[46:47], 0, s[34:35]
	v_lshl_add_u64 v[48:49], v[48:49], 0, s[34:35]
	v_lshl_add_u64 v[50:51], v[50:51], 0, s[36:37]
	s_andn2_b64 vcc, exec, s[38:39]
	v_mov_b64_e32 v[20:21], v[4:5]
	v_mov_b64_e32 v[24:25], v[8:9]
	v_mov_b64_e32 v[28:29], v[12:13]
	v_mov_b64_e32 v[32:33], v[16:17]
	s_waitcnt vmcnt(4)
	v_mov_b64_e32 v[60:61], v[56:57]
	s_waitcnt vmcnt(3)
	v_mov_b64_e32 v[52:53], v[54:55]
	s_waitcnt vmcnt(2)
	v_mov_b64_e32 v[40:41], v[58:59]
	s_cbranch_vccz .LBB0_2012

.LBB0_2016:
	v_pk_add_f32 v[20:21], v[20:21], v[24:25]
	v_pk_add_f32 v[22:23], v[22:23], v[26:27]
	v_pk_mul_f32 v[26:27], v[20:21], v[20:21]
	v_pk_mul_f32 v[24:25], v[22:23], v[22:23]
	v_add_f32_e32 v26, v26, v27
	v_add_f32_e32 v24, v24, v26
	v_add_f32_e32 v26, v25, v24
	ds_bpermute_b32 v27, v1, v26
	v_pk_add_f32 v[24:25], v[30:31], v[34:35]
	v_and_b32_e32 v34, 0xffff0000, v61
	v_mul_f32_e32 v34, 0xbfb8aa3b, v34
	v_exp_f32_e32 v34, v34
	s_waitcnt lgkmcnt(0)
	v_add_f32_e32 v30, v26, v27
	ds_bpermute_b32 v31, v62, v30
	v_pk_add_f32 v[26:27], v[28:29], v[32:33]
	v_lshlrev_b32_e32 v29, 16, v60
	v_mul_f32_e32 v29, 0xbfb8aa3b, v29
	v_exp_f32_e32 v29, v29
	s_waitcnt lgkmcnt(0)
	v_add_f32_e32 v30, v30, v31
	ds_bpermute_b32 v31, v63, v30
	v_lshlrev_b32_e32 v33, 16, v61
	v_add_f32_e32 v29, 1.0, v29
	v_mul_f32_e32 v33, 0xbfb8aa3b, v33
	v_exp_f32_e32 v33, v33
	s_waitcnt lgkmcnt(0)
	v_add_f32_e32 v30, v30, v31
	ds_bpermute_b32 v31, v64, v30
	v_add_f32_e32 v34, 1.0, v34
	v_add_f32_e32 v33, 1.0, v33
	v_lshlrev_b32_e32 v28, 16, v58
	v_and_b32_e32 v58, 0xffff0000, v58
	s_waitcnt lgkmcnt(0)
	v_add_f32_e32 v30, v30, v31
	ds_bpermute_b32 v31, v65, v30
	v_and_b32_e32 v32, 0xffff0000, v60
	v_mul_f32_e32 v60, 0xbfb8aa3b, v58
	v_exp_f32_e32 v61, v60
	v_mov_b32_e32 v72, v26
	s_waitcnt lgkmcnt(0)
	v_add_f32_e32 v31, v30, v31
	ds_bpermute_b32 v35, v66, v31
	v_rcp_f32_e32 v30, v29
	v_add_f32_e32 v61, 1.0, v61
	v_mul_f32_e32 v32, 0xbfb8aa3b, v32
	v_rcp_f32_e32 v70, v61
	s_waitcnt lgkmcnt(0)
	v_add_f32_e32 v29, v31, v35
	v_fmamk_f32 v29, v29, 0x3b800000, v67
	v_mul_f32_e32 v31, 0x4b800000, v29
	v_cmp_gt_f32_e32 vcc, s1, v29
	v_exp_f32_e32 v32, v32
	v_mov_b32_e32 v73, v24
	v_cndmask_b32_e32 v29, v29, v31, vcc
	v_rsq_f32_e32 v29, v29
	v_rcp_f32_e32 v31, v33
	v_rcp_f32_e32 v33, v34
	v_add_f32_e32 v32, 1.0, v32
	v_mul_f32_e32 v34, 0x45800000, v29
	v_cndmask_b32_e32 v34, v29, v34, vcc
	v_mul_f32_e32 v29, 0xbfb8aa3b, v28
	v_exp_f32_e32 v35, v29
	v_lshlrev_b32_e32 v29, 16, v59
	v_and_b32_e32 v59, 0xffff0000, v59
	v_rcp_f32_e32 v32, v32
	v_add_f32_e32 v35, 1.0, v35
	v_rcp_f32_e32 v60, v35
	v_mul_f32_e32 v35, 0xbfb8aa3b, v29
	v_exp_f32_e32 v35, v35
	v_pk_mul_f32 v[30:31], v[72:73], v[30:31]
	s_addk_i32 s0, 0x88
	v_lshl_add_u64 v[42:43], v[42:43], 0, s[34:35]
	v_add_f32_e32 v26, 1.0, v35
	v_rcp_f32_e32 v61, v26
	v_mul_f32_e32 v26, 0xbfb8aa3b, v59
	v_exp_f32_e32 v26, v26
	v_lshl_add_u64 v[46:47], v[46:47], 0, s[36:37]
	v_pk_mul_f32 v[28:29], v[60:61], v[28:29]
	v_lshl_add_u64 v[48:49], v[48:49], 0, s[36:37]
	v_add_f32_e32 v24, 1.0, v26
	v_rcp_f32_e32 v71, v24
	v_mov_b32_e32 v24, v27
	v_pk_mul_f32 v[28:29], v[30:31], v[28:29]
	v_pk_mul_f32 v[24:25], v[24:25], v[32:33]
	v_pk_mul_f32 v[26:27], v[70:71], v[58:59]
	s_waitcnt vmcnt(2)
	v_mov_b64_e32 v[60:61], v[54:55]
	v_pk_mul_f32 v[24:25], v[24:25], v[26:27]
	s_nop 0
	v_and_b32_sdwa v27, v28, v68 dst_sel:DWORD dst_unused:UNUSED_PAD src0_sel:WORD_1 src1_sel:DWORD
	v_add3_u32 v27, v28, v27, s3
	s_nop 0
	v_cvt_pk_bf16_f32 v25, v29, v25
	v_and_b32_sdwa v29, v24, v68 dst_sel:DWORD dst_unused:UNUSED_PAD src0_sel:WORD_1 src1_sel:DWORD
	s_nop 0
	v_add3_u32 v24, v24, v29, s3
	s_nop 0
	v_and_b32_e32 v24, 0xffff0000, v24
	s_nop 0
	v_or_b32_sdwa v24, v24, v27 dst_sel:DWORD dst_unused:UNUSED_PAD src0_sel:DWORD src1_sel:WORD_1
	v_lshl_add_u64 v[26:27], v[50:51], 0, v[36:37]
	v_add_co_u32_e32 v26, vcc, s10, v26
	v_and_b32_e32 v28, 0xffff0000, v40
	s_nop 0
	v_addc_co_u32_e32 v27, vcc, 0, v27, vcc
	global_store_dwordx2 v[26:27], v[24:25], off
	v_lshlrev_b32_e32 v24, 16, v40
	v_mul_f32_e32 v29, 0xbfb8aa3b, v24
	v_exp_f32_e32 v30, v29
	v_mul_f32_e32 v29, 0xbfb8aa3b, v28
	v_exp_f32_e32 v31, v29
	v_lshlrev_b32_e32 v25, 16, v41
	v_and_b32_e32 v29, 0xffff0000, v41
	v_mov_b32_e32 v40, v20
	v_add_f32_e32 v31, 1.0, v31
	v_rcp_f32_e32 v32, v31
	v_mul_f32_e32 v31, 0xbfb8aa3b, v25
	v_exp_f32_e32 v31, v31
	v_add_f32_e32 v30, 1.0, v30
	v_rcp_f32_e32 v30, v30
	v_mov_b32_e32 v41, v22
	v_add_f32_e32 v20, 1.0, v31
	v_rcp_f32_e32 v31, v20
	v_mul_f32_e32 v20, 0xbfb8aa3b, v29
	v_exp_f32_e32 v20, v20
	v_pk_mul_f32 v[40:41], v[40:41], v[34:35] op_sel_hi:[1,0]
	v_mov_b32_e32 v22, v21
	v_pk_mul_f32 v[40:41], v[2:3], v[40:41]
	v_add_f32_e32 v20, 1.0, v20
	v_rcp_f32_e32 v33, v20
	v_pk_mul_f32 v[24:25], v[30:31], v[24:25]
	v_pk_mul_f32 v[20:21], v[22:23], v[34:35] op_sel_hi:[1,0]
	v_pk_mul_f32 v[24:25], v[24:25], v[40:41]
	v_pk_mul_f32 v[20:21], v[38:39], v[20:21]
	v_pk_mul_f32 v[22:23], v[32:33], v[28:29]
	v_mov_b64_e32 v[30:31], v[6:7]
	v_pk_mul_f32 v[20:21], v[22:23], v[20:21]
	s_nop 0
	v_and_b32_sdwa v23, v24, v68 dst_sel:DWORD dst_unused:UNUSED_PAD src0_sel:WORD_1 src1_sel:DWORD
	v_add3_u32 v23, v24, v23, s3
	s_nop 0
	v_cvt_pk_bf16_f32 v21, v25, v21
	v_and_b32_sdwa v25, v20, v68 dst_sel:DWORD dst_unused:UNUSED_PAD src0_sel:WORD_1 src1_sel:DWORD
	s_nop 0
	v_add3_u32 v20, v20, v25, s3
	s_nop 0
	v_and_b32_e32 v20, 0xffff0000, v20
	s_nop 0
	v_or_b32_sdwa v20, v20, v23 dst_sel:DWORD dst_unused:UNUSED_PAD src0_sel:DWORD src1_sel:WORD_1
	global_store_dwordx2 v[26:27], v[20:21], off offset:2048
	v_mov_b64_e32 v[34:35], v[10:11]
	v_mov_b64_e32 v[22:23], v[14:15]
	v_mov_b64_e32 v[26:27], v[18:19]
	v_lshl_add_u64 v[50:51], v[50:51], 0, s[38:39]
	s_and_b64 vcc, exec, s[40:41]
	v_mov_b64_e32 v[28:29], v[4:5]
	v_mov_b64_e32 v[32:33], v[8:9]
	v_mov_b64_e32 v[20:21], v[12:13]
	v_mov_b64_e32 v[24:25], v[16:17]
	s_waitcnt vmcnt(3)
	v_mov_b64_e32 v[58:59], v[52:53]
	s_waitcnt vmcnt(2)
	v_mov_b64_e32 v[40:41], v[56:57]
	s_cbranch_vccnz .LBB0_2019

.LBB0_2023:
	v_pk_add_f32 v[20:21], v[20:21], v[24:25]
	v_pk_add_f32 v[22:23], v[22:23], v[26:27]
	v_pk_mul_f32 v[26:27], v[20:21], v[20:21]
	v_pk_mul_f32 v[24:25], v[22:23], v[22:23]
	v_add_f32_e32 v26, v26, v27
	v_add_f32_e32 v24, v24, v26
	v_add_f32_e32 v26, v25, v24
	ds_bpermute_b32 v27, v1, v26
	v_pk_add_f32 v[24:25], v[30:31], v[34:35]
	v_and_b32_e32 v34, 0xffff0000, v61
	v_mul_f32_e32 v34, 0xbfb8aa3b, v34
	v_exp_f32_e32 v34, v34
	s_waitcnt lgkmcnt(0)
	v_add_f32_e32 v30, v26, v27
	ds_bpermute_b32 v31, v62, v30
	v_pk_add_f32 v[26:27], v[28:29], v[32:33]
	v_lshlrev_b32_e32 v29, 16, v60
	v_mul_f32_e32 v29, 0xbfb8aa3b, v29
	v_and_b32_e32 v32, 0xffff0000, v60
	s_waitcnt lgkmcnt(0)
	v_add_f32_e32 v30, v30, v31
	ds_bpermute_b32 v31, v63, v30
	v_exp_f32_e32 v29, v29
	v_lshlrev_b32_e32 v33, 16, v61
	v_mul_f32_e32 v33, 0xbfb8aa3b, v33
	v_lshlrev_b32_e32 v28, 16, v58
	s_waitcnt lgkmcnt(0)
	v_add_f32_e32 v30, v30, v31
	ds_bpermute_b32 v31, v64, v30
	v_add_f32_e32 v29, 1.0, v29
	v_exp_f32_e32 v33, v33
	v_mul_f32_e32 v35, 0xbfb8aa3b, v28
	v_exp_f32_e32 v35, v35
	s_waitcnt lgkmcnt(0)
	v_add_f32_e32 v30, v30, v31
	ds_bpermute_b32 v31, v65, v30
	v_add_f32_e32 v33, 1.0, v33
	v_add_f32_e32 v34, 1.0, v34
	v_and_b32_e32 v58, 0xffff0000, v58
	v_add_f32_e32 v35, 1.0, v35
	s_waitcnt lgkmcnt(0)
	v_add_f32_e32 v31, v30, v31
	ds_bpermute_b32 v60, v66, v31
	v_rcp_f32_e32 v30, v29
	v_mov_b32_e32 v72, v26
	v_mul_f32_e32 v32, 0xbfb8aa3b, v32
	v_exp_f32_e32 v32, v32
	s_waitcnt lgkmcnt(0)
	v_add_f32_e32 v29, v31, v60
	v_fmamk_f32 v29, v29, 0x3b800000, v67
	v_mul_f32_e32 v31, 0x4b800000, v29
	v_cmp_gt_f32_e32 vcc, s1, v29
	v_mul_f32_e32 v60, 0xbfb8aa3b, v58
	v_exp_f32_e32 v61, v60
	v_cndmask_b32_e32 v29, v29, v31, vcc
	v_rsq_f32_e32 v29, v29
	v_rcp_f32_e32 v31, v33
	v_rcp_f32_e32 v33, v34
	v_rcp_f32_e32 v60, v35
	v_mul_f32_e32 v34, 0x45800000, v29
	v_cndmask_b32_e32 v34, v29, v34, vcc
	v_lshlrev_b32_e32 v29, 16, v59
	v_mul_f32_e32 v35, 0xbfb8aa3b, v29
	v_exp_f32_e32 v35, v35
	v_and_b32_e32 v59, 0xffff0000, v59
	v_add_f32_e32 v61, 1.0, v61
	v_rcp_f32_e32 v70, v61
	v_add_f32_e32 v26, 1.0, v35
	v_rcp_f32_e32 v61, v26
	v_mul_f32_e32 v26, 0xbfb8aa3b, v59
	v_exp_f32_e32 v26, v26
	v_add_f32_e32 v32, 1.0, v32
	v_mov_b32_e32 v73, v24
	v_rcp_f32_e32 v32, v32
	v_add_f32_e32 v24, 1.0, v26
	v_rcp_f32_e32 v71, v24
	v_pk_mul_f32 v[30:31], v[72:73], v[30:31]
	v_pk_mul_f32 v[28:29], v[60:61], v[28:29]
	v_mov_b32_e32 v24, v27
	v_pk_mul_f32 v[28:29], v[30:31], v[28:29]
	v_pk_mul_f32 v[24:25], v[24:25], v[32:33]
	v_pk_mul_f32 v[26:27], v[70:71], v[58:59]
	s_add_i32 s0, s0, s34
	v_pk_mul_f32 v[24:25], v[24:25], v[26:27]
	s_nop 0
	v_and_b32_sdwa v27, v28, v68 dst_sel:DWORD dst_unused:UNUSED_PAD src0_sel:WORD_1 src1_sel:DWORD
	v_add3_u32 v27, v28, v27, s10
	s_nop 0
	v_cvt_pk_bf16_f32 v25, v29, v25
	v_and_b32_sdwa v29, v24, v68 dst_sel:DWORD dst_unused:UNUSED_PAD src0_sel:WORD_1 src1_sel:DWORD
	s_nop 0
	v_add3_u32 v24, v24, v29, s10
	s_nop 0
	v_and_b32_e32 v24, 0xffff0000, v24
	s_nop 0
	v_or_b32_sdwa v24, v24, v27 dst_sel:DWORD dst_unused:UNUSED_PAD src0_sel:DWORD src1_sel:WORD_1
	v_lshl_add_u64 v[26:27], v[50:51], 0, v[36:37]
	v_add_co_u32_e32 v26, vcc, s11, v26
	v_and_b32_e32 v28, 0xffff0000, v44
	s_nop 0
	v_addc_co_u32_e32 v27, vcc, 0, v27, vcc
	global_store_dwordx2 v[26:27], v[24:25], off
	v_lshlrev_b32_e32 v24, 16, v44
	v_mul_f32_e32 v29, 0xbfb8aa3b, v24
	v_exp_f32_e32 v30, v29
	v_mul_f32_e32 v29, 0xbfb8aa3b, v28
	v_exp_f32_e32 v31, v29
	v_lshlrev_b32_e32 v25, 16, v45
	v_and_b32_e32 v29, 0xffff0000, v45
	v_mov_b32_e32 v44, v20
	v_add_f32_e32 v31, 1.0, v31
	v_rcp_f32_e32 v32, v31
	v_mul_f32_e32 v31, 0xbfb8aa3b, v25
	v_exp_f32_e32 v31, v31
	v_add_f32_e32 v30, 1.0, v30
	v_rcp_f32_e32 v30, v30
	v_mov_b32_e32 v45, v22
	v_add_f32_e32 v20, 1.0, v31
	v_rcp_f32_e32 v31, v20
	v_mul_f32_e32 v20, 0xbfb8aa3b, v29
	v_exp_f32_e32 v20, v20
	v_pk_mul_f32 v[44:45], v[44:45], v[34:35] op_sel_hi:[1,0]
	v_mov_b32_e32 v22, v21
	v_pk_mul_f32 v[44:45], v[2:3], v[44:45]
	v_add_f32_e32 v20, 1.0, v20
	v_rcp_f32_e32 v33, v20
	v_pk_mul_f32 v[24:25], v[30:31], v[24:25]
	v_pk_mul_f32 v[20:21], v[22:23], v[34:35] op_sel_hi:[1,0]
	v_pk_mul_f32 v[24:25], v[24:25], v[44:45]
	v_pk_mul_f32 v[20:21], v[38:39], v[20:21]
	v_pk_mul_f32 v[22:23], v[32:33], v[28:29]
	s_waitcnt vmcnt(7)
	v_mov_b64_e32 v[30:31], v[6:7]
	v_pk_mul_f32 v[20:21], v[22:23], v[20:21]
	s_nop 0
	v_and_b32_sdwa v23, v24, v68 dst_sel:DWORD dst_unused:UNUSED_PAD src0_sel:WORD_1 src1_sel:DWORD
	v_add3_u32 v23, v24, v23, s10
	s_nop 0
	v_cvt_pk_bf16_f32 v21, v25, v21
	v_and_b32_sdwa v25, v20, v68 dst_sel:DWORD dst_unused:UNUSED_PAD src0_sel:WORD_1 src1_sel:DWORD
	s_nop 0
	v_add3_u32 v20, v20, v25, s10
	s_nop 0
	v_and_b32_e32 v20, 0xffff0000, v20
	s_nop 0
	v_or_b32_sdwa v20, v20, v23 dst_sel:DWORD dst_unused:UNUSED_PAD src0_sel:DWORD src1_sel:WORD_1
	global_store_dwordx2 v[26:27], v[20:21], off offset:2048
	s_waitcnt vmcnt(7)
	v_mov_b64_e32 v[34:35], v[10:11]
	s_waitcnt vmcnt(6)
	v_mov_b64_e32 v[22:23], v[14:15]
	s_waitcnt vmcnt(5)
	v_mov_b64_e32 v[26:27], v[18:19]
	v_lshl_add_u64 v[40:41], v[40:41], 0, s[4:5]
	v_lshl_add_u64 v[46:47], v[46:47], 0, s[18:19]
	v_lshl_add_u64 v[48:49], v[48:49], 0, s[18:19]
	v_lshl_add_u64 v[50:51], v[50:51], 0, s[16:17]
	s_cmp_ge_i32 s0, s3
	v_mov_b64_e32 v[28:29], v[4:5]
	v_mov_b64_e32 v[32:33], v[8:9]
	v_mov_b64_e32 v[20:21], v[12:13]
	v_mov_b64_e32 v[24:25], v[16:17]
	s_waitcnt vmcnt(4)
	v_mov_b64_e32 v[60:61], v[54:55]
	s_waitcnt vmcnt(3)
	v_mov_b64_e32 v[58:59], v[52:53]
	s_waitcnt vmcnt(2)
	v_mov_b64_e32 v[44:45], v[56:57]
	s_cbranch_scc1 .LBB0_2026

.LBB0_2289:
	ds_read2_b32 v[52:53], v89 offset1:65
	ds_read2_b32 v[78:79], v89 offset0:130 offset1:195
	s_mul_hi_i32 s6, s51, 0x8fb823ef
	s_add_i32 s6, s6, s51
	s_lshr_b32 s7, s6, 31
	s_waitcnt lgkmcnt(1)
	s_nop 0
	s_nop 0
	v_cvt_pk_bf16_f32 v106, v52, v53
	s_waitcnt lgkmcnt(0)
	v_cvt_pk_bf16_f32 v107, v78, v79
	ds_read2_b32 v[52:53], v102 offset0:4 offset1:69
	ds_read2_b32 v[78:79], v102 offset0:134 offset1:199
	s_waitcnt lgkmcnt(1)
	v_cvt_pk_bf16_f32 v108, v52, v53
	s_ashr_i32 s6, s6, 7
	s_add_i32 s6, s6, s7
	s_waitcnt lgkmcnt(0)
	v_cvt_pk_bf16_f32 v109, v78, v79
	s_mul_i32 s7, s6, 0xe4
	s_sub_i32 s7, s51, s7
	v_lshl_or_b32 v52, s7, 6, v88
	v_ashrrev_i32_e32 v53, 31, v52
	s_lshl_b32 s6, s6, 8
	v_lshlrev_b64 v[52:53], 13, v[52:53]
	v_lshl_add_u64 v[52:53], s[20:21], 0, v[52:53]
	ds_read2_b32 v[78:79], v90 offset1:65
	s_ashr_i32 s7, s6, 31
	v_lshl_add_u64 v[52:53], s[6:7], 1, v[52:53]
	v_lshl_add_u64 v[110:111], v[70:71], 1, v[52:53]
	global_store_dwordx4 v[110:111], v[106:109], off
	ds_read2_b32 v[108:109], v90 offset0:130 offset1:195
	s_waitcnt lgkmcnt(1)
	v_cvt_pk_bf16_f32 v106, v78, v79
	s_waitcnt lgkmcnt(0)
	ds_read2_b32 v[78:79], v103 offset0:4 offset1:69
	v_cvt_pk_bf16_f32 v107, v108, v109
	ds_read2_b32 v[102:103], v103 offset0:134 offset1:199
	s_waitcnt lgkmcnt(1)
	v_cvt_pk_bf16_f32 v108, v78, v79
	s_waitcnt lgkmcnt(0)
	ds_read2_b32 v[78:79], v91 offset1:65
	v_cvt_pk_bf16_f32 v109, v102, v103
	v_lshl_add_u64 v[102:103], v[72:73], 1, v[52:53]
	global_store_dwordx4 v[102:103], v[106:109], off
	ds_read2_b32 v[102:103], v91 offset0:130 offset1:195
	s_waitcnt lgkmcnt(1)
	v_cvt_pk_bf16_f32 v106, v78, v79
	ds_read2_b32 v[78:79], v104 offset0:4 offset1:69
	s_waitcnt lgkmcnt(1)
	v_cvt_pk_bf16_f32 v107, v102, v103
	ds_read2_b32 v[102:103], v104 offset0:134 offset1:199
	s_waitcnt lgkmcnt(1)
	v_cvt_pk_bf16_f32 v108, v78, v79
	ds_read2_b32 v[78:79], v92 offset1:65
	s_waitcnt lgkmcnt(1)
	v_cvt_pk_bf16_f32 v109, v102, v103
	v_lshl_add_u64 v[102:103], v[74:75], 1, v[52:53]
	global_store_dwordx4 v[102:103], v[106:109], off
	s_waitcnt lgkmcnt(0)
	v_cvt_pk_bf16_f32 v102, v78, v79
	ds_read2_b32 v[106:107], v92 offset0:130 offset1:195
	ds_read2_b32 v[78:79], v105 offset0:4 offset1:69
	s_waitcnt lgkmcnt(1)
	v_cvt_pk_bf16_f32 v103, v106, v107
	ds_read2_b32 v[106:107], v105 offset0:134 offset1:199
	s_waitcnt lgkmcnt(1)
	v_cvt_pk_bf16_f32 v104, v78, v79
	s_waitcnt lgkmcnt(0)
	v_bfe_u32 v51, v106, 16, 1
	v_add3_u32 v51, v106, v51, s47
	v_bfe_u32 v78, v107, 16, 1
	v_lshrrev_b32_e32 v51, 16, v51
	v_add3_u32 v78, v107, v78, s47
	v_and_or_b32 v105, v78, s48, v51
	v_lshl_add_u64 v[52:53], v[76:77], 1, v[52:53]
	global_store_dwordx4 v[52:53], v[102:105], off
	s_waitcnt lgkmcnt(0)
	s_barrier

.LBB0_2382:
	ds_read2_b32 v[52:53], v89 offset1:65
	ds_read2_b32 v[78:79], v89 offset0:130 offset1:195
	v_add_u32_e32 v102, 0x400, v89
	s_mul_hi_i32 s6, s50, 0x8fb823ef
	s_add_i32 s6, s6, s50
	s_waitcnt lgkmcnt(1)
	s_nop 0
	s_nop 0
	v_cvt_pk_bf16_f32 v104, v52, v53
	s_waitcnt lgkmcnt(0)
	v_cvt_pk_bf16_f32 v105, v78, v79
	ds_read2_b32 v[52:53], v102 offset0:4 offset1:69
	ds_read2_b32 v[78:79], v102 offset0:134 offset1:199
	s_waitcnt lgkmcnt(1)
	v_cvt_pk_bf16_f32 v106, v52, v53
	s_lshr_b32 s7, s6, 31
	s_ashr_i32 s6, s6, 7
	s_add_i32 s7, s6, s7
	s_waitcnt lgkmcnt(0)
	v_cvt_pk_bf16_f32 v107, v78, v79
	s_lshl_b32 s6, s7, 8
	s_mulk_i32 s7, 0xc700
	s_add_i32 s7, s7, s38
	v_add_u32_e32 v52, s7, v88
	v_ashrrev_i32_e32 v53, 31, v52
	ds_read2_b32 v[78:79], v90 offset1:65
	v_lshlrev_b64 v[52:53], 13, v[52:53]
	v_lshl_add_u64 v[52:53], s[20:21], 0, v[52:53]
	s_ashr_i32 s7, s6, 31
	v_lshl_add_u64 v[52:53], s[6:7], 1, v[52:53]
	v_lshl_add_u64 v[108:109], v[70:71], 1, v[52:53]
	global_store_dwordx4 v[108:109], v[104:107], off
	s_waitcnt lgkmcnt(0)
	s_nop 0
	ds_read2_b32 v[106:107], v90 offset0:130 offset1:195
	v_cvt_pk_bf16_f32 v104, v78, v79
	v_add_u32_e32 v103, 0x400, v90
	ds_read2_b32 v[78:79], v103 offset0:4 offset1:69
	s_waitcnt lgkmcnt(1)
	v_cvt_pk_bf16_f32 v105, v106, v107
	ds_read2_b32 v[108:109], v103 offset0:134 offset1:199
	s_waitcnt lgkmcnt(1)
	v_cvt_pk_bf16_f32 v106, v78, v79
	s_waitcnt lgkmcnt(0)
	v_cvt_pk_bf16_f32 v107, v108, v109
	ds_read2_b32 v[78:79], v91 offset1:65
	v_lshl_add_u64 v[108:109], v[72:73], 1, v[52:53]
	global_store_dwordx4 v[108:109], v[104:107], off
	ds_read2_b32 v[104:105], v91 offset0:130 offset1:195
	s_waitcnt lgkmcnt(1)
	v_cvt_pk_bf16_f32 v106, v78, v79
	s_waitcnt lgkmcnt(0)
	v_cvt_pk_bf16_f32 v107, v104, v105
	v_add_u32_e32 v104, 0x400, v91
	ds_read2_b32 v[78:79], v104 offset0:4 offset1:69
	ds_read2_b32 v[110:111], v104 offset0:134 offset1:199
	s_waitcnt lgkmcnt(1)
	v_cvt_pk_bf16_f32 v108, v78, v79
	ds_read2_b32 v[78:79], v92 offset1:65
	s_waitcnt lgkmcnt(1)
	v_cvt_pk_bf16_f32 v109, v110, v111
	v_lshl_add_u64 v[110:111], v[74:75], 1, v[52:53]
	global_store_dwordx4 v[110:111], v[106:109], off
	s_waitcnt lgkmcnt(0)
	v_cvt_pk_bf16_f32 v106, v78, v79
	ds_read2_b32 v[108:109], v92 offset0:130 offset1:195
	v_add_u32_e32 v105, 0x400, v92
	ds_read2_b32 v[78:79], v105 offset0:4 offset1:69
	s_waitcnt lgkmcnt(1)
	v_cvt_pk_bf16_f32 v107, v108, v109
	ds_read2_b32 v[110:111], v105 offset0:134 offset1:199
	s_waitcnt lgkmcnt(1)
	v_cvt_pk_bf16_f32 v108, v78, v79
	s_waitcnt lgkmcnt(0)
	v_bfe_u32 v51, v110, 16, 1
	v_add3_u32 v51, v110, v51, s47
	v_bfe_u32 v78, v111, 16, 1
	v_lshrrev_b32_e32 v51, 16, v51
	v_add3_u32 v78, v111, v78, s47
	v_and_or_b32 v109, v78, s48, v51
	v_lshl_add_u64 v[52:53], v[76:77], 1, v[52:53]
	global_store_dwordx4 v[52:53], v[106:109], off
	s_waitcnt lgkmcnt(0)
	s_barrier
	s_add_i32 s51, s24, s50
	s_cmpk_gt_i32 s51, 0xe3f
	s_cbranch_scc1 .LBB0_2290
	ds_write2_b32 v94, v22, v23 offset1:1
	ds_write2_b32 v94, v24, v25 offset0:2 offset1:3
	ds_write2_b32 v95, v30, v31 offset1:1
	ds_write2_b32 v95, v32, v33 offset0:2 offset1:3
	ds_write2_b32 v96, v38, v39 offset1:1
	ds_write2_b32 v96, v40, v41 offset0:2 offset1:3
	ds_write2_b32 v97, v46, v47 offset1:1
	ds_write2_b32 v97, v48, v49 offset0:2 offset1:3
	ds_write2_b32 v98, v54, v55 offset1:1
	ds_write2_b32 v98, v56, v57 offset0:2 offset1:3
	ds_write2_b32 v99, v58, v59 offset1:1
	ds_write2_b32 v99, v60, v61 offset0:2 offset1:3
	ds_write2_b32 v100, v62, v63 offset1:1
	ds_write2_b32 v100, v64, v65 offset0:2 offset1:3
	ds_write2_b32 v101, v66, v67 offset1:1
	ds_write2_b32 v101, v68, v69 offset0:2 offset1:3
	s_waitcnt lgkmcnt(0)
	s_barrier
	s_add_i32 s6, s40, s50
	s_cmpk_gt_i32 s6, 0xe3f
	s_cbranch_scc1 .LBB0_2289
	s_mul_hi_i32 s7, s6, 0x8fb823ef
	s_add_i32 s7, s7, s6
	s_lshr_b32 s28, s7, 31
	s_ashr_i32 s7, s7, 7
	s_add_i32 s28, s7, s28
	s_mul_i32 s7, s28, 0xe4
	s_sub_i32 s6, s6, s7
	s_lshl_b32 s50, s6, 6
	v_or_b32_e32 v78, s50, v1
	v_cmp_lt_i32_e64 s[6:7], s41, v78
	v_mov_b32_e32 v30, v78
	s_and_saveexec_b64 s[34:35], s[6:7]
	s_cbranch_execz .LBB0_2393
	s_cmpk_gt_u32 s50, 0x37ff
	s_mov_b64 s[36:37], -1
	s_cbranch_scc0 .LBB0_2391
	v_cmp_lt_u32_e32 vcc, s44, v78
	s_and_saveexec_b64 s[36:37], vcc
	s_xor_b64 s[36:37], exec, s[36:37]
	v_cmp_gt_u32_e32 vcc, s45, v78
	s_nop 1
	v_cndmask_b32_e32 v30, -1, v78, vcc
	s_andn2_saveexec_b64 s[36:37], s[36:37]
	v_add_u32_e32 v30, 0xfffff400, v78
	s_or_b64 exec, exec, s[36:37]
	s_mov_b64 s[36:37], 0

.LBB0_2704:
	ds_read2_b32 v[52:53], v89 offset1:65
	ds_read2_b32 v[78:79], v89 offset0:130 offset1:195
	s_mul_hi_i32 s4, s30, 0x8fb823ef
	s_add_i32 s4, s4, s30
	s_lshr_b32 s5, s4, 31
	s_waitcnt lgkmcnt(1)
	s_nop 0
	s_nop 0
	v_cvt_pk_bf16_f32 v106, v52, v53
	s_waitcnt lgkmcnt(0)
	v_cvt_pk_bf16_f32 v107, v78, v79
	ds_read2_b32 v[52:53], v102 offset0:4 offset1:69
	ds_read2_b32 v[78:79], v102 offset0:134 offset1:199
	s_waitcnt lgkmcnt(1)
	v_cvt_pk_bf16_f32 v108, v52, v53
	s_ashr_i32 s4, s4, 7
	s_add_i32 s4, s4, s5
	s_waitcnt lgkmcnt(0)
	v_cvt_pk_bf16_f32 v109, v78, v79
	s_mul_i32 s5, s4, 0xe4
	s_sub_i32 s5, s30, s5
	v_lshl_or_b32 v52, s5, 6, v88
	v_ashrrev_i32_e32 v53, 31, v52
	s_lshl_b32 s4, s4, 8
	v_lshlrev_b64 v[52:53], 13, v[52:53]
	v_lshl_add_u64 v[52:53], s[6:7], 0, v[52:53]
	ds_read2_b32 v[78:79], v90 offset1:65
	s_ashr_i32 s5, s4, 31
	v_lshl_add_u64 v[52:53], s[4:5], 1, v[52:53]
	v_lshl_add_u64 v[110:111], v[70:71], 1, v[52:53]
	global_store_dwordx4 v[110:111], v[106:109], off
	ds_read2_b32 v[108:109], v90 offset0:130 offset1:195
	s_waitcnt lgkmcnt(1)
	v_cvt_pk_bf16_f32 v106, v78, v79
	s_waitcnt lgkmcnt(0)
	ds_read2_b32 v[78:79], v103 offset0:4 offset1:69
	v_cvt_pk_bf16_f32 v107, v108, v109
	ds_read2_b32 v[102:103], v103 offset0:134 offset1:199
	s_waitcnt lgkmcnt(1)
	v_cvt_pk_bf16_f32 v108, v78, v79
	s_waitcnt lgkmcnt(0)
	ds_read2_b32 v[78:79], v91 offset1:65
	v_cvt_pk_bf16_f32 v109, v102, v103
	v_lshl_add_u64 v[102:103], v[72:73], 1, v[52:53]
	global_store_dwordx4 v[102:103], v[106:109], off
	ds_read2_b32 v[102:103], v91 offset0:130 offset1:195
	s_waitcnt lgkmcnt(1)
	v_cvt_pk_bf16_f32 v106, v78, v79
	ds_read2_b32 v[78:79], v104 offset0:4 offset1:69
	s_waitcnt lgkmcnt(1)
	v_cvt_pk_bf16_f32 v107, v102, v103
	ds_read2_b32 v[102:103], v104 offset0:134 offset1:199
	s_waitcnt lgkmcnt(1)
	v_cvt_pk_bf16_f32 v108, v78, v79
	ds_read2_b32 v[78:79], v92 offset1:65
	s_waitcnt lgkmcnt(1)
	v_cvt_pk_bf16_f32 v109, v102, v103
	v_lshl_add_u64 v[102:103], v[74:75], 1, v[52:53]
	global_store_dwordx4 v[102:103], v[106:109], off
	s_waitcnt lgkmcnt(0)
	v_cvt_pk_bf16_f32 v102, v78, v79
	ds_read2_b32 v[106:107], v92 offset0:130 offset1:195
	ds_read2_b32 v[78:79], v105 offset0:4 offset1:69
	s_waitcnt lgkmcnt(1)
	v_cvt_pk_bf16_f32 v103, v106, v107
	ds_read2_b32 v[106:107], v105 offset0:134 offset1:199
	s_waitcnt lgkmcnt(1)
	v_cvt_pk_bf16_f32 v104, v78, v79
	s_waitcnt lgkmcnt(0)
	v_bfe_u32 v51, v106, 16, 1
	v_add3_u32 v51, v106, v51, s23
	v_bfe_u32 v78, v107, 16, 1
	v_lshrrev_b32_e32 v51, 16, v51
	v_add3_u32 v78, v107, v78, s23
	v_and_or_b32 v105, v78, s25, v51
	v_lshl_add_u64 v[52:53], v[76:77], 1, v[52:53]
	global_store_dwordx4 v[52:53], v[102:105], off
	s_waitcnt lgkmcnt(0)
	s_barrier

.LBB0_2797:
	ds_read2_b32 v[52:53], v89 offset1:65
	ds_read2_b32 v[78:79], v89 offset0:130 offset1:195
	v_add_u32_e32 v102, 0x400, v89
	s_mul_hi_i32 s4, s27, 0x8fb823ef
	s_add_i32 s4, s4, s27
	s_waitcnt lgkmcnt(1)
	s_nop 0
	s_nop 0
	v_cvt_pk_bf16_f32 v104, v52, v53
	s_waitcnt lgkmcnt(0)
	v_cvt_pk_bf16_f32 v105, v78, v79
	ds_read2_b32 v[52:53], v102 offset0:4 offset1:69
	ds_read2_b32 v[78:79], v102 offset0:134 offset1:199
	s_waitcnt lgkmcnt(1)
	v_cvt_pk_bf16_f32 v106, v52, v53
	s_lshr_b32 s5, s4, 31
	s_ashr_i32 s4, s4, 7
	s_add_i32 s5, s4, s5
	s_waitcnt lgkmcnt(0)
	v_cvt_pk_bf16_f32 v107, v78, v79
	s_lshl_b32 s4, s5, 8
	s_mulk_i32 s5, 0xc700
	s_add_i32 s5, s5, s10
	v_add_u32_e32 v52, s5, v88
	v_ashrrev_i32_e32 v53, 31, v52
	ds_read2_b32 v[78:79], v90 offset1:65
	v_lshlrev_b64 v[52:53], 13, v[52:53]
	v_lshl_add_u64 v[52:53], s[6:7], 0, v[52:53]
	s_ashr_i32 s5, s4, 31
	v_lshl_add_u64 v[52:53], s[4:5], 1, v[52:53]
	v_lshl_add_u64 v[108:109], v[70:71], 1, v[52:53]
	global_store_dwordx4 v[108:109], v[104:107], off
	s_waitcnt lgkmcnt(0)
	s_nop 0
	ds_read2_b32 v[106:107], v90 offset0:130 offset1:195
	v_cvt_pk_bf16_f32 v104, v78, v79
	v_add_u32_e32 v103, 0x400, v90
	ds_read2_b32 v[78:79], v103 offset0:4 offset1:69
	s_waitcnt lgkmcnt(1)
	v_cvt_pk_bf16_f32 v105, v106, v107
	ds_read2_b32 v[108:109], v103 offset0:134 offset1:199
	s_waitcnt lgkmcnt(1)
	v_cvt_pk_bf16_f32 v106, v78, v79
	s_waitcnt lgkmcnt(0)
	v_cvt_pk_bf16_f32 v107, v108, v109
	ds_read2_b32 v[78:79], v91 offset1:65
	v_lshl_add_u64 v[108:109], v[72:73], 1, v[52:53]
	global_store_dwordx4 v[108:109], v[104:107], off
	ds_read2_b32 v[104:105], v91 offset0:130 offset1:195
	s_waitcnt lgkmcnt(1)
	v_cvt_pk_bf16_f32 v106, v78, v79
	s_waitcnt lgkmcnt(0)
	v_cvt_pk_bf16_f32 v107, v104, v105
	v_add_u32_e32 v104, 0x400, v91
	ds_read2_b32 v[78:79], v104 offset0:4 offset1:69
	ds_read2_b32 v[110:111], v104 offset0:134 offset1:199
	s_waitcnt lgkmcnt(1)
	v_cvt_pk_bf16_f32 v108, v78, v79
	ds_read2_b32 v[78:79], v92 offset1:65
	s_waitcnt lgkmcnt(1)
	v_cvt_pk_bf16_f32 v109, v110, v111
	v_lshl_add_u64 v[110:111], v[74:75], 1, v[52:53]
	global_store_dwordx4 v[110:111], v[106:109], off
	s_waitcnt lgkmcnt(0)
	v_cvt_pk_bf16_f32 v106, v78, v79
	ds_read2_b32 v[108:109], v92 offset0:130 offset1:195
	v_add_u32_e32 v105, 0x400, v92
	ds_read2_b32 v[78:79], v105 offset0:4 offset1:69
	s_waitcnt lgkmcnt(1)
	v_cvt_pk_bf16_f32 v107, v108, v109
	ds_read2_b32 v[110:111], v105 offset0:134 offset1:199
	s_waitcnt lgkmcnt(1)
	v_cvt_pk_bf16_f32 v108, v78, v79
	s_waitcnt lgkmcnt(0)
	v_bfe_u32 v51, v110, 16, 1
	v_add3_u32 v51, v110, v51, s23
	v_bfe_u32 v78, v111, 16, 1
	v_lshrrev_b32_e32 v51, 16, v51
	v_add3_u32 v78, v111, v78, s23
	v_and_or_b32 v109, v78, s25, v51
	v_lshl_add_u64 v[52:53], v[76:77], 1, v[52:53]
	global_store_dwordx4 v[52:53], v[106:109], off
	s_waitcnt lgkmcnt(0)
	s_barrier
	s_add_i32 s30, s24, s27
	s_cmpk_gt_i32 s30, 0xe3f
	s_cbranch_scc1 .LBB0_2705
	ds_write2_b32 v94, v22, v23 offset1:1
	ds_write2_b32 v94, v24, v25 offset0:2 offset1:3
	ds_write2_b32 v95, v30, v31 offset1:1
	ds_write2_b32 v95, v32, v33 offset0:2 offset1:3
	ds_write2_b32 v96, v38, v39 offset1:1
	ds_write2_b32 v96, v40, v41 offset0:2 offset1:3
	ds_write2_b32 v97, v46, v47 offset1:1
	ds_write2_b32 v97, v48, v49 offset0:2 offset1:3
	ds_write2_b32 v98, v54, v55 offset1:1
	ds_write2_b32 v98, v56, v57 offset0:2 offset1:3
	ds_write2_b32 v99, v58, v59 offset1:1
	ds_write2_b32 v99, v60, v61 offset0:2 offset1:3
	ds_write2_b32 v100, v62, v63 offset1:1
	ds_write2_b32 v100, v64, v65 offset0:2 offset1:3
	ds_write2_b32 v101, v66, v67 offset1:1
	ds_write2_b32 v101, v68, v69 offset0:2 offset1:3
	s_waitcnt lgkmcnt(0)
	s_barrier
	s_add_i32 s4, s18, s27
	s_cmpk_gt_i32 s4, 0xe3f
	s_cbranch_scc1 .LBB0_2704
	s_mul_hi_i32 s5, s4, 0x8fb823ef
	s_add_i32 s5, s5, s4
	s_lshr_b32 s14, s5, 31
	s_ashr_i32 s28, s5, 7
	s_add_i32 s28, s28, s14
	s_mul_i32 s5, s28, 0xe4
	s_sub_i32 s4, s4, s5
	s_lshl_b32 s27, s4, 6
	v_or_b32_e32 v78, s27, v1
	v_cmp_lt_i32_e64 s[4:5], s19, v78
	v_mov_b32_e32 v30, v78
	s_and_saveexec_b64 s[14:15], s[4:5]
	s_cbranch_execz .LBB0_2808
	s_cmpk_gt_u32 s27, 0x37ff
	s_mov_b64 s[16:17], -1
	s_cbranch_scc0 .LBB0_2806
	v_cmp_lt_u32_e32 vcc, s20, v78
	s_and_saveexec_b64 s[16:17], vcc
	s_xor_b64 s[16:17], exec, s[16:17]
	v_cmp_gt_u32_e32 vcc, s21, v78
	s_nop 1
	v_cndmask_b32_e32 v30, -1, v78, vcc
	s_andn2_saveexec_b64 s[16:17], s[16:17]
	v_add_u32_e32 v30, 0xfffff400, v78
	s_or_b64 exec, exec, s[16:17]
	s_mov_b64 s[16:17], 0

.LBB0_2950:
	s_or_b64 exec, exec, s[22:23]
	v_lshl_add_u64 v[104:105], v[80:81], 2, s[18:19]
	v_lshl_add_u64 v[106:107], v[104:105], 0, s[16:17]
	s_waitcnt lgkmcnt(0)
	s_barrier
	v_lshl_add_u64 v[92:93], v[106:107], 0, v[50:51]
	s_waitcnt lgkmcnt(0)
	global_load_dwordx4 v[80:83], v[54:55], off
	v_lshl_add_u64 v[96:97], v[104:105], 0, v[50:51]
	global_load_dwordx4 v[92:95], v[92:93], off
	v_ashrrev_i32_e32 v49, 6, v49
	global_load_dwordx4 v[96:99], v[96:97], off
	v_lshlrev_b32_e32 v49, 2, v49
	v_and_b32_e32 v91, -16, v49
	v_add_u32_e32 v91, 0, v91
	ds_read_b96 v[100:102], v91
	v_or_b32_e32 v49, 12, v49
	v_add_u32_e32 v49, 0, v49
	v_lshlrev_b64 v[78:79], 13, v[78:79]
	v_add_u32_e32 v1, s11, v1
	s_waitcnt lgkmcnt(0)
	v_mov_b32_e32 v108, v101
	ds_read_b32 v101, v49
	v_mov_b32_e32 v109, v102
	s_waitcnt lgkmcnt(0)
	v_pk_add_f32 v[100:101], v[108:109], v[100:101]
	s_nop 0
	v_add_f32_e32 v49, v100, v101
	v_fmamk_f32 v49, v49, 0x39800000, v90
	v_mul_f32_e32 v91, 0x4b800000, v49
	v_cmp_gt_f32_e32 vcc, s27, v49
	v_lshl_add_u64 v[100:101], s[8:9], 0, v[78:79]
	s_nop 0
	v_cndmask_b32_e32 v49, v49, v91, vcc
	v_rsq_f32_e32 v91, v49
	v_mov_b32_e32 v49, v51
	v_lshl_add_u64 v[78:79], v[100:101], 0, v[48:49]
	v_mul_f32_e32 v49, 0x45800000, v91
	v_cndmask_b32_e32 v102, v91, v49, vcc
	v_pk_mul_f32 v[20:21], v[20:21], v[102:103] op_sel_hi:[1,0]
	v_pk_mul_f32 v[18:19], v[18:19], v[102:103] op_sel_hi:[1,0]
	v_pk_mul_f32 v[30:31], v[30:31], v[102:103] op_sel_hi:[1,0]
	v_pk_mul_f32 v[32:33], v[32:33], v[102:103] op_sel_hi:[1,0]
	v_pk_mul_f32 v[26:27], v[26:27], v[102:103] op_sel_hi:[1,0]
	v_pk_mul_f32 v[28:29], v[28:29], v[102:103] op_sel_hi:[1,0]
	v_pk_mul_f32 v[22:23], v[22:23], v[102:103] op_sel_hi:[1,0]
	v_pk_mul_f32 v[24:25], v[24:25], v[102:103] op_sel_hi:[1,0]
	s_andn2_b64 vcc, exec, s[0:1]
	s_waitcnt vmcnt(2)
	v_pk_mul_f32 v[18:19], v[80:81], v[18:19]
	v_pk_mul_f32 v[20:21], v[82:83], v[20:21]
	s_waitcnt vmcnt(1)
	v_pk_add_f32 v[80:81], v[94:95], 1.0 op_sel_hi:[1,0]
	v_pk_add_f32 v[82:83], v[92:93], 1.0 op_sel_hi:[1,0]
	s_waitcnt vmcnt(0)
	v_pk_fma_f32 v[20:21], v[80:81], v[20:21], v[98:99]
	v_pk_fma_f32 v[18:19], v[82:83], v[18:19], v[96:97]
	v_bfe_u32 v81, v20, 16, 1
	v_cvt_pk_bf16_f32 v18, v18, v19
	v_bfe_u32 v82, v21, 16, 1
	v_add3_u32 v20, v20, v81, s37
	v_add3_u32 v21, v21, v82, s37
	v_lshrrev_b32_e32 v20, 16, v20
	v_and_or_b32 v19, v21, s26, v20
	global_store_dwordx2 v[78:79], v[18:19], off
	v_lshl_add_u64 v[78:79], v[106:107], 0, v[58:59]
	global_load_dwordx4 v[18:21], v[70:71], off
	v_lshl_add_u64 v[82:83], v[104:105], 0, v[58:59]
	global_load_dwordx4 v[78:81], v[78:79], off
	s_waitcnt vmcnt(1)
	v_pk_mul_f32 v[18:19], v[18:19], v[32:33]
	global_load_dwordx4 v[92:95], v[82:83], off
	v_pk_mul_f32 v[20:21], v[20:21], v[30:31]
	s_waitcnt vmcnt(1)
	v_pk_add_f32 v[30:31], v[80:81], 1.0 op_sel_hi:[1,0]
	v_pk_add_f32 v[32:33], v[78:79], 1.0 op_sel_hi:[1,0]
	v_lshl_add_u64 v[82:83], v[34:35], 1, v[100:101]
	v_lshl_add_u64 v[78:79], v[104:105], 0, v[62:63]
	s_waitcnt vmcnt(0)
	v_pk_fma_f32 v[20:21], v[30:31], v[20:21], v[94:95]
	v_pk_fma_f32 v[18:19], v[32:33], v[18:19], v[92:93]
	v_bfe_u32 v32, v20, 16, 1
	v_cvt_pk_bf16_f32 v18, v18, v19
	v_bfe_u32 v33, v21, 16, 1
	v_add3_u32 v20, v20, v32, s37
	v_add3_u32 v21, v21, v33, s37
	v_lshrrev_b32_e32 v20, 16, v20
	v_and_or_b32 v19, v21, s26, v20
	global_store_dwordx2 v[82:83], v[18:19], off
	v_lshl_add_u64 v[30:31], v[106:107], 0, v[62:63]
	global_load_dwordx4 v[18:21], v[72:73], off
	v_lshl_add_u64 v[82:83], v[36:37], 1, v[100:101]
	global_load_dwordx4 v[30:33], v[30:31], off
	s_waitcnt vmcnt(1)
	v_pk_mul_f32 v[18:19], v[18:19], v[28:29]
	global_load_dwordx4 v[78:81], v[78:79], off
	v_pk_mul_f32 v[20:21], v[20:21], v[26:27]
	s_waitcnt vmcnt(1)
	v_pk_add_f32 v[26:27], v[32:33], 1.0 op_sel_hi:[1,0]
	v_pk_add_f32 v[28:29], v[30:31], 1.0 op_sel_hi:[1,0]
	v_lshl_add_u64 v[30:31], v[104:105], 0, v[66:67]
	s_waitcnt vmcnt(0)
	v_pk_fma_f32 v[20:21], v[26:27], v[20:21], v[80:81]
	v_pk_fma_f32 v[18:19], v[28:29], v[18:19], v[78:79]
	v_bfe_u32 v28, v20, 16, 1
	v_cvt_pk_bf16_f32 v18, v18, v19
	v_bfe_u32 v29, v21, 16, 1
	v_add3_u32 v20, v20, v28, s37
	v_add3_u32 v21, v21, v29, s37
	v_lshrrev_b32_e32 v20, 16, v20
	v_and_or_b32 v19, v21, s26, v20
	global_store_dwordx2 v[82:83], v[18:19], off
	v_lshl_add_u64 v[26:27], v[106:107], 0, v[66:67]
	global_load_dwordx4 v[18:21], v[74:75], off
	v_lshl_add_u64 v[78:79], v[38:39], 1, v[100:101]
	global_load_dwordx4 v[26:29], v[26:27], off
	s_waitcnt vmcnt(1)
	v_pk_mul_f32 v[18:19], v[24:25], v[18:19]
	global_load_dwordx4 v[30:33], v[30:31], off
	v_pk_mul_f32 v[20:21], v[22:23], v[20:21]
	s_waitcnt vmcnt(1)
	v_pk_add_f32 v[22:23], v[28:29], 1.0 op_sel_hi:[1,0]
	v_pk_add_f32 v[24:25], v[26:27], 1.0 op_sel_hi:[1,0]
	s_waitcnt vmcnt(0)
	v_pk_fma_f32 v[20:21], v[20:21], v[22:23], v[32:33]
	v_pk_fma_f32 v[18:19], v[18:19], v[24:25], v[30:31]
	v_bfe_u32 v24, v20, 16, 1
	v_bfe_u32 v22, v18, 16, 1
	v_bfe_u32 v23, v19, 16, 1
	v_bfe_u32 v25, v21, 16, 1
	v_add3_u32 v18, v18, v22, s37
	v_add3_u32 v20, v20, v24, s37
	v_add3_u32 v19, v19, v23, s37
	v_add3_u32 v21, v21, v25, s37
	v_lshrrev_b32_e32 v18, 16, v18
	v_lshrrev_b32_e32 v20, 16, v20
	v_and_or_b32 v18, v19, s26, v18
	v_and_or_b32 v19, v21, s26, v20
	global_store_dwordx2 v[78:79], v[18:19], off
	s_cbranch_vccz .LBB0_2969

.LBB0_3673:
	s_or_b64 exec, exec, s[16:17]
	v_lshlrev_b32_e32 v2, 2, v9
	v_add_u32_e32 v37, s38, v2
	v_add_u32_e32 v2, 0, v2
	v_add_u32_e32 v54, 0x1bc00, v2
	v_lshl_add_u32 v2, v26, 9, v37
	s_waitcnt lgkmcnt(0)
	s_barrier
	ds_read_b128 v[40:43], v2
	ds_read_b128 v[44:47], v54
	s_lshl_b64 s[16:17], s[14:15], 14
	s_add_u32 s0, s85, s16
	s_addc_u32 s1, s84, s17
	v_mov_b32_e32 v33, v3
	s_waitcnt lgkmcnt(1)
	v_mul_f32_e32 v15, 0x3fb8aa3b, v40
	v_lshl_add_u64 v[34:35], s[0:1], 0, v[32:33]
	v_add_u32_e32 v2, 0, v32
	v_exp_f32_e32 v32, v15
	s_waitcnt lgkmcnt(0)
	v_sub_f32_e32 v15, v40, v44
	v_mul_f32_e32 v15, 0x3fb8aa3b, v15
	v_exp_f32_e32 v48, v15
	v_sub_f32_e32 v15, v44, v40
	v_mul_f32_e32 v15, 0x3fb8aa3b, v15
	v_exp_f32_e32 v40, v15
	v_mul_f32_e32 v15, 0x3fb8aa3b, v41
	v_exp_f32_e32 v44, v15
	v_sub_f32_e32 v15, v41, v45
	v_mul_f32_e32 v15, 0x3fb8aa3b, v15
	v_exp_f32_e32 v50, v15
	v_sub_f32_e32 v15, v45, v41
	v_mul_f32_e32 v15, 0x3fb8aa3b, v15
	v_exp_f32_e32 v52, v15
	v_mul_f32_e32 v15, 0x3fb8aa3b, v42
	v_exp_f32_e32 v33, v15
	v_sub_f32_e32 v15, v42, v46
	v_mul_f32_e32 v15, 0x3fb8aa3b, v15
	v_exp_f32_e32 v49, v15
	v_sub_f32_e32 v15, v46, v42
	v_mul_f32_e32 v15, 0x3fb8aa3b, v15
	v_exp_f32_e32 v41, v15
	v_mul_f32_e32 v15, 0x3fb8aa3b, v43
	v_exp_f32_e32 v45, v15
	v_sub_f32_e32 v15, v43, v47
	v_mul_f32_e32 v15, 0x3fb8aa3b, v15
	v_exp_f32_e32 v51, v15
	v_sub_f32_e32 v15, v47, v43
	v_lshlrev_b32_e32 v43, 16, v31
	v_lshlrev_b32_e32 v42, 16, v30
	v_and_b32_e32 v31, 0xffff0000, v31
	v_and_b32_e32 v30, 0xffff0000, v30
	v_pk_mul_f32 v[30:31], v[30:31], s[12:13] op_sel_hi:[1,0]
	v_pk_mul_f32 v[42:43], v[42:43], s[12:13] op_sel_hi:[1,0]
	v_pk_mul_f32 v[44:45], v[30:31], v[44:45]
	v_mul_f32_e32 v15, 0x3fb8aa3b, v15
	v_pk_mul_f32 v[32:33], v[42:43], v[32:33]
	s_nop 0
	v_exp_f32_e32 v53, v15
	v_cvt_pk_bf16_f32 v33, v33, v45
	s_nop 0
	s_nop 0
	s_nop 0
	s_nop 0
	v_cvt_pk_bf16_f32 v32, v32, v44
	s_nop 0
	s_nop 0
	v_ashrrev_i32_e32 v27, 31, v26
	v_lshlrev_b64 v[44:45], 8, v[26:27]
	v_lshl_add_u64 v[44:45], v[34:35], 0, v[44:45]
	global_store_dwordx2 v[44:45], v[32:33], off
	v_pk_mul_f32 v[32:33], v[42:43], v[48:49]
	v_pk_mul_f32 v[30:31], v[30:31], v[50:51]
	s_nop 0
	s_nop 0
	s_nop 0
	v_cvt_pk_bf16_f32 v30, v32, v30
	v_cvt_pk_bf16_f32 v31, v33, v31
	s_nop 0
	s_nop 0
	v_lshlrev_b32_e32 v43, 16, v29
	v_lshlrev_b32_e32 v42, 16, v28
	v_and_b32_e32 v29, 0xffff0000, v29
	v_and_b32_e32 v28, 0xffff0000, v28
	v_mad_u64_u32 v[32:33], s[0:1], v26, s46, v[2:3]
	v_pk_mul_f32 v[40:41], v[40:41], v[42:43]
	v_pk_mul_f32 v[28:29], v[52:53], v[28:29]
	s_nop 0
	s_nop 0
	v_and_b32_sdwa v21, v40, v38 dst_sel:DWORD dst_unused:UNUSED_PAD src0_sel:WORD_1 src1_sel:DWORD
	v_and_b32_sdwa v27, v29, v38 dst_sel:DWORD dst_unused:UNUSED_PAD src0_sel:WORD_1 src1_sel:DWORD
	v_and_b32_sdwa v33, v28, v38 dst_sel:DWORD dst_unused:UNUSED_PAD src0_sel:WORD_1 src1_sel:DWORD
	v_and_b32_sdwa v15, v41, v38 dst_sel:DWORD dst_unused:UNUSED_PAD src0_sel:WORD_1 src1_sel:DWORD
	v_add3_u32 v21, v40, v21, s45
	v_add3_u32 v40, v29, v27, s45
	v_add3_u32 v33, v28, v33, s45
	v_add3_u32 v15, v41, v15, s45
	v_and_b32_e32 v27, 0xffff0000, v40
	v_and_b32_e32 v28, 0xffff0000, v33
	v_lshlrev_b32_e32 v26, 1, v26
	v_mul_u32_u24_e32 v48, 0x90, v9
	v_or_b32_sdwa v29, v27, v15 dst_sel:DWORD dst_unused:UNUSED_PAD src0_sel:DWORD src1_sel:WORD_1
	v_or_b32_sdwa v28, v28, v21 dst_sel:DWORD dst_unused:UNUSED_PAD src0_sel:DWORD src1_sel:WORD_1
	v_add3_u32 v9, s27, v26, v48
	ds_write2st64_b64 v32, v[30:31], v[28:29] offset1:66
	ds_write_b16_d16_hi v9, v21
	v_lshl_add_u32 v21, v20, 9, v37
	ds_read_b128 v[26:29], v21
	ds_write_b16_d16_hi v9, v33 offset:144
	ds_read_b128 v[30:33], v54
	ds_write_b16_d16_hi v9, v15 offset:288
	ds_write_b16_d16_hi v9, v40 offset:432
	v_ashrrev_i32_e32 v36, 6, v6
	s_waitcnt lgkmcnt(4)
	v_mul_f32_e32 v9, 0x3fb8aa3b, v26
	v_exp_f32_e32 v40, v9
	s_waitcnt lgkmcnt(2)
	v_sub_f32_e32 v9, v26, v30
	v_mul_f32_e32 v9, 0x3fb8aa3b, v9
	v_exp_f32_e32 v42, v9
	v_sub_f32_e32 v9, v30, v26
	v_mul_f32_e32 v9, 0x3fb8aa3b, v9
	v_exp_f32_e32 v26, v9
	v_mul_f32_e32 v9, 0x3fb8aa3b, v27
	v_exp_f32_e32 v30, v9
	v_sub_f32_e32 v9, v27, v31
	v_mul_f32_e32 v9, 0x3fb8aa3b, v9
	v_exp_f32_e32 v44, v9
	v_sub_f32_e32 v9, v31, v27
	v_mul_f32_e32 v9, 0x3fb8aa3b, v9
	v_exp_f32_e32 v46, v9
	v_mul_f32_e32 v9, 0x3fb8aa3b, v28
	v_exp_f32_e32 v41, v9
	v_sub_f32_e32 v9, v28, v32
	v_mul_f32_e32 v9, 0x3fb8aa3b, v9
	v_exp_f32_e32 v43, v9
	v_sub_f32_e32 v9, v32, v28
	v_mul_f32_e32 v9, 0x3fb8aa3b, v9
	v_exp_f32_e32 v27, v9
	v_mul_f32_e32 v9, 0x3fb8aa3b, v29
	v_exp_f32_e32 v31, v9
	v_sub_f32_e32 v9, v29, v33
	v_mul_f32_e32 v9, 0x3fb8aa3b, v9
	v_exp_f32_e32 v45, v9
	v_sub_f32_e32 v9, v33, v29
	v_lshlrev_b32_e32 v29, 16, v25
	v_lshlrev_b32_e32 v28, 16, v24
	v_and_b32_e32 v25, 0xffff0000, v25
	v_and_b32_e32 v24, 0xffff0000, v24
	v_pk_mul_f32 v[28:29], v[28:29], s[12:13] op_sel_hi:[1,0]
	v_pk_mul_f32 v[24:25], v[24:25], s[12:13] op_sel_hi:[1,0]
	v_pk_mul_f32 v[32:33], v[28:29], v[40:41]
	v_pk_mul_f32 v[30:31], v[24:25], v[30:31]
	v_mul_f32_e32 v9, 0x3fb8aa3b, v9
	s_nop 0
	s_nop 0
	v_exp_f32_e32 v47, v9
	v_cvt_pk_bf16_f32 v31, v33, v31
	s_nop 0
	v_cvt_pk_bf16_f32 v30, v32, v30
	s_nop 0
	s_nop 0
	v_ashrrev_i32_e32 v21, 31, v20
	v_pk_mul_f32 v[28:29], v[28:29], v[42:43]
	v_lshlrev_b64 v[32:33], 8, v[20:21]
	v_pk_mul_f32 v[24:25], v[24:25], v[44:45]
	s_nop 0
	v_lshl_add_u64 v[32:33], v[34:35], 0, v[32:33]
	s_nop 0
	v_cvt_pk_bf16_f32 v24, v28, v24
	global_store_dwordx2 v[32:33], v[30:31], off
	s_nop 0
	s_nop 0
	v_lshlrev_b32_e32 v31, 16, v23
	v_lshlrev_b32_e32 v30, 16, v22
	v_cvt_pk_bf16_f32 v25, v29, v25
	s_nop 0
	s_nop 0
	v_and_b32_e32 v23, 0xffff0000, v23
	v_and_b32_e32 v22, 0xffff0000, v22
	v_pk_mul_f32 v[26:27], v[26:27], v[30:31]
	s_nop 0
	s_nop 0
	s_nop 0
	v_pk_mul_f32 v[22:23], v[46:47], v[22:23]
	v_and_b32_sdwa v15, v26, v38 dst_sel:DWORD dst_unused:UNUSED_PAD src0_sel:WORD_1 src1_sel:DWORD
	s_nop 0
	v_mad_u64_u32 v[28:29], s[0:1], v20, s46, v[2:3]
	v_add3_u32 v15, v26, v15, s45
	v_and_b32_sdwa v21, v23, v38 dst_sel:DWORD dst_unused:UNUSED_PAD src0_sel:WORD_1 src1_sel:DWORD
	v_and_b32_sdwa v26, v22, v38 dst_sel:DWORD dst_unused:UNUSED_PAD src0_sel:WORD_1 src1_sel:DWORD
	v_and_b32_sdwa v9, v27, v38 dst_sel:DWORD dst_unused:UNUSED_PAD src0_sel:WORD_1 src1_sel:DWORD
	v_add3_u32 v29, v23, v21, s45
	v_add3_u32 v26, v22, v26, s45
	v_add3_u32 v9, v27, v9, s45
	v_and_b32_e32 v21, 0xffff0000, v29
	v_and_b32_e32 v22, 0xffff0000, v26
	v_or_b32_sdwa v23, v21, v9 dst_sel:DWORD dst_unused:UNUSED_PAD src0_sel:DWORD src1_sel:WORD_1
	v_or_b32_sdwa v22, v22, v15 dst_sel:DWORD dst_unused:UNUSED_PAD src0_sel:DWORD src1_sel:WORD_1
	v_lshlrev_b32_e32 v20, 1, v20
	ds_write2st64_b64 v28, v[24:25], v[22:23] offset1:66
	v_add3_u32 v28, s27, v20, v48
	ds_write_b16_d16_hi v28, v15
	v_lshl_add_u32 v15, v14, 9, v37
	ds_read_b128 v[20:23], v15
	ds_write_b16_d16_hi v28, v26 offset:144
	ds_read_b128 v[24:27], v54
	ds_write_b16_d16_hi v28, v9 offset:288
	ds_write_b16_d16_hi v28, v29 offset:432
	v_bfe_u32 v7, v6, 4, 2
	s_waitcnt lgkmcnt(4)
	v_mul_f32_e32 v9, 0x3fb8aa3b, v20
	v_exp_f32_e32 v28, v9
	s_waitcnt lgkmcnt(2)
	v_sub_f32_e32 v9, v20, v24
	v_mul_f32_e32 v9, 0x3fb8aa3b, v9
	v_exp_f32_e32 v30, v9
	v_sub_f32_e32 v9, v24, v20
	v_mul_f32_e32 v9, 0x3fb8aa3b, v9
	v_exp_f32_e32 v20, v9
	v_mul_f32_e32 v9, 0x3fb8aa3b, v21
	v_exp_f32_e32 v24, v9
	v_sub_f32_e32 v9, v21, v25
	v_mul_f32_e32 v9, 0x3fb8aa3b, v9
	v_exp_f32_e32 v32, v9
	v_sub_f32_e32 v9, v25, v21
	v_mul_f32_e32 v9, 0x3fb8aa3b, v9
	v_exp_f32_e32 v40, v9
	v_mul_f32_e32 v9, 0x3fb8aa3b, v22
	v_exp_f32_e32 v29, v9
	v_sub_f32_e32 v9, v22, v26
	v_mul_f32_e32 v9, 0x3fb8aa3b, v9
	v_exp_f32_e32 v31, v9
	v_sub_f32_e32 v9, v26, v22
	v_mul_f32_e32 v9, 0x3fb8aa3b, v9
	v_exp_f32_e32 v21, v9
	v_mul_f32_e32 v9, 0x3fb8aa3b, v23
	v_exp_f32_e32 v25, v9
	v_sub_f32_e32 v9, v23, v27
	v_mul_f32_e32 v9, 0x3fb8aa3b, v9
	v_exp_f32_e32 v33, v9
	v_sub_f32_e32 v9, v27, v23
	v_lshlrev_b32_e32 v23, 16, v19
	v_lshlrev_b32_e32 v22, 16, v18
	v_and_b32_e32 v19, 0xffff0000, v19
	v_and_b32_e32 v18, 0xffff0000, v18
	v_pk_mul_f32 v[22:23], v[22:23], s[12:13] op_sel_hi:[1,0]
	v_mul_f32_e32 v9, 0x3fb8aa3b, v9
	v_pk_mul_f32 v[18:19], v[18:19], s[12:13] op_sel_hi:[1,0]
	v_pk_mul_f32 v[26:27], v[22:23], v[28:29]
	v_exp_f32_e32 v41, v9
	v_pk_mul_f32 v[24:25], v[18:19], v[24:25]
	v_and_b32_sdwa v9, v27, v38 dst_sel:DWORD dst_unused:UNUSED_PAD src0_sel:WORD_1 src1_sel:DWORD
	s_nop 0
	v_add3_u32 v9, v27, v9, s45
	v_cvt_pk_bf16_f32 v24, v26, v24
	s_nop 0
	v_and_b32_sdwa v26, v25, v38 dst_sel:DWORD dst_unused:UNUSED_PAD src0_sel:WORD_1 src1_sel:DWORD
	s_nop 0
	v_add3_u32 v25, v25, v26, s45
	v_and_b32_e32 v25, 0xffff0000, v25
	v_ashrrev_i32_e32 v15, 31, v14
	v_pk_mul_f32 v[22:23], v[22:23], v[30:31]
	v_or_b32_sdwa v25, v25, v9 dst_sel:DWORD dst_unused:UNUSED_PAD src0_sel:DWORD src1_sel:WORD_1
	v_lshlrev_b64 v[26:27], 8, v[14:15]
	v_pk_mul_f32 v[18:19], v[18:19], v[32:33]
	s_nop 0
	v_and_b32_sdwa v15, v22, v38 dst_sel:DWORD dst_unused:UNUSED_PAD src0_sel:WORD_1 src1_sel:DWORD
	v_lshl_add_u64 v[26:27], v[34:35], 0, v[26:27]
	v_add3_u32 v15, v22, v15, s45
	s_nop 0
	v_cvt_pk_bf16_f32 v19, v23, v19
	v_and_b32_sdwa v23, v18, v38 dst_sel:DWORD dst_unused:UNUSED_PAD src0_sel:WORD_1 src1_sel:DWORD
	global_store_dwordx2 v[26:27], v[24:25], off
	s_nop 0
	v_add3_u32 v18, v18, v23, s45
	v_lshlrev_b32_e32 v25, 16, v17
	v_lshlrev_b32_e32 v24, 16, v16
	v_and_b32_e32 v18, 0xffff0000, v18
	v_and_b32_e32 v17, 0xffff0000, v17
	v_and_b32_e32 v16, 0xffff0000, v16
	v_pk_mul_f32 v[20:21], v[20:21], v[24:25]
	s_nop 0
	v_or_b32_sdwa v18, v18, v15 dst_sel:DWORD dst_unused:UNUSED_PAD src0_sel:DWORD src1_sel:WORD_1
	v_pk_mul_f32 v[16:17], v[40:41], v[16:17]
	v_and_b32_sdwa v9, v21, v38 dst_sel:DWORD dst_unused:UNUSED_PAD src0_sel:WORD_1 src1_sel:DWORD
	v_and_b32_sdwa v15, v20, v38 dst_sel:DWORD dst_unused:UNUSED_PAD src0_sel:WORD_1 src1_sel:DWORD
	v_mad_u64_u32 v[22:23], s[0:1], v14, s46, v[2:3]
	v_add3_u32 v15, v20, v15, s45
	v_add3_u32 v9, v21, v9, s45
	v_and_b32_sdwa v20, v17, v38 dst_sel:DWORD dst_unused:UNUSED_PAD src0_sel:WORD_1 src1_sel:DWORD
	v_and_b32_sdwa v21, v16, v38 dst_sel:DWORD dst_unused:UNUSED_PAD src0_sel:WORD_1 src1_sel:DWORD
	v_add3_u32 v23, v17, v20, s45
	v_add3_u32 v20, v16, v21, s45
	v_and_b32_e32 v16, 0xffff0000, v23
	v_and_b32_e32 v21, 0xffff0000, v20
	v_or_b32_sdwa v17, v16, v9 dst_sel:DWORD dst_unused:UNUSED_PAD src0_sel:DWORD src1_sel:WORD_1
	v_or_b32_sdwa v16, v21, v15 dst_sel:DWORD dst_unused:UNUSED_PAD src0_sel:DWORD src1_sel:WORD_1
	v_lshlrev_b32_e32 v14, 1, v14
	ds_write2st64_b64 v22, v[18:19], v[16:17] offset1:66
	v_add3_u32 v22, s27, v14, v48
	v_lshl_add_u32 v14, v8, 9, v37
	ds_write_b16_d16_hi v22, v15
	ds_read_b128 v[14:17], v14
	ds_write_b16_d16_hi v22, v20 offset:144
	ds_read_b128 v[18:21], v54
	ds_write_b16_d16_hi v22, v9 offset:288
	ds_write_b16_d16_hi v22, v23 offset:432
	s_waitcnt lgkmcnt(4)
	v_mul_f32_e32 v9, 0x3fb8aa3b, v14
	v_exp_f32_e32 v22, v9
	s_waitcnt lgkmcnt(2)
	v_sub_f32_e32 v9, v14, v18
	v_mul_f32_e32 v9, 0x3fb8aa3b, v9
	v_exp_f32_e32 v24, v9
	v_sub_f32_e32 v9, v18, v14
	v_mul_f32_e32 v9, 0x3fb8aa3b, v9
	v_exp_f32_e32 v14, v9
	v_mul_f32_e32 v9, 0x3fb8aa3b, v15
	v_exp_f32_e32 v18, v9
	v_sub_f32_e32 v9, v15, v19
	v_mul_f32_e32 v9, 0x3fb8aa3b, v9
	v_exp_f32_e32 v26, v9
	v_sub_f32_e32 v9, v19, v15
	v_mul_f32_e32 v9, 0x3fb8aa3b, v9
	v_exp_f32_e32 v28, v9
	v_mul_f32_e32 v9, 0x3fb8aa3b, v16
	v_exp_f32_e32 v23, v9
	v_sub_f32_e32 v9, v16, v20
	v_mul_f32_e32 v9, 0x3fb8aa3b, v9
	v_exp_f32_e32 v25, v9
	v_sub_f32_e32 v9, v20, v16
	v_mul_f32_e32 v9, 0x3fb8aa3b, v9
	v_exp_f32_e32 v15, v9
	v_mul_f32_e32 v9, 0x3fb8aa3b, v17
	v_exp_f32_e32 v19, v9
	v_sub_f32_e32 v9, v17, v21
	v_mul_f32_e32 v9, 0x3fb8aa3b, v9
	v_exp_f32_e32 v27, v9
	v_sub_f32_e32 v9, v21, v17
	v_lshlrev_b32_e32 v17, 16, v13
	v_lshlrev_b32_e32 v16, 16, v12
	v_and_b32_e32 v13, 0xffff0000, v13
	v_and_b32_e32 v12, 0xffff0000, v12
	v_pk_mul_f32 v[16:17], v[16:17], s[12:13] op_sel_hi:[1,0]
	v_mul_f32_e32 v9, 0x3fb8aa3b, v9
	v_pk_mul_f32 v[12:13], v[12:13], s[12:13] op_sel_hi:[1,0]
	v_pk_mul_f32 v[20:21], v[16:17], v[22:23]
	v_exp_f32_e32 v29, v9
	v_pk_mul_f32 v[18:19], v[12:13], v[18:19]
	s_nop 0
	v_and_b32_sdwa v22, v20, v38 dst_sel:DWORD dst_unused:UNUSED_PAD src0_sel:WORD_1 src1_sel:DWORD
	s_nop 0
	v_cvt_pk_bf16_f32 v19, v21, v19
	v_add3_u32 v20, v20, v22, s45
	v_and_b32_sdwa v22, v18, v38 dst_sel:DWORD dst_unused:UNUSED_PAD src0_sel:WORD_1 src1_sel:DWORD
	s_nop 0
	v_add3_u32 v18, v18, v22, s45
	v_and_b32_e32 v18, 0xffff0000, v18
	s_nop 0
	v_ashrrev_i32_e32 v9, 31, v8
	v_or_b32_sdwa v18, v18, v20 dst_sel:DWORD dst_unused:UNUSED_PAD src0_sel:DWORD src1_sel:WORD_1
	v_lshlrev_b64 v[20:21], 8, v[8:9]
	v_lshl_add_u64 v[20:21], v[34:35], 0, v[20:21]
	v_pk_mul_f32 v[16:17], v[16:17], v[24:25]
	global_store_dwordx2 v[20:21], v[18:19], off
	v_pk_mul_f32 v[12:13], v[12:13], v[26:27]
	s_nop 0
	v_and_b32_sdwa v18, v16, v38 dst_sel:DWORD dst_unused:UNUSED_PAD src0_sel:WORD_1 src1_sel:DWORD
	v_add3_u32 v16, v16, v18, s45
	s_nop 0
	v_cvt_pk_bf16_f32 v13, v17, v13
	v_and_b32_sdwa v18, v12, v38 dst_sel:DWORD dst_unused:UNUSED_PAD src0_sel:WORD_1 src1_sel:DWORD
	s_nop 0
	v_add3_u32 v12, v12, v18, s45
	v_lshlrev_b32_e32 v19, 16, v11
	v_lshlrev_b32_e32 v18, 16, v10
	v_and_b32_e32 v12, 0xffff0000, v12
	v_and_b32_e32 v11, 0xffff0000, v11
	v_and_b32_e32 v10, 0xffff0000, v10
	v_pk_mul_f32 v[14:15], v[14:15], v[18:19]
	s_nop 0
	v_or_b32_sdwa v12, v12, v16 dst_sel:DWORD dst_unused:UNUSED_PAD src0_sel:DWORD src1_sel:WORD_1
	v_mad_u64_u32 v[16:17], s[0:1], v8, s46, v[2:3]
	v_pk_mul_f32 v[10:11], v[28:29], v[10:11]
	v_and_b32_sdwa v2, v15, v38 dst_sel:DWORD dst_unused:UNUSED_PAD src0_sel:WORD_1 src1_sel:DWORD
	v_and_b32_sdwa v9, v14, v38 dst_sel:DWORD dst_unused:UNUSED_PAD src0_sel:WORD_1 src1_sel:DWORD
	v_add3_u32 v9, v14, v9, s45
	v_add3_u32 v2, v15, v2, s45
	v_and_b32_sdwa v14, v11, v38 dst_sel:DWORD dst_unused:UNUSED_PAD src0_sel:WORD_1 src1_sel:DWORD
	v_and_b32_sdwa v15, v10, v38 dst_sel:DWORD dst_unused:UNUSED_PAD src0_sel:WORD_1 src1_sel:DWORD
	v_add3_u32 v14, v11, v14, s45
	v_add3_u32 v15, v10, v15, s45
	v_and_b32_e32 v10, 0xffff0000, v14
	v_and_b32_e32 v17, 0xffff0000, v15
	v_lshlrev_b32_e32 v8, 1, v8
	v_or_b32_sdwa v11, v10, v2 dst_sel:DWORD dst_unused:UNUSED_PAD src0_sel:DWORD src1_sel:WORD_1
	v_or_b32_sdwa v10, v17, v9 dst_sel:DWORD dst_unused:UNUSED_PAD src0_sel:DWORD src1_sel:WORD_1
	v_add3_u32 v8, s27, v8, v48
	ds_write2st64_b64 v16, v[12:13], v[10:11] offset1:66
	ds_write_b16_d16_hi v8, v9
	ds_write_b16_d16_hi v8, v15 offset:144
	ds_write_b16_d16_hi v8, v2 offset:288
	ds_write_b16_d16_hi v8, v14 offset:432
	v_lshlrev_b32_e32 v2, 3, v36
	v_and_or_b32 v8, v2, s48, v39
	v_lshl_add_u32 v2, v7, 4, 0
	v_mad_u64_u32 v[28:29], s[0:1], v8, s46, v[2:3]
	s_waitcnt lgkmcnt(0)
	s_barrier
	ds_read_b128 v[8:11], v28
	v_lshlrev_b32_e32 v12, 5, v36
	v_and_or_b32 v36, v12, 32, v39
	v_mad_u32_u24 v2, v36, s46, v2
	ds_read_b128 v[12:15], v28 offset:64
	ds_read_b128 v[16:19], v2 offset:33792
	ds_read_b128 v[20:23], v2 offset:33856
	ds_read_b128 v[24:27], v28 offset:128
	s_waitcnt lgkmcnt(2)
	v_mfma_f32_16x16x32_bf16 v[16:19], v[8:11], v[16:19], 0
	s_waitcnt lgkmcnt(1)
	v_mfma_f32_16x16x32_bf16 v[16:19], v[12:15], v[20:23], v[16:19]
	ds_read_b128 v[20:23], v28 offset:192
	ds_read_b128 v[28:31], v2 offset:33920
	ds_read_b128 v[32:35], v2 offset:33984
	s_waitcnt lgkmcnt(1)
	v_mfma_f32_16x16x32_bf16 v[16:19], v[24:27], v[28:31], v[16:19]
	s_waitcnt lgkmcnt(0)
	v_mfma_f32_16x16x32_bf16 v[16:19], v[20:23], v[32:35], v[16:19]
	ds_read_b128 v[28:31], v2 offset:42240
	ds_read_b128 v[32:35], v2 offset:42304
	s_waitcnt lgkmcnt(1)
	v_mfma_f32_16x16x32_bf16 v[8:11], v[8:11], v[28:31], 0
	s_waitcnt lgkmcnt(0)
	v_mfma_f32_16x16x32_bf16 v[8:11], v[12:15], v[32:35], v[8:11]
	ds_read_b128 v[12:15], v2 offset:42368
	ds_read_b128 v[28:31], v2 offset:42432
	v_ashrrev_i32_e32 v2, 3, v6
	v_and_b32_e32 v2, -16, v2
	v_lshl_or_b32 v2, v7, 2, v2
	v_cmp_le_i32_e64 s[0:1], v36, v2
	s_waitcnt lgkmcnt(1)
	v_mfma_f32_16x16x32_bf16 v[8:11], v[24:27], v[12:15], v[8:11]
	v_lshl_add_u32 v6, v36, 1, s49
	v_cndmask_b32_e64 v7, 0, 1, s[0:1]
	v_cmp_ge_i32_e64 s[0:1], v36, v2
	s_waitcnt lgkmcnt(0)
	v_mfma_f32_16x16x32_bf16 v[8:11], v[20:23], v[28:31], v[8:11]
	v_cndmask_b32_e64 v12, 0, 1, s[0:1]
	v_cndmask_b32_e32 v7, v12, v7, vcc
	v_and_b32_e32 v7, 1, v7
	v_cmp_eq_u32_e64 s[0:1], 1, v7
	s_nop 1
	v_cndmask_b32_e64 v7, 0, v16, s[0:1]
	v_bfe_u32 v12, v7, 16, 1
	v_add3_u32 v7, v7, v12, s45
	v_mul_lo_u32 v12, v2, s47
	v_add_u32_e32 v13, v6, v12
	ds_write_b16_d16_hi v13, v7
	v_or_b32_e32 v7, 1, v2
	v_cmp_gt_i32_e64 s[0:1], v36, v2
	s_nop 1
	v_cndmask_b32_e64 v13, 0, 1, s[0:1]
	v_cmp_le_i32_e64 s[0:1], v36, v7
	s_nop 1
	v_cndmask_b32_e64 v14, 0, 1, s[0:1]
	v_cndmask_b32_e32 v13, v13, v14, vcc
	v_and_b32_e32 v13, 1, v13
	v_cmp_eq_u32_e64 s[0:1], 1, v13
	s_nop 1
	v_cndmask_b32_e64 v13, 0, v17, s[0:1]
	v_bfe_u32 v14, v13, 16, 1
	v_add3_u32 v13, v13, v14, s45
	v_add_u32_e32 v14, 0x90, v12
	v_add_u32_e32 v15, v6, v14
	ds_write_b16_d16_hi v15, v13
	v_or_b32_e32 v13, 2, v2
	v_cmp_le_i32_e64 s[0:1], v36, v13
	s_nop 1
	v_cndmask_b32_e64 v15, 0, 1, s[0:1]
	v_cmp_ge_i32_e64 s[0:1], v36, v13
	s_nop 1
	v_cndmask_b32_e64 v16, 0, 1, s[0:1]
	v_cndmask_b32_e32 v15, v16, v15, vcc
	v_and_b32_e32 v15, 1, v15
	v_cmp_eq_u32_e64 s[0:1], 1, v15
	s_nop 1
	v_cndmask_b32_e64 v15, 0, v18, s[0:1]
	v_bfe_u32 v16, v15, 16, 1
	v_add3_u32 v15, v15, v16, s45
	v_add_u32_e32 v16, 0x120, v12
	v_add_u32_e32 v17, v6, v16
	ds_write_b16_d16_hi v17, v15
	v_or_b32_e32 v15, 3, v2
	v_cmp_le_i32_e64 s[0:1], v36, v15
	s_nop 1
	v_cndmask_b32_e64 v17, 0, 1, s[0:1]
	v_cmp_ge_i32_e64 s[0:1], v36, v15
	s_nop 1
	v_cndmask_b32_e64 v18, 0, 1, s[0:1]
	v_cndmask_b32_e32 v17, v18, v17, vcc
	v_and_b32_e32 v17, 1, v17
	v_cmp_eq_u32_e64 s[0:1], 1, v17
	s_nop 1
	v_cndmask_b32_e64 v17, 0, v19, s[0:1]
	v_bfe_u32 v18, v17, 16, 1
	v_add3_u32 v17, v17, v18, s45
	v_add_u32_e32 v18, 0x1b0, v12
	v_add_u32_e32 v6, v6, v18
	ds_write_b16_d16_hi v6, v17
	v_or_b32_e32 v6, 16, v36
	v_cmp_le_i32_e64 s[0:1], v6, v2
	s_nop 1
	v_cndmask_b32_e64 v17, 0, 1, s[0:1]
	v_cmp_ge_i32_e64 s[0:1], v6, v2
	s_nop 1
	v_cndmask_b32_e64 v19, 0, 1, s[0:1]
	v_cndmask_b32_e32 v17, v19, v17, vcc
	v_and_b32_e32 v17, 1, v17
	v_cmp_eq_u32_e64 s[0:1], 1, v17
	s_nop 1
	v_cndmask_b32_e64 v8, 0, v8, s[0:1]
	v_cmp_le_i32_e64 s[0:1], v6, v7
	v_bfe_u32 v17, v8, 16, 1
	v_add3_u32 v8, v8, v17, s45
	v_cndmask_b32_e64 v7, 0, 1, s[0:1]
	v_cmp_gt_i32_e64 s[0:1], v6, v2
	v_lshlrev_b32_e32 v17, 1, v6
	v_add3_u32 v12, s49, v12, v17
	v_cndmask_b32_e64 v2, 0, 1, s[0:1]
	v_cndmask_b32_e32 v2, v2, v7, vcc
	v_and_b32_e32 v2, 1, v2
	v_cmp_eq_u32_e64 s[0:1], 1, v2
	ds_write_b16_d16_hi v12, v8
	s_nop 0
	v_cndmask_b32_e64 v2, 0, v9, s[0:1]
	v_bfe_u32 v7, v2, 16, 1
	v_add3_u32 v2, v2, v7, s45
	v_add3_u32 v7, s49, v14, v17
	v_cmp_le_i32_e64 s[0:1], v6, v13
	ds_write_b16_d16_hi v7, v2
	s_nop 0
	v_cndmask_b32_e64 v2, 0, 1, s[0:1]
	v_cmp_ge_i32_e64 s[0:1], v6, v13
	s_nop 1
	v_cndmask_b32_e64 v7, 0, 1, s[0:1]
	v_cndmask_b32_e32 v2, v7, v2, vcc
	v_and_b32_e32 v2, 1, v2
	v_cmp_eq_u32_e64 s[0:1], 1, v2
	s_nop 1
	v_cndmask_b32_e64 v2, 0, v10, s[0:1]
	v_bfe_u32 v7, v2, 16, 1
	v_add3_u32 v2, v2, v7, s45
	v_add3_u32 v7, s49, v16, v17
	v_cmp_le_i32_e64 s[0:1], v6, v15
	ds_write_b16_d16_hi v7, v2
	s_nop 0
	v_cndmask_b32_e64 v2, 0, 1, s[0:1]
	v_cmp_ge_i32_e64 s[0:1], v6, v15
	s_nop 1
	v_cndmask_b32_e64 v6, 0, 1, s[0:1]
	v_cndmask_b32_e32 v2, v6, v2, vcc
	v_and_b32_e32 v2, 1, v2
	v_cmp_eq_u32_e64 s[0:1], 1, v2
	s_nop 1
	v_cndmask_b32_e64 v2, 0, v11, s[0:1]
	v_bfe_u32 v6, v2, 16, 1
	v_add3_u32 v2, v2, v6, s45
	v_add3_u32 v6, s49, v18, v17
	ds_write_b16_d16_hi v6, v2
	v_mov_b32_e32 v6, v0
	s_waitcnt lgkmcnt(0)
	s_barrier
	s_nop 0
	v_cmp_gt_i32_e64 s[0:1], s23, v6
	s_and_saveexec_b64 s[18:19], s[0:1]
	s_cbranch_execz .LBB0_3676
	s_lshl_b64 s[0:1], s[14:15], 13
	s_add_u32 s14, s64, s0
	s_addc_u32 s15, s61, s1
	v_lshlrev_b32_e32 v7, 3, v6
	s_mov_b64 s[20:21], 0

.LBB0_3744:
	v_add_u32_e32 v27, 0x400, v26
	v_lshlrev_b32_e32 v38, 16, v10
	ds_read2_b32 v[30:31], v26 offset1:65
	ds_read2_b32 v[32:33], v26 offset0:130 offset1:195
	ds_read2_b32 v[34:35], v27 offset0:4 offset1:69
	ds_read2_b32 v[36:37], v27 offset0:134 offset1:199
	v_mul_f32_e32 v27, 0xbfb8aa3b, v38
	v_exp_f32_e32 v27, v27
	v_lshlrev_b32_e32 v39, 16, v11
	v_mul_f32_e32 v40, 0xbfb8aa3b, v39
	v_exp_f32_e32 v41, v40
	v_and_b32_e32 v10, 0xffff0000, v10
	v_add_f32_e32 v27, 1.0, v27
	v_and_b32_e32 v11, 0xffff0000, v11
	v_rcp_f32_e32 v40, v27
	v_mul_f32_e32 v27, 0xbfb8aa3b, v10
	v_exp_f32_e32 v27, v27
	v_add_f32_e32 v41, 1.0, v41
	v_mul_f32_e32 v42, 0xbfb8aa3b, v11
	v_rcp_f32_e32 v41, v41
	v_exp_f32_e32 v43, v42
	v_add_f32_e32 v27, 1.0, v27
	v_rcp_f32_e32 v42, v27
	v_pk_mul_f32 v[38:39], v[40:41], v[38:39]
	v_add_f32_e32 v27, 1.0, v43
	s_waitcnt lgkmcnt(3)
	v_mov_b32_e32 v40, v30
	v_lshlrev_b32_e32 v30, 16, v12
	v_rcp_f32_e32 v43, v27
	v_mul_f32_e32 v27, 0xbfb8aa3b, v30
	v_exp_f32_e32 v27, v27
	s_waitcnt lgkmcnt(2)
	v_mov_b32_e32 v41, v32
	v_pk_mul_f32 v[10:11], v[42:43], v[10:11]
	v_mov_b32_e32 v32, v31
	v_lshlrev_b32_e32 v31, 16, v13
	v_pk_mul_f32 v[10:11], v[10:11], v[32:33]
	v_and_b32_e32 v12, 0xffff0000, v12
	v_add_f32_e32 v27, 1.0, v27
	v_mul_f32_e32 v32, 0xbfb8aa3b, v31
	v_and_b32_e32 v13, 0xffff0000, v13
	v_exp_f32_e32 v33, v32
	v_rcp_f32_e32 v32, v27
	v_mul_f32_e32 v27, 0xbfb8aa3b, v12
	v_pk_mul_f32 v[38:39], v[38:39], v[40:41]
	v_exp_f32_e32 v27, v27
	v_mul_f32_e32 v40, 0xbfb8aa3b, v13
	v_exp_f32_e32 v41, v40
	v_add_f32_e32 v33, 1.0, v33
	v_add_f32_e32 v27, 1.0, v27
	v_rcp_f32_e32 v40, v27
	v_add_f32_e32 v27, 1.0, v41
	v_rcp_f32_e32 v33, v33
	v_rcp_f32_e32 v41, v27
	s_and_b32 s6, s39, 0xffffffc0
	v_add_u32_e32 v28, s6, v23
	v_pk_mul_f32 v[30:31], v[32:33], v[30:31]
	s_waitcnt lgkmcnt(0)
	v_mov_b32_e32 v33, v36
	v_pk_mul_f32 v[12:13], v[40:41], v[12:13]
	v_mov_b32_e32 v36, v35
	v_mov_b32_e32 v32, v34
	v_pk_mul_f32 v[12:13], v[12:13], v[36:37]
	v_ashrrev_i32_e32 v29, 31, v28
	v_pk_mul_f32 v[30:31], v[30:31], v[32:33]
	v_bfe_u32 v27, v13, 16, 1
	v_bfe_u32 v32, v12, 16, 1
	v_cvt_pk_bf16_f32 v11, v39, v11
	v_cvt_pk_bf16_f32 v10, v38, v10
	s_and_b32 s22, s38, 0x3c0
	v_add3_u32 v12, v12, v32, s36
	v_add3_u32 v13, v13, v27, s36
	v_bfe_u32 v33, v30, 16, 1
	v_bfe_u32 v34, v31, 16, 1
	v_lshlrev_b64 v[28:29], 13, v[28:29]
	v_add3_u32 v31, v31, v34, s36
	v_add3_u32 v30, v30, v33, s36
	v_lshl_add_u64 v[28:29], s[12:13], 0, v[28:29]
	s_lshl_b32 s6, s22, 1
	v_lshrrev_b32_e32 v30, 16, v30
	v_lshrrev_b32_e32 v31, 16, v31
	v_lshl_add_u64 v[28:29], v[28:29], 0, s[6:7]
	v_and_or_b32 v13, v13, s35, v31
	v_and_or_b32 v12, v12, s35, v30
	v_lshl_add_u64 v[28:29], v[28:29], 0, v[18:19]
	global_store_dwordx4 v[28:29], v[10:13], off offset:2048
	s_waitcnt lgkmcnt(0)
	s_barrier
	s_andn2_b64 vcc, exec, s[20:21]
	s_mov_b32 s38, s37
	s_waitcnt vmcnt(1)
	v_mov_b64_e32 v[10:11], v[14:15]
	s_mov_b32 s39, s29
	v_mov_b64_e32 v[12:13], v[16:17]
	s_cbranch_vccz .LBB0_3749

.LBB0_3752:
	v_ashrrev_i32_e32 v37, 8, v18
	v_and_b32_e32 v34, 0xff, v18
	v_lshlrev_b32_e32 v19, 13, v37
	v_lshlrev_b32_e32 v20, 1, v34
	v_add3_u32 v38, s25, v19, v20
	v_add3_u32 v19, s53, v19, v20
	ds_read_u16 v20, v38
	ds_read_u16 v22, v38 offset:512
	ds_read_u16 v24, v38 offset:1024
	ds_read_u16 v26, v38 offset:1536
	ds_read_u16 v28, v38 offset:2048
	ds_read_u16 v39, v38 offset:2560
	ds_read_u16 v42, v38 offset:3072
	ds_read_u16 v44, v38 offset:3584
	ds_read_u16 v21, v19
	ds_read_u16 v23, v19 offset:512
	ds_read_u16 v25, v19 offset:1024
	ds_read_u16 v27, v19 offset:1536
	ds_read_u16 v29, v19 offset:2048
	ds_read_u16 v41, v19 offset:2560
	ds_read_u16 v43, v19 offset:3072
	ds_read_u16 v45, v19 offset:3584
	s_waitcnt lgkmcnt(7)
	v_lshlrev_b32_e32 v21, 16, v21
	v_lshlrev_b32_e32 v40, 16, v39
	s_waitcnt lgkmcnt(2)
	v_lshlrev_b32_e32 v39, 16, v41
	v_xor_b32_e32 v41, 0x80000000, v39
	s_waitcnt lgkmcnt(1)
	v_lshlrev_b32_e32 v39, 16, v43
	v_xor_b32_e32 v43, 0x80000000, v39
	s_waitcnt lgkmcnt(0)
	v_lshlrev_b32_e32 v39, 16, v45
	v_xor_b32_e32 v45, 0x80000000, v39
	ds_read_u16 v39, v38 offset:4096
	ds_read_u16 v48, v38 offset:4608
	ds_read_u16 v50, v38 offset:5120
	ds_read_u16 v52, v38 offset:5632
	ds_read_u16 v54, v38 offset:6144
	ds_read_u16 v56, v38 offset:6656
	ds_read_u16 v58, v38 offset:7168
	ds_read_u16 v38, v38 offset:7680
	s_waitcnt lgkmcnt(7)
	v_lshlrev_b32_e32 v46, 16, v39
	ds_read_u16 v39, v19 offset:4096
	ds_read_u16 v49, v19 offset:4608
	ds_read_u16 v51, v19 offset:5120
	ds_read_u16 v53, v19 offset:5632
	ds_read_u16 v55, v19 offset:6144
	ds_read_u16 v57, v19 offset:6656
	ds_read_u16 v59, v19 offset:7168
	ds_read_u16 v19, v19 offset:7680
	s_waitcnt lgkmcnt(7)
	v_lshlrev_b32_e32 v39, 16, v39
	v_xor_b32_e32 v47, 0x80000000, v39
	s_waitcnt lgkmcnt(6)
	v_lshlrev_b32_e32 v39, 16, v49
	v_xor_b32_e32 v49, 0x80000000, v39
	s_waitcnt lgkmcnt(5)
	v_lshlrev_b32_e32 v39, 16, v51
	v_xor_b32_e32 v51, 0x80000000, v39
	s_waitcnt lgkmcnt(4)
	v_lshlrev_b32_e32 v39, 16, v53
	v_lshlrev_b32_e32 v29, 16, v29
	v_xor_b32_e32 v53, 0x80000000, v39
	s_waitcnt lgkmcnt(3)
	v_lshlrev_b32_e32 v39, 16, v55
	v_lshlrev_b32_e32 v20, 16, v20
	v_xor_b32_e32 v21, 0x80000000, v21
	v_lshlrev_b32_e32 v23, 16, v23
	v_lshlrev_b32_e32 v28, 16, v28
	v_xor_b32_e32 v29, 0x80000000, v29
	v_lshlrev_b32_e32 v54, 16, v54
	v_xor_b32_e32 v55, 0x80000000, v39
	s_waitcnt lgkmcnt(2)
	v_lshlrev_b32_e32 v39, 16, v57
	s_waitcnt lgkmcnt(0)
	v_lshlrev_b32_e32 v19, 16, v19
	v_lshlrev_b32_e32 v22, 16, v22
	v_xor_b32_e32 v23, 0x80000000, v23
	v_lshlrev_b32_e32 v25, 16, v25
	v_lshlrev_b32_e32 v48, 16, v48
	v_lshlrev_b32_e32 v56, 16, v56
	v_xor_b32_e32 v57, 0x80000000, v39
	v_lshlrev_b32_e32 v39, 16, v59
	v_lshlrev_b32_e32 v60, 16, v38
	v_xor_b32_e32 v61, 0x80000000, v19
	v_bfe_u32 v38, v18, 4, 4
	v_pk_add_f32 v[18:19], v[20:21], v[46:47]
	v_pk_add_f32 v[20:21], v[20:21], v[46:47] neg_lo:[0,1] neg_hi:[0,1]
	v_pk_add_f32 v[46:47], v[28:29], v[54:55]
	v_pk_add_f32 v[28:29], v[28:29], v[54:55] neg_lo:[0,1] neg_hi:[0,1]
	v_lshlrev_b32_e32 v24, 16, v24
	v_xor_b32_e32 v25, 0x80000000, v25
	v_lshlrev_b32_e32 v27, 16, v27
	v_lshlrev_b32_e32 v42, 16, v42
	v_lshlrev_b32_e32 v50, 16, v50
	v_lshlrev_b32_e32 v58, 16, v58
	v_xor_b32_e32 v59, 0x80000000, v39
	v_pk_add_f32 v[54:55], v[18:19], v[46:47]
	v_pk_add_f32 v[46:47], v[18:19], v[46:47] neg_lo:[0,1] neg_hi:[0,1]
	v_pk_add_f32 v[62:63], v[20:21], v[28:29] op_sel:[0,1] op_sel_hi:[1,0] neg_hi:[0,1]
	v_pk_add_f32 v[64:65], v[20:21], v[28:29] op_sel:[0,1] op_sel_hi:[1,0] neg_lo:[0,1]
	v_pk_add_f32 v[18:19], v[22:23], v[48:49]
	v_pk_add_f32 v[20:21], v[22:23], v[48:49] neg_lo:[0,1] neg_hi:[0,1]
	v_pk_add_f32 v[22:23], v[40:41], v[56:57]
	v_pk_add_f32 v[28:29], v[40:41], v[56:57] neg_lo:[0,1] neg_hi:[0,1]
	v_lshlrev_b32_e32 v26, 16, v26
	v_xor_b32_e32 v27, 0x80000000, v27
	v_lshlrev_b32_e32 v44, 16, v44
	v_lshlrev_b32_e32 v52, 16, v52
	v_pk_add_f32 v[40:41], v[18:19], v[22:23]
	v_pk_add_f32 v[22:23], v[18:19], v[22:23] neg_lo:[0,1] neg_hi:[0,1]
	v_pk_add_f32 v[18:19], v[20:21], v[28:29] op_sel:[0,1] op_sel_hi:[1,0] neg_hi:[0,1]
	v_pk_add_f32 v[28:29], v[20:21], v[28:29] op_sel:[0,1] op_sel_hi:[1,0] neg_lo:[0,1]
	v_pk_add_f32 v[20:21], v[24:25], v[50:51]
	v_pk_add_f32 v[24:25], v[24:25], v[50:51] neg_lo:[0,1] neg_hi:[0,1]
	v_pk_add_f32 v[48:49], v[42:43], v[58:59]
	v_pk_add_f32 v[42:43], v[42:43], v[58:59] neg_lo:[0,1] neg_hi:[0,1]
	v_pk_add_f32 v[50:51], v[20:21], v[48:49]
	v_pk_add_f32 v[48:49], v[20:21], v[48:49] neg_lo:[0,1] neg_hi:[0,1]
	v_pk_add_f32 v[56:57], v[24:25], v[42:43] op_sel:[0,1] op_sel_hi:[1,0] neg_hi:[0,1]
	v_pk_add_f32 v[42:43], v[24:25], v[42:43] op_sel:[0,1] op_sel_hi:[1,0] neg_lo:[0,1]
	v_pk_add_f32 v[20:21], v[26:27], v[52:53]
	v_pk_add_f32 v[24:25], v[26:27], v[52:53] neg_lo:[0,1] neg_hi:[0,1]
	v_pk_add_f32 v[26:27], v[44:45], v[60:61]
	v_pk_add_f32 v[44:45], v[44:45], v[60:61] neg_lo:[0,1] neg_hi:[0,1]
	v_pk_add_f32 v[52:53], v[20:21], v[26:27]
	v_pk_add_f32 v[58:59], v[20:21], v[26:27] neg_lo:[0,1] neg_hi:[0,1]
	v_pk_add_f32 v[26:27], v[24:25], v[44:45] op_sel:[0,1] op_sel_hi:[1,0] neg_hi:[0,1]
	v_pk_add_f32 v[44:45], v[24:25], v[44:45] op_sel:[0,1] op_sel_hi:[1,0] neg_lo:[0,1]
	v_mov_b64_e32 v[24:25], s[26:27]
	v_pk_mul_f32 v[20:21], v[18:19], v[24:25] op_sel:[0,0] op_sel_hi:[0,1]
	v_mad_i32_i24 v35, v37, s3, 0
	v_pk_fma_f32 v[60:61], v[18:19], v[24:25], v[20:21] op_sel:[1,1,0] op_sel_hi:[1,0,1] neg_lo:[0,1,0]
	v_mov_b64_e32 v[20:21], s[34:35]
	v_pk_mul_f32 v[18:19], v[56:57], v[20:21] op_sel:[0,0] op_sel_hi:[0,1]
	v_lshlrev_b32_e32 v39, 3, v34
	v_pk_fma_f32 v[56:57], v[56:57], v[20:21], v[18:19] op_sel:[1,1,0] op_sel_hi:[1,0,1] neg_lo:[0,1,0]
	v_mov_b64_e32 v[18:19], s[36:37]
	v_pk_mul_f32 v[66:67], v[26:27], v[18:19] op_sel:[0,0] op_sel_hi:[0,1]
	v_lshlrev_b32_e32 v74, 3, v38
	v_pk_fma_f32 v[66:67], v[26:27], v[18:19], v[66:67] op_sel:[1,1,0] op_sel_hi:[1,0,1] neg_lo:[0,1,0]
	v_pk_mul_f32 v[26:27], v[22:23], v[20:21] op_sel:[0,0] op_sel_hi:[0,1]
	v_add3_u32 v74, v35, v39, v74
	v_pk_fma_f32 v[68:69], v[22:23], v[20:21], v[26:27] op_sel:[1,1,0] op_sel_hi:[1,0,1] neg_lo:[0,1,0]
	v_mov_b64_e32 v[26:27], s[22:23]
	v_pk_mul_f32 v[22:23], v[48:49], v[26:27] op_sel:[0,0] op_sel_hi:[0,1]
	v_lshl_add_u32 v78, v38, 11, v35
	v_pk_fma_f32 v[48:49], v[48:49], v[26:27], v[22:23] op_sel:[1,1,0] op_sel_hi:[1,0,1] neg_lo:[0,1,0]
	v_mov_b64_e32 v[22:23], s[38:39]
	v_pk_mul_f32 v[70:71], v[58:59], v[22:23] op_sel:[0,0] op_sel_hi:[0,1]
	v_add_u32_e32 v39, v78, v39
	v_pk_fma_f32 v[58:59], v[58:59], v[22:23], v[70:71] op_sel:[1,1,0] op_sel_hi:[1,0,1] neg_lo:[0,1,0]
	v_pk_mul_f32 v[70:71], v[28:29], v[18:19] op_sel:[0,0] op_sel_hi:[0,1]
	s_nop 0
	v_pk_fma_f32 v[70:71], v[28:29], v[18:19], v[70:71] op_sel:[1,1,0] op_sel_hi:[1,0,1] neg_lo:[0,1,0]
	v_pk_mul_f32 v[28:29], v[42:43], v[22:23] op_sel:[0,0] op_sel_hi:[0,1]
	s_nop 0
	v_pk_fma_f32 v[42:43], v[42:43], v[22:23], v[28:29] op_sel:[1,1,0] op_sel_hi:[1,0,1] neg_lo:[0,1,0]
	v_mov_b64_e32 v[28:29], s[40:41]
	v_pk_mul_f32 v[72:73], v[44:45], v[28:29] op_sel:[0,0] op_sel_hi:[0,1]
	s_nop 0
	v_pk_fma_f32 v[44:45], v[44:45], v[28:29], v[72:73] op_sel:[1,1,0] op_sel_hi:[1,0,1] neg_lo:[0,1,0]
	v_pk_add_f32 v[72:73], v[54:55], v[50:51]
	v_pk_add_f32 v[50:51], v[54:55], v[50:51] neg_lo:[0,1] neg_hi:[0,1]
	v_pk_add_f32 v[54:55], v[40:41], v[52:53]
	v_pk_add_f32 v[40:41], v[40:41], v[52:53] neg_lo:[0,1] neg_hi:[0,1]
	v_pk_add_f32 v[52:53], v[72:73], v[54:55]
	v_pk_add_f32 v[54:55], v[72:73], v[54:55] neg_lo:[0,1] neg_hi:[0,1]
	v_pk_add_f32 v[72:73], v[50:51], v[40:41] op_sel:[0,1] op_sel_hi:[1,0] neg_hi:[0,1]
	v_pk_add_f32 v[40:41], v[50:51], v[40:41] op_sel:[0,1] op_sel_hi:[1,0] neg_lo:[0,1]
	v_pk_add_f32 v[50:51], v[62:63], v[56:57]
	v_pk_add_f32 v[56:57], v[62:63], v[56:57] neg_lo:[0,1] neg_hi:[0,1]
	v_pk_add_f32 v[62:63], v[60:61], v[66:67]
	v_pk_add_f32 v[60:61], v[60:61], v[66:67] neg_lo:[0,1] neg_hi:[0,1]
	v_pk_add_f32 v[66:67], v[50:51], v[62:63]
	v_pk_add_f32 v[50:51], v[50:51], v[62:63] neg_lo:[0,1] neg_hi:[0,1]
	v_pk_add_f32 v[62:63], v[56:57], v[60:61] op_sel:[0,1] op_sel_hi:[1,0] neg_hi:[0,1]
	v_pk_add_f32 v[56:57], v[56:57], v[60:61] op_sel:[0,1] op_sel_hi:[1,0] neg_lo:[0,1]
	v_pk_add_f32 v[60:61], v[46:47], v[48:49]
	v_pk_add_f32 v[46:47], v[46:47], v[48:49] neg_lo:[0,1] neg_hi:[0,1]
	v_pk_add_f32 v[48:49], v[68:69], v[58:59]
	v_pk_add_f32 v[58:59], v[68:69], v[58:59] neg_lo:[0,1] neg_hi:[0,1]
	v_pk_add_f32 v[68:69], v[60:61], v[48:49]
	v_pk_add_f32 v[48:49], v[60:61], v[48:49] neg_lo:[0,1] neg_hi:[0,1]
	v_pk_add_f32 v[60:61], v[46:47], v[58:59] op_sel:[0,1] op_sel_hi:[1,0] neg_hi:[0,1]
	v_pk_add_f32 v[46:47], v[46:47], v[58:59] op_sel:[0,1] op_sel_hi:[1,0] neg_lo:[0,1]
	v_pk_add_f32 v[58:59], v[64:65], v[42:43]
	v_pk_add_f32 v[42:43], v[64:65], v[42:43] neg_lo:[0,1] neg_hi:[0,1]
	v_pk_add_f32 v[64:65], v[70:71], v[44:45]
	v_pk_add_f32 v[44:45], v[70:71], v[44:45] neg_lo:[0,1] neg_hi:[0,1]
	v_pk_add_f32 v[70:71], v[58:59], v[64:65]
	v_pk_add_f32 v[58:59], v[58:59], v[64:65] neg_lo:[0,1] neg_hi:[0,1]
	v_pk_add_f32 v[64:65], v[42:43], v[44:45] op_sel:[0,1] op_sel_hi:[1,0] neg_hi:[0,1]
	v_pk_add_f32 v[42:43], v[42:43], v[44:45] op_sel:[0,1] op_sel_hi:[1,0] neg_lo:[0,1]
	v_mov_b32_e32 v45, v31
	v_mov_b32_e32 v44, v1
	ds_write_b64 v74, v[52:53]
	v_pk_mul_f32 v[52:53], v[66:67], v[44:45] op_sel:[0,0] op_sel_hi:[0,1]
	s_nop 0
	v_pk_fma_f32 v[52:53], v[66:67], v[44:45], v[52:53] op_sel:[1,1,0] op_sel_hi:[1,0,1] neg_lo:[0,1,0]
	ds_write_b64 v74, v[52:53] offset:2176
	v_pk_mul_f32 v[52:53], v[44:45], v[44:45] op_sel:[0,0] op_sel_hi:[0,1]
	s_nop 0
	v_pk_fma_f32 v[52:53], v[44:45], v[44:45], v[52:53] op_sel:[1,1,0] op_sel_hi:[1,0,1] neg_lo:[0,1,0]
	s_nop 0
	v_pk_mul_f32 v[66:67], v[68:69], v[52:53] op_sel:[0,0] op_sel_hi:[0,1]
	s_nop 0
	v_pk_fma_f32 v[66:67], v[68:69], v[52:53], v[66:67] op_sel:[1,1,0] op_sel_hi:[1,0,1] neg_lo:[0,1,0]
	ds_write_b64 v74, v[66:67] offset:4352
	v_pk_mul_f32 v[66:67], v[52:53], v[44:45] op_sel:[0,0] op_sel_hi:[0,1]
	s_nop 0
	v_pk_fma_f32 v[52:53], v[52:53], v[44:45], v[66:67] op_sel:[1,1,0] op_sel_hi:[1,0,1] neg_lo:[0,1,0]
	s_nop 0
	v_pk_mul_f32 v[66:67], v[70:71], v[52:53] op_sel:[0,0] op_sel_hi:[0,1]
	s_nop 0
	v_pk_fma_f32 v[66:67], v[70:71], v[52:53], v[66:67] op_sel:[1,1,0] op_sel_hi:[1,0,1] neg_lo:[0,1,0]
	ds_write_b64 v74, v[66:67] offset:6528
	v_pk_mul_f32 v[66:67], v[52:53], v[44:45] op_sel:[0,0] op_sel_hi:[0,1]
	s_nop 0
	v_pk_fma_f32 v[52:53], v[52:53], v[44:45], v[66:67] op_sel:[1,1,0] op_sel_hi:[1,0,1] neg_lo:[0,1,0]
	s_nop 0
	v_pk_mul_f32 v[66:67], v[72:73], v[52:53] op_sel:[0,0] op_sel_hi:[0,1]
	s_nop 0
	v_pk_fma_f32 v[66:67], v[72:73], v[52:53], v[66:67] op_sel:[1,1,0] op_sel_hi:[1,0,1] neg_lo:[0,1,0]
	ds_write_b64 v74, v[66:67] offset:8704
	v_pk_mul_f32 v[66:67], v[52:53], v[44:45] op_sel:[0,0] op_sel_hi:[0,1]
	s_nop 0
	v_pk_fma_f32 v[52:53], v[52:53], v[44:45], v[66:67] op_sel:[1,1,0] op_sel_hi:[1,0,1] neg_lo:[0,1,0]
	s_nop 0
	v_pk_mul_f32 v[66:67], v[62:63], v[52:53] op_sel:[0,0] op_sel_hi:[0,1]
	s_nop 0
	v_pk_fma_f32 v[62:63], v[62:63], v[52:53], v[66:67] op_sel:[1,1,0] op_sel_hi:[1,0,1] neg_lo:[0,1,0]
	ds_write_b64 v74, v[62:63] offset:10880
	v_pk_mul_f32 v[62:63], v[52:53], v[44:45] op_sel:[0,0] op_sel_hi:[0,1]
	s_nop 0
	v_pk_fma_f32 v[52:53], v[52:53], v[44:45], v[62:63] op_sel:[1,1,0] op_sel_hi:[1,0,1] neg_lo:[0,1,0]
	s_nop 0
	v_pk_mul_f32 v[62:63], v[60:61], v[52:53] op_sel:[0,0] op_sel_hi:[0,1]
	s_nop 0
	v_pk_fma_f32 v[60:61], v[60:61], v[52:53], v[62:63] op_sel:[1,1,0] op_sel_hi:[1,0,1] neg_lo:[0,1,0]
	ds_write_b64 v74, v[60:61] offset:13056
	v_pk_mul_f32 v[60:61], v[52:53], v[44:45] op_sel:[0,0] op_sel_hi:[0,1]
	s_nop 0
	v_pk_fma_f32 v[52:53], v[52:53], v[44:45], v[60:61] op_sel:[1,1,0] op_sel_hi:[1,0,1] neg_lo:[0,1,0]
	s_nop 0
	v_pk_mul_f32 v[60:61], v[64:65], v[52:53] op_sel:[0,0] op_sel_hi:[0,1]
	s_nop 0
	v_pk_fma_f32 v[60:61], v[64:65], v[52:53], v[60:61] op_sel:[1,1,0] op_sel_hi:[1,0,1] neg_lo:[0,1,0]
	ds_write_b64 v74, v[60:61] offset:15232
	v_pk_mul_f32 v[60:61], v[52:53], v[44:45] op_sel:[0,0] op_sel_hi:[0,1]
	s_nop 0
	v_pk_fma_f32 v[52:53], v[52:53], v[44:45], v[60:61] op_sel:[1,1,0] op_sel_hi:[1,0,1] neg_lo:[0,1,0]
	s_nop 0
	v_pk_mul_f32 v[60:61], v[54:55], v[52:53] op_sel:[0,0] op_sel_hi:[0,1]
	s_nop 0
	v_pk_fma_f32 v[54:55], v[54:55], v[52:53], v[60:61] op_sel:[1,1,0] op_sel_hi:[1,0,1] neg_lo:[0,1,0]
	ds_write_b64 v74, v[54:55] offset:17408
	v_pk_mul_f32 v[54:55], v[52:53], v[44:45] op_sel:[0,0] op_sel_hi:[0,1]
	s_nop 0
	v_pk_fma_f32 v[52:53], v[52:53], v[44:45], v[54:55] op_sel:[1,1,0] op_sel_hi:[1,0,1] neg_lo:[0,1,0]
	s_nop 0
	v_pk_mul_f32 v[54:55], v[50:51], v[52:53] op_sel:[0,0] op_sel_hi:[0,1]
	s_nop 0
	v_pk_fma_f32 v[50:51], v[50:51], v[52:53], v[54:55] op_sel:[1,1,0] op_sel_hi:[1,0,1] neg_lo:[0,1,0]
	ds_write_b64 v74, v[50:51] offset:19584
	v_pk_mul_f32 v[50:51], v[52:53], v[44:45] op_sel:[0,0] op_sel_hi:[0,1]
	s_nop 0
	v_pk_fma_f32 v[50:51], v[52:53], v[44:45], v[50:51] op_sel:[1,1,0] op_sel_hi:[1,0,1] neg_lo:[0,1,0]
	s_nop 0
	v_pk_mul_f32 v[52:53], v[48:49], v[50:51] op_sel:[0,0] op_sel_hi:[0,1]
	s_nop 0
	v_pk_fma_f32 v[48:49], v[48:49], v[50:51], v[52:53] op_sel:[1,1,0] op_sel_hi:[1,0,1] neg_lo:[0,1,0]
	ds_write_b64 v74, v[48:49] offset:21760
	v_pk_mul_f32 v[48:49], v[50:51], v[44:45] op_sel:[0,0] op_sel_hi:[0,1]
	s_nop 0
	v_pk_fma_f32 v[48:49], v[50:51], v[44:45], v[48:49] op_sel:[1,1,0] op_sel_hi:[1,0,1] neg_lo:[0,1,0]
	s_nop 0
	v_pk_mul_f32 v[50:51], v[58:59], v[48:49] op_sel:[0,0] op_sel_hi:[0,1]
	s_nop 0
	v_pk_fma_f32 v[50:51], v[58:59], v[48:49], v[50:51] op_sel:[1,1,0] op_sel_hi:[1,0,1] neg_lo:[0,1,0]
	ds_write_b64 v74, v[50:51] offset:23936
	v_pk_mul_f32 v[50:51], v[48:49], v[44:45] op_sel:[0,0] op_sel_hi:[0,1]
	s_nop 0
	v_pk_fma_f32 v[48:49], v[48:49], v[44:45], v[50:51] op_sel:[1,1,0] op_sel_hi:[1,0,1] neg_lo:[0,1,0]
	s_nop 0
	v_pk_mul_f32 v[50:51], v[40:41], v[48:49] op_sel:[0,0] op_sel_hi:[0,1]
	s_nop 0
	v_pk_fma_f32 v[40:41], v[40:41], v[48:49], v[50:51] op_sel:[1,1,0] op_sel_hi:[1,0,1] neg_lo:[0,1,0]
	ds_write_b64 v74, v[40:41] offset:26112
	v_pk_mul_f32 v[40:41], v[48:49], v[44:45] op_sel:[0,0] op_sel_hi:[0,1]
	s_nop 0
	v_pk_fma_f32 v[40:41], v[48:49], v[44:45], v[40:41] op_sel:[1,1,0] op_sel_hi:[1,0,1] neg_lo:[0,1,0]
	s_nop 0
	v_pk_mul_f32 v[48:49], v[56:57], v[40:41] op_sel:[0,0] op_sel_hi:[0,1]
	s_nop 0
	v_pk_fma_f32 v[48:49], v[56:57], v[40:41], v[48:49] op_sel:[1,1,0] op_sel_hi:[1,0,1] neg_lo:[0,1,0]
	ds_write_b64 v74, v[48:49] offset:28288
	v_pk_mul_f32 v[48:49], v[40:41], v[44:45] op_sel:[0,0] op_sel_hi:[0,1]
	s_nop 0
	v_pk_fma_f32 v[40:41], v[40:41], v[44:45], v[48:49] op_sel:[1,1,0] op_sel_hi:[1,0,1] neg_lo:[0,1,0]
	s_nop 0
	v_pk_mul_f32 v[48:49], v[46:47], v[40:41] op_sel:[0,0] op_sel_hi:[0,1]
	s_nop 0
	v_pk_fma_f32 v[46:47], v[46:47], v[40:41], v[48:49] op_sel:[1,1,0] op_sel_hi:[1,0,1] neg_lo:[0,1,0]
	ds_write_b64 v74, v[46:47] offset:30464
	v_pk_mul_f32 v[46:47], v[40:41], v[44:45] op_sel:[0,0] op_sel_hi:[0,1]
	s_nop 0
	v_pk_fma_f32 v[40:41], v[40:41], v[44:45], v[46:47] op_sel:[1,1,0] op_sel_hi:[1,0,1] neg_lo:[0,1,0]
	s_nop 0
	v_pk_mul_f32 v[44:45], v[42:43], v[40:41] op_sel:[0,0] op_sel_hi:[0,1]
	s_nop 0
	v_pk_fma_f32 v[40:41], v[42:43], v[40:41], v[44:45] op_sel:[1,1,0] op_sel_hi:[1,0,1] neg_lo:[0,1,0]
	ds_write_b64 v74, v[40:41] offset:32640
	s_waitcnt lgkmcnt(0)
	s_barrier
	ds_read2_b64 v[40:43], v39 offset1:17
	ds_read2_b64 v[44:47], v39 offset0:34 offset1:51
	ds_read2_b64 v[48:51], v39 offset0:68 offset1:85
	ds_read2_b64 v[52:55], v39 offset0:136 offset1:153
	ds_read2_b64 v[56:59], v39 offset0:102 offset1:119
	ds_read2_b64 v[60:63], v39 offset0:204 offset1:221
	ds_read2_b64 v[64:67], v39 offset0:170 offset1:187
	ds_read2_b64 v[68:71], v39 offset0:238 offset1:255
	s_waitcnt lgkmcnt(4)
	v_pk_add_f32 v[72:73], v[40:41], v[52:53]
	v_pk_add_f32 v[40:41], v[40:41], v[52:53] neg_lo:[0,1] neg_hi:[0,1]
	s_waitcnt lgkmcnt(2)
	v_pk_add_f32 v[52:53], v[48:49], v[60:61]
	v_pk_add_f32 v[48:49], v[48:49], v[60:61] neg_lo:[0,1] neg_hi:[0,1]
	v_pk_add_f32 v[60:61], v[72:73], v[52:53]
	v_pk_add_f32 v[52:53], v[72:73], v[52:53] neg_lo:[0,1] neg_hi:[0,1]
	v_pk_add_f32 v[72:73], v[40:41], v[48:49] op_sel:[0,1] op_sel_hi:[1,0] neg_hi:[0,1]
	v_pk_add_f32 v[40:41], v[40:41], v[48:49] op_sel:[0,1] op_sel_hi:[1,0] neg_lo:[0,1]
	v_pk_add_f32 v[48:49], v[42:43], v[54:55]
	v_pk_add_f32 v[42:43], v[42:43], v[54:55] neg_lo:[0,1] neg_hi:[0,1]
	v_pk_add_f32 v[54:55], v[50:51], v[62:63]
	v_pk_add_f32 v[50:51], v[50:51], v[62:63] neg_lo:[0,1] neg_hi:[0,1]
	v_pk_add_f32 v[62:63], v[48:49], v[54:55]
	v_pk_add_f32 v[48:49], v[48:49], v[54:55] neg_lo:[0,1] neg_hi:[0,1]
	v_pk_add_f32 v[54:55], v[42:43], v[50:51] op_sel:[0,1] op_sel_hi:[1,0] neg_hi:[0,1]
	v_pk_add_f32 v[42:43], v[42:43], v[50:51] op_sel:[0,1] op_sel_hi:[1,0] neg_lo:[0,1]
	s_waitcnt lgkmcnt(1)
	v_pk_add_f32 v[50:51], v[44:45], v[64:65]
	v_pk_add_f32 v[44:45], v[44:45], v[64:65] neg_lo:[0,1] neg_hi:[0,1]
	s_waitcnt lgkmcnt(0)
	v_pk_add_f32 v[64:65], v[56:57], v[68:69]
	v_pk_add_f32 v[56:57], v[56:57], v[68:69] neg_lo:[0,1] neg_hi:[0,1]
	v_pk_add_f32 v[68:69], v[50:51], v[64:65]
	v_pk_add_f32 v[50:51], v[50:51], v[64:65] neg_lo:[0,1] neg_hi:[0,1]
	v_pk_add_f32 v[64:65], v[44:45], v[56:57] op_sel:[0,1] op_sel_hi:[1,0] neg_hi:[0,1]
	v_pk_add_f32 v[44:45], v[44:45], v[56:57] op_sel:[0,1] op_sel_hi:[1,0] neg_lo:[0,1]
	v_pk_add_f32 v[56:57], v[46:47], v[66:67]
	v_pk_add_f32 v[46:47], v[46:47], v[66:67] neg_lo:[0,1] neg_hi:[0,1]
	v_pk_add_f32 v[66:67], v[58:59], v[70:71]
	v_pk_add_f32 v[58:59], v[58:59], v[70:71] neg_lo:[0,1] neg_hi:[0,1]
	v_pk_add_f32 v[70:71], v[56:57], v[66:67]
	v_pk_add_f32 v[56:57], v[56:57], v[66:67] neg_lo:[0,1] neg_hi:[0,1]
	v_pk_add_f32 v[66:67], v[46:47], v[58:59] op_sel:[0,1] op_sel_hi:[1,0] neg_hi:[0,1]
	v_pk_add_f32 v[46:47], v[46:47], v[58:59] op_sel:[0,1] op_sel_hi:[1,0] neg_lo:[0,1]
	v_pk_mul_f32 v[58:59], v[54:55], v[24:25] op_sel:[0,0] op_sel_hi:[0,1]
	s_nop 0
	v_pk_fma_f32 v[54:55], v[54:55], v[24:25], v[58:59] op_sel:[1,1,0] op_sel_hi:[1,0,1] neg_lo:[0,1,0]
	v_pk_mul_f32 v[58:59], v[64:65], v[20:21] op_sel:[0,0] op_sel_hi:[0,1]
	s_nop 0
	v_pk_fma_f32 v[58:59], v[64:65], v[20:21], v[58:59] op_sel:[1,1,0] op_sel_hi:[1,0,1] neg_lo:[0,1,0]
	v_pk_mul_f32 v[64:65], v[66:67], v[18:19] op_sel:[0,0] op_sel_hi:[0,1]
	s_nop 0
	v_pk_fma_f32 v[64:65], v[66:67], v[18:19], v[64:65] op_sel:[1,1,0] op_sel_hi:[1,0,1] neg_lo:[0,1,0]
	v_pk_mul_f32 v[66:67], v[48:49], v[20:21] op_sel:[0,0] op_sel_hi:[0,1]
	s_nop 0
	v_pk_fma_f32 v[48:49], v[48:49], v[20:21], v[66:67] op_sel:[1,1,0] op_sel_hi:[1,0,1] neg_lo:[0,1,0]
	v_pk_mul_f32 v[66:67], v[50:51], v[26:27] op_sel:[0,0] op_sel_hi:[0,1]
	s_nop 0
	v_pk_fma_f32 v[50:51], v[50:51], v[26:27], v[66:67] op_sel:[1,1,0] op_sel_hi:[1,0,1] neg_lo:[0,1,0]
	v_pk_mul_f32 v[66:67], v[56:57], v[22:23] op_sel:[0,0] op_sel_hi:[0,1]
	s_nop 0
	v_pk_fma_f32 v[56:57], v[56:57], v[22:23], v[66:67] op_sel:[1,1,0] op_sel_hi:[1,0,1] neg_lo:[0,1,0]
	v_pk_mul_f32 v[66:67], v[42:43], v[18:19] op_sel:[0,0] op_sel_hi:[0,1]
	s_nop 0
	v_pk_fma_f32 v[42:43], v[42:43], v[18:19], v[66:67] op_sel:[1,1,0] op_sel_hi:[1,0,1] neg_lo:[0,1,0]
	v_pk_mul_f32 v[66:67], v[44:45], v[22:23] op_sel:[0,0] op_sel_hi:[0,1]
	s_nop 0
	v_pk_fma_f32 v[44:45], v[44:45], v[22:23], v[66:67] op_sel:[1,1,0] op_sel_hi:[1,0,1] neg_lo:[0,1,0]
	v_pk_mul_f32 v[66:67], v[46:47], v[28:29] op_sel:[0,0] op_sel_hi:[0,1]
	s_nop 0
	v_pk_fma_f32 v[46:47], v[46:47], v[28:29], v[66:67] op_sel:[1,1,0] op_sel_hi:[1,0,1] neg_lo:[0,1,0]
	v_pk_add_f32 v[66:67], v[60:61], v[68:69]
	v_pk_add_f32 v[60:61], v[60:61], v[68:69] neg_lo:[0,1] neg_hi:[0,1]
	v_pk_add_f32 v[68:69], v[62:63], v[70:71]
	v_pk_add_f32 v[62:63], v[62:63], v[70:71] neg_lo:[0,1] neg_hi:[0,1]
	v_pk_add_f32 v[70:71], v[66:67], v[68:69]
	v_pk_add_f32 v[66:67], v[66:67], v[68:69] neg_lo:[0,1] neg_hi:[0,1]
	v_pk_add_f32 v[68:69], v[60:61], v[62:63] op_sel:[0,1] op_sel_hi:[1,0] neg_hi:[0,1]
	v_pk_add_f32 v[60:61], v[60:61], v[62:63] op_sel:[0,1] op_sel_hi:[1,0] neg_lo:[0,1]
	v_pk_add_f32 v[62:63], v[72:73], v[58:59]
	v_pk_add_f32 v[58:59], v[72:73], v[58:59] neg_lo:[0,1] neg_hi:[0,1]
	v_pk_add_f32 v[72:73], v[54:55], v[64:65]
	v_pk_add_f32 v[54:55], v[54:55], v[64:65] neg_lo:[0,1] neg_hi:[0,1]
	v_pk_add_f32 v[64:65], v[62:63], v[72:73]
	v_pk_add_f32 v[62:63], v[62:63], v[72:73] neg_lo:[0,1] neg_hi:[0,1]
	v_pk_add_f32 v[72:73], v[58:59], v[54:55] op_sel:[0,1] op_sel_hi:[1,0] neg_hi:[0,1]
	v_pk_add_f32 v[54:55], v[58:59], v[54:55] op_sel:[0,1] op_sel_hi:[1,0] neg_lo:[0,1]
	v_pk_add_f32 v[58:59], v[52:53], v[50:51]
	v_pk_add_f32 v[50:51], v[52:53], v[50:51] neg_lo:[0,1] neg_hi:[0,1]
	v_pk_add_f32 v[52:53], v[48:49], v[56:57]
	v_pk_add_f32 v[48:49], v[48:49], v[56:57] neg_lo:[0,1] neg_hi:[0,1]
	v_pk_add_f32 v[56:57], v[58:59], v[52:53]
	v_pk_add_f32 v[52:53], v[58:59], v[52:53] neg_lo:[0,1] neg_hi:[0,1]
	v_pk_add_f32 v[58:59], v[50:51], v[48:49] op_sel:[0,1] op_sel_hi:[1,0] neg_hi:[0,1]
	v_pk_add_f32 v[48:49], v[50:51], v[48:49] op_sel:[0,1] op_sel_hi:[1,0] neg_lo:[0,1]
	v_pk_add_f32 v[50:51], v[40:41], v[44:45]
	v_pk_add_f32 v[40:41], v[40:41], v[44:45] neg_lo:[0,1] neg_hi:[0,1]
	v_pk_add_f32 v[44:45], v[42:43], v[46:47]
	v_pk_add_f32 v[42:43], v[42:43], v[46:47] neg_lo:[0,1] neg_hi:[0,1]
	v_pk_add_f32 v[46:47], v[50:51], v[44:45]
	v_pk_add_f32 v[44:45], v[50:51], v[44:45] neg_lo:[0,1] neg_hi:[0,1]
	v_pk_add_f32 v[50:51], v[40:41], v[42:43] op_sel:[0,1] op_sel_hi:[1,0] neg_hi:[0,1]
	v_pk_add_f32 v[40:41], v[40:41], v[42:43] op_sel:[0,1] op_sel_hi:[1,0] neg_lo:[0,1]
	v_mov_b32_e32 v42, v30
	v_mov_b32_e32 v43, v32
	s_nop 0
	v_pk_mul_f32 v[74:75], v[64:65], v[42:43] op_sel:[0,0] op_sel_hi:[0,1]
	s_nop 0
	v_pk_fma_f32 v[64:65], v[64:65], v[42:43], v[74:75] op_sel:[1,1,0] op_sel_hi:[1,0,1] neg_lo:[0,1,0]
	ds_write2_b64 v39, v[70:71], v[64:65] offset1:17
	v_pk_mul_f32 v[64:65], v[42:43], v[42:43] op_sel:[0,0] op_sel_hi:[0,1]
	s_nop 0
	v_pk_fma_f32 v[64:65], v[42:43], v[42:43], v[64:65] op_sel:[1,1,0] op_sel_hi:[1,0,1] neg_lo:[0,1,0]
	s_nop 0
	v_pk_mul_f32 v[70:71], v[56:57], v[64:65] op_sel:[0,0] op_sel_hi:[0,1]
	s_nop 0
	v_pk_fma_f32 v[56:57], v[56:57], v[64:65], v[70:71] op_sel:[1,1,0] op_sel_hi:[1,0,1] neg_lo:[0,1,0]
	v_pk_mul_f32 v[70:71], v[64:65], v[42:43] op_sel:[0,0] op_sel_hi:[0,1]
	s_nop 0
	v_pk_fma_f32 v[64:65], v[64:65], v[42:43], v[70:71] op_sel:[1,1,0] op_sel_hi:[1,0,1] neg_lo:[0,1,0]
	s_nop 0
	v_pk_mul_f32 v[70:71], v[46:47], v[64:65] op_sel:[0,0] op_sel_hi:[0,1]
	s_nop 0
	v_pk_fma_f32 v[46:47], v[46:47], v[64:65], v[70:71] op_sel:[1,1,0] op_sel_hi:[1,0,1] neg_lo:[0,1,0]
	ds_write2_b64 v39, v[56:57], v[46:47] offset0:34 offset1:51
	v_pk_mul_f32 v[46:47], v[64:65], v[42:43] op_sel:[0,0] op_sel_hi:[0,1]
	s_nop 0
	v_pk_fma_f32 v[46:47], v[64:65], v[42:43], v[46:47] op_sel:[1,1,0] op_sel_hi:[1,0,1] neg_lo:[0,1,0]
	s_nop 0
	v_pk_mul_f32 v[56:57], v[68:69], v[46:47] op_sel:[0,0] op_sel_hi:[0,1]
	v_pk_mul_f32 v[64:65], v[46:47], v[42:43] op_sel:[0,0] op_sel_hi:[0,1]
	s_nop 0
	v_pk_fma_f32 v[56:57], v[68:69], v[46:47], v[56:57] op_sel:[1,1,0] op_sel_hi:[1,0,1] neg_lo:[0,1,0]
	v_pk_fma_f32 v[46:47], v[46:47], v[42:43], v[64:65] op_sel:[1,1,0] op_sel_hi:[1,0,1] neg_lo:[0,1,0]
	s_nop 0
	v_pk_mul_f32 v[64:65], v[72:73], v[46:47] op_sel:[0,0] op_sel_hi:[0,1]
	s_nop 0
	v_pk_fma_f32 v[64:65], v[72:73], v[46:47], v[64:65] op_sel:[1,1,0] op_sel_hi:[1,0,1] neg_lo:[0,1,0]
	ds_write2_b64 v39, v[56:57], v[64:65] offset0:68 offset1:85
	v_pk_mul_f32 v[56:57], v[46:47], v[42:43] op_sel:[0,0] op_sel_hi:[0,1]
	s_nop 0
	v_pk_fma_f32 v[46:47], v[46:47], v[42:43], v[56:57] op_sel:[1,1,0] op_sel_hi:[1,0,1] neg_lo:[0,1,0]
	s_nop 0
	v_pk_mul_f32 v[56:57], v[58:59], v[46:47] op_sel:[0,0] op_sel_hi:[0,1]
	s_nop 0
	v_pk_fma_f32 v[56:57], v[58:59], v[46:47], v[56:57] op_sel:[1,1,0] op_sel_hi:[1,0,1] neg_lo:[0,1,0]
	v_pk_mul_f32 v[58:59], v[46:47], v[42:43] op_sel:[0,0] op_sel_hi:[0,1]
	s_nop 0
	v_pk_fma_f32 v[46:47], v[46:47], v[42:43], v[58:59] op_sel:[1,1,0] op_sel_hi:[1,0,1] neg_lo:[0,1,0]
	s_nop 0
	v_pk_mul_f32 v[58:59], v[50:51], v[46:47] op_sel:[0,0] op_sel_hi:[0,1]
	s_nop 0
	v_pk_fma_f32 v[50:51], v[50:51], v[46:47], v[58:59] op_sel:[1,1,0] op_sel_hi:[1,0,1] neg_lo:[0,1,0]
	ds_write2_b64 v39, v[56:57], v[50:51] offset0:102 offset1:119
	v_pk_mul_f32 v[50:51], v[46:47], v[42:43] op_sel:[0,0] op_sel_hi:[0,1]
	s_nop 0
	v_pk_fma_f32 v[46:47], v[46:47], v[42:43], v[50:51] op_sel:[1,1,0] op_sel_hi:[1,0,1] neg_lo:[0,1,0]
	s_nop 0
	v_pk_mul_f32 v[50:51], v[66:67], v[46:47] op_sel:[0,0] op_sel_hi:[0,1]
	v_pk_mul_f32 v[56:57], v[46:47], v[42:43] op_sel:[0,0] op_sel_hi:[0,1]
	s_nop 0
	v_pk_fma_f32 v[50:51], v[66:67], v[46:47], v[50:51] op_sel:[1,1,0] op_sel_hi:[1,0,1] neg_lo:[0,1,0]
	v_pk_fma_f32 v[46:47], v[46:47], v[42:43], v[56:57] op_sel:[1,1,0] op_sel_hi:[1,0,1] neg_lo:[0,1,0]
	s_nop 0
	v_pk_mul_f32 v[56:57], v[62:63], v[46:47] op_sel:[0,0] op_sel_hi:[0,1]
	s_nop 0
	v_pk_fma_f32 v[56:57], v[62:63], v[46:47], v[56:57] op_sel:[1,1,0] op_sel_hi:[1,0,1] neg_lo:[0,1,0]
	ds_write2_b64 v39, v[50:51], v[56:57] offset0:136 offset1:153
	v_pk_mul_f32 v[50:51], v[46:47], v[42:43] op_sel:[0,0] op_sel_hi:[0,1]
	s_nop 0
	v_pk_fma_f32 v[46:47], v[46:47], v[42:43], v[50:51] op_sel:[1,1,0] op_sel_hi:[1,0,1] neg_lo:[0,1,0]
	s_nop 0
	v_pk_mul_f32 v[50:51], v[52:53], v[46:47] op_sel:[0,0] op_sel_hi:[0,1]
	s_nop 0
	v_pk_fma_f32 v[50:51], v[52:53], v[46:47], v[50:51] op_sel:[1,1,0] op_sel_hi:[1,0,1] neg_lo:[0,1,0]
	v_pk_mul_f32 v[52:53], v[46:47], v[42:43] op_sel:[0,0] op_sel_hi:[0,1]
	s_nop 0
	v_pk_fma_f32 v[46:47], v[46:47], v[42:43], v[52:53] op_sel:[1,1,0] op_sel_hi:[1,0,1] neg_lo:[0,1,0]
	s_nop 0
	v_pk_mul_f32 v[52:53], v[44:45], v[46:47] op_sel:[0,0] op_sel_hi:[0,1]
	s_nop 0
	v_pk_fma_f32 v[44:45], v[44:45], v[46:47], v[52:53] op_sel:[1,1,0] op_sel_hi:[1,0,1] neg_lo:[0,1,0]
	ds_write2_b64 v39, v[50:51], v[44:45] offset0:170 offset1:187
	v_pk_mul_f32 v[44:45], v[46:47], v[42:43] op_sel:[0,0] op_sel_hi:[0,1]
	s_nop 0
	v_pk_fma_f32 v[44:45], v[46:47], v[42:43], v[44:45] op_sel:[1,1,0] op_sel_hi:[1,0,1] neg_lo:[0,1,0]
	s_nop 0
	v_pk_mul_f32 v[46:47], v[60:61], v[44:45] op_sel:[0,0] op_sel_hi:[0,1]
	v_pk_mul_f32 v[50:51], v[44:45], v[42:43] op_sel:[0,0] op_sel_hi:[0,1]
	s_nop 0
	v_pk_fma_f32 v[46:47], v[60:61], v[44:45], v[46:47] op_sel:[1,1,0] op_sel_hi:[1,0,1] neg_lo:[0,1,0]
	v_pk_fma_f32 v[44:45], v[44:45], v[42:43], v[50:51] op_sel:[1,1,0] op_sel_hi:[1,0,1] neg_lo:[0,1,0]
	s_nop 0
	v_pk_mul_f32 v[50:51], v[54:55], v[44:45] op_sel:[0,0] op_sel_hi:[0,1]
	s_nop 0
	v_pk_fma_f32 v[50:51], v[54:55], v[44:45], v[50:51] op_sel:[1,1,0] op_sel_hi:[1,0,1] neg_lo:[0,1,0]
	ds_write2_b64 v39, v[46:47], v[50:51] offset0:204 offset1:221
	v_pk_mul_f32 v[46:47], v[44:45], v[42:43] op_sel:[0,0] op_sel_hi:[0,1]
	s_nop 0
	v_pk_fma_f32 v[44:45], v[44:45], v[42:43], v[46:47] op_sel:[1,1,0] op_sel_hi:[1,0,1] neg_lo:[0,1,0]
	s_nop 0
	v_pk_mul_f32 v[46:47], v[48:49], v[44:45] op_sel:[0,0] op_sel_hi:[0,1]
	s_nop 0
	v_pk_fma_f32 v[46:47], v[48:49], v[44:45], v[46:47] op_sel:[1,1,0] op_sel_hi:[1,0,1] neg_lo:[0,1,0]
	v_pk_mul_f32 v[48:49], v[44:45], v[42:43] op_sel:[0,0] op_sel_hi:[0,1]
	s_nop 0
	v_pk_fma_f32 v[42:43], v[44:45], v[42:43], v[48:49] op_sel:[1,1,0] op_sel_hi:[1,0,1] neg_lo:[0,1,0]
	s_nop 0
	v_pk_mul_f32 v[44:45], v[40:41], v[42:43] op_sel:[0,0] op_sel_hi:[0,1]
	s_nop 0
	v_pk_fma_f32 v[40:41], v[40:41], v[42:43], v[44:45] op_sel:[1,1,0] op_sel_hi:[1,0,1] neg_lo:[0,1,0]
	ds_write2_b64 v39, v[46:47], v[40:41] offset0:238 offset1:255
	v_mad_u32_u24 v39, v34, s54, v35
	s_waitcnt lgkmcnt(0)
	s_barrier
	ds_read2_b64 v[40:43], v39 offset1:1
	ds_read2_b64 v[44:47], v39 offset0:2 offset1:3
	ds_read2_b64 v[48:51], v39 offset0:8 offset1:9
	ds_read2_b64 v[52:55], v39 offset0:4 offset1:5
	ds_read2_b64 v[56:59], v39 offset0:6 offset1:7
	ds_read2_b64 v[60:63], v39 offset0:12 offset1:13
	ds_read2_b64 v[64:67], v39 offset0:10 offset1:11
	ds_read2_b64 v[68:71], v39 offset0:14 offset1:15
	s_waitcnt lgkmcnt(5)
	v_pk_add_f32 v[72:73], v[40:41], v[48:49]
	v_pk_add_f32 v[40:41], v[40:41], v[48:49] neg_lo:[0,1] neg_hi:[0,1]
	s_waitcnt lgkmcnt(2)
	v_pk_add_f32 v[48:49], v[52:53], v[60:61]
	v_pk_add_f32 v[52:53], v[52:53], v[60:61] neg_lo:[0,1] neg_hi:[0,1]
	v_pk_add_f32 v[60:61], v[72:73], v[48:49]
	v_pk_add_f32 v[48:49], v[72:73], v[48:49] neg_lo:[0,1] neg_hi:[0,1]
	v_pk_add_f32 v[72:73], v[40:41], v[52:53] op_sel:[0,1] op_sel_hi:[1,0] neg_hi:[0,1]
	v_pk_add_f32 v[40:41], v[40:41], v[52:53] op_sel:[0,1] op_sel_hi:[1,0] neg_lo:[0,1]
	v_pk_add_f32 v[52:53], v[42:43], v[50:51]
	v_pk_add_f32 v[42:43], v[42:43], v[50:51] neg_lo:[0,1] neg_hi:[0,1]
	v_pk_add_f32 v[50:51], v[54:55], v[62:63]
	v_pk_add_f32 v[54:55], v[54:55], v[62:63] neg_lo:[0,1] neg_hi:[0,1]
	v_pk_add_f32 v[62:63], v[52:53], v[50:51]
	v_pk_add_f32 v[50:51], v[52:53], v[50:51] neg_lo:[0,1] neg_hi:[0,1]
	v_pk_add_f32 v[52:53], v[42:43], v[54:55] op_sel:[0,1] op_sel_hi:[1,0] neg_hi:[0,1]
	v_pk_add_f32 v[42:43], v[42:43], v[54:55] op_sel:[0,1] op_sel_hi:[1,0] neg_lo:[0,1]
	s_waitcnt lgkmcnt(1)
	v_pk_add_f32 v[54:55], v[44:45], v[64:65]
	v_pk_add_f32 v[44:45], v[44:45], v[64:65] neg_lo:[0,1] neg_hi:[0,1]
	s_waitcnt lgkmcnt(0)
	v_pk_add_f32 v[64:65], v[56:57], v[68:69]
	v_pk_add_f32 v[56:57], v[56:57], v[68:69] neg_lo:[0,1] neg_hi:[0,1]
	v_pk_add_f32 v[68:69], v[54:55], v[64:65]
	v_pk_add_f32 v[54:55], v[54:55], v[64:65] neg_lo:[0,1] neg_hi:[0,1]
	v_pk_add_f32 v[64:65], v[44:45], v[56:57] op_sel:[0,1] op_sel_hi:[1,0] neg_hi:[0,1]
	v_pk_add_f32 v[44:45], v[44:45], v[56:57] op_sel:[0,1] op_sel_hi:[1,0] neg_lo:[0,1]
	v_pk_add_f32 v[56:57], v[46:47], v[66:67]
	v_pk_add_f32 v[46:47], v[46:47], v[66:67] neg_lo:[0,1] neg_hi:[0,1]
	v_pk_add_f32 v[66:67], v[58:59], v[70:71]
	v_pk_add_f32 v[58:59], v[58:59], v[70:71] neg_lo:[0,1] neg_hi:[0,1]
	v_pk_add_f32 v[70:71], v[56:57], v[66:67]
	v_pk_add_f32 v[56:57], v[56:57], v[66:67] neg_lo:[0,1] neg_hi:[0,1]
	v_pk_add_f32 v[66:67], v[46:47], v[58:59] op_sel:[0,1] op_sel_hi:[1,0] neg_hi:[0,1]
	v_pk_add_f32 v[46:47], v[46:47], v[58:59] op_sel:[0,1] op_sel_hi:[1,0] neg_lo:[0,1]
	v_pk_mul_f32 v[58:59], v[52:53], v[24:25] op_sel:[0,0] op_sel_hi:[0,1]
	s_nop 0
	v_pk_fma_f32 v[24:25], v[52:53], v[24:25], v[58:59] op_sel:[1,1,0] op_sel_hi:[1,0,1] neg_lo:[0,1,0]
	v_pk_mul_f32 v[52:53], v[64:65], v[20:21] op_sel:[0,0] op_sel_hi:[0,1]
	v_pk_mul_f32 v[58:59], v[66:67], v[18:19] op_sel:[0,0] op_sel_hi:[0,1]
	s_barrier
	v_pk_fma_f32 v[52:53], v[64:65], v[20:21], v[52:53] op_sel:[1,1,0] op_sel_hi:[1,0,1] neg_lo:[0,1,0]
	v_pk_mul_f32 v[64:65], v[50:51], v[20:21] op_sel:[0,0] op_sel_hi:[0,1]
	v_pk_fma_f32 v[58:59], v[66:67], v[18:19], v[58:59] op_sel:[1,1,0] op_sel_hi:[1,0,1] neg_lo:[0,1,0]
	s_nop 0
	v_pk_fma_f32 v[20:21], v[50:51], v[20:21], v[64:65] op_sel:[1,1,0] op_sel_hi:[1,0,1] neg_lo:[0,1,0]
	v_pk_mul_f32 v[50:51], v[54:55], v[26:27] op_sel:[0,0] op_sel_hi:[0,1]
	s_nop 0
	v_pk_fma_f32 v[26:27], v[54:55], v[26:27], v[50:51] op_sel:[1,1,0] op_sel_hi:[1,0,1] neg_lo:[0,1,0]
	v_pk_mul_f32 v[50:51], v[56:57], v[22:23] op_sel:[0,0] op_sel_hi:[0,1]
	v_pk_mul_f32 v[54:55], v[42:43], v[18:19] op_sel:[0,0] op_sel_hi:[0,1]
	s_nop 0
	v_pk_fma_f32 v[18:19], v[42:43], v[18:19], v[54:55] op_sel:[1,1,0] op_sel_hi:[1,0,1] neg_lo:[0,1,0]
	v_pk_mul_f32 v[42:43], v[44:45], v[22:23] op_sel:[0,0] op_sel_hi:[0,1]
	v_pk_fma_f32 v[50:51], v[56:57], v[22:23], v[50:51] op_sel:[1,1,0] op_sel_hi:[1,0,1] neg_lo:[0,1,0]
	v_pk_add_f32 v[54:55], v[24:25], v[58:59] neg_lo:[0,1] neg_hi:[0,1]
	v_pk_fma_f32 v[22:23], v[44:45], v[22:23], v[42:43] op_sel:[1,1,0] op_sel_hi:[1,0,1] neg_lo:[0,1,0]
	v_pk_mul_f32 v[42:43], v[46:47], v[28:29] op_sel:[0,0] op_sel_hi:[0,1]
	v_pk_add_f32 v[44:45], v[62:63], v[70:71] neg_lo:[0,1] neg_hi:[0,1]
	v_pk_fma_f32 v[28:29], v[46:47], v[28:29], v[42:43] op_sel:[1,1,0] op_sel_hi:[1,0,1] neg_lo:[0,1,0]
	v_pk_add_f32 v[42:43], v[60:61], v[68:69] neg_lo:[0,1] neg_hi:[0,1]
	v_pk_add_f32 v[74:75], v[18:19], v[28:29] neg_lo:[0,1] neg_hi:[0,1]
	v_pk_add_f32 v[46:47], v[42:43], v[44:45] op_sel:[0,1] op_sel_hi:[1,0] neg_hi:[0,1]
	v_pk_add_f32 v[42:43], v[42:43], v[44:45] op_sel:[0,1] op_sel_hi:[1,0] neg_lo:[0,1]
	v_pk_add_f32 v[44:45], v[72:73], v[52:53] neg_lo:[0,1] neg_hi:[0,1]
	v_and_b32_e32 v19, 0xf0, v36
	v_pk_add_f32 v[56:57], v[44:45], v[54:55] op_sel:[0,1] op_sel_hi:[1,0] neg_hi:[0,1]
	v_pk_add_f32 v[44:45], v[44:45], v[54:55] op_sel:[0,1] op_sel_hi:[1,0] neg_lo:[0,1]
	v_pk_add_f32 v[54:55], v[48:49], v[26:27] neg_lo:[0,1] neg_hi:[0,1]
	v_pk_add_f32 v[64:65], v[20:21], v[50:51] neg_lo:[0,1] neg_hi:[0,1]
	v_mul_i32_i24_e32 v21, 0xfffff804, v38
	v_lshlrev_b32_e32 v19, 2, v19
	v_pk_add_f32 v[66:67], v[54:55], v[64:65] op_sel:[0,1] op_sel_hi:[1,0] neg_hi:[0,1]
	v_pk_add_f32 v[54:55], v[54:55], v[64:65] op_sel:[0,1] op_sel_hi:[1,0] neg_lo:[0,1]
	v_pk_add_f32 v[64:65], v[40:41], v[22:23] neg_lo:[0,1] neg_hi:[0,1]
	v_add3_u32 v19, v78, v21, v19
	v_add_f32_e32 v21, v62, v70
	v_add_f32_e32 v23, v60, v68
	v_add_f32_e32 v24, v24, v58
	v_add_f32_e32 v27, v72, v52
	v_add_f32_e32 v25, v23, v21
	v_add_f32_e32 v29, v27, v24
	v_mul_f32_e32 v25, 0x3a800000, v25
	v_mul_f32_e32 v29, 0x3a800000, v29
	ds_write2st64_b32 v19, v25, v29 offset1:4
	v_add_f32_e32 v20, v20, v50
	v_add_f32_e32 v25, v48, v26
	v_add_f32_e32 v18, v18, v28
	v_add_f32_e32 v22, v40, v22
	v_add_f32_e32 v26, v25, v20
	v_add_f32_e32 v28, v22, v18
	v_sub_f32_e32 v20, v25, v20
	v_sub_f32_e32 v18, v22, v18
	v_mul_f32_e32 v26, 0x3a800000, v26
	v_mul_f32_e32 v28, 0x3a800000, v28
	v_mul_f32_e32 v20, 0x3a800000, v20
	v_mul_f32_e32 v18, 0x3a800000, v18
	ds_write2st64_b32 v19, v26, v28 offset0:8 offset1:12
	v_mul_f32_e32 v26, 0x3a800000, v46
	v_mul_f32_e32 v28, 0x3a800000, v56
	v_sub_f32_e32 v21, v23, v21
	v_sub_f32_e32 v23, v27, v24
	ds_write2st64_b32 v19, v20, v18 offset0:40 offset1:44
	v_mul_f32_e32 v18, 0x3a800000, v42
	v_mul_f32_e32 v20, 0x3a800000, v44
	v_pk_add_f32 v[76:77], v[64:65], v[74:75] op_sel:[0,1] op_sel_hi:[1,0] neg_hi:[0,1]
	v_pk_add_f32 v[64:65], v[64:65], v[74:75] op_sel:[0,1] op_sel_hi:[1,0] neg_lo:[0,1]
	ds_write2st64_b32 v19, v26, v28 offset0:16 offset1:20
	v_mul_f32_e32 v26, 0x3a800000, v66
	v_mul_f32_e32 v28, 0x3a800000, v76
	v_mul_f32_e32 v21, 0x3a800000, v21
	v_mul_f32_e32 v23, 0x3a800000, v23
	ds_write2st64_b32 v19, v18, v20 offset0:48 offset1:52
	v_mul_f32_e32 v18, 0x3a800000, v54
	v_mul_f32_e32 v20, 0x3a800000, v64
	v_mov_b32_e32 v22, v34
	ds_write2st64_b32 v19, v26, v28 offset0:24 offset1:28
	ds_write2st64_b32 v19, v21, v23 offset0:32 offset1:36
	ds_write2st64_b32 v19, v18, v20 offset0:56 offset1:60
	s_waitcnt lgkmcnt(0)
	s_barrier
	v_lshlrev_b32_e32 v26, 12, v37
	v_lshl_add_u32 v23, v22, 5, v35
	ds_read_b128 v[18:21], v23
	v_lshlrev_b32_e32 v28, 3, v22
	ds_read_b128 v[22:25], v23 offset:16
	v_ashrrev_i32_e32 v27, 31, v26
	v_lshlrev_b64 v[26:27], 1, v[26:27]
	s_waitcnt lgkmcnt(1)
	v_bfe_u32 v29, v18, 16, 1
	v_add3_u32 v18, v18, v29, s55
	v_bfe_u32 v29, v19, 16, 1
	v_lshrrev_b32_e32 v18, 16, v18
	v_add3_u32 v19, v19, v29, s55
	v_and_or_b32 v18, v19, s56, v18
	v_cvt_pk_bf16_f32 v19, v20, v21
	s_waitcnt lgkmcnt(0)
	v_cvt_pk_bf16_f32 v20, v22, v23
	v_cvt_pk_bf16_f32 v21, v24, v25
	v_ashrrev_i32_e32 v29, 31, v28
	v_lshl_add_u64 v[22:23], v[28:29], 1, v[26:27]
	v_lshl_add_u64 v[22:23], s[6:7], 0, v[22:23]
	global_store_dwordx4 v[22:23], v[18:21], off
	s_nop 0
	v_lshl_add_u32 v22, v34, 5, v35
	ds_read_b128 v[18:21], v22 offset:8192
	ds_read_b128 v[22:25], v22 offset:8208
	v_lshl_add_u32 v28, v34, 3, v33
	s_waitcnt lgkmcnt(1)
	v_bfe_u32 v29, v18, 16, 1
	v_add3_u32 v18, v18, v29, s55
	v_bfe_u32 v29, v19, 16, 1
	v_lshrrev_b32_e32 v18, 16, v18
	v_add3_u32 v19, v19, v29, s55
	v_and_or_b32 v18, v19, s56, v18
	v_cvt_pk_bf16_f32 v19, v20, v21
	s_waitcnt lgkmcnt(0)
	v_cvt_pk_bf16_f32 v20, v22, v23
	v_cvt_pk_bf16_f32 v21, v24, v25
	v_ashrrev_i32_e32 v29, 31, v28
	v_lshl_add_u64 v[22:23], v[28:29], 1, v[26:27]
	v_lshl_add_u64 v[22:23], s[6:7], 0, v[22:23]
	s_add_u32 s6, s6, s20
	s_addc_u32 s7, s7, s21
	s_and_b64 vcc, exec, s[44:45]
	global_store_dwordx4 v[22:23], v[18:21], off
	s_barrier
	s_cbranch_vccnz .LBB0_3755

.LBB0_3805:
	s_or_b64 exec, exec, s[52:53]
	s_lshl_b64 s[52:53], s[50:51], 15
	v_ashrrev_i32_e32 v91, 6, v38
	s_add_u32 s28, s64, s52
	v_lshlrev_b32_e32 v50, 3, v91
	v_lshlrev_b32_e32 v34, 1, v34
	s_addc_u32 s29, s63, s53
	v_add_u32_e32 v90, 0, v34
	v_lshl_add_u64 v[54:55], s[28:29], 0, v[34:35]
	v_add_u32_e32 v34, s91, v50
	v_and_b32_e32 v34, 0xfffffef8, v34
	v_cmp_eq_u32_e32 vcc, 0, v34
	s_waitcnt vmcnt(25)
	v_lshlrev_b32_e32 v96, 16, v66
	v_and_b32_e32 v94, 0xffff0000, v66
	v_lshlrev_b32_e32 v97, 16, v67
	v_and_b32_e32 v95, 0xffff0000, v67
	v_lshlrev_b32_e32 v67, 16, v59
	v_lshlrev_b32_e32 v66, 16, v58
	v_and_b32_e32 v101, 0xffff0000, v59
	v_and_b32_e32 v100, 0xffff0000, v58
	s_waitcnt vmcnt(3)
	v_mov_b32_e32 v58, v2
	v_mov_b32_e32 v59, v4
	v_mov_b32_e32 v4, v3
	v_mov_b32_e32 v2, v30
	v_mov_b32_e32 v3, v32
	v_cndmask_b32_e64 v34, 1.0, 0, vcc
	v_lshlrev_b32_e32 v87, 16, v65
	v_lshlrev_b32_e32 v86, 16, v64
	v_and_b32_e32 v105, 0xffff0000, v65
	v_and_b32_e32 v104, 0xffff0000, v64
	v_pk_mul_f32 v[64:65], v[2:3], v[66:67]
	v_pk_mul_f32 v[102:103], v[58:59], v[86:87]
	v_pk_mul_f32 v[66:67], v[64:65], v[34:35] op_sel_hi:[1,0]
	v_mov_b32_e32 v64, v26
	v_mov_b32_e32 v65, v28
	v_lshlrev_b32_e32 v89, 16, v69
	v_lshlrev_b32_e32 v88, 16, v68
	v_and_b32_e32 v87, 0xffff0000, v69
	v_and_b32_e32 v86, 0xffff0000, v68
	v_pk_fma_f32 v[68:69], v[64:65], v[96:97], v[66:67]
	v_mov_b32_e32 v66, v18
	v_mov_b32_e32 v67, v20
	v_mov_b32_e32 v32, v31
	v_pk_fma_f32 v[106:107], v[66:67], v[88:89], v[68:69]
	v_mov_b32_e32 v68, v22
	v_mov_b32_e32 v69, v24
	v_pk_mul_f32 v[30:31], v[32:33], v[100:101]
	v_pk_add_f32 v[106:107], v[68:69], v[106:107]
	v_pk_mul_f32 v[30:31], v[30:31], v[34:35] op_sel_hi:[1,0]
	v_mov_b32_e32 v28, v27
	v_mul_f32_e32 v18, 0xbfb8aa3b, v106
	v_pk_fma_f32 v[26:27], v[28:29], v[94:95], v[30:31]
	v_mov_b32_e32 v20, v19
	v_exp_f32_e32 v22, v18
	v_pk_fma_f32 v[18:19], v[20:21], v[86:87], v[26:27]
	v_mov_b32_e32 v24, v23
	v_pk_add_f32 v[18:19], v[24:25], v[18:19]
	v_mul_f32_e32 v26, 0xbfb8aa3b, v107
	v_mul_f32_e32 v23, 0xbfb8aa3b, v18
	v_exp_f32_e32 v23, v23
	v_exp_f32_e32 v27, v26
	v_mul_f32_e32 v26, 0xbfb8aa3b, v19
	v_exp_f32_e32 v51, v26
	v_add_f32_e32 v23, 1.0, v23
	v_add_f32_e32 v22, 1.0, v22
	v_rcp_f32_e32 v26, v23
	v_add_f32_e32 v23, 1.0, v27
	v_rcp_f32_e32 v22, v22
	v_rcp_f32_e32 v23, v23
	v_add_f32_e32 v27, 1.0, v51
	v_rcp_f32_e32 v27, v27
	v_lshlrev_b32_e32 v93, 16, v81
	v_lshlrev_b32_e32 v92, 16, v80
	v_and_b32_e32 v101, 0xffff0000, v81
	v_and_b32_e32 v100, 0xffff0000, v80
	v_pk_mul_f32 v[80:81], v[106:107], v[22:23]
	v_pk_mul_f32 v[30:31], v[4:5], v[104:105]
	v_pk_mul_f32 v[104:105], v[18:19], v[26:27]
	s_nop 0
	s_nop 0
	s_nop 0
	v_cvt_pk_bf16_f32 v107, v81, v105
	v_cvt_pk_bf16_f32 v106, v80, v104
	s_nop 0
	s_nop 0
	v_pk_mul_f32 v[22:23], v[34:35], v[102:103] op_sel_hi:[0,1]
	s_waitcnt vmcnt(2)
	v_mov_b32_e32 v18, v14
	v_mov_b32_e32 v19, v16
	v_lshlrev_b32_e32 v84, 16, v82
	v_lshlrev_b32_e32 v85, 16, v83
	v_pk_fma_f32 v[26:27], v[18:19], v[92:93], v[22:23]
	s_waitcnt vmcnt(1)
	v_mov_b32_e32 v22, v10
	v_mov_b32_e32 v23, v12
	v_pk_fma_f32 v[102:103], v[22:23], v[84:85], v[26:27]
	s_waitcnt vmcnt(0)
	v_mov_b32_e32 v26, v6
	v_mov_b32_e32 v27, v8
	v_pk_mul_f32 v[30:31], v[34:35], v[30:31] op_sel_hi:[0,1]
	v_mov_b32_e32 v16, v15
	v_and_b32_e32 v82, 0xffff0000, v82
	v_and_b32_e32 v83, 0xffff0000, v83
	v_pk_add_f32 v[102:103], v[26:27], v[102:103]
	v_pk_fma_f32 v[14:15], v[16:17], v[100:101], v[30:31]
	v_mov_b32_e32 v12, v11
	v_mul_f32_e32 v6, 0xbfb8aa3b, v102
	v_pk_fma_f32 v[10:11], v[12:13], v[82:83], v[14:15]
	v_mov_b32_e32 v8, v7
	v_exp_f32_e32 v108, v6
	v_pk_add_f32 v[6:7], v[8:9], v[10:11]
	v_mul_f32_e32 v14, 0xbfb8aa3b, v103
	v_mul_f32_e32 v10, 0xbfb8aa3b, v6
	v_exp_f32_e32 v11, v10
	v_exp_f32_e32 v15, v14
	v_mul_f32_e32 v14, 0xbfb8aa3b, v7
	v_exp_f32_e32 v30, v14
	v_add_f32_e32 v11, 1.0, v11
	v_add_f32_e32 v10, 1.0, v108
	v_rcp_f32_e32 v14, v11
	v_add_f32_e32 v11, 1.0, v15
	v_rcp_f32_e32 v10, v10
	v_rcp_f32_e32 v11, v11
	v_add_f32_e32 v15, 1.0, v30
	v_rcp_f32_e32 v15, v15
	s_movk_i32 s28, 0x1080
	v_pk_mul_f32 v[10:11], v[102:103], v[10:11]
	v_mad_u64_u32 v[30:31], s[28:29], v91, s28, v[90:91]
	v_pk_mul_f32 v[10:11], v[10:11], s[48:49] op_sel_hi:[1,0]
	v_pk_mul_f32 v[6:7], v[6:7], v[14:15]
	s_nop 0
	v_pk_mul_f32 v[6:7], v[6:7], s[48:49] op_sel_hi:[1,0]
	s_nop 0
	s_nop 0
	s_nop 0
	v_cvt_pk_bf16_f32 v15, v11, v7
	s_nop 0
	s_nop 0
	s_nop 0
	s_nop 0
	s_nop 0
	s_nop 0
	s_nop 0
	v_cvt_pk_bf16_f32 v14, v10, v6
	s_add_i32 s54, 0, 0x1be00
	v_lshlrev_b32_e32 v34, 5, v91
	s_waitcnt lgkmcnt(0)
	s_barrier
	ds_write2st64_b64 v30, v[106:107], v[14:15] offset1:66
	v_add_u32_e32 v14, s54, v34
	ds_read_b32 v14, v14
	s_add_i32 s55, 0, 0x1bf00
	v_add_u32_e32 v15, s55, v34
	ds_read_b32 v102, v15
	v_ashrrev_i32_e32 v51, 31, v50
	s_waitcnt lgkmcnt(1)
	v_pk_mul_f32 v[30:31], v[80:81], v[14:15] op_sel_hi:[1,0]
	v_pk_mul_f32 v[14:15], v[104:105], v[14:15] op_sel_hi:[1,0]
	v_and_b32_sdwa v80, v31, v98 dst_sel:DWORD dst_unused:UNUSED_PAD src0_sel:WORD_1 src1_sel:DWORD
	v_and_b32_sdwa v81, v30, v98 dst_sel:DWORD dst_unused:UNUSED_PAD src0_sel:WORD_1 src1_sel:DWORD
	v_add3_u32 v30, v30, v81, s79
	v_add3_u32 v31, v31, v80, s79
	v_and_b32_sdwa v80, v15, v98 dst_sel:DWORD dst_unused:UNUSED_PAD src0_sel:WORD_1 src1_sel:DWORD
	v_and_b32_sdwa v81, v14, v98 dst_sel:DWORD dst_unused:UNUSED_PAD src0_sel:WORD_1 src1_sel:DWORD
	v_add3_u32 v15, v15, v80, s79
	v_add3_u32 v14, v14, v81, s79
	v_and_b32_e32 v15, 0xffff0000, v15
	v_and_b32_e32 v14, 0xffff0000, v14
	v_or_b32_sdwa v15, v15, v31 dst_sel:DWORD dst_unused:UNUSED_PAD src0_sel:DWORD src1_sel:WORD_1
	v_or_b32_sdwa v14, v14, v30 dst_sel:DWORD dst_unused:UNUSED_PAD src0_sel:DWORD src1_sel:WORD_1
	v_lshlrev_b64 v[30:31], 9, v[50:51]
	v_lshl_add_u64 v[30:31], v[54:55], 0, v[30:31]
	s_waitcnt lgkmcnt(0)
	v_mul_f32_e32 v10, v10, v102
	global_store_dwordx2 v[30:31], v[14:15], off
	v_bfe_u32 v14, v10, 16, 1
	v_add3_u32 v10, v10, v14, s79
	v_mov_b32_e32 v14, s80
	s_movk_i32 s28, 0x240
	v_mad_u32_u24 v51, v99, s28, v14
	v_lshl_add_u32 v14, v91, 4, v51
	v_mul_f32_e32 v6, v6, v102
	ds_write_b16_d16_hi v14, v10
	v_bfe_u32 v10, v6, 16, 1
	v_add3_u32 v6, v6, v10, s79
	ds_write_b16_d16_hi v14, v6 offset:144
	v_mul_f32_e32 v6, v11, v102
	v_bfe_u32 v10, v6, 16, 1
	v_add3_u32 v6, v6, v10, s79
	ds_write_b16_d16_hi v14, v6 offset:288
	v_mul_f32_e32 v6, v7, v102
	v_bfe_u32 v7, v6, 16, 1
	v_add3_u32 v6, v6, v7, s79
	ds_write_b16_d16_hi v14, v6 offset:432
	v_pk_mul_f32 v[6:7], v[64:65], v[88:89]
	v_lshlrev_b32_e32 v81, 16, v79
	v_lshlrev_b32_e32 v80, 16, v78
	v_pk_fma_f32 v[6:7], v[2:3], v[96:97], v[6:7]
	v_pk_mul_f32 v[14:15], v[28:29], v[86:87]
	v_and_b32_e32 v79, 0xffff0000, v79
	v_and_b32_e32 v78, 0xffff0000, v78
	v_pk_fma_f32 v[6:7], v[66:67], v[80:81], v[6:7]
	v_pk_fma_f32 v[14:15], v[32:33], v[94:95], v[14:15]
	v_pk_add_f32 v[6:7], v[68:69], v[6:7]
	v_pk_fma_f32 v[14:15], v[20:21], v[78:79], v[14:15]
	v_mul_f32_e32 v11, 0xbfb8aa3b, v6
	v_pk_add_f32 v[94:95], v[24:25], v[14:15]
	v_exp_f32_e32 v11, v11
	v_mul_f32_e32 v14, 0xbfb8aa3b, v94
	v_exp_f32_e32 v15, v14
	v_mul_f32_e32 v31, 0xbfb8aa3b, v95
	v_add_f32_e32 v11, 1.0, v11
	v_rcp_f32_e32 v96, v11
	v_add_f32_e32 v11, 1.0, v15
	v_mul_f32_e32 v15, 0xbfb8aa3b, v7
	v_exp_f32_e32 v15, v15
	v_exp_f32_e32 v31, v31
	v_rcp_f32_e32 v102, v11
	v_lshlrev_b32_e32 v10, 16, v76
	v_add_f32_e32 v11, 1.0, v15
	v_rcp_f32_e32 v97, v11
	v_add_f32_e32 v11, 1.0, v31
	v_rcp_f32_e32 v103, v11
	v_and_b32_e32 v14, 0xffff0000, v76
	v_lshlrev_b32_e32 v11, 16, v77
	v_and_b32_e32 v15, 0xffff0000, v77
	v_pk_mul_f32 v[94:95], v[94:95], v[102:103]
	v_pk_mul_f32 v[76:77], v[6:7], v[96:97]
	s_nop 0
	s_nop 0
	v_cvt_pk_bf16_f32 v97, v77, v95
	v_cvt_pk_bf16_f32 v96, v76, v94
	s_nop 0
	s_nop 0
	v_pk_mul_f32 v[6:7], v[18:19], v[84:85]
	v_or_b32_e32 v30, 1, v50
	v_pk_fma_f32 v[6:7], v[58:59], v[92:93], v[6:7]
	v_and_b32_e32 v39, 15, v38
	v_pk_fma_f32 v[6:7], v[22:23], v[10:11], v[6:7]
	s_nop 0
	v_pk_add_f32 v[92:93], v[26:27], v[6:7]
	s_nop 0
	v_mul_f32_e32 v6, 0xbfb8aa3b, v92
	v_exp_f32_e32 v31, v6
	v_pk_mul_f32 v[6:7], v[16:17], v[82:83]
	s_nop 0
	v_pk_fma_f32 v[6:7], v[4:5], v[100:101], v[6:7]
	s_nop 0
	v_pk_fma_f32 v[6:7], v[12:13], v[14:15], v[6:7]
	s_nop 0
	v_pk_add_f32 v[100:101], v[8:9], v[6:7]
	s_nop 0
	v_mul_f32_e32 v6, 0xbfb8aa3b, v100
	v_exp_f32_e32 v91, v6
	s_nop 0
	v_mad_u64_u32 v[6:7], s[28:29], v30, s81, v[90:91]
	v_add_f32_e32 v7, 1.0, v31
	v_mul_f32_e32 v31, 0xbfb8aa3b, v93
	v_rcp_f32_e32 v90, v7
	v_add_f32_e32 v7, 1.0, v91
	v_exp_f32_e32 v31, v31
	v_mul_f32_e32 v91, 0xbfb8aa3b, v101
	v_exp_f32_e32 v103, v91
	v_rcp_f32_e32 v102, v7
	v_add_f32_e32 v7, 1.0, v31
	v_rcp_f32_e32 v91, v7
	v_add_f32_e32 v7, 1.0, v103
	v_rcp_f32_e32 v103, v7
	ds_write_b64 v6, v[96:97]
	v_pk_mul_f32 v[90:91], v[92:93], v[90:91]
	s_mov_b32 s28, 0xffffff0
	v_pk_mul_f32 v[92:93], v[100:101], v[102:103]
	v_pk_mul_f32 v[90:91], v[90:91], s[48:49] op_sel_hi:[1,0]
	v_pk_mul_f32 v[92:93], v[92:93], s[48:49] op_sel_hi:[1,0]
	s_nop 0
	s_nop 0
	s_nop 0
	s_nop 0
	s_nop 0
	s_nop 0
	s_nop 0
	s_nop 0
	s_nop 0
	s_nop 0
	v_cvt_pk_bf16_f32 v97, v91, v93
	v_cvt_pk_bf16_f32 v96, v90, v92
	ds_write_b64 v6, v[96:97] offset:33792
	v_lshlrev_b32_e32 v97, 2, v30
	v_add_u32_e32 v7, s54, v97
	ds_read_b32 v96, v7
	v_add_u32_e32 v97, s55, v97
	ds_read_b32 v100, v97
	v_ashrrev_i32_e32 v31, 31, v30
	v_mul_u32_u24_e32 v7, 0x240, v99
	s_waitcnt lgkmcnt(1)
	v_pk_mul_f32 v[76:77], v[76:77], v[96:97] op_sel_hi:[1,0]
	v_pk_mul_f32 v[94:95], v[94:95], v[96:97] op_sel_hi:[1,0]
	v_and_b32_sdwa v96, v77, v98 dst_sel:DWORD dst_unused:UNUSED_PAD src0_sel:WORD_1 src1_sel:DWORD
	v_and_b32_sdwa v97, v76, v98 dst_sel:DWORD dst_unused:UNUSED_PAD src0_sel:WORD_1 src1_sel:DWORD
	v_add3_u32 v76, v76, v97, s79
	v_add3_u32 v77, v77, v96, s79
	v_and_b32_sdwa v96, v95, v98 dst_sel:DWORD dst_unused:UNUSED_PAD src0_sel:WORD_1 src1_sel:DWORD
	v_and_b32_sdwa v97, v94, v98 dst_sel:DWORD dst_unused:UNUSED_PAD src0_sel:WORD_1 src1_sel:DWORD
	v_add3_u32 v95, v95, v96, s79
	v_add3_u32 v94, v94, v97, s79
	v_and_b32_e32 v95, 0xffff0000, v95
	v_and_b32_e32 v94, 0xffff0000, v94
	v_or_b32_sdwa v95, v95, v77 dst_sel:DWORD dst_unused:UNUSED_PAD src0_sel:DWORD src1_sel:WORD_1
	v_or_b32_sdwa v94, v94, v76 dst_sel:DWORD dst_unused:UNUSED_PAD src0_sel:DWORD src1_sel:WORD_1
	v_lshlrev_b64 v[76:77], 9, v[30:31]
	s_waitcnt lgkmcnt(0)
	v_mul_f32_e32 v31, v90, v100
	v_lshl_add_u64 v[96:97], v[54:55], 0, v[76:77]
	v_lshlrev_b32_e32 v30, 1, v30
	v_bfe_u32 v76, v31, 16, 1
	v_add3_u32 v31, v31, v76, s79
	v_add_u32_e32 v76, v51, v30
	ds_write_b16_d16_hi v76, v31
	v_mul_f32_e32 v31, v92, v100
	v_bfe_u32 v76, v31, 16, 1
	v_add3_u32 v31, v31, v76, s79
	v_add3_u32 v30, s80, v30, v7
	ds_write_b16_d16_hi v30, v31 offset:144
	v_mul_f32_e32 v31, v91, v100
	v_bfe_u32 v76, v31, 16, 1
	v_add3_u32 v31, v31, v76, s79
	ds_write_b16_d16_hi v30, v31 offset:288
	v_mul_f32_e32 v31, v93, v100
	v_pk_mul_f32 v[92:93], v[64:65], v[80:81]
	v_lshlrev_b32_e32 v91, 16, v75
	v_lshlrev_b32_e32 v90, 16, v74
	v_pk_fma_f32 v[88:89], v[2:3], v[88:89], v[92:93]
	v_pk_mul_f32 v[92:93], v[28:29], v[78:79]
	v_bfe_u32 v76, v31, 16, 1
	v_and_b32_e32 v75, 0xffff0000, v75
	v_and_b32_e32 v74, 0xffff0000, v74
	v_pk_fma_f32 v[88:89], v[66:67], v[90:91], v[88:89]
	v_pk_fma_f32 v[86:87], v[32:33], v[86:87], v[92:93]
	v_add3_u32 v31, v31, v76, s79
	v_pk_add_f32 v[88:89], v[68:69], v[88:89]
	v_pk_fma_f32 v[86:87], v[20:21], v[74:75], v[86:87]
	ds_write_b16_d16_hi v30, v31 offset:432
	v_mul_f32_e32 v31, 0xbfb8aa3b, v88
	v_pk_add_f32 v[86:87], v[24:25], v[86:87]
	v_exp_f32_e32 v31, v31
	v_mul_f32_e32 v77, 0xbfb8aa3b, v86
	v_exp_f32_e32 v77, v77
	v_mul_f32_e32 v93, 0xbfb8aa3b, v87
	v_add_f32_e32 v31, 1.0, v31
	v_rcp_f32_e32 v92, v31
	v_add_f32_e32 v31, 1.0, v77
	v_mul_f32_e32 v77, 0xbfb8aa3b, v89
	v_exp_f32_e32 v77, v77
	v_exp_f32_e32 v101, v93
	v_rcp_f32_e32 v100, v31
	v_lshlrev_b32_e32 v76, 16, v72
	v_add_f32_e32 v31, 1.0, v77
	v_rcp_f32_e32 v93, v31
	v_add_f32_e32 v31, 1.0, v101
	v_rcp_f32_e32 v101, v31
	v_lshlrev_b32_e32 v77, 16, v73
	v_pk_mul_f32 v[88:89], v[88:89], v[92:93]
	v_and_b32_e32 v72, 0xffff0000, v72
	v_pk_mul_f32 v[86:87], v[86:87], v[100:101]
	v_and_b32_e32 v73, 0xffff0000, v73
	v_pk_mul_f32 v[100:101], v[18:19], v[10:11]
	v_pk_fma_f32 v[84:85], v[58:59], v[84:85], v[100:101]
	v_pk_mul_f32 v[100:101], v[16:17], v[14:15]
	v_cvt_pk_bf16_f32 v93, v89, v87
	s_nop 0
	v_pk_fma_f32 v[84:85], v[22:23], v[76:77], v[84:85]
	v_pk_fma_f32 v[82:83], v[4:5], v[82:83], v[100:101]
	v_pk_add_f32 v[84:85], v[26:27], v[84:85]
	v_pk_fma_f32 v[82:83], v[12:13], v[72:73], v[82:83]
	v_mul_f32_e32 v31, 0xbfb8aa3b, v84
	v_pk_add_f32 v[82:83], v[8:9], v[82:83]
	v_exp_f32_e32 v31, v31
	v_mul_f32_e32 v100, 0xbfb8aa3b, v82
	v_exp_f32_e32 v101, v100
	v_cvt_pk_bf16_f32 v92, v88, v86
	v_add_f32_e32 v31, 1.0, v31
	s_nop 0
	v_rcp_f32_e32 v100, v31
	v_add_f32_e32 v31, 1.0, v101
	v_mul_f32_e32 v101, 0xbfb8aa3b, v85
	v_exp_f32_e32 v101, v101
	v_mul_f32_e32 v102, 0xbfb8aa3b, v83
	v_exp_f32_e32 v103, v102
	v_rcp_f32_e32 v102, v31
	v_add_f32_e32 v31, 1.0, v101
	v_rcp_f32_e32 v101, v31
	v_add_f32_e32 v31, 1.0, v103
	v_rcp_f32_e32 v103, v31
	ds_write_b64 v6, v[92:93] offset:528
	v_pk_mul_f32 v[84:85], v[84:85], v[100:101]
	v_or_b32_e32 v30, 2, v50
	v_pk_mul_f32 v[82:83], v[82:83], v[102:103]
	v_pk_mul_f32 v[84:85], v[84:85], s[48:49] op_sel_hi:[1,0]
	v_pk_mul_f32 v[82:83], v[82:83], s[48:49] op_sel_hi:[1,0]
	s_nop 0
	v_cvt_pk_bf16_f32 v93, v85, v83
	s_nop 0
	v_cvt_pk_bf16_f32 v92, v84, v82
	s_nop 0
	s_nop 0
	ds_write_b64 v6, v[92:93] offset:34320
	v_lshlrev_b32_e32 v93, 2, v30
	v_add_u32_e32 v31, s54, v93
	v_add_u32_e32 v93, s55, v93
	ds_read_b32 v92, v31
	ds_read_b32 v93, v93
	global_store_dwordx2 v[96:97], v[94:95], off
	v_ashrrev_i32_e32 v31, 31, v30
	s_waitcnt lgkmcnt(0)
	v_pk_mul_f32 v[88:89], v[88:89], v[92:93] op_sel_hi:[1,0]
	v_pk_mul_f32 v[86:87], v[86:87], v[92:93] op_sel_hi:[1,0]
	v_and_b32_sdwa v92, v89, v98 dst_sel:DWORD dst_unused:UNUSED_PAD src0_sel:WORD_1 src1_sel:DWORD
	v_and_b32_sdwa v94, v88, v98 dst_sel:DWORD dst_unused:UNUSED_PAD src0_sel:WORD_1 src1_sel:DWORD
	v_add3_u32 v88, v88, v94, s79
	v_add3_u32 v89, v89, v92, s79
	v_and_b32_sdwa v92, v87, v98 dst_sel:DWORD dst_unused:UNUSED_PAD src0_sel:WORD_1 src1_sel:DWORD
	v_and_b32_sdwa v94, v86, v98 dst_sel:DWORD dst_unused:UNUSED_PAD src0_sel:WORD_1 src1_sel:DWORD
	v_add3_u32 v87, v87, v92, s79
	v_add3_u32 v86, v86, v94, s79
	v_and_b32_e32 v87, 0xffff0000, v87
	v_and_b32_e32 v86, 0xffff0000, v86
	v_or_b32_sdwa v87, v87, v89 dst_sel:DWORD dst_unused:UNUSED_PAD src0_sel:DWORD src1_sel:WORD_1
	v_or_b32_sdwa v86, v86, v88 dst_sel:DWORD dst_unused:UNUSED_PAD src0_sel:DWORD src1_sel:WORD_1
	v_lshlrev_b64 v[88:89], 9, v[30:31]
	v_mul_f32_e32 v31, v84, v93
	v_lshlrev_b32_e32 v30, 1, v30
	v_bfe_u32 v84, v31, 16, 1
	v_add3_u32 v31, v31, v84, s79
	v_add_u32_e32 v84, v51, v30
	ds_write_b16_d16_hi v84, v31
	v_mul_f32_e32 v31, v82, v93
	v_bfe_u32 v82, v31, 16, 1
	v_add3_u32 v31, v31, v82, s79
	v_add3_u32 v30, s80, v30, v7
	ds_write_b16_d16_hi v30, v31 offset:144
	v_mul_f32_e32 v31, v85, v93
	v_bfe_u32 v82, v31, 16, 1
	v_add3_u32 v31, v31, v82, s79
	ds_write_b16_d16_hi v30, v31 offset:288
	v_mul_f32_e32 v31, v83, v93
	v_bfe_u32 v82, v31, 16, 1
	v_pk_mul_f32 v[92:93], v[64:65], v[90:91]
	v_add3_u32 v31, v31, v82, s79
	v_lshlrev_b32_e32 v83, 16, v71
	v_lshlrev_b32_e32 v82, 16, v70
	v_pk_fma_f32 v[80:81], v[2:3], v[80:81], v[92:93]
	v_pk_mul_f32 v[92:93], v[28:29], v[74:75]
	v_and_b32_e32 v71, 0xffff0000, v71
	v_and_b32_e32 v70, 0xffff0000, v70
	v_pk_fma_f32 v[80:81], v[66:67], v[82:83], v[80:81]
	v_pk_fma_f32 v[78:79], v[32:33], v[78:79], v[92:93]
	v_pk_add_f32 v[80:81], v[68:69], v[80:81]
	v_pk_fma_f32 v[78:79], v[20:21], v[70:71], v[78:79]
	ds_write_b16_d16_hi v30, v31 offset:432
	v_mul_f32_e32 v31, 0xbfb8aa3b, v80
	v_pk_add_f32 v[78:79], v[24:25], v[78:79]
	v_exp_f32_e32 v31, v31
	v_mul_f32_e32 v85, 0xbfb8aa3b, v78
	v_exp_f32_e32 v85, v85
	v_mul_f32_e32 v93, 0xbfb8aa3b, v79
	v_add_f32_e32 v31, 1.0, v31
	v_rcp_f32_e32 v92, v31
	v_add_f32_e32 v31, 1.0, v85
	v_mul_f32_e32 v85, 0xbfb8aa3b, v81
	v_exp_f32_e32 v85, v85
	v_exp_f32_e32 v95, v93
	v_rcp_f32_e32 v94, v31
	v_lshlrev_b32_e32 v30, 16, v62
	v_add_f32_e32 v31, 1.0, v85
	v_rcp_f32_e32 v93, v31
	v_add_f32_e32 v31, 1.0, v95
	v_rcp_f32_e32 v95, v31
	v_lshlrev_b32_e32 v31, 16, v63
	v_pk_mul_f32 v[80:81], v[80:81], v[92:93]
	v_and_b32_e32 v62, 0xffff0000, v62
	v_pk_mul_f32 v[78:79], v[78:79], v[94:95]
	v_and_b32_e32 v63, 0xffff0000, v63
	v_pk_mul_f32 v[94:95], v[18:19], v[76:77]
	v_pk_fma_f32 v[10:11], v[58:59], v[10:11], v[94:95]
	v_pk_mul_f32 v[94:95], v[16:17], v[72:73]
	v_cvt_pk_bf16_f32 v93, v81, v79
	s_nop 0
	v_pk_fma_f32 v[10:11], v[22:23], v[30:31], v[10:11]
	v_pk_fma_f32 v[14:15], v[4:5], v[14:15], v[94:95]
	v_pk_add_f32 v[10:11], v[26:27], v[10:11]
	v_pk_fma_f32 v[14:15], v[12:13], v[62:63], v[14:15]
	v_mul_f32_e32 v85, 0xbfb8aa3b, v10
	v_pk_add_f32 v[14:15], v[8:9], v[14:15]
	v_exp_f32_e32 v85, v85
	v_mul_f32_e32 v94, 0xbfb8aa3b, v14
	v_exp_f32_e32 v95, v94
	v_cvt_pk_bf16_f32 v92, v80, v78
	v_add_f32_e32 v85, 1.0, v85
	s_nop 0
	v_rcp_f32_e32 v94, v85
	v_add_f32_e32 v85, 1.0, v95
	v_mul_f32_e32 v95, 0xbfb8aa3b, v11
	v_exp_f32_e32 v95, v95
	v_mul_f32_e32 v96, 0xbfb8aa3b, v15
	v_exp_f32_e32 v97, v96
	v_rcp_f32_e32 v96, v85
	v_add_f32_e32 v85, 1.0, v95
	v_rcp_f32_e32 v95, v85
	v_add_f32_e32 v85, 1.0, v97
	v_rcp_f32_e32 v97, v85
	ds_write_b64 v6, v[92:93] offset:1056
	v_pk_mul_f32 v[10:11], v[10:11], v[94:95]
	v_or_b32_e32 v84, 3, v50
	v_pk_mul_f32 v[14:15], v[14:15], v[96:97]
	v_pk_mul_f32 v[10:11], v[10:11], s[48:49] op_sel_hi:[1,0]
	v_pk_mul_f32 v[14:15], v[14:15], s[48:49] op_sel_hi:[1,0]
	s_nop 0
	v_cvt_pk_bf16_f32 v93, v11, v15
	s_nop 0
	v_cvt_pk_bf16_f32 v92, v10, v14
	s_nop 0
	s_nop 0
	ds_write_b64 v6, v[92:93] offset:34848
	v_lshlrev_b32_e32 v93, 2, v84
	v_add_u32_e32 v85, s54, v93
	ds_read_b32 v92, v85
	v_lshl_add_u64 v[88:89], v[54:55], 0, v[88:89]
	global_store_dwordx2 v[88:89], v[86:87], off
	v_add_u32_e32 v86, s55, v93
	ds_read_b32 v88, v86
	s_waitcnt lgkmcnt(1)
	v_pk_mul_f32 v[80:81], v[80:81], v[92:93] op_sel_hi:[1,0]
	v_pk_mul_f32 v[78:79], v[78:79], v[92:93] op_sel_hi:[1,0]
	v_and_b32_sdwa v86, v81, v98 dst_sel:DWORD dst_unused:UNUSED_PAD src0_sel:WORD_1 src1_sel:DWORD
	v_and_b32_sdwa v87, v80, v98 dst_sel:DWORD dst_unused:UNUSED_PAD src0_sel:WORD_1 src1_sel:DWORD
	v_add3_u32 v80, v80, v87, s79
	v_add3_u32 v81, v81, v86, s79
	v_and_b32_sdwa v86, v79, v98 dst_sel:DWORD dst_unused:UNUSED_PAD src0_sel:WORD_1 src1_sel:DWORD
	v_and_b32_sdwa v87, v78, v98 dst_sel:DWORD dst_unused:UNUSED_PAD src0_sel:WORD_1 src1_sel:DWORD
	v_add3_u32 v79, v79, v86, s79
	v_add3_u32 v78, v78, v87, s79
	v_ashrrev_i32_e32 v85, 31, v84
	v_and_b32_e32 v79, 0xffff0000, v79
	v_and_b32_e32 v78, 0xffff0000, v78
	v_or_b32_sdwa v81, v79, v81 dst_sel:DWORD dst_unused:UNUSED_PAD src0_sel:DWORD src1_sel:WORD_1
	v_or_b32_sdwa v80, v78, v80 dst_sel:DWORD dst_unused:UNUSED_PAD src0_sel:DWORD src1_sel:WORD_1
	v_lshlrev_b64 v[78:79], 9, v[84:85]
	s_waitcnt lgkmcnt(0)
	v_mul_f32_e32 v10, v10, v88
	v_lshl_add_u64 v[86:87], v[54:55], 0, v[78:79]
	v_lshlrev_b32_e32 v78, 1, v84
	v_bfe_u32 v79, v10, 16, 1
	v_add3_u32 v10, v10, v79, s79
	v_add_u32_e32 v79, v51, v78
	ds_write_b16_d16_hi v79, v10
	v_mul_f32_e32 v10, v14, v88
	v_bfe_u32 v14, v10, 16, 1
	v_add3_u32 v10, v10, v14, s79
	v_add3_u32 v14, s80, v78, v7
	ds_write_b16_d16_hi v14, v10 offset:144
	v_mul_f32_e32 v10, v11, v88
	v_bfe_u32 v11, v10, 16, 1
	v_add3_u32 v10, v10, v11, s79
	v_pk_mul_f32 v[84:85], v[64:65], v[82:83]
	ds_write_b16_d16_hi v14, v10 offset:288
	v_mul_f32_e32 v10, v15, v88
	v_lshlrev_b32_e32 v79, 16, v61
	v_lshlrev_b32_e32 v78, 16, v60
	v_pk_fma_f32 v[84:85], v[2:3], v[90:91], v[84:85]
	v_pk_mul_f32 v[88:89], v[28:29], v[70:71]
	v_and_b32_e32 v61, 0xffff0000, v61
	v_and_b32_e32 v60, 0xffff0000, v60
	v_pk_fma_f32 v[84:85], v[66:67], v[78:79], v[84:85]
	v_pk_fma_f32 v[74:75], v[32:33], v[74:75], v[88:89]
	v_bfe_u32 v11, v10, 16, 1
	v_pk_add_f32 v[84:85], v[68:69], v[84:85]
	v_pk_fma_f32 v[74:75], v[20:21], v[60:61], v[74:75]
	v_add3_u32 v10, v10, v11, s79
	v_mul_f32_e32 v11, 0xbfb8aa3b, v84
	v_pk_add_f32 v[74:75], v[24:25], v[74:75]
	v_exp_f32_e32 v11, v11
	v_mul_f32_e32 v15, 0xbfb8aa3b, v74
	v_exp_f32_e32 v15, v15
	v_mul_f32_e32 v89, 0xbfb8aa3b, v75
	v_add_f32_e32 v11, 1.0, v11
	v_rcp_f32_e32 v88, v11
	v_add_f32_e32 v11, 1.0, v15
	v_mul_f32_e32 v15, 0xbfb8aa3b, v85
	v_exp_f32_e32 v15, v15
	v_exp_f32_e32 v91, v89
	v_rcp_f32_e32 v90, v11
	ds_write_b16_d16_hi v14, v10 offset:432
	v_add_f32_e32 v11, 1.0, v15
	v_rcp_f32_e32 v89, v11
	v_add_f32_e32 v11, 1.0, v91
	v_rcp_f32_e32 v91, v11
	v_lshlrev_b32_e32 v14, 16, v56
	v_lshlrev_b32_e32 v15, 16, v57
	v_pk_mul_f32 v[84:85], v[84:85], v[88:89]
	v_pk_mul_f32 v[74:75], v[74:75], v[90:91]
	v_and_b32_e32 v56, 0xffff0000, v56
	v_pk_mul_f32 v[90:91], v[18:19], v[30:31]
	v_pk_fma_f32 v[76:77], v[58:59], v[76:77], v[90:91]
	v_pk_mul_f32 v[90:91], v[16:17], v[62:63]
	v_and_b32_e32 v57, 0xffff0000, v57
	v_cvt_pk_bf16_f32 v89, v85, v75
	s_nop 0
	v_pk_fma_f32 v[76:77], v[22:23], v[14:15], v[76:77]
	v_pk_fma_f32 v[72:73], v[4:5], v[72:73], v[90:91]
	v_pk_add_f32 v[76:77], v[26:27], v[76:77]
	v_pk_fma_f32 v[72:73], v[12:13], v[56:57], v[72:73]
	v_mul_f32_e32 v11, 0xbfb8aa3b, v76
	v_pk_add_f32 v[72:73], v[8:9], v[72:73]
	v_exp_f32_e32 v11, v11
	v_mul_f32_e32 v90, 0xbfb8aa3b, v72
	v_exp_f32_e32 v91, v90
	v_cvt_pk_bf16_f32 v88, v84, v74
	v_add_f32_e32 v11, 1.0, v11
	s_nop 0
	v_rcp_f32_e32 v90, v11
	v_add_f32_e32 v11, 1.0, v91
	v_mul_f32_e32 v91, 0xbfb8aa3b, v77
	v_exp_f32_e32 v91, v91
	v_mul_f32_e32 v92, 0xbfb8aa3b, v73
	v_exp_f32_e32 v93, v92
	v_rcp_f32_e32 v92, v11
	v_add_f32_e32 v11, 1.0, v91
	v_rcp_f32_e32 v91, v11
	v_add_f32_e32 v11, 1.0, v93
	v_rcp_f32_e32 v93, v11
	ds_write_b64 v6, v[88:89] offset:1584
	v_pk_mul_f32 v[76:77], v[76:77], v[90:91]
	v_or_b32_e32 v10, 4, v50
	v_pk_mul_f32 v[72:73], v[72:73], v[92:93]
	v_pk_mul_f32 v[76:77], v[76:77], s[48:49] op_sel_hi:[1,0]
	v_pk_mul_f32 v[72:73], v[72:73], s[48:49] op_sel_hi:[1,0]
	s_nop 0
	v_cvt_pk_bf16_f32 v89, v77, v73
	s_nop 0
	v_cvt_pk_bf16_f32 v88, v76, v72
	s_nop 0
	s_nop 0
	ds_write_b64 v6, v[88:89] offset:35376
	v_lshlrev_b32_e32 v89, 2, v10
	v_add_u32_e32 v11, s54, v89
	ds_read_b32 v88, v11
	global_store_dwordx2 v[86:87], v[80:81], off
	v_add_u32_e32 v80, s55, v89
	ds_read_b32 v86, v80
	v_ashrrev_i32_e32 v11, 31, v10
	s_waitcnt lgkmcnt(1)
	v_pk_mul_f32 v[80:81], v[84:85], v[88:89] op_sel_hi:[1,0]
	v_pk_mul_f32 v[74:75], v[74:75], v[88:89] op_sel_hi:[1,0]
	v_and_b32_sdwa v84, v81, v98 dst_sel:DWORD dst_unused:UNUSED_PAD src0_sel:WORD_1 src1_sel:DWORD
	v_and_b32_sdwa v85, v80, v98 dst_sel:DWORD dst_unused:UNUSED_PAD src0_sel:WORD_1 src1_sel:DWORD
	v_add3_u32 v80, v80, v85, s79
	v_add3_u32 v81, v81, v84, s79
	v_and_b32_sdwa v84, v75, v98 dst_sel:DWORD dst_unused:UNUSED_PAD src0_sel:WORD_1 src1_sel:DWORD
	v_and_b32_sdwa v85, v74, v98 dst_sel:DWORD dst_unused:UNUSED_PAD src0_sel:WORD_1 src1_sel:DWORD
	v_add3_u32 v75, v75, v84, s79
	v_add3_u32 v74, v74, v85, s79
	v_and_b32_e32 v75, 0xffff0000, v75
	v_and_b32_e32 v74, 0xffff0000, v74
	v_or_b32_sdwa v75, v75, v81 dst_sel:DWORD dst_unused:UNUSED_PAD src0_sel:DWORD src1_sel:WORD_1
	v_or_b32_sdwa v74, v74, v80 dst_sel:DWORD dst_unused:UNUSED_PAD src0_sel:DWORD src1_sel:WORD_1
	v_lshlrev_b64 v[80:81], 9, v[10:11]
	s_waitcnt lgkmcnt(0)
	v_mul_f32_e32 v11, v76, v86
	v_lshlrev_b32_e32 v10, 1, v10
	v_bfe_u32 v76, v11, 16, 1
	v_add3_u32 v11, v11, v76, s79
	v_add_u32_e32 v76, v51, v10
	ds_write_b16_d16_hi v76, v11
	v_mul_f32_e32 v11, v72, v86
	v_bfe_u32 v72, v11, 16, 1
	v_add3_u32 v11, v11, v72, s79
	v_add3_u32 v10, s80, v10, v7
	ds_write_b16_d16_hi v10, v11 offset:144
	v_mul_f32_e32 v11, v77, v86
	v_bfe_u32 v72, v11, 16, 1
	v_add3_u32 v11, v11, v72, s79
	ds_write_b16_d16_hi v10, v11 offset:288
	v_mul_f32_e32 v11, v73, v86
	v_bfe_u32 v72, v11, 16, 1
	v_pk_mul_f32 v[84:85], v[64:65], v[78:79]
	v_add3_u32 v11, v11, v72, s79
	v_lshlrev_b32_e32 v73, 16, v53
	v_lshlrev_b32_e32 v72, 16, v52
	v_pk_fma_f32 v[82:83], v[2:3], v[82:83], v[84:85]
	v_pk_mul_f32 v[84:85], v[28:29], v[60:61]
	v_and_b32_e32 v53, 0xffff0000, v53
	v_and_b32_e32 v52, 0xffff0000, v52
	v_pk_fma_f32 v[82:83], v[66:67], v[72:73], v[82:83]
	v_pk_fma_f32 v[70:71], v[32:33], v[70:71], v[84:85]
	v_pk_add_f32 v[82:83], v[68:69], v[82:83]
	v_pk_fma_f32 v[70:71], v[20:21], v[52:53], v[70:71]
	ds_write_b16_d16_hi v10, v11 offset:432
	v_mul_f32_e32 v11, 0xbfb8aa3b, v82
	v_pk_add_f32 v[70:71], v[24:25], v[70:71]
	v_exp_f32_e32 v11, v11
	v_mul_f32_e32 v77, 0xbfb8aa3b, v70
	v_exp_f32_e32 v77, v77
	v_mul_f32_e32 v85, 0xbfb8aa3b, v71
	v_add_f32_e32 v11, 1.0, v11
	v_rcp_f32_e32 v84, v11
	v_add_f32_e32 v11, 1.0, v77
	v_mul_f32_e32 v77, 0xbfb8aa3b, v83
	v_exp_f32_e32 v77, v77
	v_exp_f32_e32 v87, v85
	v_rcp_f32_e32 v86, v11
	v_lshlrev_b32_e32 v10, 16, v48
	v_add_f32_e32 v11, 1.0, v77
	v_rcp_f32_e32 v85, v11
	v_add_f32_e32 v11, 1.0, v87
	v_rcp_f32_e32 v87, v11
	v_lshlrev_b32_e32 v11, 16, v49
	v_pk_mul_f32 v[82:83], v[82:83], v[84:85]
	v_and_b32_e32 v48, 0xffff0000, v48
	v_pk_mul_f32 v[70:71], v[70:71], v[86:87]
	v_and_b32_e32 v49, 0xffff0000, v49
	v_pk_mul_f32 v[86:87], v[18:19], v[14:15]
	v_pk_fma_f32 v[30:31], v[58:59], v[30:31], v[86:87]
	v_pk_mul_f32 v[86:87], v[16:17], v[56:57]
	v_cvt_pk_bf16_f32 v85, v83, v71
	s_nop 0
	v_pk_fma_f32 v[30:31], v[22:23], v[10:11], v[30:31]
	v_pk_fma_f32 v[62:63], v[4:5], v[62:63], v[86:87]
	v_pk_add_f32 v[30:31], v[26:27], v[30:31]
	v_pk_fma_f32 v[62:63], v[12:13], v[48:49], v[62:63]
	v_mul_f32_e32 v77, 0xbfb8aa3b, v30
	v_pk_add_f32 v[62:63], v[8:9], v[62:63]
	v_exp_f32_e32 v77, v77
	v_mul_f32_e32 v86, 0xbfb8aa3b, v62
	v_exp_f32_e32 v87, v86
	v_cvt_pk_bf16_f32 v84, v82, v70
	v_add_f32_e32 v77, 1.0, v77
	s_nop 0
	v_rcp_f32_e32 v86, v77
	v_add_f32_e32 v77, 1.0, v87
	v_mul_f32_e32 v87, 0xbfb8aa3b, v31
	v_exp_f32_e32 v87, v87
	v_mul_f32_e32 v88, 0xbfb8aa3b, v63
	v_exp_f32_e32 v89, v88
	v_rcp_f32_e32 v88, v77
	v_add_f32_e32 v77, 1.0, v87
	v_rcp_f32_e32 v87, v77
	v_add_f32_e32 v77, 1.0, v89
	v_rcp_f32_e32 v89, v77
	ds_write_b64 v6, v[84:85] offset:2112
	v_pk_mul_f32 v[30:31], v[30:31], v[86:87]
	v_or_b32_e32 v76, 5, v50
	v_pk_mul_f32 v[62:63], v[62:63], v[88:89]
	v_pk_mul_f32 v[30:31], v[30:31], s[48:49] op_sel_hi:[1,0]
	v_pk_mul_f32 v[62:63], v[62:63], s[48:49] op_sel_hi:[1,0]
	s_nop 0
	v_cvt_pk_bf16_f32 v85, v31, v63
	s_nop 0
	v_cvt_pk_bf16_f32 v84, v30, v62
	s_nop 0
	s_nop 0
	ds_write_b64 v6, v[84:85] offset:35904
	v_lshlrev_b32_e32 v85, 2, v76
	v_add_u32_e32 v77, s54, v85
	ds_read_b32 v84, v77
	v_lshl_add_u64 v[80:81], v[54:55], 0, v[80:81]
	global_store_dwordx2 v[80:81], v[74:75], off
	v_add_u32_e32 v74, s55, v85
	ds_read_b32 v80, v74
	s_waitcnt lgkmcnt(1)
	v_pk_mul_f32 v[74:75], v[82:83], v[84:85] op_sel_hi:[1,0]
	v_pk_mul_f32 v[70:71], v[70:71], v[84:85] op_sel_hi:[1,0]
	v_and_b32_sdwa v81, v75, v98 dst_sel:DWORD dst_unused:UNUSED_PAD src0_sel:WORD_1 src1_sel:DWORD
	v_and_b32_sdwa v82, v74, v98 dst_sel:DWORD dst_unused:UNUSED_PAD src0_sel:WORD_1 src1_sel:DWORD
	v_add3_u32 v74, v74, v82, s79
	v_add3_u32 v75, v75, v81, s79
	v_and_b32_sdwa v81, v71, v98 dst_sel:DWORD dst_unused:UNUSED_PAD src0_sel:WORD_1 src1_sel:DWORD
	v_and_b32_sdwa v82, v70, v98 dst_sel:DWORD dst_unused:UNUSED_PAD src0_sel:WORD_1 src1_sel:DWORD
	v_add3_u32 v71, v71, v81, s79
	v_add3_u32 v70, v70, v82, s79
	v_ashrrev_i32_e32 v77, 31, v76
	v_and_b32_e32 v71, 0xffff0000, v71
	v_and_b32_e32 v70, 0xffff0000, v70
	s_waitcnt lgkmcnt(0)
	v_mul_f32_e32 v30, v30, v80
	v_or_b32_sdwa v71, v71, v75 dst_sel:DWORD dst_unused:UNUSED_PAD src0_sel:DWORD src1_sel:WORD_1
	v_or_b32_sdwa v70, v70, v74 dst_sel:DWORD dst_unused:UNUSED_PAD src0_sel:DWORD src1_sel:WORD_1
	v_lshlrev_b64 v[74:75], 9, v[76:77]
	v_lshlrev_b32_e32 v76, 1, v76
	v_bfe_u32 v77, v30, 16, 1
	v_add3_u32 v30, v30, v77, s79
	v_add_u32_e32 v77, v51, v76
	ds_write_b16_d16_hi v77, v30
	v_mul_f32_e32 v30, v62, v80
	v_bfe_u32 v62, v30, 16, 1
	v_add3_u32 v30, v30, v62, s79
	v_add3_u32 v62, s80, v76, v7
	ds_write_b16_d16_hi v62, v30 offset:144
	v_mul_f32_e32 v30, v31, v80
	v_bfe_u32 v31, v30, 16, 1
	v_add3_u32 v30, v30, v31, s79
	ds_write_b16_d16_hi v62, v30 offset:288
	v_mul_f32_e32 v30, v63, v80
	v_pk_mul_f32 v[80:81], v[64:65], v[72:73]
	v_lshlrev_b32_e32 v77, 16, v47
	v_lshlrev_b32_e32 v76, 16, v46
	v_pk_fma_f32 v[78:79], v[2:3], v[78:79], v[80:81]
	v_pk_mul_f32 v[80:81], v[28:29], v[52:53]
	v_and_b32_e32 v47, 0xffff0000, v47
	v_and_b32_e32 v46, 0xffff0000, v46
	v_pk_fma_f32 v[78:79], v[66:67], v[76:77], v[78:79]
	v_pk_fma_f32 v[60:61], v[32:33], v[60:61], v[80:81]
	v_bfe_u32 v31, v30, 16, 1
	v_pk_add_f32 v[78:79], v[68:69], v[78:79]
	v_pk_fma_f32 v[60:61], v[20:21], v[46:47], v[60:61]
	v_add3_u32 v30, v30, v31, s79
	v_mul_f32_e32 v31, 0xbfb8aa3b, v78
	v_pk_add_f32 v[60:61], v[24:25], v[60:61]
	v_exp_f32_e32 v31, v31
	v_mul_f32_e32 v63, 0xbfb8aa3b, v60
	v_exp_f32_e32 v63, v63
	v_mul_f32_e32 v81, 0xbfb8aa3b, v61
	v_add_f32_e32 v31, 1.0, v31
	v_rcp_f32_e32 v80, v31
	v_add_f32_e32 v31, 1.0, v63
	v_mul_f32_e32 v63, 0xbfb8aa3b, v79
	v_exp_f32_e32 v63, v63
	v_exp_f32_e32 v83, v81
	v_rcp_f32_e32 v82, v31
	ds_write_b16_d16_hi v62, v30 offset:432
	v_add_f32_e32 v31, 1.0, v63
	v_rcp_f32_e32 v81, v31
	v_add_f32_e32 v31, 1.0, v83
	v_rcp_f32_e32 v83, v31
	v_lshlrev_b32_e32 v62, 16, v44
	v_lshlrev_b32_e32 v63, 16, v45
	v_pk_mul_f32 v[78:79], v[78:79], v[80:81]
	v_pk_mul_f32 v[60:61], v[60:61], v[82:83]
	v_and_b32_e32 v44, 0xffff0000, v44
	v_pk_mul_f32 v[82:83], v[18:19], v[10:11]
	v_pk_fma_f32 v[14:15], v[58:59], v[14:15], v[82:83]
	v_pk_mul_f32 v[82:83], v[16:17], v[48:49]
	v_and_b32_e32 v45, 0xffff0000, v45
	v_cvt_pk_bf16_f32 v81, v79, v61
	s_nop 0
	v_pk_fma_f32 v[14:15], v[22:23], v[62:63], v[14:15]
	v_pk_fma_f32 v[56:57], v[4:5], v[56:57], v[82:83]
	v_pk_add_f32 v[14:15], v[26:27], v[14:15]
	v_pk_fma_f32 v[56:57], v[12:13], v[44:45], v[56:57]
	v_mul_f32_e32 v31, 0xbfb8aa3b, v14
	v_pk_add_f32 v[56:57], v[8:9], v[56:57]
	v_exp_f32_e32 v31, v31
	v_mul_f32_e32 v82, 0xbfb8aa3b, v56
	v_exp_f32_e32 v83, v82
	v_cvt_pk_bf16_f32 v80, v78, v60
	v_add_f32_e32 v31, 1.0, v31
	s_nop 0
	v_rcp_f32_e32 v82, v31
	v_add_f32_e32 v31, 1.0, v83
	v_mul_f32_e32 v83, 0xbfb8aa3b, v15
	v_exp_f32_e32 v83, v83
	v_mul_f32_e32 v84, 0xbfb8aa3b, v57
	v_exp_f32_e32 v85, v84
	v_rcp_f32_e32 v84, v31
	v_add_f32_e32 v31, 1.0, v83
	v_rcp_f32_e32 v83, v31
	v_add_f32_e32 v31, 1.0, v85
	v_rcp_f32_e32 v85, v31
	ds_write_b64 v6, v[80:81] offset:2640
	v_pk_mul_f32 v[14:15], v[14:15], v[82:83]
	v_or_b32_e32 v30, 6, v50
	v_pk_mul_f32 v[56:57], v[56:57], v[84:85]
	v_pk_mul_f32 v[14:15], v[14:15], s[48:49] op_sel_hi:[1,0]
	v_pk_mul_f32 v[56:57], v[56:57], s[48:49] op_sel_hi:[1,0]
	s_nop 0
	v_cvt_pk_bf16_f32 v81, v15, v57
	s_nop 0
	v_cvt_pk_bf16_f32 v80, v14, v56
	s_nop 0
	s_nop 0
	ds_write_b64 v6, v[80:81] offset:36432
	v_lshlrev_b32_e32 v81, 2, v30
	v_add_u32_e32 v31, s54, v81
	ds_read_b32 v80, v31
	v_lshl_add_u64 v[74:75], v[54:55], 0, v[74:75]
	global_store_dwordx2 v[74:75], v[70:71], off
	v_add_u32_e32 v70, s55, v81
	ds_read_b32 v74, v70
	s_waitcnt lgkmcnt(1)
	v_pk_mul_f32 v[70:71], v[78:79], v[80:81] op_sel_hi:[1,0]
	v_pk_mul_f32 v[60:61], v[60:61], v[80:81] op_sel_hi:[1,0]
	v_and_b32_sdwa v75, v71, v98 dst_sel:DWORD dst_unused:UNUSED_PAD src0_sel:WORD_1 src1_sel:DWORD
	v_and_b32_sdwa v78, v70, v98 dst_sel:DWORD dst_unused:UNUSED_PAD src0_sel:WORD_1 src1_sel:DWORD
	v_add3_u32 v70, v70, v78, s79
	v_add3_u32 v71, v71, v75, s79
	v_and_b32_sdwa v75, v61, v98 dst_sel:DWORD dst_unused:UNUSED_PAD src0_sel:WORD_1 src1_sel:DWORD
	v_and_b32_sdwa v78, v60, v98 dst_sel:DWORD dst_unused:UNUSED_PAD src0_sel:WORD_1 src1_sel:DWORD
	v_add3_u32 v61, v61, v75, s79
	v_add3_u32 v60, v60, v78, s79
	v_ashrrev_i32_e32 v31, 31, v30
	v_and_b32_e32 v61, 0xffff0000, v61
	v_and_b32_e32 v60, 0xffff0000, v60
	s_waitcnt lgkmcnt(0)
	v_mul_f32_e32 v14, v14, v74
	v_or_b32_sdwa v61, v61, v71 dst_sel:DWORD dst_unused:UNUSED_PAD src0_sel:DWORD src1_sel:WORD_1
	v_or_b32_sdwa v60, v60, v70 dst_sel:DWORD dst_unused:UNUSED_PAD src0_sel:DWORD src1_sel:WORD_1
	v_lshlrev_b64 v[70:71], 9, v[30:31]
	v_lshlrev_b32_e32 v30, 1, v30
	v_bfe_u32 v31, v14, 16, 1
	v_add3_u32 v14, v14, v31, s79
	v_add_u32_e32 v31, v51, v30
	ds_write_b16_d16_hi v31, v14
	v_mul_f32_e32 v14, v56, v74
	v_bfe_u32 v31, v14, 16, 1
	v_add3_u32 v14, v14, v31, s79
	v_add3_u32 v30, s80, v30, v7
	ds_write_b16_d16_hi v30, v14 offset:144
	v_mul_f32_e32 v14, v15, v74
	v_bfe_u32 v15, v14, 16, 1
	v_add3_u32 v14, v14, v15, s79
	ds_write_b16_d16_hi v30, v14 offset:288
	v_mul_f32_e32 v14, v57, v74
	v_bfe_u32 v15, v14, 16, 1
	v_add3_u32 v14, v14, v15, s79
	ds_write_b16_d16_hi v30, v14 offset:432
	v_or_b32_e32 v14, 7, v50
	v_add_u32_e32 v15, s91, v14
	v_and_b32_e32 v15, 0xffffefff, v15
	v_cmp_eq_u32_e32 vcc, s82, v15
	v_lshlrev_b32_e32 v56, 16, v42
	v_lshlrev_b32_e32 v57, 16, v43
	v_pk_mul_f32 v[64:65], v[64:65], v[76:77]
	v_cndmask_b32_e64 v30, 1.0, 0, vcc
	v_and_b32_e32 v42, 0xffff0000, v42
	v_and_b32_e32 v43, 0xffff0000, v43
	v_pk_fma_f32 v[2:3], v[2:3], v[72:73], v[64:65]
	v_pk_mul_f32 v[56:57], v[66:67], v[56:57]
	v_pk_mul_f32 v[28:29], v[28:29], v[46:47]
	v_pk_fma_f32 v[2:3], v[56:57], v[30:31], v[2:3] op_sel_hi:[1,0,1]
	v_pk_fma_f32 v[28:29], v[32:33], v[52:53], v[28:29]
	v_pk_mul_f32 v[20:21], v[20:21], v[42:43]
	v_pk_add_f32 v[2:3], v[68:69], v[2:3]
	v_pk_fma_f32 v[20:21], v[20:21], v[30:31], v[28:29] op_sel_hi:[1,0,1]
	v_mul_f32_e32 v15, 0xbfb8aa3b, v2
	v_pk_add_f32 v[20:21], v[24:25], v[20:21]
	v_exp_f32_e32 v15, v15
	v_mul_f32_e32 v24, 0xbfb8aa3b, v20
	v_exp_f32_e32 v25, v24
	v_mul_f32_e32 v28, 0xbfb8aa3b, v21
	v_add_f32_e32 v15, 1.0, v15
	v_rcp_f32_e32 v24, v15
	v_add_f32_e32 v15, 1.0, v25
	v_mul_f32_e32 v25, 0xbfb8aa3b, v3
	v_exp_f32_e32 v25, v25
	v_exp_f32_e32 v29, v28
	v_rcp_f32_e32 v28, v15
	v_lshlrev_b32_e32 v75, 16, v41
	v_add_f32_e32 v15, 1.0, v25
	v_rcp_f32_e32 v25, v15
	v_add_f32_e32 v15, 1.0, v29
	v_rcp_f32_e32 v29, v15
	v_lshlrev_b32_e32 v74, 16, v40
	v_pk_mul_f32 v[18:19], v[18:19], v[62:63]
	v_pk_mul_f32 v[2:3], v[2:3], v[24:25]
	v_pk_mul_f32 v[20:21], v[20:21], v[28:29]
	v_pk_fma_f32 v[10:11], v[58:59], v[10:11], v[18:19]
	v_pk_mul_f32 v[18:19], v[22:23], v[74:75]
	v_and_b32_e32 v33, 0xffff0000, v41
	v_and_b32_e32 v32, 0xffff0000, v40
	v_cvt_pk_bf16_f32 v25, v3, v21
	s_nop 0
	v_pk_fma_f32 v[10:11], v[30:31], v[18:19], v[10:11] op_sel_hi:[0,1,1]
	v_pk_mul_f32 v[16:17], v[16:17], v[44:45]
	s_nop 0
	v_pk_add_f32 v[10:11], v[26:27], v[10:11]
	v_pk_fma_f32 v[4:5], v[4:5], v[48:49], v[16:17]
	v_pk_mul_f32 v[12:13], v[12:13], v[32:33]
	v_mul_f32_e32 v15, 0xbfb8aa3b, v10
	v_pk_fma_f32 v[4:5], v[30:31], v[12:13], v[4:5] op_sel_hi:[0,1,1]
	v_exp_f32_e32 v15, v15
	v_pk_add_f32 v[4:5], v[8:9], v[4:5]
	v_mul_f32_e32 v12, 0xbfb8aa3b, v11
	v_mul_f32_e32 v8, 0xbfb8aa3b, v4
	v_exp_f32_e32 v9, v8
	v_exp_f32_e32 v13, v12
	v_mul_f32_e32 v12, 0xbfb8aa3b, v5
	v_add_f32_e32 v8, 1.0, v15
	v_exp_f32_e32 v15, v12
	v_add_f32_e32 v9, 1.0, v9
	v_rcp_f32_e32 v12, v9
	v_add_f32_e32 v9, 1.0, v13
	v_rcp_f32_e32 v8, v8
	v_rcp_f32_e32 v9, v9
	v_add_f32_e32 v13, 1.0, v15
	v_rcp_f32_e32 v13, v13
	v_cvt_pk_bf16_f32 v24, v2, v20
	v_pk_mul_f32 v[8:9], v[10:11], v[8:9]
	s_nop 0
	v_pk_mul_f32 v[8:9], v[8:9], s[48:49] op_sel_hi:[1,0]
	v_pk_mul_f32 v[4:5], v[4:5], v[12:13]
	s_nop 0
	v_pk_mul_f32 v[4:5], v[4:5], s[48:49] op_sel_hi:[1,0]
	s_nop 0
	s_nop 0
	s_nop 0
	v_cvt_pk_bf16_f32 v11, v9, v5
	s_nop 0
	s_nop 0
	s_nop 0
	s_nop 0
	s_nop 0
	s_nop 0
	s_nop 0
	s_nop 0
	s_nop 0
	v_cvt_pk_bf16_f32 v10, v8, v4
	s_nop 0
	ds_write_b64 v6, v[10:11] offset:36960
	v_lshlrev_b32_e32 v10, 2, v14
	ds_write_b64 v6, v[24:25] offset:3168
	v_add_u32_e32 v6, s54, v10
	ds_read_b32 v6, v6
	v_add_u32_e32 v10, s55, v10
	ds_read_b32 v12, v10
	v_ashrrev_i32_e32 v15, 31, v14
	v_lshl_add_u64 v[70:71], v[54:55], 0, v[70:71]
	s_waitcnt lgkmcnt(1)
	v_pk_mul_f32 v[2:3], v[2:3], v[6:7] op_sel_hi:[1,0]
	v_pk_mul_f32 v[10:11], v[20:21], v[6:7] op_sel_hi:[1,0]
	v_and_b32_sdwa v13, v2, v98 dst_sel:DWORD dst_unused:UNUSED_PAD src0_sel:WORD_1 src1_sel:DWORD
	v_and_b32_sdwa v6, v3, v98 dst_sel:DWORD dst_unused:UNUSED_PAD src0_sel:WORD_1 src1_sel:DWORD
	v_add3_u32 v2, v2, v13, s79
	v_and_b32_sdwa v13, v10, v98 dst_sel:DWORD dst_unused:UNUSED_PAD src0_sel:WORD_1 src1_sel:DWORD
	v_add3_u32 v3, v3, v6, s79
	v_and_b32_sdwa v6, v11, v98 dst_sel:DWORD dst_unused:UNUSED_PAD src0_sel:WORD_1 src1_sel:DWORD
	v_add3_u32 v10, v10, v13, s79
	v_add3_u32 v6, v11, v6, s79
	v_and_b32_e32 v10, 0xffff0000, v10
	v_and_b32_e32 v6, 0xffff0000, v6
	v_or_b32_sdwa v2, v10, v2 dst_sel:DWORD dst_unused:UNUSED_PAD src0_sel:DWORD src1_sel:WORD_1
	v_lshlrev_b64 v[10:11], 9, v[14:15]
	v_or_b32_sdwa v3, v6, v3 dst_sel:DWORD dst_unused:UNUSED_PAD src0_sel:DWORD src1_sel:WORD_1
	v_lshl_add_u64 v[10:11], v[54:55], 0, v[10:11]
	global_store_dwordx2 v[10:11], v[2:3], off
	s_waitcnt lgkmcnt(0)
	v_mul_f32_e32 v3, v8, v12
	v_lshlrev_b32_e32 v2, 1, v14
	v_bfe_u32 v6, v3, 16, 1
	v_add3_u32 v3, v3, v6, s79
	v_add_u32_e32 v6, v51, v2
	ds_write_b16_d16_hi v6, v3
	v_mul_f32_e32 v3, v4, v12
	v_bfe_u32 v4, v3, 16, 1
	v_add3_u32 v3, v3, v4, s79
	v_add3_u32 v2, s80, v2, v7
	ds_write_b16_d16_hi v2, v3 offset:144
	v_mul_f32_e32 v3, v9, v12
	v_bfe_u32 v4, v3, 16, 1
	v_add3_u32 v3, v3, v4, s79
	ds_write_b16_d16_hi v2, v3 offset:288
	v_mul_f32_e32 v3, v5, v12
	v_bfe_u32 v4, v3, 16, 1
	v_add3_u32 v3, v3, v4, s79
	ds_write_b16_d16_hi v2, v3 offset:432
	v_and_b32_e32 v3, 48, v99
	v_and_or_b32 v2, v50, s28, v39
	v_add_u32_e32 v6, 0, v3
	v_mad_u64_u32 v[32:33], s[28:29], v2, s81, v[6:7]
	global_store_dwordx2 v[70:71], v[60:61], off
	s_waitcnt lgkmcnt(0)
	s_barrier
	ds_read_b128 v[2:5], v32
	v_and_or_b32 v10, v34, 32, v39
	v_mad_u32_u24 v11, v10, s81, v6
	ds_read_b128 v[12:15], v32 offset:64
	ds_read_b128 v[6:9], v11 offset:33792
	ds_read_b128 v[16:19], v11 offset:33856
	ds_read_b128 v[20:23], v32 offset:128
	s_waitcnt lgkmcnt(2)
	v_mfma_f32_16x16x32_bf16 v[6:9], v[2:5], v[6:9], 0
	s_add_i32 s28, 0, 0x1bd00
	s_waitcnt lgkmcnt(1)
	v_mfma_f32_16x16x32_bf16 v[6:9], v[12:15], v[16:19], v[6:9]
	ds_read_b128 v[16:19], v32 offset:192
	ds_read_b128 v[24:27], v11 offset:33920
	ds_read_b128 v[28:31], v11 offset:33984
	s_waitcnt lgkmcnt(1)
	v_mfma_f32_16x16x32_bf16 v[6:9], v[20:23], v[24:27], v[6:9]
	ds_read_b128 v[24:27], v32 offset:256
	s_waitcnt lgkmcnt(1)
	v_mfma_f32_16x16x32_bf16 v[6:9], v[16:19], v[28:31], v[6:9]
	ds_read_b128 v[28:31], v32 offset:320
	ds_read_b128 v[40:43], v11 offset:34048
	ds_read_b128 v[44:47], v11 offset:34112
	s_waitcnt lgkmcnt(1)
	v_mfma_f32_16x16x32_bf16 v[6:9], v[24:27], v[40:43], v[6:9]
	ds_read_b128 v[40:43], v32 offset:384
	s_waitcnt lgkmcnt(1)
	v_mfma_f32_16x16x32_bf16 v[6:9], v[28:31], v[44:47], v[6:9]
	ds_read_b128 v[44:47], v32 offset:448
	ds_read_b128 v[48:51], v11 offset:34176
	ds_read_b128 v[52:55], v11 offset:34240
	s_waitcnt lgkmcnt(1)
	v_mfma_f32_16x16x32_bf16 v[6:9], v[40:43], v[48:51], v[6:9]
	s_waitcnt lgkmcnt(0)
	v_mfma_f32_16x16x32_bf16 v[6:9], v[44:47], v[52:55], v[6:9]
	ds_read_b128 v[48:51], v11 offset:42240
	ds_read_b128 v[52:55], v11 offset:42304
	s_waitcnt lgkmcnt(1)
	v_mfma_f32_16x16x32_bf16 v[2:5], v[2:5], v[48:51], 0
	s_waitcnt lgkmcnt(0)
	v_mfma_f32_16x16x32_bf16 v[2:5], v[12:15], v[52:55], v[2:5]
	ds_read_b128 v[12:15], v11 offset:42368
	ds_read_b128 v[48:51], v11 offset:42432
	s_waitcnt lgkmcnt(1)
	v_mfma_f32_16x16x32_bf16 v[2:5], v[20:23], v[12:15], v[2:5]
	s_waitcnt lgkmcnt(0)
	v_mfma_f32_16x16x32_bf16 v[2:5], v[16:19], v[48:51], v[2:5]
	ds_read_b128 v[12:15], v11 offset:42496
	ds_read_b128 v[16:19], v11 offset:42560
	s_waitcnt lgkmcnt(1)
	v_mfma_f32_16x16x32_bf16 v[2:5], v[24:27], v[12:15], v[2:5]
	s_waitcnt lgkmcnt(0)
	v_mfma_f32_16x16x32_bf16 v[2:5], v[28:31], v[16:19], v[2:5]
	ds_read_b128 v[12:15], v11 offset:42624
	ds_read_b128 v[16:19], v11 offset:42688
	v_ashrrev_i32_e32 v11, 3, v38
	v_and_b32_e32 v11, -16, v11
	s_waitcnt lgkmcnt(1)
	v_mfma_f32_16x16x32_bf16 v[2:5], v[40:43], v[12:15], v[2:5]
	v_lshrrev_b32_e32 v12, 2, v99
	v_and_or_b32 v11, v12, 12, v11
	v_cmp_le_i32_e32 vcc, v10, v11
	s_waitcnt lgkmcnt(0)
	v_mfma_f32_16x16x32_bf16 v[2:5], v[44:47], v[16:19], v[2:5]
	v_mov_b32_e32 v15, 0
	v_cndmask_b32_e64 v12, 0, 1, vcc
	v_cmp_ge_i32_e32 vcc, v10, v11
	v_lshl_add_u32 v19, v10, 2, s28
	s_nop 0
	v_cndmask_b32_e64 v13, 0, 1, vcc
	v_cndmask_b32_e64 v12, v13, v12, s[6:7]
	v_and_b32_e32 v12, 1, v12
	v_cmp_eq_u32_e32 vcc, 1, v12
	v_lshl_add_u32 v12, v11, 2, 0
	v_mov_b32_e32 v13, 0
	s_and_saveexec_b64 s[54:55], vcc
	s_cbranch_execz .LBB0_3807
	v_add_u32_e32 v13, 0x1bc00, v12
	ds_read_b32 v13, v13
	ds_read_b32 v14, v19
	s_waitcnt lgkmcnt(0)
	v_add_f32_e32 v13, v13, v14
	v_mul_f32_e32 v13, 0x3fb8aa3b, v13
	v_exp_f32_e32 v13, v13
	s_nop 0
	v_mul_f32_e32 v13, v6, v13

.LBB0_3842:
	v_add_u32_e32 v27, 0x400, v26
	v_lshlrev_b32_e32 v38, 16, v10
	ds_read2_b32 v[30:31], v26 offset1:65
	ds_read2_b32 v[32:33], v26 offset0:130 offset1:195
	ds_read2_b32 v[34:35], v27 offset0:4 offset1:69
	ds_read2_b32 v[36:37], v27 offset0:134 offset1:199
	v_mul_f32_e32 v27, 0xbfb8aa3b, v38
	v_exp_f32_e32 v27, v27
	v_lshlrev_b32_e32 v39, 16, v11
	v_mul_f32_e32 v40, 0xbfb8aa3b, v39
	v_exp_f32_e32 v41, v40
	v_and_b32_e32 v10, 0xffff0000, v10
	v_add_f32_e32 v27, 1.0, v27
	v_and_b32_e32 v11, 0xffff0000, v11
	v_rcp_f32_e32 v40, v27
	v_mul_f32_e32 v27, 0xbfb8aa3b, v10
	v_exp_f32_e32 v27, v27
	v_add_f32_e32 v41, 1.0, v41
	v_mul_f32_e32 v42, 0xbfb8aa3b, v11
	v_rcp_f32_e32 v41, v41
	v_exp_f32_e32 v43, v42
	v_add_f32_e32 v27, 1.0, v27
	v_rcp_f32_e32 v42, v27
	v_pk_mul_f32 v[38:39], v[40:41], v[38:39]
	v_add_f32_e32 v27, 1.0, v43
	s_waitcnt lgkmcnt(3)
	v_mov_b32_e32 v40, v30
	v_lshlrev_b32_e32 v30, 16, v12
	v_rcp_f32_e32 v43, v27
	v_mul_f32_e32 v27, 0xbfb8aa3b, v30
	v_exp_f32_e32 v27, v27
	s_waitcnt lgkmcnt(2)
	v_mov_b32_e32 v41, v32
	v_pk_mul_f32 v[10:11], v[42:43], v[10:11]
	v_mov_b32_e32 v32, v31
	v_lshlrev_b32_e32 v31, 16, v13
	v_pk_mul_f32 v[10:11], v[10:11], v[32:33]
	v_and_b32_e32 v12, 0xffff0000, v12
	v_add_f32_e32 v27, 1.0, v27
	v_mul_f32_e32 v32, 0xbfb8aa3b, v31
	v_and_b32_e32 v13, 0xffff0000, v13
	v_exp_f32_e32 v33, v32
	v_rcp_f32_e32 v32, v27
	v_mul_f32_e32 v27, 0xbfb8aa3b, v12
	v_pk_mul_f32 v[38:39], v[38:39], v[40:41]
	v_exp_f32_e32 v27, v27
	v_mul_f32_e32 v40, 0xbfb8aa3b, v13
	v_exp_f32_e32 v41, v40
	v_add_f32_e32 v33, 1.0, v33
	v_add_f32_e32 v27, 1.0, v27
	v_rcp_f32_e32 v40, v27
	v_add_f32_e32 v27, 1.0, v41
	v_rcp_f32_e32 v33, v33
	v_rcp_f32_e32 v41, v27
	s_and_b32 s4, s33, 0xffffffc0
	v_add_u32_e32 v28, s4, v23
	v_pk_mul_f32 v[30:31], v[32:33], v[30:31]
	s_waitcnt lgkmcnt(0)
	v_mov_b32_e32 v33, v36
	v_pk_mul_f32 v[12:13], v[40:41], v[12:13]
	v_mov_b32_e32 v36, v35
	v_mov_b32_e32 v32, v34
	v_pk_mul_f32 v[12:13], v[12:13], v[36:37]
	v_ashrrev_i32_e32 v29, 31, v28
	v_pk_mul_f32 v[30:31], v[30:31], v[32:33]
	v_bfe_u32 v27, v13, 16, 1
	v_bfe_u32 v32, v12, 16, 1
	v_cvt_pk_bf16_f32 v11, v39, v11
	v_cvt_pk_bf16_f32 v10, v38, v10
	s_and_b32 s14, s31, 0x3c0
	v_add3_u32 v12, v12, v32, s19
	v_add3_u32 v13, v13, v27, s19
	v_bfe_u32 v33, v30, 16, 1
	v_bfe_u32 v34, v31, 16, 1
	v_lshlrev_b64 v[28:29], 13, v[28:29]
	v_add3_u32 v31, v31, v34, s19
	v_add3_u32 v30, v30, v33, s19
	v_lshl_add_u64 v[28:29], s[12:13], 0, v[28:29]
	s_lshl_b32 s4, s14, 1
	v_lshrrev_b32_e32 v30, 16, v30
	v_lshrrev_b32_e32 v31, 16, v31
	v_lshl_add_u64 v[28:29], v[28:29], 0, s[4:5]
	v_and_or_b32 v13, v13, s18, v31
	v_and_or_b32 v12, v12, s18, v30
	v_lshl_add_u64 v[28:29], v[28:29], 0, v[18:19]
	global_store_dwordx4 v[28:29], v[10:13], off offset:2048
	s_waitcnt lgkmcnt(0)
	s_barrier
	s_andn2_b64 vcc, exec, s[6:7]
	s_mov_b32 s31, s21
	s_waitcnt vmcnt(1)
	v_mov_b64_e32 v[10:11], v[14:15]
	s_mov_b32 s33, s20
	v_mov_b64_e32 v[12:13], v[16:17]
	s_cbranch_vccz .LBB0_3847

.LBB0_3906:
	ds_read2_b32 v[20:21], v18 offset1:65
	ds_read2_b32 v[22:23], v18 offset0:130 offset1:195
	v_add_u32_e32 v19, 0x400, v18
	ds_read2_b32 v[26:27], v19 offset0:4 offset1:69
	ds_read2_b32 v[28:29], v19 offset0:134 offset1:199
	s_and_b32 s8, s46, 0xffffffc0
	s_waitcnt lgkmcnt(3)
	s_nop 0
	v_cvt_pk_bf16_f32 v20, v20, v21
	s_waitcnt lgkmcnt(2)
	v_cvt_pk_bf16_f32 v21, v22, v23
	s_waitcnt lgkmcnt(1)
	v_cvt_pk_bf16_f32 v22, v26, v27
	v_add_u32_e32 v24, s8, v15
	v_ashrrev_i32_e32 v25, 31, v24
	s_and_b32 s0, s0, 0x3c0
	s_waitcnt lgkmcnt(0)
	v_cvt_pk_bf16_f32 v23, v28, v29
	v_lshlrev_b64 v[24:25], 11, v[24:25]
	v_lshl_add_u64 v[24:25], s[14:15], 0, v[24:25]
	s_lshl_b32 s0, s0, 1
	v_lshl_add_u64 v[24:25], v[24:25], 0, s[0:1]
	v_lshl_add_u64 v[24:25], v[24:25], 0, v[10:11]
	global_store_dwordx4 v[24:25], v[20:23], off
	s_waitcnt lgkmcnt(0)
	s_barrier
	s_andn2_b64 vcc, exec, s[6:7]
	s_mov_b32 s0, s47
	s_mov_b32 s46, s45
	s_cbranch_vccz .LBB0_3911

.LBB0_3970:
	ds_read2_b32 v[20:21], v18 offset1:65
	ds_read2_b32 v[22:23], v18 offset0:130 offset1:195
	v_add_u32_e32 v19, 0x400, v18
	ds_read2_b32 v[26:27], v19 offset0:4 offset1:69
	ds_read2_b32 v[28:29], v19 offset0:134 offset1:199
	s_and_b32 s0, s10, 0xffffffc0
	s_waitcnt lgkmcnt(3)
	s_nop 0
	v_cvt_pk_bf16_f32 v20, v20, v21
	s_waitcnt lgkmcnt(2)
	v_cvt_pk_bf16_f32 v21, v22, v23
	s_waitcnt lgkmcnt(1)
	v_cvt_pk_bf16_f32 v22, v26, v27
	v_add_u32_e32 v24, s0, v15
	v_ashrrev_i32_e32 v25, 31, v24
	s_and_b32 s3, s3, 0x3c0
	s_waitcnt lgkmcnt(0)
	v_cvt_pk_bf16_f32 v23, v28, v29
	v_lshlrev_b64 v[24:25], 11, v[24:25]
	v_lshl_add_u64 v[24:25], s[14:15], 0, v[24:25]
	s_lshl_b32 s0, s3, 1
	v_lshl_add_u64 v[24:25], v[24:25], 0, s[0:1]
	v_lshl_add_u64 v[24:25], v[24:25], 0, v[10:11]
	global_store_dwordx4 v[24:25], v[20:23], off
	s_waitcnt lgkmcnt(0)
	s_barrier
	s_andn2_b64 vcc, exec, s[4:5]
	s_mov_b32 s3, s19
	s_mov_b32 s10, s17
	s_cbranch_vccz .LBB0_3975

.LBB0_4050:
	v_pk_add_f32 v[28:29], v[28:29], v[32:33]
	v_pk_add_f32 v[30:31], v[30:31], v[34:35]
	v_pk_mul_f32 v[34:35], v[28:29], v[28:29]
	v_pk_mul_f32 v[32:33], v[30:31], v[30:31]
	v_add_f32_e32 v34, v34, v35
	v_add_f32_e32 v32, v32, v34
	v_add_f32_e32 v32, v33, v32
	ds_bpermute_b32 v33, v1, v32
	v_pk_add_f32 v[22:23], v[22:23], v[26:27]
	v_pk_add_f32 v[20:21], v[20:21], v[24:25]
	v_lshlrev_b32_e32 v25, 16, v60
	v_mul_f32_e32 v25, 0xbfb8aa3b, v25
	s_waitcnt lgkmcnt(0)
	v_add_f32_e32 v26, v32, v33
	ds_bpermute_b32 v27, v62, v26
	v_and_b32_e32 v32, 0xffff0000, v60
	v_exp_f32_e32 v25, v25
	v_lshlrev_b32_e32 v33, 16, v61
	v_and_b32_e32 v34, 0xffff0000, v61
	s_waitcnt lgkmcnt(0)
	v_add_f32_e32 v26, v26, v27
	ds_bpermute_b32 v27, v63, v26
	v_add_f32_e32 v25, 1.0, v25
	v_mul_f32_e32 v33, 0xbfb8aa3b, v33
	v_mul_f32_e32 v34, 0xbfb8aa3b, v34
	v_lshlrev_b32_e32 v24, 16, v58
	s_waitcnt lgkmcnt(0)
	v_add_f32_e32 v26, v26, v27
	ds_bpermute_b32 v27, v64, v26
	v_exp_f32_e32 v33, v33
	v_exp_f32_e32 v34, v34
	v_mul_f32_e32 v35, 0xbfb8aa3b, v24
	v_exp_f32_e32 v35, v35
	s_waitcnt lgkmcnt(0)
	v_add_f32_e32 v26, v26, v27
	ds_bpermute_b32 v27, v65, v26
	v_add_f32_e32 v33, 1.0, v33
	v_add_f32_e32 v34, 1.0, v34
	v_and_b32_e32 v58, 0xffff0000, v58
	v_add_f32_e32 v35, 1.0, v35
	s_waitcnt lgkmcnt(0)
	v_add_f32_e32 v27, v26, v27
	ds_bpermute_b32 v60, v66, v27
	v_rcp_f32_e32 v26, v25
	v_mov_b32_e32 v72, v20
	v_mul_f32_e32 v32, 0xbfb8aa3b, v32
	v_exp_f32_e32 v32, v32
	s_waitcnt lgkmcnt(0)
	v_add_f32_e32 v25, v27, v60
	v_fmamk_f32 v25, v25, 0x3b800000, v67
	v_mul_f32_e32 v27, 0x4b800000, v25
	v_cmp_gt_f32_e32 vcc, s3, v25
	v_mul_f32_e32 v60, 0xbfb8aa3b, v58
	v_exp_f32_e32 v61, v60
	v_cndmask_b32_e32 v25, v25, v27, vcc
	v_rsq_f32_e32 v25, v25
	v_rcp_f32_e32 v27, v33
	v_rcp_f32_e32 v33, v34
	v_rcp_f32_e32 v60, v35
	v_mul_f32_e32 v34, 0x45800000, v25
	v_cndmask_b32_e32 v34, v25, v34, vcc
	v_lshlrev_b32_e32 v25, 16, v59
	v_mul_f32_e32 v35, 0xbfb8aa3b, v25
	v_exp_f32_e32 v35, v35
	v_and_b32_e32 v59, 0xffff0000, v59
	v_add_f32_e32 v61, 1.0, v61
	v_rcp_f32_e32 v70, v61
	v_add_f32_e32 v20, 1.0, v35
	v_rcp_f32_e32 v61, v20
	v_mul_f32_e32 v20, 0xbfb8aa3b, v59
	v_exp_f32_e32 v20, v20
	v_add_f32_e32 v32, 1.0, v32
	v_rcp_f32_e32 v32, v32
	v_mov_b32_e32 v73, v22
	v_add_f32_e32 v20, 1.0, v20
	v_rcp_f32_e32 v71, v20
	v_pk_mul_f32 v[26:27], v[72:73], v[26:27]
	v_pk_mul_f32 v[24:25], v[60:61], v[24:25]
	v_mov_b32_e32 v22, v21
	v_pk_mul_f32 v[24:25], v[26:27], v[24:25]
	v_pk_mul_f32 v[20:21], v[22:23], v[32:33]
	v_pk_mul_f32 v[22:23], v[70:71], v[58:59]
	v_lshl_add_u64 v[40:41], v[40:41], 0, s[0:1]
	v_pk_mul_f32 v[20:21], v[20:21], v[22:23]
	s_nop 0
	v_and_b32_sdwa v23, v24, v68 dst_sel:DWORD dst_unused:UNUSED_PAD src0_sel:WORD_1 src1_sel:DWORD
	v_add3_u32 v23, v24, v23, s11
	s_nop 0
	v_cvt_pk_bf16_f32 v21, v25, v21
	v_and_b32_sdwa v25, v20, v68 dst_sel:DWORD dst_unused:UNUSED_PAD src0_sel:WORD_1 src1_sel:DWORD
	s_nop 0
	v_add3_u32 v20, v20, v25, s11
	s_nop 0
	v_and_b32_e32 v20, 0xffff0000, v20
	s_nop 0
	v_or_b32_sdwa v20, v20, v23 dst_sel:DWORD dst_unused:UNUSED_PAD src0_sel:DWORD src1_sel:WORD_1
	v_lshl_add_u64 v[22:23], v[50:51], 0, v[36:37]
	v_add_co_u32_e32 v22, vcc, s10, v22
	v_and_b32_e32 v24, 0xffff0000, v44
	s_nop 0
	v_addc_co_u32_e32 v23, vcc, 0, v23, vcc
	global_store_dwordx2 v[22:23], v[20:21], off
	v_lshlrev_b32_e32 v20, 16, v44
	v_mul_f32_e32 v25, 0xbfb8aa3b, v20
	v_exp_f32_e32 v26, v25
	v_mul_f32_e32 v25, 0xbfb8aa3b, v24
	v_exp_f32_e32 v27, v25
	v_lshlrev_b32_e32 v21, 16, v45
	v_and_b32_e32 v25, 0xffff0000, v45
	v_add_f32_e32 v26, 1.0, v26
	v_add_f32_e32 v27, 1.0, v27
	v_rcp_f32_e32 v32, v27
	v_mul_f32_e32 v27, 0xbfb8aa3b, v21
	v_exp_f32_e32 v27, v27
	v_mov_b32_e32 v44, v28
	v_mul_f32_e32 v28, 0xbfb8aa3b, v25
	v_rcp_f32_e32 v26, v26
	v_add_f32_e32 v27, 1.0, v27
	v_rcp_f32_e32 v27, v27
	v_exp_f32_e32 v28, v28
	v_mov_b32_e32 v45, v30
	v_pk_mul_f32 v[44:45], v[44:45], v[34:35] op_sel_hi:[1,0]
	v_pk_mul_f32 v[20:21], v[26:27], v[20:21]
	v_add_f32_e32 v26, 1.0, v28
	v_rcp_f32_e32 v33, v26
	v_mov_b32_e32 v30, v29
	v_pk_mul_f32 v[44:45], v[2:3], v[44:45]
	v_pk_mul_f32 v[26:27], v[30:31], v[34:35] op_sel_hi:[1,0]
	v_pk_mul_f32 v[20:21], v[20:21], v[44:45]
	v_pk_mul_f32 v[26:27], v[38:39], v[26:27]
	v_pk_mul_f32 v[24:25], v[32:33], v[24:25]
	s_waitcnt vmcnt(5)
	v_mov_b64_e32 v[30:31], v[14:15]
	v_pk_mul_f32 v[24:25], v[24:25], v[26:27]
	v_and_b32_sdwa v26, v21, v68 dst_sel:DWORD dst_unused:UNUSED_PAD src0_sel:WORD_1 src1_sel:DWORD
	v_and_b32_sdwa v27, v20, v68 dst_sel:DWORD dst_unused:UNUSED_PAD src0_sel:WORD_1 src1_sel:DWORD
	v_add3_u32 v20, v20, v27, s11
	v_add3_u32 v21, v21, v26, s11
	v_and_b32_sdwa v26, v25, v68 dst_sel:DWORD dst_unused:UNUSED_PAD src0_sel:WORD_1 src1_sel:DWORD
	v_and_b32_sdwa v27, v24, v68 dst_sel:DWORD dst_unused:UNUSED_PAD src0_sel:WORD_1 src1_sel:DWORD
	v_add3_u32 v25, v25, v26, s11
	v_add3_u32 v24, v24, v27, s11
	v_and_b32_e32 v25, 0xffff0000, v25
	v_and_b32_e32 v24, 0xffff0000, v24
	v_or_b32_sdwa v21, v25, v21 dst_sel:DWORD dst_unused:UNUSED_PAD src0_sel:DWORD src1_sel:WORD_1
	v_or_b32_sdwa v20, v24, v20 dst_sel:DWORD dst_unused:UNUSED_PAD src0_sel:DWORD src1_sel:WORD_1
	global_store_dwordx2 v[22:23], v[20:21], off offset:2048
	v_mov_b64_e32 v[22:23], v[6:7]
	v_mov_b64_e32 v[26:27], v[10:11]
	s_waitcnt vmcnt(5)
	v_mov_b64_e32 v[34:35], v[18:19]
	v_lshl_add_u64 v[46:47], v[46:47], 0, s[20:21]
	v_lshl_add_u64 v[48:49], v[48:49], 0, s[20:21]
	v_lshl_add_u64 v[50:51], v[50:51], 0, s[22:23]
	s_andn2_b64 vcc, exec, s[26:27]
	v_mov_b64_e32 v[20:21], v[4:5]
	v_mov_b64_e32 v[24:25], v[8:9]
	v_mov_b64_e32 v[28:29], v[12:13]
	v_mov_b64_e32 v[32:33], v[16:17]
	s_waitcnt vmcnt(4)
	v_mov_b64_e32 v[60:61], v[54:55]
	s_waitcnt vmcnt(3)
	v_mov_b64_e32 v[58:59], v[52:53]
	s_waitcnt vmcnt(2)
	v_mov_b64_e32 v[44:45], v[56:57]
	s_cbranch_vccz .LBB0_4053

.LBB0_4057:
	v_pk_add_f32 v[28:29], v[28:29], v[32:33]
	v_pk_add_f32 v[30:31], v[30:31], v[34:35]
	v_pk_mul_f32 v[34:35], v[28:29], v[28:29]
	v_pk_mul_f32 v[32:33], v[30:31], v[30:31]
	v_add_f32_e32 v34, v34, v35
	v_add_f32_e32 v32, v32, v34
	v_add_f32_e32 v32, v33, v32
	ds_bpermute_b32 v33, v1, v32
	v_pk_add_f32 v[22:23], v[22:23], v[26:27]
	v_pk_add_f32 v[20:21], v[20:21], v[24:25]
	v_lshlrev_b32_e32 v25, 16, v60
	v_mul_f32_e32 v25, 0xbfb8aa3b, v25
	s_waitcnt lgkmcnt(0)
	v_add_f32_e32 v26, v32, v33
	ds_bpermute_b32 v27, v62, v26
	v_exp_f32_e32 v25, v25
	v_lshlrev_b32_e32 v33, 16, v61
	v_and_b32_e32 v34, 0xffff0000, v61
	v_mul_f32_e32 v33, 0xbfb8aa3b, v33
	s_waitcnt lgkmcnt(0)
	v_add_f32_e32 v26, v26, v27
	ds_bpermute_b32 v27, v63, v26
	v_add_f32_e32 v25, 1.0, v25
	v_mul_f32_e32 v34, 0xbfb8aa3b, v34
	v_exp_f32_e32 v33, v33
	v_exp_f32_e32 v34, v34
	s_waitcnt lgkmcnt(0)
	v_add_f32_e32 v26, v26, v27
	ds_bpermute_b32 v27, v64, v26
	v_add_f32_e32 v33, 1.0, v33
	v_add_f32_e32 v34, 1.0, v34
	v_lshlrev_b32_e32 v24, 16, v58
	v_and_b32_e32 v58, 0xffff0000, v58
	s_waitcnt lgkmcnt(0)
	v_add_f32_e32 v26, v26, v27
	ds_bpermute_b32 v27, v65, v26
	v_and_b32_e32 v32, 0xffff0000, v60
	v_mul_f32_e32 v60, 0xbfb8aa3b, v58
	v_exp_f32_e32 v61, v60
	v_mov_b32_e32 v72, v20
	s_waitcnt lgkmcnt(0)
	v_add_f32_e32 v27, v26, v27
	ds_bpermute_b32 v35, v66, v27
	v_rcp_f32_e32 v26, v25
	v_add_f32_e32 v61, 1.0, v61
	v_mul_f32_e32 v32, 0xbfb8aa3b, v32
	v_rcp_f32_e32 v70, v61
	s_waitcnt lgkmcnt(0)
	v_add_f32_e32 v25, v27, v35
	v_fmamk_f32 v25, v25, 0x3b800000, v67
	v_mul_f32_e32 v27, 0x4b800000, v25
	v_cmp_gt_f32_e32 vcc, s10, v25
	v_exp_f32_e32 v32, v32
	v_mov_b32_e32 v73, v22
	v_cndmask_b32_e32 v25, v25, v27, vcc
	v_rsq_f32_e32 v25, v25
	v_rcp_f32_e32 v27, v33
	v_rcp_f32_e32 v33, v34
	v_add_f32_e32 v32, 1.0, v32
	v_mul_f32_e32 v34, 0x45800000, v25
	v_cndmask_b32_e32 v34, v25, v34, vcc
	v_mul_f32_e32 v25, 0xbfb8aa3b, v24
	v_exp_f32_e32 v35, v25
	v_lshlrev_b32_e32 v25, 16, v59
	v_and_b32_e32 v59, 0xffff0000, v59
	v_rcp_f32_e32 v32, v32
	v_add_f32_e32 v35, 1.0, v35
	v_rcp_f32_e32 v60, v35
	v_mul_f32_e32 v35, 0xbfb8aa3b, v25
	v_exp_f32_e32 v35, v35
	v_pk_mul_f32 v[26:27], v[72:73], v[26:27]
	v_mov_b32_e32 v22, v21
	s_addk_i32 s20, 0x80
	v_add_f32_e32 v20, 1.0, v35
	v_rcp_f32_e32 v61, v20
	v_mul_f32_e32 v20, 0xbfb8aa3b, v59
	v_exp_f32_e32 v20, v20
	v_lshl_add_u64 v[40:41], v[40:41], 0, s[0:1]
	v_pk_mul_f32 v[24:25], v[60:61], v[24:25]
	v_lshl_add_u64 v[44:45], v[44:45], 0, s[22:23]
	v_add_f32_e32 v20, 1.0, v20
	v_rcp_f32_e32 v71, v20
	v_pk_mul_f32 v[24:25], v[26:27], v[24:25]
	v_pk_mul_f32 v[20:21], v[22:23], v[32:33]
	v_lshl_add_u64 v[46:47], v[46:47], 0, s[22:23]
	v_pk_mul_f32 v[22:23], v[70:71], v[58:59]
	s_waitcnt vmcnt(2)
	v_mov_b64_e32 v[60:61], v[54:55]
	v_pk_mul_f32 v[20:21], v[20:21], v[22:23]
	s_nop 0
	v_and_b32_sdwa v23, v24, v68 dst_sel:DWORD dst_unused:UNUSED_PAD src0_sel:WORD_1 src1_sel:DWORD
	v_add3_u32 v23, v24, v23, s11
	s_nop 0
	v_cvt_pk_bf16_f32 v21, v25, v21
	v_and_b32_sdwa v25, v20, v68 dst_sel:DWORD dst_unused:UNUSED_PAD src0_sel:WORD_1 src1_sel:DWORD
	s_nop 0
	v_add3_u32 v20, v20, v25, s11
	s_nop 0
	v_and_b32_e32 v20, 0xffff0000, v20
	s_nop 0
	v_or_b32_sdwa v20, v20, v23 dst_sel:DWORD dst_unused:UNUSED_PAD src0_sel:DWORD src1_sel:WORD_1
	v_lshl_add_u64 v[22:23], v[50:51], 0, v[36:37]
	v_add_co_u32_e32 v22, vcc, s3, v22
	v_and_b32_e32 v24, 0xffff0000, v48
	s_nop 0
	v_addc_co_u32_e32 v23, vcc, 0, v23, vcc
	global_store_dwordx2 v[22:23], v[20:21], off
	v_lshlrev_b32_e32 v20, 16, v48
	v_mul_f32_e32 v25, 0xbfb8aa3b, v20
	v_exp_f32_e32 v26, v25
	v_mul_f32_e32 v25, 0xbfb8aa3b, v24
	v_exp_f32_e32 v27, v25
	v_lshlrev_b32_e32 v21, 16, v49
	v_and_b32_e32 v25, 0xffff0000, v49
	v_add_f32_e32 v26, 1.0, v26
	v_add_f32_e32 v27, 1.0, v27
	v_rcp_f32_e32 v32, v27
	v_mul_f32_e32 v27, 0xbfb8aa3b, v21
	v_exp_f32_e32 v27, v27
	v_mov_b32_e32 v48, v28
	v_mul_f32_e32 v28, 0xbfb8aa3b, v25
	v_rcp_f32_e32 v26, v26
	v_add_f32_e32 v27, 1.0, v27
	v_rcp_f32_e32 v27, v27
	v_exp_f32_e32 v28, v28
	v_mov_b32_e32 v49, v30
	v_pk_mul_f32 v[48:49], v[48:49], v[34:35] op_sel_hi:[1,0]
	v_pk_mul_f32 v[20:21], v[26:27], v[20:21]
	v_add_f32_e32 v26, 1.0, v28
	v_rcp_f32_e32 v33, v26
	v_mov_b32_e32 v30, v29
	v_pk_mul_f32 v[48:49], v[2:3], v[48:49]
	v_pk_mul_f32 v[26:27], v[30:31], v[34:35] op_sel_hi:[1,0]
	v_pk_mul_f32 v[20:21], v[20:21], v[48:49]
	v_pk_mul_f32 v[26:27], v[38:39], v[26:27]
	v_pk_mul_f32 v[24:25], v[32:33], v[24:25]
	v_mov_b64_e32 v[30:31], v[14:15]
	v_pk_mul_f32 v[24:25], v[24:25], v[26:27]
	v_and_b32_sdwa v26, v21, v68 dst_sel:DWORD dst_unused:UNUSED_PAD src0_sel:WORD_1 src1_sel:DWORD
	v_and_b32_sdwa v27, v20, v68 dst_sel:DWORD dst_unused:UNUSED_PAD src0_sel:WORD_1 src1_sel:DWORD
	v_add3_u32 v20, v20, v27, s11
	v_add3_u32 v21, v21, v26, s11
	v_and_b32_sdwa v26, v25, v68 dst_sel:DWORD dst_unused:UNUSED_PAD src0_sel:WORD_1 src1_sel:DWORD
	v_and_b32_sdwa v27, v24, v68 dst_sel:DWORD dst_unused:UNUSED_PAD src0_sel:WORD_1 src1_sel:DWORD
	v_add3_u32 v25, v25, v26, s11
	v_add3_u32 v24, v24, v27, s11
	v_and_b32_e32 v25, 0xffff0000, v25
	v_and_b32_e32 v24, 0xffff0000, v24
	v_or_b32_sdwa v21, v25, v21 dst_sel:DWORD dst_unused:UNUSED_PAD src0_sel:DWORD src1_sel:WORD_1
	v_or_b32_sdwa v20, v24, v20 dst_sel:DWORD dst_unused:UNUSED_PAD src0_sel:DWORD src1_sel:WORD_1
	global_store_dwordx2 v[22:23], v[20:21], off offset:2048
	v_mov_b64_e32 v[22:23], v[6:7]
	v_mov_b64_e32 v[26:27], v[10:11]
	v_mov_b64_e32 v[34:35], v[18:19]
	v_lshl_add_u64 v[50:51], v[50:51], 0, s[26:27]
	s_and_b64 vcc, exec, s[34:35]
	v_mov_b64_e32 v[20:21], v[4:5]
	v_mov_b64_e32 v[24:25], v[8:9]
	v_mov_b64_e32 v[28:29], v[12:13]
	v_mov_b64_e32 v[32:33], v[16:17]
	s_waitcnt vmcnt(3)
	v_mov_b64_e32 v[58:59], v[52:53]
	s_waitcnt vmcnt(2)
	v_mov_b64_e32 v[48:49], v[56:57]
	s_cbranch_vccnz .LBB0_4060

.LBB0_4064:
	v_pk_add_f32 v[28:29], v[28:29], v[32:33]
	v_pk_add_f32 v[30:31], v[30:31], v[34:35]
	v_pk_mul_f32 v[34:35], v[28:29], v[28:29]
	v_pk_mul_f32 v[32:33], v[30:31], v[30:31]
	v_add_f32_e32 v34, v34, v35
	v_add_f32_e32 v32, v32, v34
	v_add_f32_e32 v32, v33, v32
	ds_bpermute_b32 v33, v1, v32
	v_pk_add_f32 v[22:23], v[22:23], v[26:27]
	v_pk_add_f32 v[20:21], v[20:21], v[24:25]
	v_lshlrev_b32_e32 v25, 16, v60
	v_mul_f32_e32 v25, 0xbfb8aa3b, v25
	s_waitcnt lgkmcnt(0)
	v_add_f32_e32 v26, v32, v33
	ds_bpermute_b32 v27, v62, v26
	v_and_b32_e32 v32, 0xffff0000, v60
	v_exp_f32_e32 v25, v25
	v_lshlrev_b32_e32 v33, 16, v61
	v_and_b32_e32 v34, 0xffff0000, v61
	s_waitcnt lgkmcnt(0)
	v_add_f32_e32 v26, v26, v27
	ds_bpermute_b32 v27, v63, v26
	v_add_f32_e32 v25, 1.0, v25
	v_mul_f32_e32 v33, 0xbfb8aa3b, v33
	v_mul_f32_e32 v34, 0xbfb8aa3b, v34
	v_lshlrev_b32_e32 v24, 16, v58
	s_waitcnt lgkmcnt(0)
	v_add_f32_e32 v26, v26, v27
	ds_bpermute_b32 v27, v64, v26
	v_exp_f32_e32 v33, v33
	v_exp_f32_e32 v34, v34
	v_mul_f32_e32 v35, 0xbfb8aa3b, v24
	v_exp_f32_e32 v35, v35
	s_waitcnt lgkmcnt(0)
	v_add_f32_e32 v26, v26, v27
	ds_bpermute_b32 v27, v65, v26
	v_add_f32_e32 v33, 1.0, v33
	v_add_f32_e32 v34, 1.0, v34
	v_and_b32_e32 v58, 0xffff0000, v58
	v_add_f32_e32 v35, 1.0, v35
	s_waitcnt lgkmcnt(0)
	v_add_f32_e32 v27, v26, v27
	ds_bpermute_b32 v60, v66, v27
	v_rcp_f32_e32 v26, v25
	v_mov_b32_e32 v72, v20
	v_mul_f32_e32 v32, 0xbfb8aa3b, v32
	v_exp_f32_e32 v32, v32
	s_waitcnt lgkmcnt(0)
	v_add_f32_e32 v25, v27, v60
	v_fmamk_f32 v25, v25, 0x3b800000, v67
	v_mul_f32_e32 v27, 0x4b800000, v25
	v_cmp_gt_f32_e32 vcc, s11, v25
	v_mul_f32_e32 v60, 0xbfb8aa3b, v58
	v_exp_f32_e32 v61, v60
	v_cndmask_b32_e32 v25, v25, v27, vcc
	v_rsq_f32_e32 v25, v25
	v_rcp_f32_e32 v27, v33
	v_rcp_f32_e32 v33, v34
	v_rcp_f32_e32 v60, v35
	v_mul_f32_e32 v34, 0x45800000, v25
	v_cndmask_b32_e32 v34, v25, v34, vcc
	v_lshlrev_b32_e32 v25, 16, v59
	v_mul_f32_e32 v35, 0xbfb8aa3b, v25
	v_exp_f32_e32 v35, v35
	v_and_b32_e32 v59, 0xffff0000, v59
	v_add_f32_e32 v61, 1.0, v61
	v_rcp_f32_e32 v70, v61
	v_add_f32_e32 v20, 1.0, v35
	v_rcp_f32_e32 v61, v20
	v_mul_f32_e32 v20, 0xbfb8aa3b, v59
	v_exp_f32_e32 v20, v20
	v_add_f32_e32 v32, 1.0, v32
	v_rcp_f32_e32 v32, v32
	v_mov_b32_e32 v73, v22
	v_add_f32_e32 v20, 1.0, v20
	v_rcp_f32_e32 v71, v20
	v_pk_mul_f32 v[26:27], v[72:73], v[26:27]
	v_pk_mul_f32 v[24:25], v[60:61], v[24:25]
	v_mov_b32_e32 v22, v21
	v_pk_mul_f32 v[24:25], v[26:27], v[24:25]
	v_pk_mul_f32 v[20:21], v[22:23], v[32:33]
	v_pk_mul_f32 v[22:23], v[70:71], v[58:59]
	s_add_i32 s20, s20, s22
	v_pk_mul_f32 v[20:21], v[20:21], v[22:23]
	s_nop 0
	v_and_b32_sdwa v23, v24, v68 dst_sel:DWORD dst_unused:UNUSED_PAD src0_sel:WORD_1 src1_sel:DWORD
	v_add3_u32 v23, v24, v23, s12
	s_nop 0
	v_cvt_pk_bf16_f32 v21, v25, v21
	v_and_b32_sdwa v25, v20, v68 dst_sel:DWORD dst_unused:UNUSED_PAD src0_sel:WORD_1 src1_sel:DWORD
	s_nop 0
	v_add3_u32 v20, v20, v25, s12
	s_nop 0
	v_and_b32_e32 v20, 0xffff0000, v20
	s_nop 0
	v_or_b32_sdwa v20, v20, v23 dst_sel:DWORD dst_unused:UNUSED_PAD src0_sel:DWORD src1_sel:WORD_1
	v_lshl_add_u64 v[22:23], v[50:51], 0, v[36:37]
	v_add_co_u32_e32 v22, vcc, s10, v22
	v_and_b32_e32 v24, 0xffff0000, v44
	s_nop 0
	v_addc_co_u32_e32 v23, vcc, 0, v23, vcc
	global_store_dwordx2 v[22:23], v[20:21], off
	v_lshlrev_b32_e32 v20, 16, v44
	v_mul_f32_e32 v25, 0xbfb8aa3b, v20
	v_exp_f32_e32 v26, v25
	v_mul_f32_e32 v25, 0xbfb8aa3b, v24
	v_exp_f32_e32 v27, v25
	v_lshlrev_b32_e32 v21, 16, v45
	v_and_b32_e32 v25, 0xffff0000, v45
	v_add_f32_e32 v26, 1.0, v26
	v_add_f32_e32 v27, 1.0, v27
	v_rcp_f32_e32 v32, v27
	v_mul_f32_e32 v27, 0xbfb8aa3b, v21
	v_exp_f32_e32 v27, v27
	v_mov_b32_e32 v44, v28
	v_mul_f32_e32 v28, 0xbfb8aa3b, v25
	v_rcp_f32_e32 v26, v26
	v_add_f32_e32 v27, 1.0, v27
	v_rcp_f32_e32 v27, v27
	v_exp_f32_e32 v28, v28
	v_mov_b32_e32 v45, v30
	v_pk_mul_f32 v[44:45], v[44:45], v[34:35] op_sel_hi:[1,0]
	v_pk_mul_f32 v[20:21], v[26:27], v[20:21]
	v_add_f32_e32 v26, 1.0, v28
	v_rcp_f32_e32 v33, v26
	v_mov_b32_e32 v30, v29
	v_pk_mul_f32 v[44:45], v[2:3], v[44:45]
	v_pk_mul_f32 v[26:27], v[30:31], v[34:35] op_sel_hi:[1,0]
	v_pk_mul_f32 v[20:21], v[20:21], v[44:45]
	v_pk_mul_f32 v[26:27], v[38:39], v[26:27]
	v_pk_mul_f32 v[24:25], v[32:33], v[24:25]
	s_waitcnt vmcnt(5)
	v_mov_b64_e32 v[30:31], v[14:15]
	v_pk_mul_f32 v[24:25], v[24:25], v[26:27]
	v_and_b32_sdwa v26, v21, v68 dst_sel:DWORD dst_unused:UNUSED_PAD src0_sel:WORD_1 src1_sel:DWORD
	v_and_b32_sdwa v27, v20, v68 dst_sel:DWORD dst_unused:UNUSED_PAD src0_sel:WORD_1 src1_sel:DWORD
	v_add3_u32 v20, v20, v27, s12
	v_add3_u32 v21, v21, v26, s12
	v_and_b32_sdwa v26, v25, v68 dst_sel:DWORD dst_unused:UNUSED_PAD src0_sel:WORD_1 src1_sel:DWORD
	v_and_b32_sdwa v27, v24, v68 dst_sel:DWORD dst_unused:UNUSED_PAD src0_sel:WORD_1 src1_sel:DWORD
	v_add3_u32 v25, v25, v26, s12
	v_add3_u32 v24, v24, v27, s12
	v_and_b32_e32 v25, 0xffff0000, v25
	v_and_b32_e32 v24, 0xffff0000, v24
	v_or_b32_sdwa v21, v25, v21 dst_sel:DWORD dst_unused:UNUSED_PAD src0_sel:DWORD src1_sel:WORD_1
	v_or_b32_sdwa v20, v24, v20 dst_sel:DWORD dst_unused:UNUSED_PAD src0_sel:DWORD src1_sel:WORD_1
	global_store_dwordx2 v[22:23], v[20:21], off offset:2048
	v_mov_b64_e32 v[22:23], v[6:7]
	v_mov_b64_e32 v[26:27], v[10:11]
	s_waitcnt vmcnt(5)
	v_mov_b64_e32 v[34:35], v[18:19]
	v_lshl_add_u64 v[40:41], v[40:41], 0, s[0:1]
	v_lshl_add_u64 v[46:47], v[46:47], 0, s[4:5]
	v_lshl_add_u64 v[48:49], v[48:49], 0, s[4:5]
	v_lshl_add_u64 v[50:51], v[50:51], 0, s[8:9]
	s_cmp_ge_i32 s20, s3
	v_mov_b64_e32 v[20:21], v[4:5]
	v_mov_b64_e32 v[24:25], v[8:9]
	v_mov_b64_e32 v[28:29], v[12:13]
	v_mov_b64_e32 v[32:33], v[16:17]
	s_waitcnt vmcnt(4)
	v_mov_b64_e32 v[60:61], v[54:55]
	s_waitcnt vmcnt(3)
	v_mov_b64_e32 v[58:59], v[52:53]
	s_waitcnt vmcnt(2)
	v_mov_b64_e32 v[44:45], v[56:57]
	s_cbranch_scc1 .LBB0_4067
